# instruction selection: all compiler-emitted v_pk_mul/add/fma_f32 split into scalar f32 pairs (packed f32 costs ~16 cycles here); otherwise v8
# speedup vs baseline: 1.0022x; 1.0022x over previous
; #define GAS __attribute__((address_space(1)))
; __device__ __forceinline__ unsigned cvt_pk_bf16(float lo, float hi) { unsigned r; asm("v_cvt_pk_bf16_f32 %0, %1, %2" : "=v"(r) : "v"(lo), "v"(hi)); return r; }
; __device__ __forceinline__ float wave_sum(float v) { return sum_x32(sum_row32(v)); }
; __device__ __forceinline__ void rms_phase(const gfl* x, const gfl* g, gbf* out, int gw, int NGW, int lane) {
;     ...
;     for (int m = gw; m < MG; m += NGW) {
;         const int mn = m + NGW < MG ? m + NGW : m;
;         { const GAS f32x4* xr = (const GAS f32x4*)(x + (size_t)mn * DM) + lane;
; #pragma unroll
;           for (int j = 0; j < 4; ++j) vn[j] = xr[64 * j]; }
;         float s = 0.f;
; #pragma unroll
;         for (int j = 0; j < 4; ++j) s += (v[j].x * v[j].x + v[j].y * v[j].y) + (v[j].z * v[j].z + v[j].w * v[j].w);
;         const float rstd = __builtin_amdgcn_rsqf(wave_sum(s) * (1.f / DM) + EPS);
;         GAS unsigned long long* o8 = (GAS unsigned long long*)(out + (size_t)m * DM) + lane;
; #pragma unroll
;         for (int j = 0; j < 4; ++j) { const f32x4 w = v[j] * rstd * gv[j]; o8[64 * j] = (unsigned long long)cvt_pk_bf16(w.x, w.y) | ((unsigned long long)cvt_pk_bf16(w.z, w.w) << 32); }
; #pragma unroll
;         for (int j = 0; j < 4; ++j) v[j] = vn[j];
;     }
.LBB0_130:
	s_add_i32 s2, s8, s4
	s_cmp_lt_i32 s2, 0x10000
	s_cselect_b64 s[0:1], -1, 0
	s_waitcnt vmcnt(1)
	v_mul_f32_e32 v41, v23, v23
	v_mul_f32_e32 v42, v25, v25
	s_waitcnt vmcnt(0)
	v_mul_f32_e32 v43, v31, v31
	v_mul_f32_e32 v44, v33, v33
	s_and_b64 vcc, s[0:1], exec
	v_mul_f32_e32 v45, v27, v27
	v_mul_f32_e32 v46, v29, v29
	v_mul_f32_e32 v39, v39, v39
	v_mul_f32_e32 v40, v40, v40
	v_fmac_f32_e32 v41, v22, v22
	v_fmac_f32_e32 v42, v24, v24
	v_fmac_f32_e32 v43, v30, v30
	v_fmac_f32_e32 v44, v32, v32
	s_cselect_b32 s10, s2, s8
	v_fmac_f32_e32 v45, v26, v26
	v_fmac_f32_e32 v46, v28, v28
	v_fmac_f32_e32 v39, v0, v0
	v_fmac_f32_e32 v40, v38, v38
	v_add_f32_e32 v0, v41, v42
	v_add_f32_e32 v38, v43, v44
	s_ashr_i32 s11, s10, 31
	v_add_f32_e32 v41, v45, v46
	v_add_f32_e32 v0, v0, v38
	s_lshl_b64 s[0:1], s[10:11], 12
	v_add_f32_e32 v39, v39, v40
	v_add_f32_e32 v0, v41, v0
	v_lshl_add_u64 v[50:51], v[34:35], 0, s[0:1]
	v_add_f32_e32 v0, v39, v0
	global_load_dwordx4 v[38:41], v[50:51], off offset:3072
	global_load_dwordx4 v[42:45], v[50:51], off
	global_load_dwordx4 v[46:49], v[50:51], off offset:1024
	s_nop 0
	global_load_dwordx4 v[50:53], v[50:51], off offset:2048
	ds_swizzle_b32 v54, v0 offset:swizzle(SWAP,1)
	s_mov_b32 s8, s2
	s_waitcnt lgkmcnt(0)
	v_add_f32_e32 v0, v0, v54
	ds_swizzle_b32 v54, v0 offset:swizzle(SWAP,2)
	s_waitcnt lgkmcnt(0)
	v_add_f32_e32 v0, v0, v54
	ds_swizzle_b32 v54, v0 offset:swizzle(SWAP,4)
	s_waitcnt lgkmcnt(0)
	v_add_f32_e32 v0, v0, v54
	ds_swizzle_b32 v54, v0 offset:swizzle(SWAP,8)
	s_waitcnt lgkmcnt(0)
	v_add_f32_e32 v0, v0, v54
	ds_swizzle_b32 v54, v0 offset:swizzle(SWAP,16)
	s_waitcnt lgkmcnt(0)
	v_add_f32_e32 v0, v0, v54
	v_mov_b32_e32 v54, v0
	s_nop 1
	v_permlane32_swap_b32_e32 v0, v54
	v_add_f32_e32 v0, v0, v54
	v_fmamk_f32 v0, v0, 0x3a800000, v218
	v_rsq_f32_e32 v0, v0
	s_nop 0
	v_mul_f32_e32 v22, v22, v0
	v_mul_f32_e32 v23, v23, v0
	v_mul_f32_e32 v18, v18, v0
	v_mul_f32_e32 v19, v19, v0
	v_mul_f32_e32 v24, v24, v0
	v_mul_f32_e32 v25, v25, v0
	v_mul_f32_e32 v26, v26, v0
	v_mul_f32_e32 v27, v27, v0
	v_mul_f32_e32 v20, v20, v0
	v_mul_f32_e32 v21, v21, v0
	v_mul_f32_e32 v22, v2, v22
	v_mul_f32_e32 v23, v3, v23
	v_mul_f32_e32 v18, v14, v18
	v_mul_f32_e32 v19, v15, v19
	v_mul_f32_e32 v30, v30, v0
	v_mul_f32_e32 v31, v31, v0
	v_mul_f32_e32 v32, v32, v0
	v_mul_f32_e32 v33, v33, v0
	v_mul_f32_e32 v28, v28, v0
	v_mul_f32_e32 v29, v29, v0
	v_mul_f32_e32 v24, v4, v24
	v_mul_f32_e32 v25, v5, v25
	v_mul_f32_e32 v26, v10, v26
	v_mul_f32_e32 v27, v11, v27
	v_mul_f32_e32 v20, v16, v20
	v_mul_f32_e32 v21, v17, v21
	v_cvt_pk_bf16_f32 v22, v22, v23
	v_cvt_pk_bf16_f32 v23, v24, v25
	v_cvt_pk_bf16_f32 v18, v18, v19
	v_mul_f32_e32 v32, v8, v32
	v_mul_f32_e32 v33, v9, v33
	v_cvt_pk_bf16_f32 v19, v20, v21
	v_mul_f32_e32 v30, v6, v30
	v_mul_f32_e32 v31, v7, v31
	v_mul_f32_e32 v28, v12, v28
	v_mul_f32_e32 v29, v13, v29
	v_cvt_pk_bf16_f32 v24, v30, v31
	v_cvt_pk_bf16_f32 v25, v32, v33
	v_cvt_pk_bf16_f32 v26, v26, v27
	s_waitcnt vmcnt(3)
	v_mov_b32_e32 v0, v38
	v_cvt_pk_bf16_f32 v27, v28, v29
	global_store_dwordx2 v[36:37], v[22:23], off offset:-1024
	global_store_dwordx2 v[36:37], v[24:25], off offset:-512
	global_store_dwordx2 v[36:37], v[26:27], off
	global_store_dwordx2 v[36:37], v[18:19], off offset:512
	v_mov_b64_e32 v[18:19], v[38:39]
	v_lshl_add_u64 v[36:37], v[36:37], 0, s[6:7]
	v_mov_b64_e32 v[20:21], v[40:41]
	s_waitcnt vmcnt(6)
	v_mov_b32_e32 v22, v42
	v_mov_b32_e32 v23, v43
	v_mov_b32_e32 v24, v44
	v_mov_b32_e32 v25, v45
	s_waitcnt vmcnt(5)
	v_mov_b32_e32 v30, v46
	v_mov_b32_e32 v31, v47
	v_mov_b32_e32 v32, v48
	v_mov_b32_e32 v33, v49
	s_waitcnt vmcnt(4)
	v_mov_b32_e32 v26, v50
	v_mov_b32_e32 v27, v51
	v_mov_b32_e32 v28, v52
	v_mov_b32_e32 v29, v53
	v_mov_b32_e32 v38, v40
	v_mov_b32_e32 v40, v41
	s_cbranch_vccnz .LBB0_130

; #define GAS __attribute__((address_space(1)))
; __device__ __forceinline__ unsigned cvt_pk_bf16(float lo, float hi) { unsigned r; asm("v_cvt_pk_bf16_f32 %0, %1, %2" : "=v"(r) : "v"(lo), "v"(hi)); return r; }
; template <int M> __device__ __forceinline__ float swz_xor(float v) { return __int_as_float(__builtin_amdgcn_ds_swizzle(__float_as_int(v), 0x1f | (M << 10))); }
; __device__ __forceinline__ float sum_x32(float v) { auto rr = __builtin_amdgcn_permlane32_swap(__float_as_uint(v), __float_as_uint(v), false, false); return __uint_as_float(rr[0]) + __uint_as_float(rr[1]); }
;     __device__ __forceinline__ void operator()(const f32x4 (&acc)[2][2][4][2], const Unit& u, int wr, int wc, int fr, int fq) const {
;     ...
;         for (int ai = 0; ai < 2; ++ai)
; #pragma unroll
;             for (int m = 0; m < 4; ++m) { const int row = row0 + ai * HALF + m * 16; gbf* rowp = O + (size_t)row * ldc + col0;
;                 const float rs = rsv[ai][m];
; #pragma unroll
;                 for (int bj = 0; bj < 2; ++bj) { const f32x4 v0 = acc[ai][bj][m][0] * rs, v1 = acc[ai][bj][m][1] * rs;
;                     u32x4 w; w.x = cvt_pk_bf16(v0[0], v0[1]); w.y = cvt_pk_bf16(v0[2], v0[3]); w.z = cvt_pk_bf16(v1[0], v1[1]); w.w = cvt_pk_bf16(v1[2], v1[3]);
;                     *(GAS u32x4*)(rowp + bj * HALF) = w;
;                     if (ktile) { float q = (v0[0] * v0[0] + v0[1] * v0[1]) + (v0[2] * v0[2] + v0[3] * v0[3]) + (v1[0] * v1[0] + v1[1] * v1[1]) + (v1[2] * v1[2] + v1[3] * v1[3]);
;                         q += swz_xor<16>(q); q = sum_x32(q); mxsq[bj] = __builtin_fmaxf(mxsq[bj], q); } } }
.LBB0_157:
	s_and_b32 s10, s76, -2
	s_cmp_eq_u32 s10, 2
	v_lshl_or_b32 v152, s76, 8, v166
	s_cselect_b64 s[28:29], -1, 0
	s_cmp_lg_u32 s10, 2
	v_mov_b64_e32 v[162:163], s[12:13]
	s_movk_i32 s10, 0x1e00
	v_ashrrev_i32_e32 v153, 31, v152
	v_mad_i64_i32 v[162:163], s[10:11], v142, s10, v[162:163]
	v_lshl_add_u64 v[162:163], v[152:153], 1, v[162:163]
	v_mul_f32_e32 v128, v128, v160
	v_mul_f32_e32 v129, v129, v160
	v_mul_f32_e32 v126, v126, v160
	v_mul_f32_e32 v127, v127, v160
	v_mul_f32_e32 v124, v124, v160
	v_mul_f32_e32 v125, v125, v160
	v_mul_f32_e32 v122, v122, v160
	v_mul_f32_e32 v123, v123, v160
	v_readlane_b32 s95, v254, 54
	v_cvt_pk_bf16_f32 v168, v126, v127
	v_cvt_pk_bf16_f32 v169, v128, v129
	v_cvt_pk_bf16_f32 v170, v122, v123
	v_cvt_pk_bf16_f32 v171, v124, v125
	global_store_dwordx4 v[162:163], v[168:171], off
	s_cbranch_scc1 .LBB0_159
	v_mul_f32_e32 v128, v128, v128
	v_mul_f32_e32 v129, v129, v129
	v_mul_f32_e32 v126, v126, v126
	v_mul_f32_e32 v127, v127, v127
	v_mov_b32_e32 v169, v129
	v_mov_b32_e32 v168, v126
	v_pk_mov_b32 v[126:127], v[126:127], v[128:129] op_sel:[1,0]
	v_mul_f32_e32 v124, v124, v124
	v_mul_f32_e32 v125, v125, v125
	v_mul_f32_e32 v122, v122, v122
	v_mul_f32_e32 v123, v123, v123
	v_add_f32_e32 v126, v126, v168
	v_add_f32_e32 v127, v127, v169
	v_mov_b32_e32 v128, v124
	v_mov_b32_e32 v129, v122
	v_mov_b32_e32 v122, v125
	v_add_f32_e32 v122, v128, v122
	v_add_f32_e32 v123, v129, v123
	v_add_f32_e32 v0, v126, v127
	v_add_f32_e32 v0, v123, v0
	v_add_f32_e32 v0, v122, v0
	ds_swizzle_b32 v122, v0 offset:swizzle(SWAP,16)
	s_waitcnt lgkmcnt(0)
	v_add_f32_e32 v0, v0, v122
	v_mov_b32_e32 v122, v0
	s_nop 1
	v_permlane32_swap_b32_e32 v0, v122
	v_add_f32_e32 v0, v0, v122
	v_max_f32_e32 v0, 0, v0
	s_branch .LBB0_160

; #define GAS __attribute__((address_space(1)))
; __device__ __forceinline__ unsigned cvt_pk_bf16(float lo, float hi) { unsigned r; asm("v_cvt_pk_bf16_f32 %0, %1, %2" : "=v"(r) : "v"(lo), "v"(hi)); return r; }
; template <int M> __device__ __forceinline__ float swz_xor(float v) { return __int_as_float(__builtin_amdgcn_ds_swizzle(__float_as_int(v), 0x1f | (M << 10))); }
; __device__ __forceinline__ float sum_x32(float v) { auto rr = __builtin_amdgcn_permlane32_swap(__float_as_uint(v), __float_as_uint(v), false, false); return __uint_as_float(rr[0]) + __uint_as_float(rr[1]); }
;     __device__ __forceinline__ void operator()(const f32x4 (&acc)[2][2][4][2], const Unit& u, int wr, int wc, int fr, int fq) const {
;     ...
;         for (int ai = 0; ai < 2; ++ai)
; #pragma unroll
;             for (int m = 0; m < 4; ++m) { const int row = row0 + ai * HALF + m * 16; gbf* rowp = O + (size_t)row * ldc + col0;
;                 const float rs = rsv[ai][m];
; #pragma unroll
;                 for (int bj = 0; bj < 2; ++bj) { const f32x4 v0 = acc[ai][bj][m][0] * rs, v1 = acc[ai][bj][m][1] * rs;
;                     u32x4 w; w.x = cvt_pk_bf16(v0[0], v0[1]); w.y = cvt_pk_bf16(v0[2], v0[3]); w.z = cvt_pk_bf16(v1[0], v1[1]); w.w = cvt_pk_bf16(v1[2], v1[3]);
;                     *(GAS u32x4*)(rowp + bj * HALF) = w;
;                     if (ktile) { float q = (v0[0] * v0[0] + v0[1] * v0[1]) + (v0[2] * v0[2] + v0[3] * v0[3]) + (v1[0] * v1[0] + v1[1] * v1[1]) + (v1[2] * v1[2] + v1[3] * v1[3]);
;                         q += swz_xor<16>(q); q = sum_x32(q); mxsq[bj] = __builtin_fmaxf(mxsq[bj], q); } } }
.LBB0_160:
	v_mov_b64_e32 v[122:123], v[0:1]
	v_mov_b32_e32 v161, v160
	v_mov_b32_e32 v124, v160
	v_mov_b32_e32 v125, v160
	v_cndmask_b32_e64 v0, 0, 1, s[28:29]
	v_mul_f32_e32 v120, v120, v124
	v_mul_f32_e32 v121, v121, v125
	v_mul_f32_e32 v118, v118, v160
	v_mul_f32_e32 v119, v119, v161
	v_mul_f32_e32 v116, v116, v124
	v_mul_f32_e32 v117, v117, v125
	v_mul_f32_e32 v114, v114, v160
	v_mul_f32_e32 v115, v115, v161
	v_cmp_ne_u32_e64 s[10:11], 1, v0
	s_andn2_b64 vcc, exec, s[28:29]
	v_cvt_pk_bf16_f32 v124, v118, v119
	v_cvt_pk_bf16_f32 v125, v120, v121
	v_cvt_pk_bf16_f32 v126, v114, v115
	v_cvt_pk_bf16_f32 v127, v116, v117
	global_store_dwordx4 v[162:163], v[124:127], off offset:256
	s_cbranch_vccnz .LBB0_162
	v_mul_f32_e32 v120, v120, v120
	v_mul_f32_e32 v121, v121, v121
	v_mul_f32_e32 v118, v118, v118
	v_mul_f32_e32 v119, v119, v119
	v_mov_b32_e32 v125, v121
	v_mov_b32_e32 v124, v118
	v_pk_mov_b32 v[118:119], v[118:119], v[120:121] op_sel:[1,0]
	v_mul_f32_e32 v116, v116, v116
	v_mul_f32_e32 v117, v117, v117
	v_mul_f32_e32 v114, v114, v114
	v_mul_f32_e32 v115, v115, v115
	v_add_f32_e32 v118, v118, v124
	v_add_f32_e32 v119, v119, v125
	v_mov_b32_e32 v120, v116
	v_mov_b32_e32 v121, v114
	v_mov_b32_e32 v114, v117
	v_add_f32_e32 v114, v120, v114
	v_add_f32_e32 v115, v121, v115
	v_add_f32_e32 v0, v118, v119
	v_add_f32_e32 v0, v115, v0
	v_add_f32_e32 v0, v114, v0
	ds_swizzle_b32 v114, v0 offset:swizzle(SWAP,16)
	s_waitcnt lgkmcnt(0)
	v_add_f32_e32 v0, v0, v114
	v_mov_b32_e32 v114, v0
	s_nop 1
	v_permlane32_swap_b32_e32 v0, v114
	v_add_f32_e32 v0, v0, v114
	v_max_f32_e32 v114, v123, v123
	v_max_f32_e32 v123, v114, v0
.LBB0_162:
	v_or_b32_e32 v0, 16, v142
	v_mov_b64_e32 v[114:115], s[12:13]
	s_movk_i32 s28, 0x1e00
	v_mad_i64_i32 v[114:115], s[28:29], v0, s28, v[114:115]
	v_lshl_add_u64 v[114:115], v[152:153], 1, v[114:115]
	v_mul_f32_e32 v112, v112, v158
	v_mul_f32_e32 v113, v113, v158
	v_mul_f32_e32 v110, v110, v158
	v_mul_f32_e32 v111, v111, v158
	v_mul_f32_e32 v108, v108, v158
	v_mul_f32_e32 v109, v109, v158
	v_mul_f32_e32 v106, v106, v158
	v_mul_f32_e32 v107, v107, v158
	s_and_b64 vcc, exec, s[10:11]
	v_cvt_pk_bf16_f32 v116, v110, v111
	v_cvt_pk_bf16_f32 v117, v112, v113
	v_cvt_pk_bf16_f32 v118, v106, v107
	v_cvt_pk_bf16_f32 v119, v108, v109
	global_store_dwordx4 v[114:115], v[116:119], off
	s_cbranch_vccnz .LBB0_164
	v_mul_f32_e32 v112, v112, v112
	v_mul_f32_e32 v113, v113, v113
	v_mul_f32_e32 v110, v110, v110
	v_mul_f32_e32 v111, v111, v111
	v_mov_b32_e32 v117, v113
	v_mov_b32_e32 v116, v110
	v_pk_mov_b32 v[110:111], v[110:111], v[112:113] op_sel:[1,0]
	v_mul_f32_e32 v108, v108, v108
	v_mul_f32_e32 v109, v109, v109
	v_mul_f32_e32 v106, v106, v106
	v_mul_f32_e32 v107, v107, v107
	v_add_f32_e32 v110, v110, v116
	v_add_f32_e32 v111, v111, v117
	v_mov_b32_e32 v112, v108
	v_mov_b32_e32 v113, v106
	v_mov_b32_e32 v106, v109
	v_add_f32_e32 v106, v112, v106
	v_add_f32_e32 v107, v113, v107
	v_add_f32_e32 v0, v110, v111
	v_add_f32_e32 v0, v107, v0
	v_add_f32_e32 v0, v106, v0
	ds_swizzle_b32 v106, v0 offset:swizzle(SWAP,16)
	s_waitcnt lgkmcnt(0)
	v_add_f32_e32 v0, v0, v106
	v_mov_b32_e32 v106, v0
	s_nop 1
	v_permlane32_swap_b32_e32 v0, v106
	v_add_f32_e32 v0, v0, v106
	v_max_f32_e32 v106, v122, v122
	v_max_f32_e32 v122, v106, v0
.LBB0_164:
	v_mov_b32_e32 v159, v158
	v_mov_b32_e32 v106, v158
	v_mov_b32_e32 v107, v158
	v_mul_f32_e32 v104, v104, v106
	v_mul_f32_e32 v105, v105, v107
	v_mul_f32_e32 v102, v102, v158
	v_mul_f32_e32 v103, v103, v159
	v_mul_f32_e32 v100, v100, v106
	v_mul_f32_e32 v101, v101, v107
	v_mul_f32_e32 v98, v98, v158
	v_mul_f32_e32 v99, v99, v159
	s_and_b64 vcc, exec, s[10:11]
	v_cvt_pk_bf16_f32 v106, v102, v103
	v_cvt_pk_bf16_f32 v107, v104, v105
	v_cvt_pk_bf16_f32 v108, v98, v99
	v_cvt_pk_bf16_f32 v109, v100, v101
	global_store_dwordx4 v[114:115], v[106:109], off offset:256
	s_cbranch_vccnz .LBB0_166
	v_mul_f32_e32 v104, v104, v104
	v_mul_f32_e32 v105, v105, v105
	v_mul_f32_e32 v102, v102, v102
	v_mul_f32_e32 v103, v103, v103
	v_mov_b32_e32 v107, v105
	v_mov_b32_e32 v106, v102
	v_pk_mov_b32 v[102:103], v[102:103], v[104:105] op_sel:[1,0]
	v_mul_f32_e32 v100, v100, v100
	v_mul_f32_e32 v101, v101, v101
	v_mul_f32_e32 v98, v98, v98
	v_mul_f32_e32 v99, v99, v99
	v_add_f32_e32 v102, v102, v106
	v_add_f32_e32 v103, v103, v107
	v_mov_b32_e32 v104, v100
	v_mov_b32_e32 v105, v98
	v_mov_b32_e32 v98, v101
	v_add_f32_e32 v98, v104, v98
	v_add_f32_e32 v99, v105, v99
	v_add_f32_e32 v0, v102, v103
	v_add_f32_e32 v0, v99, v0
	v_add_f32_e32 v0, v98, v0
	ds_swizzle_b32 v98, v0 offset:swizzle(SWAP,16)
	s_waitcnt lgkmcnt(0)
	v_add_f32_e32 v0, v0, v98
	v_mov_b32_e32 v98, v0
	s_nop 1
	v_permlane32_swap_b32_e32 v0, v98
	v_add_f32_e32 v0, v0, v98
	v_max_f32_e32 v98, v123, v123
	v_max_f32_e32 v123, v98, v0
.LBB0_166:
	v_or_b32_e32 v0, 32, v142
	v_mov_b64_e32 v[98:99], s[12:13]
	s_movk_i32 s28, 0x1e00
	v_mad_i64_i32 v[98:99], s[28:29], v0, s28, v[98:99]
	v_lshl_add_u64 v[98:99], v[152:153], 1, v[98:99]
	v_mul_f32_e32 v96, v96, v156
	v_mul_f32_e32 v97, v97, v156
	v_mul_f32_e32 v94, v94, v156
	v_mul_f32_e32 v95, v95, v156
	v_mul_f32_e32 v92, v92, v156
	v_mul_f32_e32 v93, v93, v156
	v_mul_f32_e32 v90, v90, v156
	v_mul_f32_e32 v91, v91, v156
	s_and_b64 vcc, exec, s[10:11]
	v_cvt_pk_bf16_f32 v100, v94, v95
	v_cvt_pk_bf16_f32 v101, v96, v97
	v_cvt_pk_bf16_f32 v102, v90, v91
	v_cvt_pk_bf16_f32 v103, v92, v93
	global_store_dwordx4 v[98:99], v[100:103], off
	s_cbranch_vccnz .LBB0_168
	v_mul_f32_e32 v96, v96, v96
	v_mul_f32_e32 v97, v97, v97
	v_mul_f32_e32 v94, v94, v94
	v_mul_f32_e32 v95, v95, v95
	v_mov_b32_e32 v101, v97
	v_mov_b32_e32 v100, v94
	v_pk_mov_b32 v[94:95], v[94:95], v[96:97] op_sel:[1,0]
	v_mul_f32_e32 v92, v92, v92
	v_mul_f32_e32 v93, v93, v93
	v_mul_f32_e32 v90, v90, v90
	v_mul_f32_e32 v91, v91, v91
	v_add_f32_e32 v94, v94, v100
	v_add_f32_e32 v95, v95, v101
	v_mov_b32_e32 v96, v92
	v_mov_b32_e32 v97, v90
	v_mov_b32_e32 v90, v93
	v_add_f32_e32 v90, v96, v90
	v_add_f32_e32 v91, v97, v91
	v_add_f32_e32 v0, v94, v95
	v_add_f32_e32 v0, v91, v0
	v_add_f32_e32 v0, v90, v0
	ds_swizzle_b32 v90, v0 offset:swizzle(SWAP,16)
	s_waitcnt lgkmcnt(0)
	v_add_f32_e32 v0, v0, v90
	v_mov_b32_e32 v90, v0
	s_nop 1
	v_permlane32_swap_b32_e32 v0, v90
	v_add_f32_e32 v0, v0, v90
	v_max_f32_e32 v90, v122, v122
	v_max_f32_e32 v122, v90, v0
; #define GAS __attribute__((address_space(1)))
; __device__ __forceinline__ unsigned cvt_pk_bf16(float lo, float hi) { unsigned r; asm("v_cvt_pk_bf16_f32 %0, %1, %2" : "=v"(r) : "v"(lo), "v"(hi)); return r; }
; template <int M> __device__ __forceinline__ float swz_xor(float v) { return __int_as_float(__builtin_amdgcn_ds_swizzle(__float_as_int(v), 0x1f | (M << 10))); }
; __device__ __forceinline__ float sum_x32(float v) { auto rr = __builtin_amdgcn_permlane32_swap(__float_as_uint(v), __float_as_uint(v), false, false); return __uint_as_float(rr[0]) + __uint_as_float(rr[1]); }
;     __device__ __forceinline__ void operator()(const f32x4 (&acc)[2][2][4][2], const Unit& u, int wr, int wc, int fr, int fq) const {
;     ...
;         for (int ai = 0; ai < 2; ++ai)
; #pragma unroll
;             for (int m = 0; m < 4; ++m) { const int row = row0 + ai * HALF + m * 16; gbf* rowp = O + (size_t)row * ldc + col0;
;                 const float rs = rsv[ai][m];
; #pragma unroll
;                 for (int bj = 0; bj < 2; ++bj) { const f32x4 v0 = acc[ai][bj][m][0] * rs, v1 = acc[ai][bj][m][1] * rs;
;                     u32x4 w; w.x = cvt_pk_bf16(v0[0], v0[1]); w.y = cvt_pk_bf16(v0[2], v0[3]); w.z = cvt_pk_bf16(v1[0], v1[1]); w.w = cvt_pk_bf16(v1[2], v1[3]);
;                     *(GAS u32x4*)(rowp + bj * HALF) = w;
;                     if (ktile) { float q = (v0[0] * v0[0] + v0[1] * v0[1]) + (v0[2] * v0[2] + v0[3] * v0[3]) + (v1[0] * v1[0] + v1[1] * v1[1]) + (v1[2] * v1[2] + v1[3] * v1[3]);
;                         q += swz_xor<16>(q); q = sum_x32(q); mxsq[bj] = __builtin_fmaxf(mxsq[bj], q); } } }
.LBB0_168:
	v_mov_b32_e32 v157, v156
	v_mov_b32_e32 v90, v156
	v_mov_b32_e32 v91, v156
	v_mul_f32_e32 v88, v88, v90
	v_mul_f32_e32 v89, v89, v91
	v_mul_f32_e32 v86, v86, v156
	v_mul_f32_e32 v87, v87, v157
	v_mul_f32_e32 v84, v84, v90
	v_mul_f32_e32 v85, v85, v91
	v_mul_f32_e32 v82, v82, v156
	v_mul_f32_e32 v83, v83, v157
	s_and_b64 vcc, exec, s[10:11]
	v_cvt_pk_bf16_f32 v90, v86, v87
	v_cvt_pk_bf16_f32 v91, v88, v89
	v_cvt_pk_bf16_f32 v92, v82, v83
	v_cvt_pk_bf16_f32 v93, v84, v85
	global_store_dwordx4 v[98:99], v[90:93], off offset:256
	s_cbranch_vccnz .LBB0_170
	v_mul_f32_e32 v88, v88, v88
	v_mul_f32_e32 v89, v89, v89
	v_mul_f32_e32 v86, v86, v86
	v_mul_f32_e32 v87, v87, v87
	v_mov_b32_e32 v91, v89
	v_mov_b32_e32 v90, v86
	v_pk_mov_b32 v[86:87], v[86:87], v[88:89] op_sel:[1,0]
	v_mul_f32_e32 v84, v84, v84
	v_mul_f32_e32 v85, v85, v85
	v_mul_f32_e32 v82, v82, v82
	v_mul_f32_e32 v83, v83, v83
	v_add_f32_e32 v86, v86, v90
	v_add_f32_e32 v87, v87, v91
	v_mov_b32_e32 v88, v84
	v_mov_b32_e32 v89, v82
	v_mov_b32_e32 v82, v85
	v_add_f32_e32 v82, v88, v82
	v_add_f32_e32 v83, v89, v83
	v_add_f32_e32 v0, v86, v87
	v_add_f32_e32 v0, v83, v0
	v_add_f32_e32 v0, v82, v0
	ds_swizzle_b32 v82, v0 offset:swizzle(SWAP,16)
	s_waitcnt lgkmcnt(0)
	v_add_f32_e32 v0, v0, v82
	v_mov_b32_e32 v82, v0
	s_nop 1
	v_permlane32_swap_b32_e32 v0, v82
	v_add_f32_e32 v0, v0, v82
	v_max_f32_e32 v82, v123, v123
	v_max_f32_e32 v123, v82, v0
.LBB0_170:
	v_or_b32_e32 v0, 48, v142
	v_mov_b64_e32 v[82:83], s[12:13]
	s_movk_i32 s28, 0x1e00
	v_mad_i64_i32 v[82:83], s[28:29], v0, s28, v[82:83]
	v_lshl_add_u64 v[82:83], v[152:153], 1, v[82:83]
	v_mul_f32_e32 v80, v80, v154
	v_mul_f32_e32 v81, v81, v154
	v_mul_f32_e32 v78, v78, v154
	v_mul_f32_e32 v79, v79, v154
	v_mul_f32_e32 v76, v76, v154
	v_mul_f32_e32 v77, v77, v154
	v_mul_f32_e32 v74, v74, v154
	v_mul_f32_e32 v75, v75, v154
	s_and_b64 vcc, exec, s[10:11]
	v_cvt_pk_bf16_f32 v84, v78, v79
	v_cvt_pk_bf16_f32 v85, v80, v81
	v_cvt_pk_bf16_f32 v86, v74, v75
	v_cvt_pk_bf16_f32 v87, v76, v77
	global_store_dwordx4 v[82:83], v[84:87], off
	s_cbranch_vccnz .LBB0_172
	v_mul_f32_e32 v80, v80, v80
	v_mul_f32_e32 v81, v81, v81
	v_mul_f32_e32 v78, v78, v78
	v_mul_f32_e32 v79, v79, v79
	v_mov_b32_e32 v85, v81
	v_mov_b32_e32 v84, v78
	v_pk_mov_b32 v[78:79], v[78:79], v[80:81] op_sel:[1,0]
	v_mul_f32_e32 v76, v76, v76
	v_mul_f32_e32 v77, v77, v77
	v_mul_f32_e32 v74, v74, v74
	v_mul_f32_e32 v75, v75, v75
	v_add_f32_e32 v78, v78, v84
	v_add_f32_e32 v79, v79, v85
	v_mov_b32_e32 v80, v76
	v_mov_b32_e32 v81, v74
	v_mov_b32_e32 v74, v77
	v_add_f32_e32 v74, v80, v74
	v_add_f32_e32 v75, v81, v75
	v_add_f32_e32 v0, v78, v79
	v_add_f32_e32 v0, v75, v0
	v_add_f32_e32 v0, v74, v0
	ds_swizzle_b32 v74, v0 offset:swizzle(SWAP,16)
	s_waitcnt lgkmcnt(0)
	v_add_f32_e32 v0, v0, v74
	v_mov_b32_e32 v74, v0
	s_nop 1
	v_permlane32_swap_b32_e32 v0, v74
	v_add_f32_e32 v0, v0, v74
	v_max_f32_e32 v74, v122, v122
	v_max_f32_e32 v122, v74, v0
.LBB0_172:
	v_mov_b32_e32 v155, v154
	v_mov_b32_e32 v74, v154
	v_mov_b32_e32 v75, v154
	v_mul_f32_e32 v72, v72, v74
	v_mul_f32_e32 v73, v73, v75
	v_mul_f32_e32 v70, v70, v154
	v_mul_f32_e32 v71, v71, v155
	v_mul_f32_e32 v68, v68, v74
	v_mul_f32_e32 v69, v69, v75
	v_mul_f32_e32 v66, v66, v154
	v_mul_f32_e32 v67, v67, v155
	s_and_b64 vcc, exec, s[10:11]
	v_cvt_pk_bf16_f32 v74, v70, v71
	v_cvt_pk_bf16_f32 v75, v72, v73
	v_cvt_pk_bf16_f32 v76, v66, v67
	v_cvt_pk_bf16_f32 v77, v68, v69
	global_store_dwordx4 v[82:83], v[74:77], off offset:256
	s_cbranch_vccnz .LBB0_174
	v_mul_f32_e32 v72, v72, v72
	v_mul_f32_e32 v73, v73, v73
	v_mul_f32_e32 v70, v70, v70
	v_mul_f32_e32 v71, v71, v71
	v_mov_b32_e32 v75, v73
	v_mov_b32_e32 v74, v70
	v_pk_mov_b32 v[70:71], v[70:71], v[72:73] op_sel:[1,0]
	v_mul_f32_e32 v68, v68, v68
	v_mul_f32_e32 v69, v69, v69
	v_mul_f32_e32 v66, v66, v66
	v_mul_f32_e32 v67, v67, v67
	v_add_f32_e32 v70, v70, v74
	v_add_f32_e32 v71, v71, v75
	v_mov_b32_e32 v72, v68
	v_mov_b32_e32 v73, v66
	v_mov_b32_e32 v66, v69
	v_add_f32_e32 v66, v72, v66
	v_add_f32_e32 v67, v73, v67
	v_add_f32_e32 v0, v70, v71
	v_add_f32_e32 v0, v67, v0
	v_add_f32_e32 v0, v66, v0
	ds_swizzle_b32 v66, v0 offset:swizzle(SWAP,16)
	s_waitcnt lgkmcnt(0)
	v_add_f32_e32 v0, v0, v66
	v_mov_b32_e32 v66, v0
	s_nop 1
	v_permlane32_swap_b32_e32 v0, v66
	v_add_f32_e32 v0, v0, v66
	v_max_f32_e32 v66, v123, v123
	v_max_f32_e32 v123, v66, v0
.LBB0_174:
	v_add_u32_e32 v0, 0x80, v142
	v_mov_b64_e32 v[66:67], s[12:13]
	s_movk_i32 s28, 0x1e00
	v_mad_i64_i32 v[66:67], s[28:29], v0, s28, v[66:67]
	v_lshl_add_u64 v[66:67], v[152:153], 1, v[66:67]
	v_mul_f32_e32 v64, v64, v150
	v_mul_f32_e32 v65, v65, v150
	v_mul_f32_e32 v62, v62, v150
	v_mul_f32_e32 v63, v63, v150
	v_mul_f32_e32 v60, v60, v150
	v_mul_f32_e32 v61, v61, v150
	v_mul_f32_e32 v58, v58, v150
	v_mul_f32_e32 v59, v59, v150
	s_and_b64 vcc, exec, s[10:11]
	v_cvt_pk_bf16_f32 v68, v62, v63
	v_cvt_pk_bf16_f32 v69, v64, v65
	v_cvt_pk_bf16_f32 v70, v58, v59
	v_cvt_pk_bf16_f32 v71, v60, v61
	global_store_dwordx4 v[66:67], v[68:71], off
	s_cbranch_vccnz .LBB0_176
	v_mul_f32_e32 v64, v64, v64
	v_mul_f32_e32 v65, v65, v65
	v_mul_f32_e32 v62, v62, v62
	v_mul_f32_e32 v63, v63, v63
	v_mov_b32_e32 v69, v65
	v_mov_b32_e32 v68, v62
	v_pk_mov_b32 v[62:63], v[62:63], v[64:65] op_sel:[1,0]
	v_mul_f32_e32 v60, v60, v60
	v_mul_f32_e32 v61, v61, v61
	v_mul_f32_e32 v58, v58, v58
	v_mul_f32_e32 v59, v59, v59
	v_add_f32_e32 v62, v62, v68
	v_add_f32_e32 v63, v63, v69
	v_mov_b32_e32 v64, v60
	v_mov_b32_e32 v65, v58
	v_mov_b32_e32 v58, v61
	v_add_f32_e32 v58, v64, v58
	v_add_f32_e32 v59, v65, v59
	v_add_f32_e32 v0, v62, v63
	v_add_f32_e32 v0, v59, v0
	v_add_f32_e32 v0, v58, v0
	ds_swizzle_b32 v58, v0 offset:swizzle(SWAP,16)
	s_waitcnt lgkmcnt(0)
	v_add_f32_e32 v0, v0, v58
	v_mov_b32_e32 v58, v0
	s_nop 1
	v_permlane32_swap_b32_e32 v0, v58
	v_add_f32_e32 v0, v0, v58
	v_max_f32_e32 v58, v122, v122
	v_max_f32_e32 v122, v58, v0
; #define GAS __attribute__((address_space(1)))
; __device__ __forceinline__ unsigned cvt_pk_bf16(float lo, float hi) { unsigned r; asm("v_cvt_pk_bf16_f32 %0, %1, %2" : "=v"(r) : "v"(lo), "v"(hi)); return r; }
; template <int M> __device__ __forceinline__ float swz_xor(float v) { return __int_as_float(__builtin_amdgcn_ds_swizzle(__float_as_int(v), 0x1f | (M << 10))); }
; __device__ __forceinline__ float sum_x32(float v) { auto rr = __builtin_amdgcn_permlane32_swap(__float_as_uint(v), __float_as_uint(v), false, false); return __uint_as_float(rr[0]) + __uint_as_float(rr[1]); }
;     __device__ __forceinline__ void operator()(const f32x4 (&acc)[2][2][4][2], const Unit& u, int wr, int wc, int fr, int fq) const {
;     ...
;         for (int ai = 0; ai < 2; ++ai)
; #pragma unroll
;             for (int m = 0; m < 4; ++m) { const int row = row0 + ai * HALF + m * 16; gbf* rowp = O + (size_t)row * ldc + col0;
;                 const float rs = rsv[ai][m];
; #pragma unroll
;                 for (int bj = 0; bj < 2; ++bj) { const f32x4 v0 = acc[ai][bj][m][0] * rs, v1 = acc[ai][bj][m][1] * rs;
;                     u32x4 w; w.x = cvt_pk_bf16(v0[0], v0[1]); w.y = cvt_pk_bf16(v0[2], v0[3]); w.z = cvt_pk_bf16(v1[0], v1[1]); w.w = cvt_pk_bf16(v1[2], v1[3]);
;                     *(GAS u32x4*)(rowp + bj * HALF) = w;
;                     if (ktile) { float q = (v0[0] * v0[0] + v0[1] * v0[1]) + (v0[2] * v0[2] + v0[3] * v0[3]) + (v1[0] * v1[0] + v1[1] * v1[1]) + (v1[2] * v1[2] + v1[3] * v1[3]);
;                         q += swz_xor<16>(q); q = sum_x32(q); mxsq[bj] = __builtin_fmaxf(mxsq[bj], q); } } }
.LBB0_176:
	v_mov_b32_e32 v151, v150
	v_mov_b32_e32 v58, v150
	v_mov_b32_e32 v59, v150
	v_mul_f32_e32 v56, v56, v58
	v_mul_f32_e32 v57, v57, v59
	v_mul_f32_e32 v54, v54, v150
	v_mul_f32_e32 v55, v55, v151
	v_mul_f32_e32 v52, v52, v58
	v_mul_f32_e32 v53, v53, v59
	v_mul_f32_e32 v50, v50, v150
	v_mul_f32_e32 v51, v51, v151
	s_and_b64 vcc, exec, s[10:11]
	v_cvt_pk_bf16_f32 v58, v54, v55
	v_cvt_pk_bf16_f32 v59, v56, v57
	v_cvt_pk_bf16_f32 v60, v50, v51
	v_cvt_pk_bf16_f32 v61, v52, v53
	global_store_dwordx4 v[66:67], v[58:61], off offset:256
	s_cbranch_vccnz .LBB0_178
	v_mul_f32_e32 v56, v56, v56
	v_mul_f32_e32 v57, v57, v57
	v_mul_f32_e32 v54, v54, v54
	v_mul_f32_e32 v55, v55, v55
	v_mov_b32_e32 v59, v57
	v_mov_b32_e32 v58, v54
	v_pk_mov_b32 v[54:55], v[54:55], v[56:57] op_sel:[1,0]
	v_mul_f32_e32 v52, v52, v52
	v_mul_f32_e32 v53, v53, v53
	v_mul_f32_e32 v50, v50, v50
	v_mul_f32_e32 v51, v51, v51
	v_add_f32_e32 v54, v54, v58
	v_add_f32_e32 v55, v55, v59
	v_mov_b32_e32 v56, v52
	v_mov_b32_e32 v57, v50
	v_mov_b32_e32 v50, v53
	v_add_f32_e32 v50, v56, v50
	v_add_f32_e32 v51, v57, v51
	v_add_f32_e32 v0, v54, v55
	v_add_f32_e32 v0, v51, v0
	v_add_f32_e32 v0, v50, v0
	ds_swizzle_b32 v50, v0 offset:swizzle(SWAP,16)
	s_waitcnt lgkmcnt(0)
	v_add_f32_e32 v0, v0, v50
	v_mov_b32_e32 v50, v0
	s_nop 1
	v_permlane32_swap_b32_e32 v0, v50
	v_add_f32_e32 v0, v0, v50
	v_max_f32_e32 v50, v123, v123
	v_max_f32_e32 v123, v50, v0
.LBB0_178:
	v_add_u32_e32 v0, 0x90, v142
	v_mov_b64_e32 v[50:51], s[12:13]
	s_movk_i32 s28, 0x1e00
	v_mad_i64_i32 v[50:51], s[28:29], v0, s28, v[50:51]
	v_lshl_add_u64 v[50:51], v[152:153], 1, v[50:51]
	v_mul_f32_e32 v48, v48, v146
	v_mul_f32_e32 v49, v49, v146
	v_mul_f32_e32 v46, v46, v146
	v_mul_f32_e32 v47, v47, v146
	v_mul_f32_e32 v44, v44, v146
	v_mul_f32_e32 v45, v45, v146
	v_mul_f32_e32 v42, v42, v146
	v_mul_f32_e32 v43, v43, v146
	s_and_b64 vcc, exec, s[10:11]
	v_cvt_pk_bf16_f32 v52, v46, v47
	v_cvt_pk_bf16_f32 v53, v48, v49
	v_cvt_pk_bf16_f32 v54, v42, v43
	v_cvt_pk_bf16_f32 v55, v44, v45
	global_store_dwordx4 v[50:51], v[52:55], off
	s_cbranch_vccnz .LBB0_180
	v_mul_f32_e32 v48, v48, v48
	v_mul_f32_e32 v49, v49, v49
	v_mul_f32_e32 v46, v46, v46
	v_mul_f32_e32 v47, v47, v47
	v_mov_b32_e32 v53, v49
	v_mov_b32_e32 v52, v46
	v_pk_mov_b32 v[46:47], v[46:47], v[48:49] op_sel:[1,0]
	v_mul_f32_e32 v44, v44, v44
	v_mul_f32_e32 v45, v45, v45
	v_mul_f32_e32 v42, v42, v42
	v_mul_f32_e32 v43, v43, v43
	v_add_f32_e32 v46, v46, v52
	v_add_f32_e32 v47, v47, v53
	v_mov_b32_e32 v48, v44
	v_mov_b32_e32 v49, v42
	v_mov_b32_e32 v42, v45
	v_add_f32_e32 v42, v48, v42
	v_add_f32_e32 v43, v49, v43
	v_add_f32_e32 v0, v46, v47
	v_add_f32_e32 v0, v43, v0
	v_add_f32_e32 v0, v42, v0
	ds_swizzle_b32 v42, v0 offset:swizzle(SWAP,16)
	s_waitcnt lgkmcnt(0)
	v_add_f32_e32 v0, v0, v42
	v_mov_b32_e32 v42, v0
	s_nop 1
	v_permlane32_swap_b32_e32 v0, v42
	v_add_f32_e32 v0, v0, v42
	v_max_f32_e32 v42, v122, v122
	v_max_f32_e32 v122, v42, v0
.LBB0_180:
	v_mov_b32_e32 v147, v146
	v_mov_b32_e32 v42, v146
	v_mov_b32_e32 v43, v146
	v_mul_f32_e32 v40, v40, v42
	v_mul_f32_e32 v41, v41, v43
	v_mul_f32_e32 v38, v38, v146
	v_mul_f32_e32 v39, v39, v147
	v_mul_f32_e32 v36, v36, v42
	v_mul_f32_e32 v37, v37, v43
	v_mul_f32_e32 v34, v34, v146
	v_mul_f32_e32 v35, v35, v147
	s_and_b64 vcc, exec, s[10:11]
	v_cvt_pk_bf16_f32 v42, v38, v39
	v_cvt_pk_bf16_f32 v43, v40, v41
	v_cvt_pk_bf16_f32 v44, v34, v35
	v_cvt_pk_bf16_f32 v45, v36, v37
	global_store_dwordx4 v[50:51], v[42:45], off offset:256
	s_cbranch_vccnz .LBB0_182
	v_mul_f32_e32 v40, v40, v40
	v_mul_f32_e32 v41, v41, v41
	v_mul_f32_e32 v38, v38, v38
	v_mul_f32_e32 v39, v39, v39
	v_mov_b32_e32 v43, v41
	v_mov_b32_e32 v42, v38
	v_pk_mov_b32 v[38:39], v[38:39], v[40:41] op_sel:[1,0]
	v_mul_f32_e32 v36, v36, v36
	v_mul_f32_e32 v37, v37, v37
	v_mul_f32_e32 v34, v34, v34
	v_mul_f32_e32 v35, v35, v35
	v_add_f32_e32 v38, v38, v42
	v_add_f32_e32 v39, v39, v43
	v_mov_b32_e32 v40, v36
	v_mov_b32_e32 v41, v34
	v_mov_b32_e32 v34, v37
	v_add_f32_e32 v34, v40, v34
	v_add_f32_e32 v35, v41, v35
	v_add_f32_e32 v0, v38, v39
	v_add_f32_e32 v0, v35, v0
	v_add_f32_e32 v0, v34, v0
	ds_swizzle_b32 v34, v0 offset:swizzle(SWAP,16)
	s_waitcnt lgkmcnt(0)
	v_add_f32_e32 v0, v0, v34
	v_mov_b32_e32 v34, v0
	s_nop 1
	v_permlane32_swap_b32_e32 v0, v34
	v_add_f32_e32 v0, v0, v34
	v_max_f32_e32 v34, v123, v123
	v_max_f32_e32 v123, v34, v0
.LBB0_182:
	v_add_u32_e32 v0, 0xa0, v142
	v_mov_b64_e32 v[34:35], s[12:13]
	s_movk_i32 s28, 0x1e00
	v_mad_i64_i32 v[34:35], s[28:29], v0, s28, v[34:35]
	v_lshl_add_u64 v[34:35], v[152:153], 1, v[34:35]
	v_mul_f32_e32 v32, v32, v144
	v_mul_f32_e32 v33, v33, v144
	v_mul_f32_e32 v30, v30, v144
	v_mul_f32_e32 v31, v31, v144
	v_mul_f32_e32 v28, v28, v144
	v_mul_f32_e32 v29, v29, v144
	v_mul_f32_e32 v26, v26, v144
	v_mul_f32_e32 v27, v27, v144
	s_and_b64 vcc, exec, s[10:11]
	v_cvt_pk_bf16_f32 v36, v30, v31
	v_cvt_pk_bf16_f32 v37, v32, v33
	v_cvt_pk_bf16_f32 v38, v26, v27
	v_cvt_pk_bf16_f32 v39, v28, v29
	global_store_dwordx4 v[34:35], v[36:39], off
	s_cbranch_vccnz .LBB0_184
	v_mul_f32_e32 v32, v32, v32
	v_mul_f32_e32 v33, v33, v33
	v_mul_f32_e32 v30, v30, v30
	v_mul_f32_e32 v31, v31, v31
	v_mov_b32_e32 v37, v33
	v_mov_b32_e32 v36, v30
	v_pk_mov_b32 v[30:31], v[30:31], v[32:33] op_sel:[1,0]
	v_mul_f32_e32 v28, v28, v28
	v_mul_f32_e32 v29, v29, v29
	v_mul_f32_e32 v26, v26, v26
	v_mul_f32_e32 v27, v27, v27
	v_add_f32_e32 v30, v30, v36
	v_add_f32_e32 v31, v31, v37
	v_mov_b32_e32 v32, v28
	v_mov_b32_e32 v33, v26
	v_mov_b32_e32 v26, v29
	v_add_f32_e32 v26, v32, v26
	v_add_f32_e32 v27, v33, v27
	v_add_f32_e32 v0, v30, v31
	v_add_f32_e32 v0, v27, v0
	v_add_f32_e32 v0, v26, v0
	ds_swizzle_b32 v26, v0 offset:swizzle(SWAP,16)
	s_waitcnt lgkmcnt(0)
	v_add_f32_e32 v0, v0, v26
	v_mov_b32_e32 v26, v0
	s_nop 1
	v_permlane32_swap_b32_e32 v0, v26
	v_add_f32_e32 v0, v0, v26
	v_max_f32_e32 v26, v122, v122
	v_max_f32_e32 v122, v26, v0
; #define GAS __attribute__((address_space(1)))
; __device__ __forceinline__ unsigned cvt_pk_bf16(float lo, float hi) { unsigned r; asm("v_cvt_pk_bf16_f32 %0, %1, %2" : "=v"(r) : "v"(lo), "v"(hi)); return r; }
; template <int M> __device__ __forceinline__ float swz_xor(float v) { return __int_as_float(__builtin_amdgcn_ds_swizzle(__float_as_int(v), 0x1f | (M << 10))); }
; __device__ __forceinline__ float sum_x32(float v) { auto rr = __builtin_amdgcn_permlane32_swap(__float_as_uint(v), __float_as_uint(v), false, false); return __uint_as_float(rr[0]) + __uint_as_float(rr[1]); }
;     __device__ __forceinline__ void operator()(const f32x4 (&acc)[2][2][4][2], const Unit& u, int wr, int wc, int fr, int fq) const {
;     ...
;         for (int ai = 0; ai < 2; ++ai)
; #pragma unroll
;             for (int m = 0; m < 4; ++m) { const int row = row0 + ai * HALF + m * 16; gbf* rowp = O + (size_t)row * ldc + col0;
;                 const float rs = rsv[ai][m];
; #pragma unroll
;                 for (int bj = 0; bj < 2; ++bj) { const f32x4 v0 = acc[ai][bj][m][0] * rs, v1 = acc[ai][bj][m][1] * rs;
;                     u32x4 w; w.x = cvt_pk_bf16(v0[0], v0[1]); w.y = cvt_pk_bf16(v0[2], v0[3]); w.z = cvt_pk_bf16(v1[0], v1[1]); w.w = cvt_pk_bf16(v1[2], v1[3]);
;                     *(GAS u32x4*)(rowp + bj * HALF) = w;
;                     if (ktile) { float q = (v0[0] * v0[0] + v0[1] * v0[1]) + (v0[2] * v0[2] + v0[3] * v0[3]) + (v1[0] * v1[0] + v1[1] * v1[1]) + (v1[2] * v1[2] + v1[3] * v1[3]);
;                         q += swz_xor<16>(q); q = sum_x32(q); mxsq[bj] = __builtin_fmaxf(mxsq[bj], q); } } }
;         if (ktile) {
; #pragma unroll
;             for (int bj = 0; bj < 2; ++bj) { float q = mxsq[bj];
;                 q = __builtin_fmaxf(q, swz_xor<1>(q)); q = __builtin_fmaxf(q, swz_xor<2>(q)); q = __builtin_fmaxf(q, swz_xor<4>(q)); q = __builtin_fmaxf(q, swz_xor<8>(q));
;                 if (fr == 0 && fq == 0) { const int b = (u.pm * BM) / S, grp = (u.pn - 2) * 8 + bj * 4 + wc;
;                     (void)__hip_atomic_fetch_max(kn2 + b * 16 + grp, __float_as_uint(q), __ATOMIC_RELAXED, __HIP_MEMORY_SCOPE_AGENT); } }
.LBB0_184:
	v_mov_b32_e32 v145, v144
	v_mov_b32_e32 v26, v144
	v_mov_b32_e32 v27, v144
	v_mul_f32_e32 v24, v24, v26
	v_mul_f32_e32 v25, v25, v27
	v_mul_f32_e32 v22, v22, v144
	v_mul_f32_e32 v23, v23, v145
	v_mul_f32_e32 v20, v20, v26
	v_mul_f32_e32 v21, v21, v27
	v_mul_f32_e32 v18, v18, v144
	v_mul_f32_e32 v19, v19, v145
	s_and_b64 vcc, exec, s[10:11]
	v_cvt_pk_bf16_f32 v26, v22, v23
	v_cvt_pk_bf16_f32 v27, v24, v25
	v_cvt_pk_bf16_f32 v28, v18, v19
	v_cvt_pk_bf16_f32 v29, v20, v21
	global_store_dwordx4 v[34:35], v[26:29], off offset:256
	s_cbranch_vccnz .LBB0_186
	v_mul_f32_e32 v24, v24, v24
	v_mul_f32_e32 v25, v25, v25
	v_mul_f32_e32 v22, v22, v22
	v_mul_f32_e32 v23, v23, v23
	v_mov_b32_e32 v27, v25
	v_mov_b32_e32 v26, v22
	v_pk_mov_b32 v[22:23], v[22:23], v[24:25] op_sel:[1,0]
	v_mul_f32_e32 v20, v20, v20
	v_mul_f32_e32 v21, v21, v21
	v_mul_f32_e32 v18, v18, v18
	v_mul_f32_e32 v19, v19, v19
	v_add_f32_e32 v22, v22, v26
	v_add_f32_e32 v23, v23, v27
	v_mov_b32_e32 v24, v20
	v_mov_b32_e32 v25, v18
	v_mov_b32_e32 v18, v21
	v_add_f32_e32 v18, v24, v18
	v_add_f32_e32 v19, v25, v19
	v_add_f32_e32 v0, v22, v23
	v_add_f32_e32 v0, v19, v0
	v_add_f32_e32 v0, v18, v0
	ds_swizzle_b32 v18, v0 offset:swizzle(SWAP,16)
	s_waitcnt lgkmcnt(0)
	v_add_f32_e32 v0, v0, v18
	v_mov_b32_e32 v18, v0
	s_nop 1
	v_permlane32_swap_b32_e32 v0, v18
	v_add_f32_e32 v0, v0, v18
	v_max_f32_e32 v18, v123, v123
	v_max_f32_e32 v123, v18, v0
.LBB0_186:
	v_add_u32_e32 v0, 0xb0, v142
	v_mov_b64_e32 v[18:19], s[12:13]
	s_movk_i32 s28, 0x1e00
	v_mad_i64_i32 v[18:19], s[28:29], v0, s28, v[18:19]
	v_lshl_add_u64 v[18:19], v[152:153], 1, v[18:19]
	v_mul_f32_e32 v16, v16, v148
	v_mul_f32_e32 v17, v17, v148
	v_mul_f32_e32 v14, v14, v148
	v_mul_f32_e32 v15, v15, v148
	v_mul_f32_e32 v12, v12, v148
	v_mul_f32_e32 v13, v13, v148
	v_mul_f32_e32 v10, v10, v148
	v_mul_f32_e32 v11, v11, v148
	s_and_b64 vcc, exec, s[10:11]
	v_cvt_pk_bf16_f32 v20, v14, v15
	v_cvt_pk_bf16_f32 v21, v16, v17
	v_cvt_pk_bf16_f32 v22, v10, v11
	v_cvt_pk_bf16_f32 v23, v12, v13
	global_store_dwordx4 v[18:19], v[20:23], off
	s_cbranch_vccnz .LBB0_188
	v_mul_f32_e32 v16, v16, v16
	v_mul_f32_e32 v17, v17, v17
	v_mul_f32_e32 v14, v14, v14
	v_mul_f32_e32 v15, v15, v15
	v_mov_b32_e32 v21, v17
	v_mov_b32_e32 v20, v14
	v_pk_mov_b32 v[14:15], v[14:15], v[16:17] op_sel:[1,0]
	v_mul_f32_e32 v12, v12, v12
	v_mul_f32_e32 v13, v13, v13
	v_mul_f32_e32 v10, v10, v10
	v_mul_f32_e32 v11, v11, v11
	v_add_f32_e32 v14, v14, v20
	v_add_f32_e32 v15, v15, v21
	v_mov_b32_e32 v16, v12
	v_mov_b32_e32 v17, v10
	v_mov_b32_e32 v10, v13
	v_add_f32_e32 v10, v16, v10
	v_add_f32_e32 v11, v17, v11
	v_add_f32_e32 v0, v14, v15
	v_add_f32_e32 v0, v11, v0
	v_add_f32_e32 v0, v10, v0
	ds_swizzle_b32 v10, v0 offset:swizzle(SWAP,16)
	s_waitcnt lgkmcnt(0)
	v_add_f32_e32 v0, v0, v10
	v_mov_b32_e32 v10, v0
	s_nop 1
	v_permlane32_swap_b32_e32 v0, v10
	v_add_f32_e32 v0, v0, v10
	v_max_f32_e32 v10, v122, v122
	v_max_f32_e32 v122, v10, v0
.LBB0_188:
	v_mov_b32_e32 v149, v148
	v_mov_b32_e32 v10, v148
	v_mov_b32_e32 v11, v148
	v_mul_f32_e32 v8, v8, v10
	v_mul_f32_e32 v9, v9, v11
	v_mul_f32_e32 v6, v6, v148
	v_mul_f32_e32 v7, v7, v149
	v_mul_f32_e32 v4, v4, v10
	v_mul_f32_e32 v5, v5, v11
	v_mul_f32_e32 v2, v2, v148
	v_mul_f32_e32 v3, v3, v149
	s_and_b64 vcc, exec, s[10:11]
	v_cvt_pk_bf16_f32 v10, v6, v7
	v_cvt_pk_bf16_f32 v11, v8, v9
	v_cvt_pk_bf16_f32 v12, v2, v3
	v_cvt_pk_bf16_f32 v13, v4, v5
	global_store_dwordx4 v[18:19], v[10:13], off offset:256
	s_cbranch_vccnz .LBB0_200
	v_mul_f32_e32 v0, v7, v7
	v_fmac_f32_e32 v0, v6, v6
	v_mul_f32_e32 v6, v9, v9
	v_fmac_f32_e32 v6, v8, v8
	v_add_f32_e32 v0, v0, v6
	ds_swizzle_b32 v6, v122 offset:swizzle(SWAP,1)
	v_mul_f32_e32 v3, v3, v3
	v_fmac_f32_e32 v3, v2, v2
	v_add_f32_e32 v0, v3, v0
	v_max_f32_e32 v2, v122, v122
	s_waitcnt lgkmcnt(0)
	v_max_f32_e32 v3, v6, v6
	v_max_f32_e32 v2, v2, v3
	ds_swizzle_b32 v3, v2 offset:swizzle(SWAP,2)
	v_mul_f32_e32 v5, v5, v5
	v_fmac_f32_e32 v5, v4, v4
	v_add_f32_e32 v0, v5, v0
	ds_swizzle_b32 v4, v0 offset:swizzle(SWAP,16)
	s_waitcnt lgkmcnt(0)
	v_max_f32_e32 v3, v3, v3
	v_max_f32_e32 v3, v2, v3
	ds_swizzle_b32 v5, v3 offset:swizzle(SWAP,4)
	s_lshl_b32 s10, s76, 3
	v_add_f32_e32 v0, v0, v4
	v_mov_b32_e32 v2, v0
	s_nop 1
	v_permlane32_swap_b32_e32 v0, v2
	s_waitcnt lgkmcnt(0)
	v_max_f32_e32 v4, v5, v5
	v_max_f32_e32 v3, v3, v4
	ds_swizzle_b32 v4, v3 offset:swizzle(SWAP,8)
	s_add_i32 s76, s10, s83
	s_and_saveexec_b64 s[10:11], s[6:7]
	s_cbranch_execz .LBB0_194
	s_waitcnt lgkmcnt(0)
	v_max_f32_e32 v4, v4, v4
	v_max_f32_e32 v3, v3, v3
	s_mov_b64 s[28:29], exec
	v_max_f32_e32 v3, v3, v4
	s_mov_b32 s38, 0

; #define GAS __attribute__((address_space(1)))
; __device__ __forceinline__ unsigned cvt_pk_bf16(float lo, float hi) { unsigned r; asm("v_cvt_pk_bf16_f32 %0, %1, %2" : "=v"(r) : "v"(lo), "v"(hi)); return r; }
;     __device__ __forceinline__ void operator()(const f32x4 (&acc)[2][2][4][2], const Unit& u, int wr, int wc, int fr, int fq) const {
;     ...
; #pragma unroll
;         for (int ai = 0; ai < 2; ++ai)
; #pragma unroll
;             for (int m = 0; m < 4; ++m) { gbf* rowp = O + (size_t)(row0 + ai * HALF + m * 16) * ldc + col0;
; #pragma unroll
;                 for (int bj = 0; bj < 2; ++bj) { const f32x4 v0 = acc[ai][bj][m][0] * cs[bj][0], v1 = acc[ai][bj][m][1] * cs[bj][1];
;                     u32x4 w; w.x = cvt_pk_bf16(v0[0], v0[1]); w.y = cvt_pk_bf16(v0[2], v0[3]); w.z = cvt_pk_bf16(v1[0], v1[1]); w.w = cvt_pk_bf16(v1[2], v1[3]);
;                     *(GAS u32x4*)(rowp + bj * HALF) = w; } }
.LBB0_224:
	v_lshl_add_u32 v154, s44, 8, v160
	v_ashrrev_i32_e32 v155, 31, v154
	v_lshlrev_b64 v[164:165], 17, v[154:155]
	v_lshl_add_u64 v[164:165], s[10:11], 0, v[164:165]
	v_lshlrev_b64 v[166:167], 1, v[146:147]
	v_lshl_add_u64 v[146:147], v[164:165], 0, v[166:167]
	v_mul_f32_e32 v128, v128, v144
	v_mul_f32_e32 v129, v129, v145
	v_mul_f32_e32 v126, v126, v142
	v_mul_f32_e32 v127, v127, v143
	v_mul_f32_e32 v164, v124, v148
	v_mul_f32_e32 v165, v125, v149
	v_mul_f32_e32 v124, v122, v140
	v_mul_f32_e32 v125, v123, v141
	v_cvt_pk_bf16_f32 v122, v126, v127
	v_cvt_pk_bf16_f32 v123, v128, v129
	v_mul_f32_e32 v118, v118, v152
	v_mul_f32_e32 v119, v119, v153
	v_cvt_pk_bf16_f32 v124, v124, v125
	v_cvt_pk_bf16_f32 v125, v164, v165
	global_store_dwordx4 v[146:147], v[122:125], off
	v_mul_f32_e32 v120, v120, v156
	v_mul_f32_e32 v121, v121, v157
	v_mul_f32_e32 v114, v114, v142
	v_mul_f32_e32 v115, v115, v143
	v_mul_f32_e32 v122, v112, v158
	v_mul_f32_e32 v123, v113, v159
	v_mul_f32_e32 v112, v110, v150
	v_mul_f32_e32 v113, v111, v151
	v_cvt_pk_bf16_f32 v110, v118, v119
	v_cvt_pk_bf16_f32 v111, v120, v121
	v_mul_f32_e32 v102, v102, v152
	v_mul_f32_e32 v103, v103, v153
	v_cvt_pk_bf16_f32 v112, v112, v113
	v_cvt_pk_bf16_f32 v113, v122, v123
	global_store_dwordx4 v[146:147], v[110:113], off offset:256
	v_mul_f32_e32 v104, v104, v156
	v_mul_f32_e32 v105, v105, v157
	v_mul_f32_e32 v98, v98, v142
	v_mul_f32_e32 v99, v99, v143
	v_or_b32_e32 v110, 16, v154
	v_ashrrev_i32_e32 v111, 31, v110
	v_lshlrev_b64 v[110:111], 17, v[110:111]
	v_lshl_add_u64 v[110:111], s[10:11], 0, v[110:111]
	v_lshl_add_u64 v[110:111], v[110:111], 0, v[166:167]
	v_mul_f32_e32 v112, v116, v144
	v_mul_f32_e32 v113, v117, v145
	v_mul_f32_e32 v116, v108, v148
	v_mul_f32_e32 v117, v109, v149
	v_mul_f32_e32 v108, v106, v140
	v_mul_f32_e32 v109, v107, v141
	v_cvt_pk_bf16_f32 v106, v114, v115
	v_cvt_pk_bf16_f32 v107, v112, v113
	v_mul_f32_e32 v86, v86, v152
	v_mul_f32_e32 v87, v87, v153
	v_cvt_pk_bf16_f32 v108, v108, v109
	v_cvt_pk_bf16_f32 v109, v116, v117
	global_store_dwordx4 v[110:111], v[106:109], off
	v_mul_f32_e32 v88, v88, v156
	v_mul_f32_e32 v89, v89, v157
	v_mul_f32_e32 v82, v82, v142
	v_mul_f32_e32 v83, v83, v143
	v_mul_f32_e32 v106, v96, v158
	v_mul_f32_e32 v107, v97, v159
	v_mul_f32_e32 v96, v94, v150
	v_mul_f32_e32 v97, v95, v151
	v_cvt_pk_bf16_f32 v94, v102, v103
	v_cvt_pk_bf16_f32 v95, v104, v105
	v_mul_f32_e32 v72, v72, v156
	v_mul_f32_e32 v73, v73, v157
	v_cvt_pk_bf16_f32 v96, v96, v97
	v_cvt_pk_bf16_f32 v97, v106, v107
	global_store_dwordx4 v[110:111], v[94:97], off offset:256
	v_mul_f32_e32 v70, v70, v152
	v_mul_f32_e32 v71, v71, v153
	s_mov_b64 s[8:9], 0x1000000
	v_or_b32_e32 v94, 32, v154
	v_ashrrev_i32_e32 v95, 31, v94
	v_lshlrev_b64 v[94:95], 17, v[94:95]
	v_lshl_add_u64 v[94:95], s[10:11], 0, v[94:95]
	v_lshl_add_u64 v[94:95], v[94:95], 0, v[166:167]
	v_mul_f32_e32 v96, v100, v144
	v_mul_f32_e32 v97, v101, v145
	v_mul_f32_e32 v100, v92, v148
	v_mul_f32_e32 v101, v93, v149
	v_mul_f32_e32 v92, v90, v140
	v_mul_f32_e32 v93, v91, v141
	v_cvt_pk_bf16_f32 v90, v98, v99
	v_cvt_pk_bf16_f32 v91, v96, v97
	v_mul_f32_e32 v62, v62, v142
	v_mul_f32_e32 v63, v63, v143
	v_cvt_pk_bf16_f32 v92, v92, v93
	v_cvt_pk_bf16_f32 v93, v100, v101
	global_store_dwordx4 v[94:95], v[90:93], off
	v_mul_f32_e32 v64, v64, v144
	v_mul_f32_e32 v65, v65, v145
	v_mul_f32_e32 v56, v56, v156
	v_mul_f32_e32 v57, v57, v157
	v_mul_f32_e32 v90, v80, v158
	v_mul_f32_e32 v91, v81, v159
	v_mul_f32_e32 v80, v78, v150
	v_mul_f32_e32 v81, v79, v151
	v_cvt_pk_bf16_f32 v78, v86, v87
	v_cvt_pk_bf16_f32 v79, v88, v89
	v_mul_f32_e32 v54, v54, v152
	v_mul_f32_e32 v55, v55, v153
	v_cvt_pk_bf16_f32 v80, v80, v81
	v_cvt_pk_bf16_f32 v81, v90, v91
	global_store_dwordx4 v[94:95], v[78:81], off offset:256
	v_mul_f32_e32 v50, v50, v142
	v_mul_f32_e32 v51, v51, v143
	v_mul_f32_e32 v40, v40, v156
	v_mul_f32_e32 v41, v41, v157
	v_or_b32_e32 v78, 48, v154
	v_ashrrev_i32_e32 v79, 31, v78
	v_lshlrev_b64 v[78:79], 17, v[78:79]
	v_lshl_add_u64 v[78:79], s[10:11], 0, v[78:79]
	v_lshl_add_u64 v[78:79], v[78:79], 0, v[166:167]
	v_mul_f32_e32 v80, v84, v144
	v_mul_f32_e32 v81, v85, v145
	v_mul_f32_e32 v84, v76, v148
	v_mul_f32_e32 v85, v77, v149
	v_mul_f32_e32 v76, v74, v140
	v_mul_f32_e32 v77, v75, v141
	v_cvt_pk_bf16_f32 v74, v82, v83
	v_cvt_pk_bf16_f32 v75, v80, v81
	v_mul_f32_e32 v38, v38, v152
; #define GAS __attribute__((address_space(1)))
; __device__ __forceinline__ unsigned cvt_pk_bf16(float lo, float hi) { unsigned r; asm("v_cvt_pk_bf16_f32 %0, %1, %2" : "=v"(r) : "v"(lo), "v"(hi)); return r; }
; #define PG8_BAR __builtin_amdgcn_s_barrier()
;     __device__ __forceinline__ void operator()(const f32x4 (&acc)[2][2][4][2], const Unit& u, int wr, int wc, int fr, int fq) const {
;     ...
; #pragma unroll
;         for (int ai = 0; ai < 2; ++ai)
; #pragma unroll
;             for (int m = 0; m < 4; ++m) { gbf* rowp = O + (size_t)(row0 + ai * HALF + m * 16) * ldc + col0;
; #pragma unroll
;                 for (int bj = 0; bj < 2; ++bj) { const f32x4 v0 = acc[ai][bj][m][0] * cs[bj][0], v1 = acc[ai][bj][m][1] * cs[bj][1];
;                     u32x4 w; w.x = cvt_pk_bf16(v0[0], v0[1]); w.y = cvt_pk_bf16(v0[2], v0[3]); w.z = cvt_pk_bf16(v1[0], v1[1]); w.w = cvt_pk_bf16(v1[2], v1[3]);
;                     *(GAS u32x4*)(rowp + bj * HALF) = w; } }
;     ...
;         if constexpr (ALIGN_EPI) { if (wr == 0) PG8_BAR; }
;         E(acc, cur, wr, wc, fr, fq);
;         if (!has_next) break;
; #pragma unroll
;         for (int a = 0; a < 2; ++a)
; #pragma unroll
;             for (int b = 0; b < 2; ++b)
; #pragma unroll
;                 for (int m = 0; m < 4; ++m)
; #pragma unroll
;                     for (int n = 0; n < 2; ++n) acc[a][b][m][n] = (f32x4){0.f, 0.f, 0.f, 0.f};
;         cur = nxt; cA = nA; cB = nB; ++ui;
;         if constexpr (ALIGN_EPI) { if (wr == 1) PG8_BAR; }
	v_mul_f32_e32 v39, v39, v153
	v_cvt_pk_bf16_f32 v76, v76, v77
	v_cvt_pk_bf16_f32 v77, v84, v85
	global_store_dwordx4 v[78:79], v[74:77], off
	v_mul_f32_e32 v34, v34, v142
	v_mul_f32_e32 v35, v35, v143
	v_mul_f32_e32 v24, v24, v156
	v_mul_f32_e32 v25, v25, v157
	v_mul_f32_e32 v74, v68, v158
	v_mul_f32_e32 v75, v69, v159
	v_mul_f32_e32 v68, v66, v150
	v_mul_f32_e32 v69, v67, v151
	v_cvt_pk_bf16_f32 v66, v70, v71
	v_cvt_pk_bf16_f32 v67, v72, v73
	v_mul_f32_e32 v22, v22, v152
	v_mul_f32_e32 v23, v23, v153
	v_cvt_pk_bf16_f32 v68, v68, v69
	v_cvt_pk_bf16_f32 v69, v74, v75
	global_store_dwordx4 v[78:79], v[66:69], off offset:256
	v_mul_f32_e32 v18, v18, v142
	v_mul_f32_e32 v19, v19, v143
	v_mul_f32_e32 v8, v8, v156
	v_mul_f32_e32 v9, v9, v157
	v_lshl_add_u64 v[66:67], v[146:147], 0, s[8:9]
	s_mov_b32 s8, 0x1000000
	v_mul_f32_e32 v68, v60, v148
	v_mul_f32_e32 v69, v61, v149
	v_mul_f32_e32 v60, v58, v140
	v_mul_f32_e32 v61, v59, v141
	v_cvt_pk_bf16_f32 v58, v62, v63
	v_add_co_u32_e32 v62, vcc, s8, v146
	v_cvt_pk_bf16_f32 v59, v64, v65
	v_cvt_pk_bf16_f32 v60, v60, v61
	v_cvt_pk_bf16_f32 v61, v68, v69
	s_mov_b64 s[8:9], 0x1200000
	s_nop 0
	v_addc_co_u32_e32 v63, vcc, 0, v147, vcc
	global_store_dwordx4 v[62:63], v[58:61], off
	v_mul_f32_e32 v6, v6, v152
	v_mul_f32_e32 v7, v7, v153
	s_nop 0
	v_mul_f32_e32 v58, v48, v158
	v_mul_f32_e32 v59, v49, v159
	v_mul_f32_e32 v48, v46, v150
	v_mul_f32_e32 v49, v47, v151
	v_cvt_pk_bf16_f32 v46, v54, v55
	v_cvt_pk_bf16_f32 v47, v56, v57
	s_nop 0
	v_cvt_pk_bf16_f32 v48, v48, v49
	v_cvt_pk_bf16_f32 v49, v58, v59
	global_store_dwordx4 v[66:67], v[46:49], off offset:256
	s_nop 1
	v_lshl_add_u64 v[46:47], v[146:147], 0, s[8:9]
	v_mul_f32_e32 v48, v52, v144
	v_mul_f32_e32 v49, v53, v145
	s_mov_b32 s8, 0x1200000
	v_mul_f32_e32 v52, v44, v148
	v_mul_f32_e32 v53, v45, v149
	v_mul_f32_e32 v44, v42, v140
	v_mul_f32_e32 v45, v43, v141
	v_cvt_pk_bf16_f32 v43, v48, v49
	v_add_co_u32_e32 v48, vcc, s8, v146
	v_cvt_pk_bf16_f32 v42, v50, v51
	v_cvt_pk_bf16_f32 v44, v44, v45
	v_cvt_pk_bf16_f32 v45, v52, v53
	s_mov_b64 s[8:9], 0x1400000
	s_nop 0
	v_addc_co_u32_e32 v49, vcc, 0, v147, vcc
	global_store_dwordx4 v[48:49], v[42:45], off
	s_nop 1
	v_mul_f32_e32 v42, v32, v158
	v_mul_f32_e32 v43, v33, v159
	v_mul_f32_e32 v32, v30, v150
	v_mul_f32_e32 v33, v31, v151
	v_cvt_pk_bf16_f32 v30, v38, v39
	v_cvt_pk_bf16_f32 v31, v40, v41
	s_nop 0
	v_cvt_pk_bf16_f32 v32, v32, v33
	v_cvt_pk_bf16_f32 v33, v42, v43
	global_store_dwordx4 v[46:47], v[30:33], off offset:256
	s_nop 1
	v_lshl_add_u64 v[30:31], v[146:147], 0, s[8:9]
	v_mul_f32_e32 v32, v36, v144
	v_mul_f32_e32 v33, v37, v145
	s_mov_b32 s8, 0x1400000
	v_mul_f32_e32 v36, v28, v148
	v_mul_f32_e32 v37, v29, v149
	v_mul_f32_e32 v28, v26, v140
	v_mul_f32_e32 v29, v27, v141
	v_cvt_pk_bf16_f32 v27, v32, v33
	v_add_co_u32_e32 v32, vcc, s8, v146
	v_cvt_pk_bf16_f32 v26, v34, v35
	v_cvt_pk_bf16_f32 v28, v28, v29
	v_cvt_pk_bf16_f32 v29, v36, v37
	s_mov_b64 s[8:9], 0x1600000
	s_nop 0
	v_addc_co_u32_e32 v33, vcc, 0, v147, vcc
	global_store_dwordx4 v[32:33], v[26:29], off
	s_nop 1
	v_mul_f32_e32 v26, v16, v158
	v_mul_f32_e32 v27, v17, v159
	v_mul_f32_e32 v16, v14, v150
	v_mul_f32_e32 v17, v15, v151
	v_cvt_pk_bf16_f32 v14, v22, v23
	v_cvt_pk_bf16_f32 v15, v24, v25
	s_nop 0
	v_cvt_pk_bf16_f32 v16, v16, v17
	v_cvt_pk_bf16_f32 v17, v26, v27
	global_store_dwordx4 v[30:31], v[14:17], off offset:256
	s_nop 1
	v_lshl_add_u64 v[14:15], v[146:147], 0, s[8:9]
	v_mul_f32_e32 v16, v20, v144
	v_mul_f32_e32 v17, v21, v145
	s_mov_b32 s8, 0x1600000
	v_mul_f32_e32 v20, v12, v148
	v_mul_f32_e32 v21, v13, v149
	v_mul_f32_e32 v12, v10, v140
	v_mul_f32_e32 v13, v11, v141
	v_cvt_pk_bf16_f32 v11, v16, v17
	v_add_co_u32_e32 v16, vcc, s8, v146
	v_cvt_pk_bf16_f32 v10, v18, v19
	v_cvt_pk_bf16_f32 v12, v12, v13
	v_cvt_pk_bf16_f32 v13, v20, v21
	s_nop 1
	v_addc_co_u32_e32 v17, vcc, 0, v147, vcc
	global_store_dwordx4 v[16:17], v[10:13], off
	s_andn2_b64 vcc, exec, s[6:7]
	s_mov_b64 s[6:7], -1
	v_mul_f32_e32 v10, v4, v158
	v_mul_f32_e32 v11, v5, v159
	v_mul_f32_e32 v4, v2, v150
	v_mul_f32_e32 v5, v3, v151
	v_cvt_pk_bf16_f32 v2, v6, v7
	v_cvt_pk_bf16_f32 v3, v8, v9
	s_nop 0
	v_cvt_pk_bf16_f32 v4, v4, v5
	v_cvt_pk_bf16_f32 v5, v10, v11
	global_store_dwordx4 v[14:15], v[2:5], off offset:256
	s_cbranch_vccnz .LBB0_209
	s_andn2_b64 vcc, exec, s[4:5]
	s_cbranch_vccnz .LBB0_208
	s_barrier
	s_branch .LBB0_208

; #define GAS __attribute__((address_space(1)))
; __device__ __forceinline__ float unif(float v) { return __int_as_float(__builtin_amdgcn_readfirstlane(__float_as_int(v))); }
; __global__ void __launch_bounds__(512, 2) mega_fwd(Params p) {
;     ...
;               const float lam_init = l == 0 ? 0.2f : 0.35550906758f;
;               float d1 = 0.f, d2 = 0.f;
;               for (int i = 0; i < 64; ++i) { d1 += ((const gfl*)pp->in[5])[l * 64 + i] * ((const gfl*)pp->in[6])[l * 64 + i]; d2 += ((const gfl*)pp->in[7])[l * 64 + i] * ((const gfl*)pp->in[8])[l * 64 + i]; }
;               const float lam = unif(__expf(d1) - __expf(d2) + lam_init);
;               const int NQA = S / 128, nA = NB * 4 * NQA;
;               const gfl* subln = uni(((const gfl*)pp->in[9]) + l * 128);
;               const GAS unsigned* kn2 = uni((const GAS unsigned*)(ws + WS_KN2));
;               const float oml = unif(1.f - lam_init);
.LBB0_286:
	s_add_u32 s20, s2, s6
	s_addc_u32 s21, s8, s7
	global_load_dwordx4 v[4:7], v1, s[20:21] offset:16
	global_load_dwordx4 v[8:11], v1, s[20:21]
	s_add_u32 s20, s11, s6
	s_addc_u32 s21, s16, s7
	global_load_dwordx4 v[12:15], v1, s[20:21] offset:16
	global_load_dwordx4 v[16:19], v1, s[20:21]
	s_add_u32 s20, s9, s6
	s_addc_u32 s21, s10, s7
	global_load_dwordx4 v[20:23], v1, s[20:21] offset:16
	global_load_dwordx4 v[24:27], v1, s[20:21]
	s_add_u32 s20, s0, s6
	s_addc_u32 s21, s1, s7
	global_load_dwordx4 v[28:31], v1, s[20:21] offset:16
	global_load_dwordx4 v[32:35], v1, s[20:21]
	s_add_u32 s6, s6, 32
	s_addc_u32 s7, s7, 0
	s_cmpk_eq_i32 s6, 0x100
	s_waitcnt vmcnt(6)
	v_mov_b32_e32 v36, v8
	v_mov_b32_e32 v8, v10
	s_waitcnt vmcnt(5)
	v_mov_b32_e32 v10, v12
	s_waitcnt vmcnt(4)
	v_mov_b32_e32 v38, v16
	v_mov_b32_e32 v16, v18
	s_waitcnt vmcnt(2)
	v_mov_b32_e32 v37, v24
	v_mov_b32_e32 v24, v9
	v_mov_b32_e32 v9, v26
	s_waitcnt vmcnt(0)
	v_mov_b32_e32 v39, v32
	v_fma_f32 v2, v36, v38, v2
	v_fma_f32 v3, v37, v39, v3
	v_mov_b32_e32 v32, v17
	v_fma_f32 v2, v24, v32, v2
	v_fma_f32 v3, v25, v33, v3
	v_mov_b32_e32 v17, v34
	v_fma_f32 v2, v8, v16, v2
	v_fma_f32 v3, v9, v17, v3
	v_mov_b32_e32 v26, v11
	v_mov_b32_e32 v34, v19
	v_fma_f32 v2, v26, v34, v2
	v_fma_f32 v3, v27, v35, v3
	v_mov_b32_e32 v8, v4
	v_mov_b32_e32 v9, v20
	v_mov_b32_e32 v11, v28
	v_fma_f32 v2, v8, v10, v2
	v_fma_f32 v3, v9, v11, v3
	v_mov_b32_e32 v20, v5
	v_mov_b32_e32 v28, v13
	v_fma_f32 v2, v20, v28, v2
	v_fma_f32 v3, v21, v29, v3
	v_mov_b32_e32 v4, v6
	v_mov_b32_e32 v5, v22
	v_mov_b32_e32 v8, v14
	v_mov_b32_e32 v9, v30
	v_fma_f32 v2, v4, v8, v2
	v_fma_f32 v3, v5, v9, v3
	v_mov_b32_e32 v22, v7
	v_mov_b32_e32 v30, v15
	v_fma_f32 v2, v22, v30, v2
	v_fma_f32 v3, v23, v31, v3
	s_cbranch_scc0 .LBB0_286
	s_cmp_eq_u32 s19, 0
	s_cselect_b64 vcc, -1, 0
	s_add_u32 s92, s12, 0xc000000
	s_addc_u32 s93, s13, 0
	s_add_u32 s34, s12, 0x2a000000
	s_addc_u32 s35, s13, 0
	v_mul_f32_e32 v0, 0x3fb8aa3b, v2
	v_mul_f32_e32 v2, 0x3fb8aa3b, v3
	s_add_u32 s0, s12, 0x30000000
	v_exp_f32_e32 v0, v0
	v_exp_f32_e32 v2, v2
	v_writelane_b32 v254, s0, 61
	s_addc_u32 s0, s13, 0
	s_cmp_eq_u32 s28, 0
	s_cselect_b64 s[94:95], -1, 0
	v_mov_b32_e32 v3, 0x3eb60549
	v_mov_b32_e32 v4, 0x3e4ccccd
	v_writelane_b32 v254, s0, 62
	s_and_b64 s[0:1], s[94:95], exec
	v_cndmask_b32_e32 v3, v3, v4, vcc
	v_sub_f32_e32 v0, v0, v2
	s_movk_i32 s0, 0x1000
	v_add_f32_e32 v0, v3, v0
	s_cselect_b32 s6, s0, 0x2000
	v_readfirstlane_b32 s0, v0
	s_lshr_b32 s39, s6, 7
	s_nop 0
	v_writelane_b32 v255, s0, 0
	s_load_dwordx2 s[0:1], s[4:5], 0x48
	s_lshl_b32 s4, s19, 7
	s_ashr_i32 s5, s4, 31
	s_lshl_b64 s[4:5], s[4:5], 2
	s_waitcnt lgkmcnt(0)
	s_add_u32 s0, s0, s4
	s_addc_u32 s1, s1, s5
	v_writelane_b32 v255, s0, 1
	s_add_u32 s40, s12, 0x1f80000
	s_addc_u32 s41, s13, 0
	v_writelane_b32 v255, s1, 2
	v_readfirstlane_b32 s0, v3
	s_cmpk_eq_i32 s44, 0x100
	s_mov_b64 s[4:5], -1
	v_sub_f32_e64 v207, 1.0, s0
	s_cbranch_scc1 .LBB0_354
	s_and_b64 s[0:1], s[94:95], exec
	v_writelane_b32 v255, s6, 3
	s_cselect_b32 s0, 6, 5
	v_writelane_b32 v255, s28, 5
	s_lshl_b32 s84, s39, s0
	v_writelane_b32 v255, s19, 6
	s_cmp_ge_i32 s45, s84
	s_cbranch_scc1 .LBB0_353
	s_add_i32 s0, s39, -1
	v_writelane_b32 v255, s0, 7
	s_nop 0
	v_readlane_b32 s0, v255, 3
	s_nop 1
	v_cvt_f32_u32_e32 v209, s0
	s_and_b64 s[0:1], s[94:95], exec
	s_cselect_b32 s87, 5, 6
	s_cselect_b32 s90, 12, 13
	s_branch .LBB0_291

; __device__ __forceinline__ int crow(int r, int hi) { return (r & 3) + 8 * (r >> 2) + 4 * hi; }
; template <int TYPE> ...
;     ...
;     if (first || __any(mx > 8.f)) {
;         const float dl = first ? mx : __builtin_fmaxf(mx, 0.f), alpha = __builtin_amdgcn_exp2f(-dl);
;         lsum *= alpha; mref += dl;
; #pragma unroll
;         for (int r = 0; r < 16; ++r) { s0[r] -= dl; s1[r] -= dl; }
;         if (hi == 0) wsf[r32] = alpha;
; #pragma unroll
;         for (int r = 0; r < 16; ++r) { const float al = wsf[crow(r, hi)];
; #pragma unroll
;             for (int d = 0; d < 4; ++d) o[d][r] *= al; }
.LBB0_314:
	v_mov_b64_e32 v[128:129], v[64:65]
	v_mov_b64_e32 v[112:113], v[48:49]
	v_mov_b64_e32 v[96:97], v[32:33]
	v_mov_b64_e32 v[80:81], v[16:17]
	s_andn2_b64 vcc, exec, s[26:27]
	v_mov_b32_e32 v201, v248
	v_mov_b32_e32 v206, v204
	v_mov_b64_e32 v[126:127], v[62:63]
	v_mov_b64_e32 v[124:125], v[60:61]
	v_mov_b64_e32 v[122:123], v[58:59]
	v_mov_b64_e32 v[120:121], v[56:57]
	v_mov_b64_e32 v[118:119], v[54:55]
	v_mov_b64_e32 v[116:117], v[52:53]
	v_mov_b64_e32 v[114:115], v[50:51]
	v_mov_b64_e32 v[110:111], v[46:47]
	v_mov_b64_e32 v[108:109], v[44:45]
	v_mov_b64_e32 v[106:107], v[42:43]
	v_mov_b64_e32 v[104:105], v[40:41]
	v_mov_b64_e32 v[102:103], v[38:39]
	v_mov_b64_e32 v[100:101], v[36:37]
	v_mov_b64_e32 v[98:99], v[34:35]
	v_mov_b64_e32 v[94:95], v[30:31]
	v_mov_b64_e32 v[92:93], v[28:29]
	v_mov_b64_e32 v[90:91], v[26:27]
	v_mov_b64_e32 v[88:89], v[24:25]
	v_mov_b64_e32 v[86:87], v[22:23]
	v_mov_b64_e32 v[84:85], v[20:21]
	v_mov_b64_e32 v[82:83], v[18:19]
	v_mov_b64_e32 v[78:79], v[14:15]
	v_mov_b64_e32 v[76:77], v[12:13]
	v_mov_b64_e32 v[74:75], v[10:11]
	v_mov_b64_e32 v[72:73], v[8:9]
	v_mov_b64_e32 v[70:71], v[6:7]
	v_mov_b64_e32 v[68:69], v[4:5]
	v_mov_b64_e32 v[66:67], v[2:3]
	s_cbranch_vccnz .LBB0_318
	v_max_f32_e32 v66, v249, v249
	v_max_f32_e32 v66, 0, v66
	v_cndmask_b32_e64 v66, v66, v249, s[22:23]
	v_exp_f32_e64 v67, -v66
	s_and_saveexec_b64 s[26:27], s[10:11]
	ds_write_b32 v214, v67
	s_or_b64 exec, exec, s[26:27]
	v_mul_f32_e32 v201, v248, v67
	v_pk_add_f32 v[130:131], v[130:131], v[66:67] op_sel_hi:[1,0] neg_lo:[0,1] neg_hi:[0,1]
	v_pk_add_f32 v[146:147], v[146:147], v[66:67] op_sel_hi:[1,0] neg_lo:[0,1] neg_hi:[0,1]
	v_pk_add_f32 v[132:133], v[132:133], v[66:67] op_sel_hi:[1,0] neg_lo:[0,1] neg_hi:[0,1]
	v_pk_add_f32 v[148:149], v[148:149], v[66:67] op_sel_hi:[1,0] neg_lo:[0,1] neg_hi:[0,1]
	v_pk_add_f32 v[134:135], v[134:135], v[66:67] op_sel_hi:[1,0] neg_lo:[0,1] neg_hi:[0,1]
	v_pk_add_f32 v[150:151], v[150:151], v[66:67] op_sel_hi:[1,0] neg_lo:[0,1] neg_hi:[0,1]
	v_pk_add_f32 v[136:137], v[136:137], v[66:67] op_sel_hi:[1,0] neg_lo:[0,1] neg_hi:[0,1]
	v_pk_add_f32 v[152:153], v[152:153], v[66:67] op_sel_hi:[1,0] neg_lo:[0,1] neg_hi:[0,1]
	v_pk_add_f32 v[138:139], v[138:139], v[66:67] op_sel_hi:[1,0] neg_lo:[0,1] neg_hi:[0,1]
	v_pk_add_f32 v[154:155], v[154:155], v[66:67] op_sel_hi:[1,0] neg_lo:[0,1] neg_hi:[0,1]
	v_pk_add_f32 v[140:141], v[140:141], v[66:67] op_sel_hi:[1,0] neg_lo:[0,1] neg_hi:[0,1]
	v_pk_add_f32 v[156:157], v[156:157], v[66:67] op_sel_hi:[1,0] neg_lo:[0,1] neg_hi:[0,1]
	v_pk_add_f32 v[142:143], v[142:143], v[66:67] op_sel_hi:[1,0] neg_lo:[0,1] neg_hi:[0,1]
	v_pk_add_f32 v[158:159], v[158:159], v[66:67] op_sel_hi:[1,0] neg_lo:[0,1] neg_hi:[0,1]
	v_add_u32_e32 v67, s43, v0
	ds_read_b128 v[114:117], v67 offset:64
	ds_read_b128 v[118:121], v67 offset:96
	ds_read_b128 v[184:187], v67
	ds_read_b128 v[192:195], v67 offset:32
	v_add_f32_e32 v206, v204, v66
	v_pk_add_f32 v[144:145], v[144:145], v[66:67] op_sel_hi:[1,0] neg_lo:[0,1] neg_hi:[0,1]
	v_pk_add_f32 v[160:161], v[160:161], v[66:67] op_sel_hi:[1,0] neg_lo:[0,1] neg_hi:[0,1]
	s_waitcnt lgkmcnt(0)
	v_mul_f32_e32 v78, v14, v118
	v_mul_f32_e32 v79, v15, v119
	v_mul_f32_e32 v74, v10, v114
	v_mul_f32_e32 v75, v11, v115
	v_mul_f32_e32 v70, v6, v192
	v_mul_f32_e32 v71, v7, v193
	v_mul_f32_e32 v80, v16, v120
	v_mul_f32_e32 v81, v17, v121
	v_mul_f32_e32 v76, v12, v116
	v_mul_f32_e32 v77, v13, v117
	v_mul_f32_e32 v72, v8, v194
	v_mul_f32_e32 v73, v9, v195
	v_mul_f32_e32 v68, v4, v186
	v_mul_f32_e32 v69, v5, v187
	v_mul_f32_e32 v66, v2, v184
	v_mul_f32_e32 v67, v3, v185
	v_mul_f32_e32 v94, v30, v118
	v_mul_f32_e32 v95, v31, v119
	v_mul_f32_e32 v90, v26, v114
	v_mul_f32_e32 v91, v27, v115
	v_mul_f32_e32 v86, v22, v192
	v_mul_f32_e32 v87, v23, v193
	v_mul_f32_e32 v96, v32, v120
	v_mul_f32_e32 v97, v33, v121
	v_mul_f32_e32 v92, v28, v116
	v_mul_f32_e32 v93, v29, v117
	v_mul_f32_e32 v88, v24, v194
	v_mul_f32_e32 v89, v25, v195
	v_mul_f32_e32 v84, v20, v186
	v_mul_f32_e32 v85, v21, v187
	v_mul_f32_e32 v82, v18, v184
	v_mul_f32_e32 v83, v19, v185
	v_mul_f32_e32 v110, v46, v118
	v_mul_f32_e32 v111, v47, v119
	v_mul_f32_e32 v106, v42, v114
	v_mul_f32_e32 v107, v43, v115
	v_mul_f32_e32 v102, v38, v192
	v_mul_f32_e32 v103, v39, v193
	v_mul_f32_e32 v112, v48, v120
	v_mul_f32_e32 v113, v49, v121
	v_mul_f32_e32 v108, v44, v116
	v_mul_f32_e32 v109, v45, v117
	v_mul_f32_e32 v104, v40, v194
	v_mul_f32_e32 v105, v41, v195
	v_mul_f32_e32 v100, v36, v186
	v_mul_f32_e32 v101, v37, v187
	v_mul_f32_e32 v98, v34, v184
	v_mul_f32_e32 v99, v35, v185
	v_mul_f32_e32 v126, v62, v118
	v_mul_f32_e32 v127, v63, v119
	v_mul_f32_e32 v122, v58, v114
	v_mul_f32_e32 v123, v59, v115
	v_mul_f32_e32 v118, v54, v192
	v_mul_f32_e32 v119, v55, v193
	v_mul_f32_e32 v128, v64, v120
	v_mul_f32_e32 v129, v65, v121
	v_mul_f32_e32 v124, v60, v116
	v_mul_f32_e32 v125, v61, v117
	v_mul_f32_e32 v120, v56, v194
	v_mul_f32_e32 v121, v57, v195
	v_mul_f32_e32 v116, v52, v186
	v_mul_f32_e32 v117, v53, v187
	v_mul_f32_e32 v114, v50, v184
	v_mul_f32_e32 v115, v51, v185

; __device__ __forceinline__ int crow(int r, int hi) { return (r & 3) + 8 * (r >> 2) + 4 * hi; }
; template <int TYPE> ...
;     ...
;     if (first || __any(mx > 8.f)) {
;         const float dl = first ? mx : __builtin_fmaxf(mx, 0.f), alpha = __builtin_amdgcn_exp2f(-dl);
;         lsum *= alpha; mref += dl;
; #pragma unroll
;         for (int r = 0; r < 16; ++r) { s0[r] -= dl; s1[r] -= dl; }
;         if (hi == 0) wsf[r32] = alpha;
; #pragma unroll
;         for (int r = 0; r < 16; ++r) { const float al = wsf[crow(r, hi)];
; #pragma unroll
;             for (int d = 0; d < 4; ++d) o[d][r] *= al; }
.LBB0_323:
	s_andn2_b64 vcc, exec, s[24:25]
	s_cbranch_vccnz .LBB0_327
	v_max_f32_e32 v99, v98, v98
	v_max_f32_e32 v99, 0, v99
	v_cndmask_b32_e64 v98, v99, v98, s[22:23]
	v_exp_f32_e64 v99, -v98
	s_and_saveexec_b64 s[22:23], s[10:11]
	ds_write_b32 v214, v99
	s_or_b64 exec, exec, s[22:23]
	v_add_u32_e32 v110, s43, v0
	v_mul_f32_e32 v248, v248, v99
	v_add_f32_e32 v204, v204, v98
	v_sub_f32_e32 v97, v97, v98
	v_sub_f32_e32 v96, v96, v98
	v_sub_f32_e32 v95, v95, v98
	v_sub_f32_e32 v94, v94, v98
	v_sub_f32_e32 v93, v93, v98
	v_sub_f32_e32 v92, v92, v98
	v_sub_f32_e32 v91, v91, v98
	v_sub_f32_e32 v90, v90, v98
	v_sub_f32_e32 v89, v89, v98
	v_sub_f32_e32 v88, v88, v98
	v_sub_f32_e32 v87, v87, v98
	v_sub_f32_e32 v86, v86, v98
	v_sub_f32_e32 v85, v85, v98
	v_sub_f32_e32 v84, v84, v98
	v_sub_f32_e32 v83, v83, v98
	v_sub_f32_e32 v82, v82, v98
	v_sub_f32_e32 v81, v81, v98
	v_sub_f32_e32 v80, v80, v98
	v_sub_f32_e32 v79, v79, v98
	v_sub_f32_e32 v78, v78, v98
	v_sub_f32_e32 v77, v77, v98
	v_sub_f32_e32 v76, v76, v98
	v_sub_f32_e32 v75, v75, v98
	v_sub_f32_e32 v74, v74, v98
	v_sub_f32_e32 v73, v73, v98
	v_sub_f32_e32 v72, v72, v98
	v_sub_f32_e32 v71, v71, v98
	v_sub_f32_e32 v70, v70, v98
	v_sub_f32_e32 v69, v69, v98
	v_sub_f32_e32 v68, v68, v98
	v_sub_f32_e32 v67, v67, v98
	v_sub_f32_e32 v66, v66, v98
	ds_read_b128 v[98:101], v110
	ds_read_b128 v[102:105], v110 offset:32
	ds_read_b128 v[106:109], v110 offset:64
	ds_read_b128 v[110:113], v110 offset:96
	s_waitcnt lgkmcnt(0)
	v_mul_f32_e32 v4, v4, v100
	v_mul_f32_e32 v5, v5, v101
	v_mul_f32_e32 v6, v6, v102
	v_mul_f32_e32 v7, v7, v103
	v_mul_f32_e32 v10, v10, v106
	v_mul_f32_e32 v11, v11, v107
	v_mul_f32_e32 v14, v14, v110
	v_mul_f32_e32 v15, v15, v111
	v_mul_f32_e32 v16, v16, v112
	v_mul_f32_e32 v17, v17, v113
	v_mul_f32_e32 v12, v12, v108
	v_mul_f32_e32 v13, v13, v109
	v_mul_f32_e32 v8, v8, v104
	v_mul_f32_e32 v9, v9, v105
	v_mul_f32_e32 v2, v2, v98
	v_mul_f32_e32 v3, v3, v99
	v_mul_f32_e32 v30, v30, v110
	v_mul_f32_e32 v31, v31, v111
	v_mul_f32_e32 v26, v26, v106
	v_mul_f32_e32 v27, v27, v107
	v_mul_f32_e32 v22, v22, v102
	v_mul_f32_e32 v23, v23, v103
	v_mul_f32_e32 v32, v32, v112
	v_mul_f32_e32 v33, v33, v113
	v_mul_f32_e32 v28, v28, v108
	v_mul_f32_e32 v29, v29, v109
	v_mul_f32_e32 v24, v24, v104
	v_mul_f32_e32 v25, v25, v105
	v_mul_f32_e32 v20, v20, v100
	v_mul_f32_e32 v21, v21, v101
	v_mul_f32_e32 v18, v18, v98
	v_mul_f32_e32 v19, v19, v99
	v_mul_f32_e32 v46, v46, v110
	v_mul_f32_e32 v47, v47, v111
	v_mul_f32_e32 v42, v42, v106
	v_mul_f32_e32 v43, v43, v107
	v_mul_f32_e32 v38, v38, v102
	v_mul_f32_e32 v39, v39, v103
	v_mul_f32_e32 v48, v48, v112
	v_mul_f32_e32 v49, v49, v113
	v_mul_f32_e32 v44, v44, v108
	v_mul_f32_e32 v45, v45, v109
	v_mul_f32_e32 v40, v40, v104
	v_mul_f32_e32 v41, v41, v105
	v_mul_f32_e32 v36, v36, v100
	v_mul_f32_e32 v37, v37, v101
	v_mul_f32_e32 v34, v34, v98
	v_mul_f32_e32 v35, v35, v99
	v_mul_f32_e32 v62, v62, v110
	v_mul_f32_e32 v63, v63, v111
	v_mul_f32_e32 v58, v58, v106
	v_mul_f32_e32 v59, v59, v107
	v_mul_f32_e32 v54, v54, v102
	v_mul_f32_e32 v55, v55, v103
	v_mul_f32_e32 v64, v64, v112
	v_mul_f32_e32 v65, v65, v113
	v_mul_f32_e32 v60, v60, v108
	v_mul_f32_e32 v61, v61, v109
	v_mul_f32_e32 v56, v56, v104
	v_mul_f32_e32 v57, v57, v105
	v_mul_f32_e32 v52, v52, v100
	v_mul_f32_e32 v53, v53, v101
	v_mul_f32_e32 v50, v50, v98
	v_mul_f32_e32 v51, v51, v99

; #define LAS __attribute__((address_space(3)))
; __device__ __forceinline__ float nopack(float v) { asm("" : "+v"(v)); return v; }
; template <int TYPE> ...
;     ...
;     if (TYPE == 2) {
; #pragma unroll
;         for (int r = 0; r < 16; ++r) { const float c = (float)((r & 7) + 16 * (r >> 3));
;             s0[r] = __builtin_fmaf(nslope, __builtin_fabsf(dbase + c), -mref); s1[r] = __builtin_fmaf(nslope, __builtin_fabsf(dbase + (c + 32.f)), -mref); }
;     } else {
;         const float sg = nslope, bl = __builtin_fmaf(sg, dbase, -mref);
; #pragma unroll
;         for (int r = 0; r < 16; ++r) { const float c = (float)((r & 7) + 16 * (r >> 3)); s0[r] = nopack(__builtin_fmaf(sg, c, bl)); s1[r] = nopack(__builtin_fmaf(sg, c + 32.f, bl)); }
;     }
; #pragma unroll
;     for (int dc = 0; dc < 4; ++dc) {
;         const bf16x8 a0 = *(const LAS bf16x8*)(lds + kad[dc]);
;         const bf16x8 a1 = *(const LAS bf16x8*)(lds + kad[dc] + 8192);
;         s0 = __builtin_amdgcn_mfma_f32_32x32x16_bf16(a0, qf[dc], s0, 0, 0, 0);
;         s1 = __builtin_amdgcn_mfma_f32_32x32x16_bf16(a1, qf[dc], s1, 0, 0, 0);
;     }
.LBB0_328:
	s_or_b32 s24, s76, 64
	s_or_b32 s25, s76, 0x7f
	v_cvt_f32_u32_e32 v2, s24
	s_cmp_gt_i32 s33, s25
	s_cselect_b64 s[22:23], -1, 0
	s_cmp_gt_i32 s24, s2
	s_cselect_b64 s[26:27], -1, 0
	s_or_b64 s[26:27], s[22:23], s[26:27]
	v_sub_f32_e32 v208, v2, v236
	s_mov_b64 s[22:23], -1
	s_and_b64 vcc, exec, s[26:27]
	s_cbranch_vccnz .LBB0_334
	v_pk_add_f32 v[6:7], v[208:209], s[50:51] op_sel_hi:[0,1]
	v_pk_add_f32 v[2:3], v[208:209], s[46:47] op_sel_hi:[0,1]
	v_pk_add_f32 v[4:5], v[208:209], s[48:49] op_sel_hi:[0,1]
	v_pk_add_f32 v[8:9], v[208:209], s[52:53] op_sel_hi:[0,1]
	v_and_b32_e32 v7, 0x7fffffff, v7
	v_and_b32_e32 v6, 0x7fffffff, v6
	v_mov_b32_e32 v201, v200
	v_and_b32_e32 v3, 0x7fffffff, v3
	v_and_b32_e32 v2, 0x7fffffff, v2
	v_and_b32_e32 v5, 0x7fffffff, v5
	v_and_b32_e32 v4, 0x7fffffff, v4
	v_and_b32_e32 v9, 0x7fffffff, v9
	v_and_b32_e32 v8, 0x7fffffff, v8
	v_pk_fma_f32 v[136:137], v[200:201], v[6:7], v[206:207] op_sel_hi:[1,1,0] neg_lo:[0,0,1] neg_hi:[0,0,1]
	v_pk_add_f32 v[6:7], v[208:209], s[60:61] op_sel_hi:[0,1]
	s_add_i32 s26, s89, 0
	v_pk_fma_f32 v[138:139], v[200:201], v[8:9], v[206:207] op_sel_hi:[1,1,0] neg_lo:[0,0,1] neg_hi:[0,0,1]
	v_pk_fma_f32 v[134:135], v[200:201], v[4:5], v[206:207] op_sel_hi:[1,1,0] neg_lo:[0,0,1] neg_hi:[0,0,1]
	v_pk_fma_f32 v[132:133], v[200:201], v[2:3], v[206:207] op_sel_hi:[1,1,0] neg_lo:[0,0,1] neg_hi:[0,0,1]
	v_pk_add_f32 v[8:9], v[208:209], s[62:63] op_sel_hi:[0,1]
	v_pk_add_f32 v[2:3], v[208:209], s[66:67] op_sel_hi:[0,1]
	v_pk_add_f32 v[4:5], v[208:209], s[68:69] op_sel_hi:[0,1]
	v_add_u32_e32 v24, s26, v213
	v_and_b32_e32 v7, 0x7fffffff, v7
	v_and_b32_e32 v6, 0x7fffffff, v6
	v_and_b32_e32 v19, 0x7fffffff, v5
	v_and_b32_e32 v18, 0x7fffffff, v4
	v_and_b32_e32 v21, 0x7fffffff, v3
	v_and_b32_e32 v20, 0x7fffffff, v2
	ds_read_b128 v[2:5], v24 offset:32768
	v_and_b32_e32 v23, 0x7fffffff, v9
	v_and_b32_e32 v22, 0x7fffffff, v8
	v_pk_fma_f32 v[160:161], v[200:201], v[6:7], v[206:207] op_sel_hi:[1,1,0] neg_lo:[0,0,1] neg_hi:[0,0,1]
	ds_read_b128 v[6:9], v24 offset:40960
	v_add_f32_e32 v17, 1.0, v208
	v_pk_add_f32 v[10:11], v[208:209], s[54:55] op_sel_hi:[0,1]
	v_pk_add_f32 v[12:13], v[208:209], s[56:57] op_sel_hi:[0,1]
	v_pk_add_f32 v[14:15], v[208:209], s[58:59] op_sel_hi:[0,1]
	v_and_b32_e32 v11, 0x7fffffff, v11
	v_and_b32_e32 v10, 0x7fffffff, v10
	v_and_b32_e32 v13, 0x7fffffff, v13
	v_and_b32_e32 v12, 0x7fffffff, v12
	v_and_b32_e32 v15, 0x7fffffff, v15
	v_and_b32_e32 v14, 0x7fffffff, v14
	v_and_b32_e32 v16, 0x7fffffff, v208
	v_and_b32_e32 v17, 0x7fffffff, v17
	v_pk_fma_f32 v[144:145], v[200:201], v[14:15], v[206:207] op_sel_hi:[1,1,0] neg_lo:[0,0,1] neg_hi:[0,0,1]
	v_pk_fma_f32 v[142:143], v[200:201], v[12:13], v[206:207] op_sel_hi:[1,1,0] neg_lo:[0,0,1] neg_hi:[0,0,1]
	v_pk_fma_f32 v[140:141], v[200:201], v[10:11], v[206:207] op_sel_hi:[1,1,0] neg_lo:[0,0,1] neg_hi:[0,0,1]
	v_pk_fma_f32 v[130:131], v[202:203], v[16:17], v[206:207] op_sel_hi:[1,1,0] neg_lo:[0,0,1] neg_hi:[0,0,1]
	v_pk_add_f32 v[10:11], v[208:209], s[64:65] op_sel_hi:[0,1]
	v_pk_add_f32 v[12:13], v[208:209], s[70:71] op_sel_hi:[0,1]
	v_pk_add_f32 v[14:15], v[208:209], s[72:73] op_sel_hi:[0,1]
	v_pk_add_f32 v[16:17], v[208:209], s[74:75] op_sel_hi:[0,1]
	v_and_b32_e32 v17, 0x7fffffff, v17
	v_and_b32_e32 v16, 0x7fffffff, v16
	v_and_b32_e32 v15, 0x7fffffff, v15
	v_and_b32_e32 v14, 0x7fffffff, v14
	v_and_b32_e32 v13, 0x7fffffff, v13
	v_and_b32_e32 v12, 0x7fffffff, v12
	v_and_b32_e32 v11, 0x7fffffff, v11
	v_and_b32_e32 v10, 0x7fffffff, v10
	v_pk_fma_f32 v[158:159], v[200:201], v[22:23], v[206:207] op_sel_hi:[1,1,0] neg_lo:[0,0,1] neg_hi:[0,0,1]
	v_pk_fma_f32 v[156:157], v[200:201], v[10:11], v[206:207] op_sel_hi:[1,1,0] neg_lo:[0,0,1] neg_hi:[0,0,1]
	v_pk_fma_f32 v[154:155], v[200:201], v[20:21], v[206:207] op_sel_hi:[1,1,0] neg_lo:[0,0,1] neg_hi:[0,0,1]
	v_pk_fma_f32 v[152:153], v[200:201], v[18:19], v[206:207] op_sel_hi:[1,1,0] neg_lo:[0,0,1] neg_hi:[0,0,1]
	v_pk_fma_f32 v[150:151], v[200:201], v[12:13], v[206:207] op_sel_hi:[1,1,0] neg_lo:[0,0,1] neg_hi:[0,0,1]
	v_pk_fma_f32 v[148:149], v[200:201], v[14:15], v[206:207] op_sel_hi:[1,1,0] neg_lo:[0,0,1] neg_hi:[0,0,1]
	v_pk_fma_f32 v[146:147], v[202:203], v[16:17], v[206:207] op_sel_hi:[1,1,0] neg_lo:[0,0,1] neg_hi:[0,0,1]
	s_waitcnt lgkmcnt(0)
	v_mfma_f32_32x32x16_bf16 v[130:145], v[2:5], v[162:165], v[130:145]
	v_mov_b64_e32 v[50:51], v[114:115]
	v_mov_b64_e32 v[34:35], v[98:99]
	v_mov_b64_e32 v[18:19], v[82:83]
	v_mov_b32_e32 v201, v249
	v_mov_b32_e32 v204, v206
	v_mov_b64_e32 v[52:53], v[116:117]
	v_mov_b64_e32 v[54:55], v[118:119]
	v_mfma_f32_32x32x16_bf16 v[146:161], v[6:9], v[162:165], v[146:161]
	ds_read_b128 v[2:5], v247 offset:32768
	ds_read_b128 v[6:9], v247 offset:40960
	v_mov_b64_e32 v[56:57], v[120:121]
	v_mov_b64_e32 v[58:59], v[122:123]
	v_mov_b64_e32 v[60:61], v[124:125]
	v_mov_b64_e32 v[62:63], v[126:127]
	v_mov_b64_e32 v[64:65], v[128:129]
	v_mov_b64_e32 v[36:37], v[100:101]
	s_waitcnt lgkmcnt(0)
	v_mfma_f32_32x32x16_bf16 v[130:145], v[2:5], v[166:169], v[130:145]
	v_mov_b64_e32 v[38:39], v[102:103]
	v_mov_b64_e32 v[40:41], v[104:105]
	v_mov_b64_e32 v[42:43], v[106:107]
	v_mov_b64_e32 v[44:45], v[108:109]
	v_mov_b64_e32 v[46:47], v[110:111]
	v_mov_b64_e32 v[48:49], v[112:113]
	v_mov_b64_e32 v[20:21], v[84:85]
	v_mfma_f32_32x32x16_bf16 v[146:161], v[6:9], v[166:169], v[146:161]
	ds_read_b128 v[2:5], v246 offset:32768
	ds_read_b128 v[6:9], v246 offset:40960
	v_mov_b64_e32 v[22:23], v[86:87]
	v_mov_b64_e32 v[24:25], v[88:89]
	v_mov_b64_e32 v[26:27], v[90:91]
	v_mov_b64_e32 v[28:29], v[92:93]
	v_mov_b64_e32 v[30:31], v[94:95]
	v_mov_b64_e32 v[32:33], v[96:97]
	s_waitcnt lgkmcnt(0)
; __device__ __forceinline__ float max_x32(float v) { auto rr = __builtin_amdgcn_permlane32_swap(__float_as_uint(v), __float_as_uint(v), false, false); return __builtin_fmaxf(__uint_as_float(rr[0]), __uint_as_float(rr[1])); }
; __device__ __forceinline__ float max3f(float a, float b, float c) { float r; asm("v_max3_f32 %0, %1, %2, %3" : "=v"(r) : "v"(a), "v"(b), "v"(c)); return r; }
; __device__ __forceinline__ float max2f(float a, float b) { float r; asm("v_max_f32_e32 %0, %1, %2" : "=v"(r) : "v"(a), "v"(b)); return r; }
; __device__ __forceinline__ int crow(int r, int hi) { return (r & 3) + 8 * (r >> 2) + 4 * hi; }
; template <int TYPE> ...
;     ...
;     if (chk) {
;     asm volatile("s_nop 15\n\ts_nop 7" : "+v"(s0), "+v"(s1));
;     float mx = max3f(s0[0], s1[0], s0[1]), mx2 = max3f(s1[1], s0[2], s1[2]);
; #pragma unroll
;     for (int r = 3; r < 15; r += 2) { mx = max3f(mx, s0[r], s1[r]); mx2 = max3f(mx2, s0[r + 1], s1[r + 1]); }
;     mx = max3f(mx, s0[15], s1[15]); mx = max2f(mx, mx2);
;     mx = max_x32(mx);
;     if (first || __any(mx > 8.f)) {
;         const float dl = first ? mx : __builtin_fmaxf(mx, 0.f), alpha = __builtin_amdgcn_exp2f(-dl);
;         lsum *= alpha; mref += dl;
; #pragma unroll
;         for (int r = 0; r < 16; ++r) { s0[r] -= dl; s1[r] -= dl; }
;         if (hi == 0) wsf[r32] = alpha;
; #pragma unroll
;         for (int r = 0; r < 16; ++r) { const float al = wsf[crow(r, hi)];
; #pragma unroll
;             for (int d = 0; d < 4; ++d) o[d][r] *= al; }
	v_mfma_f32_32x32x16_bf16 v[130:145], v[2:5], v[170:173], v[130:145]
	v_mfma_f32_32x32x16_bf16 v[146:161], v[6:9], v[170:173], v[146:161]
	ds_read_b128 v[2:5], v245 offset:32768
	ds_read_b128 v[6:9], v245 offset:40960
	s_waitcnt lgkmcnt(0)
	v_mfma_f32_32x32x16_bf16 v[130:145], v[2:5], v[174:177], v[130:145]
	v_mfma_f32_32x32x16_bf16 v[146:161], v[6:9], v[174:177], v[146:161]
	s_nop 15
	s_nop 7
	s_nop 0
	v_max3_f32 v2, v130, v146, v131
	v_max3_f32 v3, v147, v132, v148
	s_nop 0
	v_max3_f32 v2, v2, v133, v149
	v_max3_f32 v3, v3, v134, v150
	s_nop 0
	v_max3_f32 v2, v2, v135, v151
	v_max3_f32 v3, v3, v136, v152
	s_nop 0
	v_max3_f32 v2, v2, v137, v153
	v_max3_f32 v3, v3, v138, v154
	s_nop 0
	v_max3_f32 v2, v2, v139, v155
	v_max3_f32 v3, v3, v140, v156
	s_nop 0
	v_max3_f32 v2, v2, v141, v157
	v_max3_f32 v3, v3, v142, v158
	s_nop 0
	v_max3_f32 v2, v2, v143, v159
	v_max3_f32 v3, v3, v144, v160
	s_nop 0
	v_max3_f32 v2, v2, v145, v161
	s_nop 0
	v_max_f32_e32 v2, v2, v3
	s_nop 0
	v_mov_b32_e32 v3, v2
	s_nop 1
	v_permlane32_swap_b32_e32 v2, v3
	v_max_f32_e32 v3, v3, v3
	v_max_f32_e32 v2, v2, v2
	v_max_f32_e32 v248, v2, v3
	v_mov_b64_e32 v[2:3], v[66:67]
	v_cmp_lt_f32_e32 vcc, s18, v248
	v_mov_b64_e32 v[4:5], v[68:69]
	v_mov_b64_e32 v[6:7], v[70:71]
	v_mov_b64_e32 v[8:9], v[72:73]
	v_mov_b64_e32 v[10:11], v[74:75]
	v_mov_b64_e32 v[12:13], v[76:77]
	v_mov_b64_e32 v[14:15], v[78:79]
	v_mov_b64_e32 v[16:17], v[80:81]
	s_cbranch_vccz .LBB0_333
	v_max_f32_e32 v2, v248, v248
	v_max_f32_e32 v2, 0, v2
	v_exp_f32_e64 v3, -v2
	s_and_saveexec_b64 s[22:23], s[10:11]
	ds_write_b32 v214, v3
	s_or_b64 exec, exec, s[22:23]
	v_mul_f32_e32 v201, v249, v3
	v_pk_add_f32 v[130:131], v[130:131], v[2:3] op_sel_hi:[1,0] neg_lo:[0,1] neg_hi:[0,1]
	v_pk_add_f32 v[146:147], v[146:147], v[2:3] op_sel_hi:[1,0] neg_lo:[0,1] neg_hi:[0,1]
	v_pk_add_f32 v[132:133], v[132:133], v[2:3] op_sel_hi:[1,0] neg_lo:[0,1] neg_hi:[0,1]
	v_pk_add_f32 v[148:149], v[148:149], v[2:3] op_sel_hi:[1,0] neg_lo:[0,1] neg_hi:[0,1]
	v_pk_add_f32 v[134:135], v[134:135], v[2:3] op_sel_hi:[1,0] neg_lo:[0,1] neg_hi:[0,1]
	v_pk_add_f32 v[150:151], v[150:151], v[2:3] op_sel_hi:[1,0] neg_lo:[0,1] neg_hi:[0,1]
	v_pk_add_f32 v[136:137], v[136:137], v[2:3] op_sel_hi:[1,0] neg_lo:[0,1] neg_hi:[0,1]
	v_pk_add_f32 v[152:153], v[152:153], v[2:3] op_sel_hi:[1,0] neg_lo:[0,1] neg_hi:[0,1]
	v_pk_add_f32 v[138:139], v[138:139], v[2:3] op_sel_hi:[1,0] neg_lo:[0,1] neg_hi:[0,1]
	v_pk_add_f32 v[154:155], v[154:155], v[2:3] op_sel_hi:[1,0] neg_lo:[0,1] neg_hi:[0,1]
	v_pk_add_f32 v[140:141], v[140:141], v[2:3] op_sel_hi:[1,0] neg_lo:[0,1] neg_hi:[0,1]
	v_pk_add_f32 v[156:157], v[156:157], v[2:3] op_sel_hi:[1,0] neg_lo:[0,1] neg_hi:[0,1]
	v_pk_add_f32 v[142:143], v[142:143], v[2:3] op_sel_hi:[1,0] neg_lo:[0,1] neg_hi:[0,1]
	v_pk_add_f32 v[158:159], v[158:159], v[2:3] op_sel_hi:[1,0] neg_lo:[0,1] neg_hi:[0,1]
	v_add_u32_e32 v3, s43, v0
	ds_read_b128 v[50:53], v3 offset:64
	ds_read_b128 v[54:57], v3 offset:96
	ds_read_b128 v[184:187], v3
	ds_read_b128 v[192:195], v3 offset:32
	v_add_f32_e32 v204, v206, v2
	v_pk_add_f32 v[144:145], v[144:145], v[2:3] op_sel_hi:[1,0] neg_lo:[0,1] neg_hi:[0,1]
	v_pk_add_f32 v[160:161], v[160:161], v[2:3] op_sel_hi:[1,0] neg_lo:[0,1] neg_hi:[0,1]
	s_waitcnt lgkmcnt(0)
	v_mul_f32_e32 v14, v78, v54
	v_mul_f32_e32 v15, v79, v55
	v_mul_f32_e32 v10, v74, v50
	v_mul_f32_e32 v11, v75, v51
	v_mul_f32_e32 v6, v70, v192
	v_mul_f32_e32 v7, v71, v193
	v_mul_f32_e32 v16, v80, v56
	v_mul_f32_e32 v17, v81, v57
	v_mul_f32_e32 v12, v76, v52
	v_mul_f32_e32 v13, v77, v53
	v_mul_f32_e32 v8, v72, v194
	v_mul_f32_e32 v9, v73, v195
	v_mul_f32_e32 v4, v68, v186
	v_mul_f32_e32 v5, v69, v187
	v_mul_f32_e32 v2, v66, v184
	v_mul_f32_e32 v3, v67, v185
	v_mul_f32_e32 v30, v94, v54
	v_mul_f32_e32 v31, v95, v55
	v_mul_f32_e32 v26, v90, v50
	v_mul_f32_e32 v27, v91, v51
	v_mul_f32_e32 v22, v86, v192
	v_mul_f32_e32 v23, v87, v193
	v_mul_f32_e32 v32, v96, v56
	v_mul_f32_e32 v33, v97, v57
	v_mul_f32_e32 v28, v92, v52
	v_mul_f32_e32 v29, v93, v53
	v_mul_f32_e32 v24, v88, v194
	v_mul_f32_e32 v25, v89, v195
	v_mul_f32_e32 v20, v84, v186
	v_mul_f32_e32 v21, v85, v187
	v_mul_f32_e32 v18, v82, v184
	v_mul_f32_e32 v19, v83, v185
	v_mul_f32_e32 v46, v110, v54
	v_mul_f32_e32 v47, v111, v55
	v_mul_f32_e32 v42, v106, v50
	v_mul_f32_e32 v43, v107, v51
	v_mul_f32_e32 v38, v102, v192
	v_mul_f32_e32 v39, v103, v193
	v_mul_f32_e32 v48, v112, v56
	v_mul_f32_e32 v49, v113, v57
	v_mul_f32_e32 v44, v108, v52
	v_mul_f32_e32 v45, v109, v53
	v_mul_f32_e32 v40, v104, v194
	v_mul_f32_e32 v41, v105, v195
	v_mul_f32_e32 v36, v100, v186
	v_mul_f32_e32 v37, v101, v187
	v_mul_f32_e32 v34, v98, v184
	v_mul_f32_e32 v35, v99, v185
	v_mul_f32_e32 v62, v126, v54
	v_mul_f32_e32 v63, v127, v55
	v_mul_f32_e32 v58, v122, v50
	v_mul_f32_e32 v59, v123, v51
	v_mul_f32_e32 v54, v118, v192
	v_mul_f32_e32 v55, v119, v193
	v_mul_f32_e32 v64, v128, v56
	v_mul_f32_e32 v65, v129, v57
	v_mul_f32_e32 v60, v124, v52
	v_mul_f32_e32 v61, v125, v53
	v_mul_f32_e32 v56, v120, v194
	v_mul_f32_e32 v57, v121, v195
	v_mul_f32_e32 v52, v116, v186
	v_mul_f32_e32 v53, v117, v187
	v_mul_f32_e32 v50, v114, v184
	v_mul_f32_e32 v51, v115, v185

; #define LAS __attribute__((address_space(3)))
; __device__ __forceinline__ float max_x32(float v) { auto rr = __builtin_amdgcn_permlane32_swap(__float_as_uint(v), __float_as_uint(v), false, false); return __builtin_fmaxf(__uint_as_float(rr[0]), __uint_as_float(rr[1])); }
; __device__ __forceinline__ float nopack(float v) { asm("" : "+v"(v)); return v; }
; __device__ __forceinline__ float max3f(float a, float b, float c) { float r; asm("v_max3_f32 %0, %1, %2, %3" : "=v"(r) : "v"(a), "v"(b), "v"(c)); return r; }
; __device__ __forceinline__ float max2f(float a, float b) { float r; asm("v_max_f32_e32 %0, %1, %2" : "=v"(r) : "v"(a), "v"(b)); return r; }
; __device__ __forceinline__ int crow(int r, int hi) { return (r & 3) + 8 * (r >> 2) + 4 * hi; }
; template <int TYPE> ...
;     ...
;         const float sg = nslope, bl = __builtin_fmaf(sg, dbase, -mref);
; #pragma unroll
;         for (int r = 0; r < 16; ++r) { const float c = (float)((r & 7) + 16 * (r >> 3)); s0[r] = nopack(__builtin_fmaf(sg, c, bl)); s1[r] = nopack(__builtin_fmaf(sg, c + 32.f, bl)); }
;     }
; #pragma unroll
;     for (int dc = 0; dc < 4; ++dc) {
;         const bf16x8 a0 = *(const LAS bf16x8*)(lds + kad[dc]);
;         const bf16x8 a1 = *(const LAS bf16x8*)(lds + kad[dc] + 8192);
;         s0 = __builtin_amdgcn_mfma_f32_32x32x16_bf16(a0, qf[dc], s0, 0, 0, 0);
;         s1 = __builtin_amdgcn_mfma_f32_32x32x16_bf16(a1, qf[dc], s1, 0, 0, 0);
;     }
;     if (chk) {
;     asm volatile("s_nop 15\n\ts_nop 7" : "+v"(s0), "+v"(s1));
;     float mx = max3f(s0[0], s1[0], s0[1]), mx2 = max3f(s1[1], s0[2], s1[2]);
; #pragma unroll
;     for (int r = 3; r < 15; r += 2) { mx = max3f(mx, s0[r], s1[r]); mx2 = max3f(mx2, s0[r + 1], s1[r + 1]); }
;     mx = max3f(mx, s0[15], s1[15]); mx = max2f(mx, mx2);
;     mx = max_x32(mx);
;     if (first || __any(mx > 8.f)) {
;         const float dl = first ? mx : __builtin_fmaxf(mx, 0.f), alpha = __builtin_amdgcn_exp2f(-dl);
;         lsum *= alpha; mref += dl;
; #pragma unroll
;         for (int r = 0; r < 16; ++r) { s0[r] -= dl; s1[r] -= dl; }
;         if (hi == 0) wsf[r32] = alpha;
; #pragma unroll
;         for (int r = 0; r < 16; ++r) { const float al = wsf[crow(r, hi)];
; #pragma unroll
;             for (int d = 0; d < 4; ++d) o[d][r] *= al; }
.LBB0_334:
	s_and_b64 vcc, exec, s[22:23]
	s_cbranch_vccz .LBB0_341
	s_sub_i32 s26, s24, s2
	s_sub_i32 s25, s33, s25
	s_cmp_gt_i32 s24, s33
	s_cselect_b64 s[22:23], -1, 0
	v_cndmask_b32_e64 v42, v211, -v211, s[22:23]
	s_and_b64 s[22:23], s[22:23], exec
	s_cselect_b32 s22, s26, s25
	s_add_i32 s24, s89, 0
	v_add_u32_e32 v15, s24, v213
	ds_read_b128 v[34:37], v15 offset:32768
	ds_read_b128 v[38:41], v15 offset:40960
	v_fma_f32 v17, v42, v208, -v206
	v_fma_f32 v18, 0, v42, v17
	v_fmamk_f32 v2, v42, 0x42000000, v17
	v_add_f32_e32 v19, v42, v17
	v_fmamk_f32 v3, v42, 0x42040000, v17
	v_fma_f32 v20, 2.0, v42, v17
	v_fmamk_f32 v4, v42, 0x42080000, v17
	v_fmamk_f32 v21, v42, 0x40400000, v17
	v_fmamk_f32 v5, v42, 0x420c0000, v17
	v_fma_f32 v22, 4.0, v42, v17
	v_fmamk_f32 v6, v42, 0x42100000, v17
	v_fmamk_f32 v23, v42, 0x40a00000, v17
	v_fmamk_f32 v7, v42, 0x42140000, v17
	v_fmamk_f32 v24, v42, 0x40c00000, v17
	v_fmamk_f32 v8, v42, 0x42180000, v17
	v_fmamk_f32 v25, v42, 0x40e00000, v17
	v_fmamk_f32 v9, v42, 0x421c0000, v17
	v_fmamk_f32 v26, v42, 0x41800000, v17
	v_fmamk_f32 v10, v42, 0x42400000, v17
	v_fmamk_f32 v27, v42, 0x41880000, v17
	v_fmamk_f32 v11, v42, 0x42440000, v17
	v_fmamk_f32 v28, v42, 0x41900000, v17
	v_fmamk_f32 v12, v42, 0x42480000, v17
	v_fmamk_f32 v29, v42, 0x41980000, v17
	v_fmamk_f32 v13, v42, 0x424c0000, v17
	v_fmamk_f32 v30, v42, 0x41a00000, v17
	v_fmamk_f32 v14, v42, 0x42500000, v17
	v_fmamk_f32 v31, v42, 0x41a80000, v17
	v_fmamk_f32 v32, v42, 0x41b00000, v17
	v_fmamk_f32 v33, v42, 0x41b80000, v17
	v_fmamk_f32 v15, v42, 0x42540000, v17
	v_fmamk_f32 v16, v42, 0x42580000, v17
	v_fmac_f32_e32 v17, 0x425c0000, v42
	s_waitcnt lgkmcnt(0)
	v_mfma_f32_32x32x16_bf16 v[18:33], v[34:37], v[162:165], v[18:33]
	v_mfma_f32_32x32x16_bf16 v[2:17], v[38:41], v[162:165], v[2:17]
	ds_read_b128 v[34:37], v247 offset:32768
	ds_read_b128 v[38:41], v247 offset:40960
	s_waitcnt lgkmcnt(0)
	v_mfma_f32_32x32x16_bf16 v[18:33], v[34:37], v[166:169], v[18:33]
	v_mfma_f32_32x32x16_bf16 v[2:17], v[38:41], v[166:169], v[2:17]
	ds_read_b128 v[34:37], v246 offset:32768
	ds_read_b128 v[38:41], v246 offset:40960
	s_waitcnt lgkmcnt(0)
	v_mfma_f32_32x32x16_bf16 v[18:33], v[34:37], v[170:173], v[18:33]
	v_mfma_f32_32x32x16_bf16 v[2:17], v[38:41], v[170:173], v[2:17]
	ds_read_b128 v[34:37], v245 offset:32768
	ds_read_b128 v[38:41], v245 offset:40960
	s_waitcnt lgkmcnt(0)
	v_mfma_f32_32x32x16_bf16 v[18:33], v[34:37], v[174:177], v[18:33]
	v_cvt_f32_i32_e32 v34, s22
	v_fma_f32 v34, -v211, v34, v244
	v_cmp_gt_f32_e32 vcc, s14, v34
	v_mfma_f32_32x32x16_bf16 v[2:17], v[38:41], v[174:177], v[2:17]
	s_cbranch_vccnz .LBB0_340
	s_nop 15
	s_nop 7
	s_nop 0
	v_max3_f32 v34, v18, v2, v19
	v_max3_f32 v35, v3, v20, v4
	s_nop 0
	v_max3_f32 v34, v34, v21, v5
	v_max3_f32 v35, v35, v22, v6
	s_nop 0
	v_max3_f32 v34, v34, v23, v7
	v_max3_f32 v35, v35, v24, v8
	s_nop 0
	v_max3_f32 v34, v34, v25, v9
	v_max3_f32 v35, v35, v26, v10
	s_nop 0
	v_max3_f32 v34, v34, v27, v11
	v_max3_f32 v35, v35, v28, v12
	s_nop 0
	v_max3_f32 v34, v34, v29, v13
	v_max3_f32 v35, v35, v30, v14
	s_nop 0
	v_max3_f32 v34, v34, v31, v15
	v_max3_f32 v35, v35, v32, v16
	s_nop 0
	v_max3_f32 v34, v34, v33, v17
	s_nop 0
	v_max_f32_e32 v34, v34, v35
	s_nop 0
	v_mov_b32_e32 v35, v34
	s_nop 1
	v_permlane32_swap_b32_e32 v34, v35
	v_max_f32_e32 v35, v35, v35
	v_max_f32_e32 v34, v34, v34
	v_max_f32_e32 v34, v34, v35
	v_cmp_lt_f32_e32 vcc, s18, v34
	s_cbranch_vccz .LBB0_340
	v_max_f32_e32 v34, v34, v34
	v_max_f32_e32 v34, 0, v34
	v_exp_f32_e64 v35, -v34
	s_and_saveexec_b64 s[22:23], s[10:11]
	ds_write_b32 v214, v35
	s_or_b64 exec, exec, s[22:23]
	v_add_u32_e32 v46, s43, v0
	v_mul_f32_e32 v249, v249, v35
	v_add_f32_e32 v206, v206, v34
	v_sub_f32_e32 v33, v33, v34
	v_sub_f32_e32 v32, v32, v34
	v_sub_f32_e32 v31, v31, v34
	v_sub_f32_e32 v30, v30, v34
	v_sub_f32_e32 v29, v29, v34
	v_sub_f32_e32 v28, v28, v34
	v_sub_f32_e32 v27, v27, v34
	v_sub_f32_e32 v26, v26, v34
	v_sub_f32_e32 v25, v25, v34
	v_sub_f32_e32 v24, v24, v34
	v_sub_f32_e32 v23, v23, v34
	v_sub_f32_e32 v22, v22, v34
	v_sub_f32_e32 v21, v21, v34
	v_sub_f32_e32 v20, v20, v34
	v_sub_f32_e32 v19, v19, v34
	v_sub_f32_e32 v18, v18, v34
	v_sub_f32_e32 v17, v17, v34
	v_sub_f32_e32 v16, v16, v34
	v_sub_f32_e32 v15, v15, v34
	v_sub_f32_e32 v14, v14, v34
	v_sub_f32_e32 v13, v13, v34
	v_sub_f32_e32 v12, v12, v34
	v_sub_f32_e32 v11, v11, v34
	v_sub_f32_e32 v10, v10, v34
	v_sub_f32_e32 v9, v9, v34
	v_sub_f32_e32 v8, v8, v34
	v_sub_f32_e32 v7, v7, v34
	v_sub_f32_e32 v6, v6, v34
	v_sub_f32_e32 v5, v5, v34
	v_sub_f32_e32 v4, v4, v34
	v_sub_f32_e32 v3, v3, v34
	v_sub_f32_e32 v2, v2, v34
	ds_read_b128 v[34:37], v46
	ds_read_b128 v[38:41], v46 offset:32
	ds_read_b128 v[42:45], v46 offset:64
	ds_read_b128 v[46:49], v46 offset:96
	s_waitcnt lgkmcnt(0)
	v_mul_f32_e32 v68, v68, v36
	v_mul_f32_e32 v69, v69, v37
	v_mul_f32_e32 v70, v70, v38
	v_mul_f32_e32 v71, v71, v39
	v_mul_f32_e32 v74, v74, v42
	v_mul_f32_e32 v75, v75, v43
	v_mul_f32_e32 v78, v78, v46
	v_mul_f32_e32 v79, v79, v47
	v_mul_f32_e32 v80, v80, v48
	v_mul_f32_e32 v81, v81, v49
	v_mul_f32_e32 v76, v76, v44
	v_mul_f32_e32 v77, v77, v45
	v_mul_f32_e32 v72, v72, v40
	v_mul_f32_e32 v73, v73, v41
	v_mul_f32_e32 v66, v66, v34
	v_mul_f32_e32 v67, v67, v35
	v_mul_f32_e32 v94, v94, v46
	v_mul_f32_e32 v95, v95, v47
	v_mul_f32_e32 v90, v90, v42
	v_mul_f32_e32 v91, v91, v43
	v_mul_f32_e32 v86, v86, v38
	v_mul_f32_e32 v87, v87, v39
	v_mul_f32_e32 v96, v96, v48
	v_mul_f32_e32 v97, v97, v49
	v_mul_f32_e32 v92, v92, v44
	v_mul_f32_e32 v93, v93, v45
	v_mul_f32_e32 v88, v88, v40
	v_mul_f32_e32 v89, v89, v41
	v_mul_f32_e32 v84, v84, v36
	v_mul_f32_e32 v85, v85, v37
	v_mul_f32_e32 v82, v82, v34
	v_mul_f32_e32 v83, v83, v35
	v_mul_f32_e32 v110, v110, v46
	v_mul_f32_e32 v111, v111, v47
	v_mul_f32_e32 v106, v106, v42
	v_mul_f32_e32 v107, v107, v43
	v_mul_f32_e32 v102, v102, v38
	v_mul_f32_e32 v103, v103, v39
	v_mul_f32_e32 v112, v112, v48
	v_mul_f32_e32 v113, v113, v49
	v_mul_f32_e32 v108, v108, v44
	v_mul_f32_e32 v109, v109, v45
	v_mul_f32_e32 v104, v104, v40
	v_mul_f32_e32 v105, v105, v41
	v_mul_f32_e32 v100, v100, v36
	v_mul_f32_e32 v101, v101, v37
	v_mul_f32_e32 v98, v98, v34
	v_mul_f32_e32 v99, v99, v35
	v_mul_f32_e32 v126, v126, v46
	v_mul_f32_e32 v127, v127, v47
	v_mul_f32_e32 v122, v122, v42
	v_mul_f32_e32 v123, v123, v43
	v_mul_f32_e32 v118, v118, v38
	v_mul_f32_e32 v119, v119, v39
	v_mul_f32_e32 v128, v128, v48
	v_mul_f32_e32 v129, v129, v49
	v_mul_f32_e32 v124, v124, v44
	v_mul_f32_e32 v125, v125, v45
	v_mul_f32_e32 v120, v120, v40
	v_mul_f32_e32 v121, v121, v41
	v_mul_f32_e32 v116, v116, v36
	v_mul_f32_e32 v117, v117, v37
	v_mul_f32_e32 v114, v114, v34
	v_mul_f32_e32 v115, v115, v35

; __device__ __forceinline__ float max_x32(float v) { auto rr = __builtin_amdgcn_permlane32_swap(__float_as_uint(v), __float_as_uint(v), false, false); return __builtin_fmaxf(__uint_as_float(rr[0]), __uint_as_float(rr[1])); }
; __device__ __forceinline__ float max3f(float a, float b, float c) { float r; asm("v_max3_f32 %0, %1, %2, %3" : "=v"(r) : "v"(a), "v"(b), "v"(c)); return r; }
; __device__ __forceinline__ float max2f(float a, float b) { float r; asm("v_max_f32_e32 %0, %1, %2" : "=v"(r) : "v"(a), "v"(b)); return r; }
; __device__ __forceinline__ int crow(int r, int hi) { return (r & 3) + 8 * (r >> 2) + 4 * hi; }
; template <int TYPE> ...
;     ...
;     if (chk) {
;     asm volatile("s_nop 15\n\ts_nop 7" : "+v"(s0), "+v"(s1));
;     float mx = max3f(s0[0], s1[0], s0[1]), mx2 = max3f(s1[1], s0[2], s1[2]);
; #pragma unroll
;     for (int r = 3; r < 15; r += 2) { mx = max3f(mx, s0[r], s1[r]); mx2 = max3f(mx2, s0[r + 1], s1[r + 1]); }
;     mx = max3f(mx, s0[15], s1[15]); mx = max2f(mx, mx2);
;     mx = max_x32(mx);
;     if (first || __any(mx > 8.f)) {
;         const float dl = first ? mx : __builtin_fmaxf(mx, 0.f), alpha = __builtin_amdgcn_exp2f(-dl);
;         lsum *= alpha; mref += dl;
; #pragma unroll
;         for (int r = 0; r < 16; ++r) { s0[r] -= dl; s1[r] -= dl; }
;         if (hi == 0) wsf[r32] = alpha;
; #pragma unroll
;         for (int r = 0; r < 16; ++r) { const float al = wsf[crow(r, hi)];
; #pragma unroll
;             for (int d = 0; d < 4; ++d) o[d][r] *= al; }
.Lattq_qkdone_s0:
	s_waitcnt lgkmcnt(11)
	ds_read_b128 v[114:117], v187 offset:16384
	ds_read_b128 v[118:121], v187 offset:20480
	ds_read_b128 v[122:125], v187 offset:24576
	ds_read_b128 v[126:129], v187 offset:28672
	s_nop 6
	s_andn2_b64 vcc, exec, s[24:25]
	s_cbranch_vccnz .Lattq_exp_s0
	v_max3_f32 v201, v66, v67, v68
	v_max3_f32 v251, v82, v83, v84
	v_max3_f32 v201, v201, v69, v70
	v_max3_f32 v251, v251, v85, v86
	v_max3_f32 v201, v201, v71, v72
	v_max3_f32 v251, v251, v87, v88
	v_max3_f32 v201, v201, v73, v74
	v_max3_f32 v251, v251, v89, v90
	v_max3_f32 v201, v201, v75, v76
	v_max3_f32 v251, v251, v91, v92
	v_max3_f32 v201, v201, v77, v78
	v_max3_f32 v251, v251, v93, v94
	v_max3_f32 v201, v201, v79, v80
	v_max3_f32 v251, v251, v95, v96
	v_max3_f32 v201, v201, v81, v97
	v_max_f32_e32 v201, v201, v251
	v_mov_b32_e32 v251, v201
	s_nop 1
	v_permlane32_swap_b32_e32 v201, v251
	v_max_f32_e32 v201, v201, v251
	v_cmp_lt_f32_e32 vcc, s18, v201
	s_or_b64 s[24:25], s[22:23], vcc
	s_cmp_lg_u64 s[24:25], 0
	s_cbranch_scc0 .Lattq_exp_s0
	v_max_f32_e32 v251, 0, v201
	v_cndmask_b32_e64 v201, v251, v201, s[22:23]
	s_nop 0
	v_exp_f32_e64 v251, -v201
	s_and_saveexec_b64 s[24:25], s[12:13]
	ds_write_b32 v214, v251
	s_or_b64 exec, exec, s[24:25]
	v_mul_f32_e32 v248, v248, v251
	v_add_f32_e32 v204, v204, v201
	v_sub_f32_e32 v66, v66, v201
	v_sub_f32_e32 v82, v82, v201
	v_sub_f32_e32 v67, v67, v201
	v_sub_f32_e32 v83, v83, v201
	v_sub_f32_e32 v68, v68, v201
	v_sub_f32_e32 v84, v84, v201
	v_sub_f32_e32 v69, v69, v201
	v_sub_f32_e32 v85, v85, v201
	v_sub_f32_e32 v70, v70, v201
	v_sub_f32_e32 v86, v86, v201
	v_sub_f32_e32 v71, v71, v201
	v_sub_f32_e32 v87, v87, v201
	v_sub_f32_e32 v72, v72, v201
	v_sub_f32_e32 v88, v88, v201
	v_sub_f32_e32 v73, v73, v201
	v_sub_f32_e32 v89, v89, v201
	v_sub_f32_e32 v74, v74, v201
	v_sub_f32_e32 v90, v90, v201
	v_sub_f32_e32 v75, v75, v201
	v_sub_f32_e32 v91, v91, v201
	v_sub_f32_e32 v76, v76, v201
	v_sub_f32_e32 v92, v92, v201
	v_sub_f32_e32 v77, v77, v201
	v_sub_f32_e32 v93, v93, v201
	v_sub_f32_e32 v78, v78, v201
	v_sub_f32_e32 v94, v94, v201
	v_sub_f32_e32 v79, v79, v201
	v_sub_f32_e32 v95, v95, v201
	v_sub_f32_e32 v80, v80, v201
	v_sub_f32_e32 v96, v96, v201
	v_sub_f32_e32 v81, v81, v201
	v_sub_f32_e32 v97, v97, v201
	v_add_u32_e32 v249, s42, v0
	ds_read_b128 v[192:195], v249
	s_waitcnt lgkmcnt(0)
	v_mul_f32_e32 v2, v2, v192
	v_mul_f32_e32 v3, v3, v193
	v_mul_f32_e32 v4, v4, v194
	v_mul_f32_e32 v5, v5, v195
	v_mul_f32_e32 v18, v18, v192
	v_mul_f32_e32 v19, v19, v193
	v_mul_f32_e32 v20, v20, v194
	v_mul_f32_e32 v21, v21, v195
	v_mul_f32_e32 v34, v34, v192
	v_mul_f32_e32 v35, v35, v193
	v_mul_f32_e32 v36, v36, v194
	v_mul_f32_e32 v37, v37, v195
	v_mul_f32_e32 v50, v50, v192
	v_mul_f32_e32 v51, v51, v193
	v_mul_f32_e32 v52, v52, v194
	v_mul_f32_e32 v53, v53, v195
	ds_read_b128 v[192:195], v249 offset:32
	s_waitcnt lgkmcnt(0)
	v_mul_f32_e32 v6, v6, v192
	v_mul_f32_e32 v7, v7, v193
	v_mul_f32_e32 v8, v8, v194
	v_mul_f32_e32 v9, v9, v195
	v_mul_f32_e32 v22, v22, v192
	v_mul_f32_e32 v23, v23, v193
	v_mul_f32_e32 v24, v24, v194
	v_mul_f32_e32 v25, v25, v195
	v_mul_f32_e32 v38, v38, v192
	v_mul_f32_e32 v39, v39, v193
	v_mul_f32_e32 v40, v40, v194
	v_mul_f32_e32 v41, v41, v195
	v_mul_f32_e32 v54, v54, v192
	v_mul_f32_e32 v55, v55, v193
	v_mul_f32_e32 v56, v56, v194
	v_mul_f32_e32 v57, v57, v195
	ds_read_b128 v[192:195], v249 offset:64
	s_waitcnt lgkmcnt(0)
	v_mul_f32_e32 v10, v10, v192
	v_mul_f32_e32 v11, v11, v193
	v_mul_f32_e32 v12, v12, v194
	v_mul_f32_e32 v13, v13, v195
	v_mul_f32_e32 v26, v26, v192
	v_mul_f32_e32 v27, v27, v193
	v_mul_f32_e32 v28, v28, v194
	v_mul_f32_e32 v29, v29, v195
	v_mul_f32_e32 v42, v42, v192
	v_mul_f32_e32 v43, v43, v193
	v_mul_f32_e32 v44, v44, v194
	v_mul_f32_e32 v45, v45, v195
	v_mul_f32_e32 v58, v58, v192
	v_mul_f32_e32 v59, v59, v193
	v_mul_f32_e32 v60, v60, v194
	v_mul_f32_e32 v61, v61, v195
	ds_read_b128 v[192:195], v249 offset:96
	s_waitcnt lgkmcnt(0)
	v_mul_f32_e32 v14, v14, v192
	v_mul_f32_e32 v15, v15, v193
	v_mul_f32_e32 v16, v16, v194
	v_mul_f32_e32 v17, v17, v195
	v_mul_f32_e32 v30, v30, v192
	v_mul_f32_e32 v31, v31, v193
	v_mul_f32_e32 v32, v32, v194
	v_mul_f32_e32 v33, v33, v195
	v_mul_f32_e32 v46, v46, v192
	v_mul_f32_e32 v47, v47, v193
	v_mul_f32_e32 v48, v48, v194
	v_mul_f32_e32 v49, v49, v195
	v_mul_f32_e32 v62, v62, v192
	v_mul_f32_e32 v63, v63, v193
	v_mul_f32_e32 v64, v64, v194
	v_mul_f32_e32 v65, v65, v195

; #define LAS __attribute__((address_space(3)))
; __device__ __forceinline__ float max_x32(float v) { auto rr = __builtin_amdgcn_permlane32_swap(__float_as_uint(v), __float_as_uint(v), false, false); return __builtin_fmaxf(__uint_as_float(rr[0]), __uint_as_float(rr[1])); }
; __device__ __forceinline__ float max3f(float a, float b, float c) { float r; asm("v_max3_f32 %0, %1, %2, %3" : "=v"(r) : "v"(a), "v"(b), "v"(c)); return r; }
; __device__ __forceinline__ float max2f(float a, float b) { float r; asm("v_max_f32_e32 %0, %1, %2" : "=v"(r) : "v"(a), "v"(b)); return r; }
; __device__ __forceinline__ int crow(int r, int hi) { return (r & 3) + 8 * (r >> 2) + 4 * hi; }
; template <int TYPE> ...
;     ...
;     for (int dc = 0; dc < 4; ++dc) {
;         const bf16x8 a0 = *(const LAS bf16x8*)(lds + kad[dc]);
;         const bf16x8 a1 = *(const LAS bf16x8*)(lds + kad[dc] + 8192);
;         s0 = __builtin_amdgcn_mfma_f32_32x32x16_bf16(a0, qf[dc], s0, 0, 0, 0);
;         s1 = __builtin_amdgcn_mfma_f32_32x32x16_bf16(a1, qf[dc], s1, 0, 0, 0);
;     }
;     if (chk) {
;     asm volatile("s_nop 15\n\ts_nop 7" : "+v"(s0), "+v"(s1));
;     float mx = max3f(s0[0], s1[0], s0[1]), mx2 = max3f(s1[1], s0[2], s1[2]);
; #pragma unroll
;     for (int r = 3; r < 15; r += 2) { mx = max3f(mx, s0[r], s1[r]); mx2 = max3f(mx2, s0[r + 1], s1[r + 1]); }
;     mx = max3f(mx, s0[15], s1[15]); mx = max2f(mx, mx2);
;     mx = max_x32(mx);
;     if (first || __any(mx > 8.f)) {
;         const float dl = first ? mx : __builtin_fmaxf(mx, 0.f), alpha = __builtin_amdgcn_exp2f(-dl);
;         lsum *= alpha; mref += dl;
; #pragma unroll
;         for (int r = 0; r < 16; ++r) { s0[r] -= dl; s1[r] -= dl; }
;         if (hi == 0) wsf[r32] = alpha;
; #pragma unroll
;         for (int r = 0; r < 16; ++r) { const float al = wsf[crow(r, hi)];
; #pragma unroll
;             for (int d = 0; d < 4; ++d) o[d][r] *= al; }
.Lattq_qk_s1:
	s_waitcnt lgkmcnt(8)
	s_nop 1
	v_mfma_f32_32x32x16_bf16 v[66:81], v[130:133], v[162:165], v[66:81]
	v_mfma_f32_32x32x16_bf16 v[82:97], v[134:137], v[162:165], v[82:97]
	v_mfma_f32_32x32x16_bf16 v[66:81], v[138:141], v[166:169], v[66:81]
	v_mfma_f32_32x32x16_bf16 v[82:97], v[142:145], v[166:169], v[82:97]
	ds_read_b128 v[130:133], v186 offset:49152
	ds_read_b128 v[134:137], v186 offset:53248
	ds_read_b128 v[138:141], v186 offset:57344
	ds_read_b128 v[142:145], v186 offset:61440
	v_mfma_f32_32x32x16_bf16 v[66:81], v[146:149], v[170:173], v[66:81]
	v_mfma_f32_32x32x16_bf16 v[82:97], v[150:153], v[170:173], v[82:97]
	v_mfma_f32_32x32x16_bf16 v[66:81], v[154:157], v[174:177], v[66:81]
	v_mfma_f32_32x32x16_bf16 v[82:97], v[158:161], v[174:177], v[82:97]
	s_waitcnt lgkmcnt(11)
	ds_read_b128 v[146:149], v187 offset:49152
	ds_read_b128 v[150:153], v187 offset:53248
	ds_read_b128 v[154:157], v187 offset:57344
	ds_read_b128 v[158:161], v187 offset:61440
	s_nop 6
	s_andn2_b64 vcc, exec, s[24:25]
	s_cbranch_vccnz .Lattq_exp_s1
	v_max3_f32 v201, v66, v67, v68
	v_max3_f32 v251, v82, v83, v84
	v_max3_f32 v201, v201, v69, v70
	v_max3_f32 v251, v251, v85, v86
	v_max3_f32 v201, v201, v71, v72
	v_max3_f32 v251, v251, v87, v88
	v_max3_f32 v201, v201, v73, v74
	v_max3_f32 v251, v251, v89, v90
	v_max3_f32 v201, v201, v75, v76
	v_max3_f32 v251, v251, v91, v92
	v_max3_f32 v201, v201, v77, v78
	v_max3_f32 v251, v251, v93, v94
	v_max3_f32 v201, v201, v79, v80
	v_max3_f32 v251, v251, v95, v96
	v_max3_f32 v201, v201, v81, v97
	v_max_f32_e32 v201, v201, v251
	v_mov_b32_e32 v251, v201
	s_nop 1
	v_permlane32_swap_b32_e32 v201, v251
	v_max_f32_e32 v201, v201, v251
	v_cmp_lt_f32_e32 vcc, s18, v201
	s_or_b64 s[24:25], s[22:23], vcc
	s_cmp_lg_u64 s[24:25], 0
	s_cbranch_scc0 .Lattq_exp_s1
	v_max_f32_e32 v251, 0, v201
	v_cndmask_b32_e64 v201, v251, v201, s[22:23]
	s_nop 0
	v_exp_f32_e64 v251, -v201
	s_and_saveexec_b64 s[24:25], s[12:13]
	ds_write_b32 v214, v251
	s_or_b64 exec, exec, s[24:25]
	v_mul_f32_e32 v248, v248, v251
	v_add_f32_e32 v204, v204, v201
	v_sub_f32_e32 v66, v66, v201
	v_sub_f32_e32 v82, v82, v201
	v_sub_f32_e32 v67, v67, v201
	v_sub_f32_e32 v83, v83, v201
	v_sub_f32_e32 v68, v68, v201
	v_sub_f32_e32 v84, v84, v201
	v_sub_f32_e32 v69, v69, v201
	v_sub_f32_e32 v85, v85, v201
	v_sub_f32_e32 v70, v70, v201
	v_sub_f32_e32 v86, v86, v201
	v_sub_f32_e32 v71, v71, v201
	v_sub_f32_e32 v87, v87, v201
	v_sub_f32_e32 v72, v72, v201
	v_sub_f32_e32 v88, v88, v201
	v_sub_f32_e32 v73, v73, v201
	v_sub_f32_e32 v89, v89, v201
	v_sub_f32_e32 v74, v74, v201
	v_sub_f32_e32 v90, v90, v201
	v_sub_f32_e32 v75, v75, v201
	v_sub_f32_e32 v91, v91, v201
	v_sub_f32_e32 v76, v76, v201
	v_sub_f32_e32 v92, v92, v201
	v_sub_f32_e32 v77, v77, v201
	v_sub_f32_e32 v93, v93, v201
	v_sub_f32_e32 v78, v78, v201
	v_sub_f32_e32 v94, v94, v201
	v_sub_f32_e32 v79, v79, v201
	v_sub_f32_e32 v95, v95, v201
	v_sub_f32_e32 v80, v80, v201
	v_sub_f32_e32 v96, v96, v201
	v_sub_f32_e32 v81, v81, v201
	v_sub_f32_e32 v97, v97, v201
	v_add_u32_e32 v249, s42, v0
	ds_read_b128 v[192:195], v249
	s_waitcnt lgkmcnt(0)
	v_mul_f32_e32 v2, v2, v192
	v_mul_f32_e32 v3, v3, v193
	v_mul_f32_e32 v4, v4, v194
	v_mul_f32_e32 v5, v5, v195
	v_mul_f32_e32 v18, v18, v192
	v_mul_f32_e32 v19, v19, v193
	v_mul_f32_e32 v20, v20, v194
	v_mul_f32_e32 v21, v21, v195
	v_mul_f32_e32 v34, v34, v192
	v_mul_f32_e32 v35, v35, v193
	v_mul_f32_e32 v36, v36, v194
	v_mul_f32_e32 v37, v37, v195
	v_mul_f32_e32 v50, v50, v192
	v_mul_f32_e32 v51, v51, v193
	v_mul_f32_e32 v52, v52, v194
	v_mul_f32_e32 v53, v53, v195
	ds_read_b128 v[192:195], v249 offset:32
	s_waitcnt lgkmcnt(0)
	v_mul_f32_e32 v6, v6, v192
	v_mul_f32_e32 v7, v7, v193
	v_mul_f32_e32 v8, v8, v194
	v_mul_f32_e32 v9, v9, v195
	v_mul_f32_e32 v22, v22, v192
	v_mul_f32_e32 v23, v23, v193
	v_mul_f32_e32 v24, v24, v194
	v_mul_f32_e32 v25, v25, v195
	v_mul_f32_e32 v38, v38, v192
	v_mul_f32_e32 v39, v39, v193
	v_mul_f32_e32 v40, v40, v194
	v_mul_f32_e32 v41, v41, v195
	v_mul_f32_e32 v54, v54, v192
	v_mul_f32_e32 v55, v55, v193
	v_mul_f32_e32 v56, v56, v194
	v_mul_f32_e32 v57, v57, v195
	ds_read_b128 v[192:195], v249 offset:64
	s_waitcnt lgkmcnt(0)
	v_mul_f32_e32 v10, v10, v192
	v_mul_f32_e32 v11, v11, v193
	v_mul_f32_e32 v12, v12, v194
	v_mul_f32_e32 v13, v13, v195
	v_mul_f32_e32 v26, v26, v192
	v_mul_f32_e32 v27, v27, v193
	v_mul_f32_e32 v28, v28, v194
	v_mul_f32_e32 v29, v29, v195
	v_mul_f32_e32 v42, v42, v192
	v_mul_f32_e32 v43, v43, v193
	v_mul_f32_e32 v44, v44, v194
	v_mul_f32_e32 v45, v45, v195
	v_mul_f32_e32 v58, v58, v192
	v_mul_f32_e32 v59, v59, v193
	v_mul_f32_e32 v60, v60, v194
	v_mul_f32_e32 v61, v61, v195
	ds_read_b128 v[192:195], v249 offset:96
	s_waitcnt lgkmcnt(0)
	v_mul_f32_e32 v14, v14, v192
	v_mul_f32_e32 v15, v15, v193
	v_mul_f32_e32 v16, v16, v194
	v_mul_f32_e32 v17, v17, v195
	v_mul_f32_e32 v30, v30, v192
	v_mul_f32_e32 v31, v31, v193
	v_mul_f32_e32 v32, v32, v194
	v_mul_f32_e32 v33, v33, v195
	v_mul_f32_e32 v46, v46, v192
	v_mul_f32_e32 v47, v47, v193
	v_mul_f32_e32 v48, v48, v194
	v_mul_f32_e32 v49, v49, v195
	v_mul_f32_e32 v62, v62, v192
	v_mul_f32_e32 v63, v63, v193
	v_mul_f32_e32 v64, v64, v194
	v_mul_f32_e32 v65, v65, v195

; #define LAS __attribute__((address_space(3)))
; __device__ __forceinline__ float max_x32(float v) { auto rr = __builtin_amdgcn_permlane32_swap(__float_as_uint(v), __float_as_uint(v), false, false); return __builtin_fmaxf(__uint_as_float(rr[0]), __uint_as_float(rr[1])); }
; __device__ __forceinline__ int crow(int r, int hi) { return (r & 3) + 8 * (r >> 2) + 4 * hi; }
; template <int NDV, bool MASK, int KPITCH, int VPITCH> ...
;     ...
;     for (int dc = 0; dc < 4; ++dc) {
;         const bf16x8 a0 = *(const LAS bf16x8*)(kp + dc * 32);
;         const bf16x8 a1 = *(const LAS bf16x8*)(kp + 32 * KPITCH + dc * 32);
;         s0 = __builtin_amdgcn_mfma_f32_32x32x16_bf16(a0, qf[dc], s0, 0, 0, 0);
;         s1 = __builtin_amdgcn_mfma_f32_32x32x16_bf16(a1, qf[dc], s1, 0, 0, 0);
;     }
;     float mx = -3.0e38f;
; #pragma unroll
;     for (int r = 0; r < 16; ++r) {
;         const float c = (float)((r & 7) + 16 * (r >> 3));
;         const float d0 = __builtin_fabsf(dbase + c), d1 = __builtin_fabsf(dbase + (c + 32.f));
;         float t0 = __builtin_fmaf(nslope, d0, s0[r]), t1 = __builtin_fmaf(nslope, d1, s1[r]);
;         if (MASK) { t0 = d0 <= 128.f ? t0 : -1e30f; t1 = d1 <= 128.f ? t1 : -1e30f; }
;         s0[r] = t0; s1[r] = t1; mx = __builtin_fmaxf(mx, __builtin_fmaxf(t0, t1));
;     }
;     mx = max_x32(mx);
;     if (__any(mx > mref + 8.f)) {
;         const float mnew = __builtin_fmaxf(mref, mx); const float alpha = __builtin_amdgcn_exp2f(mref - mnew);
;         lsum *= alpha; mref = mnew;
;         if (hi == 0) wsf[r32] = alpha;
; #pragma unroll
;         for (int r = 0; r < 16; ++r) { const float al = wsf[crow(r, hi)];
; #pragma unroll
;             for (int d = 0; d < NDV; ++d) o[d][r] *= al; }
;     }
.Lwb_qk:
	s_nop 1
	v_mfma_f32_32x32x16_bf16 v[34:49], v[138:141], v[66:69], v[34:49]
	v_mfma_f32_32x32x16_bf16 v[50:65], v[142:145], v[66:69], v[50:65]
	ds_read_b128 v[138:141], v118 offset:18432
	ds_read_b128 v[142:145], v118 offset:23040
	v_mfma_f32_32x32x16_bf16 v[34:49], v[146:149], v[70:73], v[34:49]
	v_mfma_f32_32x32x16_bf16 v[50:65], v[150:153], v[70:73], v[50:65]
	ds_read_b128 v[146:149], v118 offset:18464
	ds_read_b128 v[150:153], v118 offset:23072
	v_mfma_f32_32x32x16_bf16 v[34:49], v[154:157], v[74:77], v[34:49]
	v_mfma_f32_32x32x16_bf16 v[50:65], v[158:161], v[74:77], v[50:65]
	ds_read_b128 v[154:157], v118 offset:18496
	ds_read_b128 v[158:161], v118 offset:23104
	v_mfma_f32_32x32x16_bf16 v[34:49], v[162:165], v[78:81], v[34:49]
	v_mfma_f32_32x32x16_bf16 v[50:65], v[166:169], v[78:81], v[50:65]
	s_waitcnt lgkmcnt(13)
	ds_read_b128 v[162:165], v118 offset:18528
	ds_read_b128 v[166:169], v118 offset:23136
	s_nop 9
	v_max3_f32 v212, v34, v35, v36
	v_max3_f32 v213, v50, v51, v52
	v_max3_f32 v212, v212, v37, v38
	v_max3_f32 v213, v213, v53, v54
	v_max3_f32 v212, v212, v39, v40
	v_max3_f32 v213, v213, v55, v56
	v_max3_f32 v212, v212, v41, v42
	v_max3_f32 v213, v213, v57, v58
	v_max3_f32 v212, v212, v43, v44
	v_max3_f32 v213, v213, v59, v60
	v_max3_f32 v212, v212, v45, v46
	v_max3_f32 v213, v213, v61, v62
	v_max3_f32 v212, v212, v47, v48
	v_max3_f32 v213, v213, v63, v64
	v_max3_f32 v212, v212, v49, v65
	v_max_f32_e32 v212, v212, v213
	v_mov_b32_e32 v213, v212
	s_nop 1
	v_permlane32_swap_b32_e32 v212, v213
	v_max_f32_e32 v212, v212, v213
	v_mov_b32_e32 v213, 0x41000000
	v_cmp_gt_f32_e32 vcc, v212, v213
	s_cbranch_vccz .Lwb_exp
	v_max_f32_e32 v212, 0, v212
	s_nop 0
	v_exp_f32_e64 v213, -v212
	s_and_saveexec_b64 s[16:17], s[6:7]
	ds_write_b32 v85, v213
	s_or_b64 exec, exec, s[16:17]
	v_mul_f32_e32 v87, v87, v213
	v_add_f32_e32 v120, v120, v212
	v_sub_f32_e32 v34, v34, v212
	v_sub_f32_e32 v50, v50, v212
	v_sub_f32_e32 v35, v35, v212
	v_sub_f32_e32 v51, v51, v212
	v_sub_f32_e32 v36, v36, v212
	v_sub_f32_e32 v52, v52, v212
	v_sub_f32_e32 v37, v37, v212
	v_sub_f32_e32 v53, v53, v212
	v_sub_f32_e32 v38, v38, v212
	v_sub_f32_e32 v54, v54, v212
	v_sub_f32_e32 v39, v39, v212
	v_sub_f32_e32 v55, v55, v212
	v_sub_f32_e32 v40, v40, v212
	v_sub_f32_e32 v56, v56, v212
	v_sub_f32_e32 v41, v41, v212
	v_sub_f32_e32 v57, v57, v212
	v_sub_f32_e32 v42, v42, v212
	v_sub_f32_e32 v58, v58, v212
	v_sub_f32_e32 v43, v43, v212
	v_sub_f32_e32 v59, v59, v212
	v_sub_f32_e32 v44, v44, v212
	v_sub_f32_e32 v60, v60, v212
	v_sub_f32_e32 v45, v45, v212
	v_sub_f32_e32 v61, v61, v212
	v_sub_f32_e32 v46, v46, v212
	v_sub_f32_e32 v62, v62, v212
	v_sub_f32_e32 v47, v47, v212
	v_sub_f32_e32 v63, v63, v212
	v_sub_f32_e32 v48, v48, v212
	v_sub_f32_e32 v64, v64, v212
	v_sub_f32_e32 v49, v49, v212
	v_sub_f32_e32 v65, v65, v212
	v_add_u32_e32 v121, s22, v95
	ds_read_b128 v[208:211], v121
	s_waitcnt lgkmcnt(0)
	v_mul_f32_e32 v2, v2, v208
	v_mul_f32_e32 v3, v3, v209
	v_mul_f32_e32 v4, v4, v210
	v_mul_f32_e32 v5, v5, v211
	v_mul_f32_e32 v18, v18, v208
	v_mul_f32_e32 v19, v19, v209
	v_mul_f32_e32 v20, v20, v210
	v_mul_f32_e32 v21, v21, v211
	ds_read_b128 v[208:211], v121 offset:32
	s_waitcnt lgkmcnt(0)
	v_mul_f32_e32 v6, v6, v208
	v_mul_f32_e32 v7, v7, v209
	v_mul_f32_e32 v8, v8, v210
	v_mul_f32_e32 v9, v9, v211
	v_mul_f32_e32 v22, v22, v208
	v_mul_f32_e32 v23, v23, v209
	v_mul_f32_e32 v24, v24, v210
	v_mul_f32_e32 v25, v25, v211
	ds_read_b128 v[208:211], v121 offset:64
	s_waitcnt lgkmcnt(0)
	v_mul_f32_e32 v10, v10, v208
	v_mul_f32_e32 v11, v11, v209
	v_mul_f32_e32 v12, v12, v210
	v_mul_f32_e32 v13, v13, v211
	v_mul_f32_e32 v26, v26, v208
	v_mul_f32_e32 v27, v27, v209
	v_mul_f32_e32 v28, v28, v210
	v_mul_f32_e32 v29, v29, v211
	ds_read_b128 v[208:211], v121 offset:96
	s_waitcnt lgkmcnt(0)
	v_mul_f32_e32 v14, v14, v208
	v_mul_f32_e32 v15, v15, v209
	v_mul_f32_e32 v16, v16, v210
	v_mul_f32_e32 v17, v17, v211
	v_mul_f32_e32 v30, v30, v208
	v_mul_f32_e32 v31, v31, v209
	v_mul_f32_e32 v32, v32, v210
	v_mul_f32_e32 v33, v33, v211

; #define GAS __attribute__((address_space(1)))
; __device__ __forceinline__ unsigned cvt_pk_bf16(float lo, float hi) { unsigned r; asm("v_cvt_pk_bf16_f32 %0, %1, %2" : "=v"(r) : "v"(lo), "v"(hi)); return r; }
; template <int M> __device__ __forceinline__ float swz_xor(float v) { return __int_as_float(__builtin_amdgcn_ds_swizzle(__float_as_int(v), 0x1f | (M << 10))); }
;     __device__ __forceinline__ void operator()(const f32x4 (&acc)[2][2][4][2], const Unit& u, int wr, int wc, int fr, int fq) const {
;     ...
;         f32x4 gv[2][2];
; #pragma unroll
;         for (int bj = 0; bj < 2; ++bj)
; #pragma unroll
;             for (int n = 0; n < 2; ++n) gv[bj][n] = do_norm ? *(const GAS f32x4*)(gn + col0 + bj * HALF + n * 16) : (f32x4){0.f, 0.f, 0.f, 0.f};
; #pragma unroll
;         for (int ai = 0; ai < 2; ++ai)
; #pragma unroll
;             for (int mh = 0; mh < 2; ++mh) {
;                 f32x4 bsv[2][2][2];
; #pragma unroll
;                 for (int mm = 0; mm < 2; ++mm) { const size_t off = (size_t)(row0 + ai * HALF + (2 * mh + mm) * 16) * ldc + col0;
; #pragma unroll
;                     for (int bj = 0; bj < 2; ++bj)
; #pragma unroll
;                         for (int n = 0; n < 2; ++n) bsv[mm][bj][n] = *(const GAS f32x4*)(base + off + bj * HALF + n * 16); }
; #pragma unroll
;                 for (int mm = 0; mm < 2; ++mm) { const int m = 2 * mh + mm, row = row0 + ai * HALF + m * 16; const size_t off = (size_t)row * ldc + col0; float sq = 0.f;
; #pragma unroll
;                     for (int bj = 0; bj < 2; ++bj)
; #pragma unroll
;                         for (int n = 0; n < 2; ++n) { const f32x4 v = bsv[mm][bj][n] + acc[ai][bj][m][n]; *(GAS f32x4*)(out + off + bj * HALF + n * 16) = v;
;                             if (do_norm) { sq += (v[0] * v[0] + v[1] * v[1]) + (v[2] * v[2] + v[3] * v[3]); const f32x4 w = v * gv[bj][n];
;                                 u32x2 pk; pk.x = cvt_pk_bf16(w[0], w[1]); pk.y = cvt_pk_bf16(w[2], w[3]); *(GAS u32x2*)(xb + off + bj * HALF + n * 16) = pk; } }
;                     if (do_norm) { sq += swz_xor<16>(sq); sq = sum_x32(sq); if (fq == 0) (void)__hip_atomic_fetch_add(ssq + row, (unsigned long long)(sq * 1048576.f + 0.5f), __ATOMIC_RELAXED, __HIP_MEMORY_SCOPE_AGENT); } }
.LBB0_625:
	s_lshl_b32 s27, s85, 8
	v_mov_b32_e32 v148, v181
	v_mov_b32_e32 v149, v180
	s_lshl_b32 s26, s86, 8
	s_or_b32 s27, s27, s45
	s_add_i32 s26, s26, s44
	v_lshl_add_u32 v172, v149, 2, s27
	v_ashrrev_i32_e32 v173, 31, v172
	v_add_u32_e32 v174, s26, v148
	v_lshlrev_b64 v[146:147], 2, v[172:173]
	v_ashrrev_i32_e32 v175, 31, v174
	v_lshl_add_u64 v[46:47], s[20:21], 0, v[146:147]
	v_lshl_add_u64 v[176:177], s[16:17], 0, v[146:147]
	v_lshlrev_b64 v[146:147], 12, v[174:175]
	v_lshl_add_u64 v[146:147], v[176:177], 0, v[146:147]
	global_load_dwordx4 v[62:65], v[46:47], off
	global_load_dwordx4 v[58:61], v[46:47], off offset:64
	global_load_dwordx4 v[54:57], v[46:47], off offset:512
	s_nop 0
	global_load_dwordx4 v[46:49], v[46:47], off offset:576
	s_nop 0
	global_load_dwordx4 v[184:187], v[146:147], off
	global_load_dwordx4 v[192:195], v[146:147], off offset:64
	global_load_dwordx4 v[196:199], v[146:147], off offset:512
	global_load_dwordx4 v[162:165], v[146:147], off offset:576
	v_add_u32_e32 v178, 16, v174
	v_ashrrev_i32_e32 v179, 31, v178
	v_lshlrev_b64 v[146:147], 12, v[178:179]
	v_lshl_add_u64 v[146:147], v[176:177], 0, v[146:147]
	v_cmp_eq_u32_e32 vcc, 0, v149
	global_load_dwordx4 v[158:161], v[146:147], off
	global_load_dwordx4 v[154:157], v[146:147], off offset:64
	global_load_dwordx4 v[150:153], v[146:147], off offset:512
	s_nop 0
	global_load_dwordx4 v[146:149], v[146:147], off offset:576
	v_lshlrev_b64 v[200:201], 10, v[174:175]
	v_lshl_add_u64 v[200:201], v[200:201], 0, v[172:173]
	s_waitcnt vmcnt(0)
	v_add_f32_e32 v144, v144, v186
	v_add_f32_e32 v145, v145, v187
	v_add_f32_e32 v142, v142, v184
	v_add_f32_e32 v143, v143, v185
	v_lshl_add_u64 v[184:185], v[200:201], 2, s[12:13]
	v_mul_f32_e32 v186, v143, v143
	v_mul_f32_e32 v187, v145, v145
	global_store_dwordx4 v[184:185], v[142:145], off
	v_fmac_f32_e32 v186, v142, v142
	v_fmac_f32_e32 v187, v144, v144
	v_mul_f32_e32 v144, v64, v144
	v_mul_f32_e32 v145, v65, v145
	v_mul_f32_e32 v142, v62, v142
	v_mul_f32_e32 v143, v63, v143
	v_add_f32_e32 v138, v138, v192
	v_add_f32_e32 v139, v139, v193
	v_cvt_pk_bf16_f32 v142, v142, v143
	v_cvt_pk_bf16_f32 v143, v144, v145
	v_lshl_add_u64 v[144:145], v[200:201], 1, s[22:23]
	global_store_dwordx2 v[144:145], v[142:143], off
	v_add_f32_e32 v140, v140, v194
	v_add_f32_e32 v141, v141, v195
	v_mul_f32_e32 v142, v139, v139
	global_store_dwordx4 v[184:185], v[138:141], off offset:64
	v_fmac_f32_e32 v142, v138, v138
	v_mul_f32_e32 v143, v141, v141
	v_mul_f32_e32 v138, v58, v138
	v_mul_f32_e32 v139, v59, v139
	v_fmac_f32_e32 v143, v140, v140
	v_mul_f32_e32 v140, v60, v140
	v_mul_f32_e32 v141, v61, v141
	v_cvt_pk_bf16_f32 v138, v138, v139
	v_add_f32_e32 v136, v136, v198
	v_add_f32_e32 v137, v137, v199
	v_cvt_pk_bf16_f32 v139, v140, v141
	v_add_f32_e32 v134, v134, v196
	v_add_f32_e32 v135, v135, v197
	global_store_dwordx2 v[144:145], v[138:139], off offset:32
	v_mul_f32_e32 v138, v135, v135
	v_mul_f32_e32 v139, v137, v137
	global_store_dwordx4 v[184:185], v[134:137], off offset:512
	v_fmac_f32_e32 v138, v134, v134
	v_fmac_f32_e32 v139, v136, v136
	v_mul_f32_e32 v136, v56, v136
	v_mul_f32_e32 v137, v57, v137
	v_mul_f32_e32 v134, v54, v134
	v_mul_f32_e32 v135, v55, v135
	v_add_f32_e32 v132, v132, v164
	v_add_f32_e32 v133, v133, v165
	v_add_f32_e32 v130, v130, v162
	v_add_f32_e32 v131, v131, v163
	v_cvt_pk_bf16_f32 v134, v134, v135
	v_cvt_pk_bf16_f32 v135, v136, v137
	global_store_dwordx2 v[144:145], v[134:135], off offset:256
	global_store_dwordx4 v[184:185], v[130:133], off offset:576
	v_mul_f32_e32 v136, v46, v130
	v_mul_f32_e32 v137, v47, v131
	v_add_f32_e32 v186, v186, v187
	v_mul_f32_e32 v131, v131, v131
	v_add_f32_e32 v142, v142, v143
	v_fmac_f32_e32 v131, v130, v130
	v_mul_f32_e32 v130, v133, v133
	v_add_f32_e32 v142, v186, v142
	v_add_f32_e32 v138, v138, v139
	v_fmac_f32_e32 v130, v132, v132
	v_add_f32_e32 v138, v142, v138
	v_add_f32_e32 v130, v131, v130
	v_add_f32_e32 v130, v138, v130
	ds_swizzle_b32 v131, v130 offset:swizzle(SWAP,16)
	v_mul_f32_e32 v134, v48, v132
	v_mul_f32_e32 v135, v49, v133
	v_cvt_pk_bf16_f32 v136, v136, v137
	s_waitcnt lgkmcnt(0)
	v_add_f32_e32 v130, v130, v131
	v_mov_b32_e32 v131, v130
	s_nop 1
	v_permlane32_swap_b32_e32 v130, v131
	v_cvt_pk_bf16_f32 v137, v134, v135
	global_store_dwordx2 v[144:145], v[136:137], off offset:288
	s_and_saveexec_b64 s[26:27], vcc
	s_cbranch_execz .LBB0_627
	v_add_f32_e32 v130, v130, v131
	s_mov_b32 s28, 0x49800000
	v_fma_f32 v130, v130, s28, 0.5
	v_trunc_f32_e32 v130, v130
	v_mul_f32_e32 v131, 0x2f800000, v130
	v_floor_f32_e32 v131, v131
	v_fmac_f32_e32 v130, 0xcf800000, v131
	v_cvt_u32_f32_e32 v130, v130
	v_cvt_u32_f32_e32 v131, v131
	v_lshl_add_u64 v[132:133], v[174:175], 3, s[10:11]
	global_atomic_add_x2 v[132:133], v[130:131], off
; #define GAS __attribute__((address_space(1)))
; __device__ __forceinline__ unsigned cvt_pk_bf16(float lo, float hi) { unsigned r; asm("v_cvt_pk_bf16_f32 %0, %1, %2" : "=v"(r) : "v"(lo), "v"(hi)); return r; }
; template <int M> __device__ __forceinline__ float swz_xor(float v) { return __int_as_float(__builtin_amdgcn_ds_swizzle(__float_as_int(v), 0x1f | (M << 10))); }
; __device__ __forceinline__ float sum_x32(float v) { auto rr = __builtin_amdgcn_permlane32_swap(__float_as_uint(v), __float_as_uint(v), false, false); return __uint_as_float(rr[0]) + __uint_as_float(rr[1]); }
;     __device__ __forceinline__ void operator()(const f32x4 (&acc)[2][2][4][2], const Unit& u, int wr, int wc, int fr, int fq) const {
;     ...
;         for (int ai = 0; ai < 2; ++ai)
; #pragma unroll
;             for (int mh = 0; mh < 2; ++mh) {
;                 f32x4 bsv[2][2][2];
; #pragma unroll
;                 for (int mm = 0; mm < 2; ++mm) { const size_t off = (size_t)(row0 + ai * HALF + (2 * mh + mm) * 16) * ldc + col0;
; #pragma unroll
;                     for (int bj = 0; bj < 2; ++bj)
; #pragma unroll
;                         for (int n = 0; n < 2; ++n) bsv[mm][bj][n] = *(const GAS f32x4*)(base + off + bj * HALF + n * 16); }
; #pragma unroll
;                 for (int mm = 0; mm < 2; ++mm) { const int m = 2 * mh + mm, row = row0 + ai * HALF + m * 16; const size_t off = (size_t)row * ldc + col0; float sq = 0.f;
; #pragma unroll
;                     for (int bj = 0; bj < 2; ++bj)
; #pragma unroll
;                         for (int n = 0; n < 2; ++n) { const f32x4 v = bsv[mm][bj][n] + acc[ai][bj][m][n]; *(GAS f32x4*)(out + off + bj * HALF + n * 16) = v;
;                             if (do_norm) { sq += (v[0] * v[0] + v[1] * v[1]) + (v[2] * v[2] + v[3] * v[3]); const f32x4 w = v * gv[bj][n];
;                                 u32x2 pk; pk.x = cvt_pk_bf16(w[0], w[1]); pk.y = cvt_pk_bf16(w[2], w[3]); *(GAS u32x2*)(xb + off + bj * HALF + n * 16) = pk; } }
;                     if (do_norm) { sq += swz_xor<16>(sq); sq = sum_x32(sq); if (fq == 0) (void)__hip_atomic_fetch_add(ssq + row, (unsigned long long)(sq * 1048576.f + 0.5f), __ATOMIC_RELAXED, __HIP_MEMORY_SCOPE_AGENT); } }
.LBB0_627:
	s_or_b64 exec, exec, s[26:27]
	v_lshlrev_b64 v[130:131], 10, v[178:179]
	v_lshl_add_u64 v[130:131], v[130:131], 0, v[172:173]
	v_add_f32_e32 v128, v128, v160
	v_add_f32_e32 v129, v129, v161
	v_add_f32_e32 v126, v126, v158
	v_add_f32_e32 v127, v127, v159
	v_lshl_add_u64 v[132:133], v[130:131], 2, s[12:13]
	v_mul_f32_e32 v134, v127, v127
	v_mul_f32_e32 v135, v129, v129
	global_store_dwordx4 v[132:133], v[126:129], off
	v_fmac_f32_e32 v134, v126, v126
	v_fmac_f32_e32 v135, v128, v128
	v_mul_f32_e32 v128, v64, v128
	v_mul_f32_e32 v129, v65, v129
	v_mul_f32_e32 v126, v62, v126
	v_mul_f32_e32 v127, v63, v127
	v_add_f32_e32 v122, v122, v154
	v_add_f32_e32 v123, v123, v155
	v_cvt_pk_bf16_f32 v126, v126, v127
	v_cvt_pk_bf16_f32 v127, v128, v129
	v_lshl_add_u64 v[128:129], v[130:131], 1, s[22:23]
	global_store_dwordx2 v[128:129], v[126:127], off
	v_add_f32_e32 v124, v124, v156
	v_add_f32_e32 v125, v125, v157
	v_mul_f32_e32 v126, v123, v123
	global_store_dwordx4 v[132:133], v[122:125], off offset:64
	v_fmac_f32_e32 v126, v122, v122
	v_mul_f32_e32 v127, v125, v125
	v_mul_f32_e32 v122, v58, v122
	v_mul_f32_e32 v123, v59, v123
	v_add_f32_e32 v118, v118, v150
	v_add_f32_e32 v119, v119, v151
	v_cvt_pk_bf16_f32 v122, v122, v123
	v_fmac_f32_e32 v127, v124, v124
	v_mul_f32_e32 v124, v60, v124
	v_mul_f32_e32 v125, v61, v125
	v_add_f32_e32 v120, v120, v152
	v_add_f32_e32 v121, v121, v153
	v_cvt_pk_bf16_f32 v123, v124, v125
	global_store_dwordx2 v[128:129], v[122:123], off offset:32
	v_mul_f32_e32 v122, v119, v119
	global_store_dwordx4 v[132:133], v[118:121], off offset:512
	v_fmac_f32_e32 v122, v118, v118
	v_mul_f32_e32 v123, v121, v121
	v_mul_f32_e32 v118, v54, v118
	v_mul_f32_e32 v119, v55, v119
	v_fmac_f32_e32 v123, v120, v120
	v_mul_f32_e32 v120, v56, v120
	v_mul_f32_e32 v121, v57, v121
	v_cvt_pk_bf16_f32 v118, v118, v119
	v_add_f32_e32 v116, v116, v148
	v_add_f32_e32 v117, v117, v149
	v_cvt_pk_bf16_f32 v119, v120, v121
	v_add_f32_e32 v114, v114, v146
	v_add_f32_e32 v115, v115, v147
	v_add_f32_e32 v134, v134, v135
	v_add_f32_e32 v126, v126, v127
	global_store_dwordx2 v[128:129], v[118:119], off offset:256
	global_store_dwordx4 v[132:133], v[114:117], off offset:576
	v_mul_f32_e32 v118, v48, v116
	v_mul_f32_e32 v119, v49, v117
	v_mul_f32_e32 v120, v115, v115
	v_mul_f32_e32 v117, v117, v117
	v_add_f32_e32 v126, v134, v126
	v_add_f32_e32 v122, v122, v123
	v_fmac_f32_e32 v120, v114, v114
	v_fmac_f32_e32 v117, v116, v116
	v_add_f32_e32 v122, v126, v122
	v_add_f32_e32 v116, v120, v117
	v_add_f32_e32 v116, v122, v116
	ds_swizzle_b32 v117, v116 offset:swizzle(SWAP,16)
	v_mul_f32_e32 v114, v46, v114
	v_mul_f32_e32 v115, v47, v115
	s_nop 0
	v_cvt_pk_bf16_f32 v114, v114, v115
	v_cvt_pk_bf16_f32 v115, v118, v119
	global_store_dwordx2 v[128:129], v[114:115], off offset:288
	s_waitcnt lgkmcnt(0)
	v_add_f32_e32 v114, v116, v117
	v_mov_b32_e32 v115, v114
	s_nop 1
	v_permlane32_swap_b32_e32 v114, v115
	s_and_saveexec_b64 s[26:27], vcc
	s_cbranch_execz .LBB0_629
	v_add_f32_e32 v114, v114, v115
	s_mov_b32 s28, 0x49800000
	v_fma_f32 v114, v114, s28, 0.5
	v_trunc_f32_e32 v114, v114
	v_mul_f32_e32 v115, 0x2f800000, v114
	v_floor_f32_e32 v115, v115
	v_fmac_f32_e32 v114, 0xcf800000, v115
	v_cvt_u32_f32_e32 v114, v114
	v_cvt_u32_f32_e32 v115, v115
	v_lshl_add_u64 v[116:117], v[178:179], 3, s[10:11]
	global_atomic_add_x2 v[116:117], v[114:115], off
.LBB0_629:
	s_or_b64 exec, exec, s[26:27]
	v_add_u32_e32 v136, 32, v174
	v_ashrrev_i32_e32 v137, 31, v136
	v_lshlrev_b64 v[114:115], 12, v[136:137]
	v_lshl_add_u64 v[114:115], v[176:177], 0, v[114:115]
	global_load_dwordx4 v[138:141], v[114:115], off
	global_load_dwordx4 v[142:145], v[114:115], off offset:64
	global_load_dwordx4 v[146:149], v[114:115], off offset:512
	global_load_dwordx4 v[130:133], v[114:115], off offset:576
	v_add_u32_e32 v134, 48, v174
	v_ashrrev_i32_e32 v135, 31, v134
	v_lshlrev_b64 v[114:115], 12, v[134:135]
	v_lshl_add_u64 v[114:115], v[176:177], 0, v[114:115]
	global_load_dwordx4 v[126:129], v[114:115], off
	global_load_dwordx4 v[122:125], v[114:115], off offset:64
	global_load_dwordx4 v[118:121], v[114:115], off offset:512
	s_nop 0
	global_load_dwordx4 v[114:117], v[114:115], off offset:576
	v_lshlrev_b64 v[150:151], 10, v[136:137]
	v_lshl_add_u64 v[150:151], v[150:151], 0, v[172:173]
	s_waitcnt vmcnt(7)
	v_add_f32_e32 v112, v112, v140
	v_add_f32_e32 v113, v113, v141
	v_add_f32_e32 v110, v110, v138
	v_add_f32_e32 v111, v111, v139
	v_lshl_add_u64 v[138:139], v[150:151], 2, s[12:13]
	v_mul_f32_e32 v140, v111, v111
	v_mul_f32_e32 v141, v113, v113
	global_store_dwordx4 v[138:139], v[110:113], off
	v_fmac_f32_e32 v140, v110, v110
	v_fmac_f32_e32 v141, v112, v112
	v_mul_f32_e32 v112, v64, v112
	v_mul_f32_e32 v113, v65, v113
	v_mul_f32_e32 v110, v62, v110
	v_mul_f32_e32 v111, v63, v111
	s_waitcnt vmcnt(7)
	v_add_f32_e32 v106, v106, v142
	v_add_f32_e32 v107, v107, v143
	v_cvt_pk_bf16_f32 v110, v110, v111
	v_cvt_pk_bf16_f32 v111, v112, v113
	v_lshl_add_u64 v[112:113], v[150:151], 1, s[22:23]
	global_store_dwordx2 v[112:113], v[110:111], off
	v_add_f32_e32 v108, v108, v144
	v_add_f32_e32 v109, v109, v145
	v_mul_f32_e32 v110, v107, v107
	global_store_dwordx4 v[138:139], v[106:109], off offset:64
	v_fmac_f32_e32 v110, v106, v106
	v_mul_f32_e32 v111, v109, v109
	v_mul_f32_e32 v106, v58, v106
	v_mul_f32_e32 v107, v59, v107
	v_fmac_f32_e32 v111, v108, v108
	v_mul_f32_e32 v108, v60, v108
	v_mul_f32_e32 v109, v61, v109
	v_cvt_pk_bf16_f32 v106, v106, v107
	s_waitcnt vmcnt(8)
; #define GAS __attribute__((address_space(1)))
; __device__ __forceinline__ unsigned cvt_pk_bf16(float lo, float hi) { unsigned r; asm("v_cvt_pk_bf16_f32 %0, %1, %2" : "=v"(r) : "v"(lo), "v"(hi)); return r; }
; template <int M> __device__ __forceinline__ float swz_xor(float v) { return __int_as_float(__builtin_amdgcn_ds_swizzle(__float_as_int(v), 0x1f | (M << 10))); }
; __device__ __forceinline__ float sum_x32(float v) { auto rr = __builtin_amdgcn_permlane32_swap(__float_as_uint(v), __float_as_uint(v), false, false); return __uint_as_float(rr[0]) + __uint_as_float(rr[1]); }
;     __device__ __forceinline__ void operator()(const f32x4 (&acc)[2][2][4][2], const Unit& u, int wr, int wc, int fr, int fq) const {
;     ...
;         for (int ai = 0; ai < 2; ++ai)
; #pragma unroll
;             for (int mh = 0; mh < 2; ++mh) {
;                 f32x4 bsv[2][2][2];
; #pragma unroll
;                 for (int mm = 0; mm < 2; ++mm) { const size_t off = (size_t)(row0 + ai * HALF + (2 * mh + mm) * 16) * ldc + col0;
; #pragma unroll
;                     for (int bj = 0; bj < 2; ++bj)
; #pragma unroll
;                         for (int n = 0; n < 2; ++n) bsv[mm][bj][n] = *(const GAS f32x4*)(base + off + bj * HALF + n * 16); }
; #pragma unroll
;                 for (int mm = 0; mm < 2; ++mm) { const int m = 2 * mh + mm, row = row0 + ai * HALF + m * 16; const size_t off = (size_t)row * ldc + col0; float sq = 0.f;
; #pragma unroll
;                     for (int bj = 0; bj < 2; ++bj)
; #pragma unroll
;                         for (int n = 0; n < 2; ++n) { const f32x4 v = bsv[mm][bj][n] + acc[ai][bj][m][n]; *(GAS f32x4*)(out + off + bj * HALF + n * 16) = v;
;                             if (do_norm) { sq += (v[0] * v[0] + v[1] * v[1]) + (v[2] * v[2] + v[3] * v[3]); const f32x4 w = v * gv[bj][n];
;                                 u32x2 pk; pk.x = cvt_pk_bf16(w[0], w[1]); pk.y = cvt_pk_bf16(w[2], w[3]); *(GAS u32x2*)(xb + off + bj * HALF + n * 16) = pk; } }
;                     if (do_norm) { sq += swz_xor<16>(sq); sq = sum_x32(sq); if (fq == 0) (void)__hip_atomic_fetch_add(ssq + row, (unsigned long long)(sq * 1048576.f + 0.5f), __ATOMIC_RELAXED, __HIP_MEMORY_SCOPE_AGENT); } }
	v_add_f32_e32 v104, v104, v148
	v_add_f32_e32 v105, v105, v149
	v_cvt_pk_bf16_f32 v107, v108, v109
	v_add_f32_e32 v102, v102, v146
	v_add_f32_e32 v103, v103, v147
	global_store_dwordx2 v[112:113], v[106:107], off offset:32
	v_mul_f32_e32 v106, v103, v103
	v_mul_f32_e32 v107, v105, v105
	global_store_dwordx4 v[138:139], v[102:105], off offset:512
	v_fmac_f32_e32 v106, v102, v102
	v_fmac_f32_e32 v107, v104, v104
	v_mul_f32_e32 v104, v56, v104
	v_mul_f32_e32 v105, v57, v105
	v_mul_f32_e32 v102, v54, v102
	v_mul_f32_e32 v103, v55, v103
	s_waitcnt vmcnt(9)
	v_add_f32_e32 v100, v100, v132
	v_add_f32_e32 v101, v101, v133
	v_add_f32_e32 v98, v98, v130
	v_add_f32_e32 v99, v99, v131
	v_cvt_pk_bf16_f32 v102, v102, v103
	v_cvt_pk_bf16_f32 v103, v104, v105
	global_store_dwordx2 v[112:113], v[102:103], off offset:256
	global_store_dwordx4 v[138:139], v[98:101], off offset:576
	v_mul_f32_e32 v104, v46, v98
	v_mul_f32_e32 v105, v47, v99
	v_add_f32_e32 v140, v140, v141
	v_mul_f32_e32 v99, v99, v99
	v_add_f32_e32 v110, v110, v111
	v_fmac_f32_e32 v99, v98, v98
	v_mul_f32_e32 v98, v101, v101
	v_add_f32_e32 v110, v140, v110
	v_add_f32_e32 v106, v106, v107
	v_fmac_f32_e32 v98, v100, v100
	v_add_f32_e32 v106, v110, v106
	v_add_f32_e32 v98, v99, v98
	v_add_f32_e32 v98, v106, v98
	ds_swizzle_b32 v99, v98 offset:swizzle(SWAP,16)
	v_mul_f32_e32 v102, v48, v100
	v_mul_f32_e32 v103, v49, v101
	v_cvt_pk_bf16_f32 v104, v104, v105
	s_waitcnt lgkmcnt(0)
	v_add_f32_e32 v98, v98, v99
	v_mov_b32_e32 v99, v98
	s_nop 1
	v_permlane32_swap_b32_e32 v98, v99
	v_cvt_pk_bf16_f32 v105, v102, v103
	global_store_dwordx2 v[112:113], v[104:105], off offset:288
	s_and_saveexec_b64 s[26:27], vcc
	v_readlane_b32 s95, v254, 54
	s_cbranch_execz .LBB0_631
	v_add_f32_e32 v98, v98, v99
	s_mov_b32 s28, 0x49800000
	v_fma_f32 v98, v98, s28, 0.5
	v_trunc_f32_e32 v98, v98
	v_mul_f32_e32 v99, 0x2f800000, v98
	v_floor_f32_e32 v99, v99
	v_fmac_f32_e32 v98, 0xcf800000, v99
	v_cvt_u32_f32_e32 v98, v98
	v_cvt_u32_f32_e32 v99, v99
	v_lshl_add_u64 v[100:101], v[136:137], 3, s[10:11]
	global_atomic_add_x2 v[100:101], v[98:99], off
.LBB0_631:
	s_or_b64 exec, exec, s[26:27]
	v_lshlrev_b64 v[98:99], 10, v[134:135]
	v_lshl_add_u64 v[98:99], v[98:99], 0, v[172:173]
	s_waitcnt vmcnt(11)
	v_add_f32_e32 v96, v96, v128
	v_add_f32_e32 v97, v97, v129
	v_add_f32_e32 v94, v94, v126
	v_add_f32_e32 v95, v95, v127
	v_lshl_add_u64 v[100:101], v[98:99], 2, s[12:13]
	v_mul_f32_e32 v102, v95, v95
	v_mul_f32_e32 v103, v97, v97
	global_store_dwordx4 v[100:101], v[94:97], off
	v_fmac_f32_e32 v102, v94, v94
	v_fmac_f32_e32 v103, v96, v96
	v_mul_f32_e32 v96, v64, v96
	v_mul_f32_e32 v97, v65, v97
	v_mul_f32_e32 v94, v62, v94
	v_mul_f32_e32 v95, v63, v95
	s_waitcnt vmcnt(11)
	v_add_f32_e32 v90, v90, v122
	v_add_f32_e32 v91, v91, v123
	v_cvt_pk_bf16_f32 v94, v94, v95
	v_cvt_pk_bf16_f32 v95, v96, v97
	v_lshl_add_u64 v[96:97], v[98:99], 1, s[22:23]
	global_store_dwordx2 v[96:97], v[94:95], off
	v_add_f32_e32 v92, v92, v124
	v_add_f32_e32 v93, v93, v125
	v_mul_f32_e32 v94, v91, v91
	global_store_dwordx4 v[100:101], v[90:93], off offset:64
	v_fmac_f32_e32 v94, v90, v90
	v_mul_f32_e32 v95, v93, v93
	v_mul_f32_e32 v90, v58, v90
	v_mul_f32_e32 v91, v59, v91
	s_waitcnt vmcnt(12)
	v_add_f32_e32 v86, v86, v118
	v_add_f32_e32 v87, v87, v119
	v_cvt_pk_bf16_f32 v90, v90, v91
	v_fmac_f32_e32 v95, v92, v92
	v_mul_f32_e32 v92, v60, v92
	v_mul_f32_e32 v93, v61, v93
	v_add_f32_e32 v88, v88, v120
	v_add_f32_e32 v89, v89, v121
	v_cvt_pk_bf16_f32 v91, v92, v93
	global_store_dwordx2 v[96:97], v[90:91], off offset:32
	v_mul_f32_e32 v90, v87, v87
	global_store_dwordx4 v[100:101], v[86:89], off offset:512
	v_fmac_f32_e32 v90, v86, v86
	v_mul_f32_e32 v91, v89, v89
	v_mul_f32_e32 v86, v54, v86
	v_mul_f32_e32 v87, v55, v87
	v_fmac_f32_e32 v91, v88, v88
	v_mul_f32_e32 v88, v56, v88
	v_mul_f32_e32 v89, v57, v89
	v_cvt_pk_bf16_f32 v86, v86, v87
	s_waitcnt vmcnt(13)
	v_add_f32_e32 v84, v84, v116
	v_add_f32_e32 v85, v85, v117
	v_cvt_pk_bf16_f32 v87, v88, v89
	v_add_f32_e32 v82, v82, v114
	v_add_f32_e32 v83, v83, v115
	v_add_f32_e32 v102, v102, v103
	v_add_f32_e32 v94, v94, v95
	global_store_dwordx2 v[96:97], v[86:87], off offset:256
	global_store_dwordx4 v[100:101], v[82:85], off offset:576
	v_mul_f32_e32 v86, v48, v84
	v_mul_f32_e32 v87, v49, v85
	v_mul_f32_e32 v88, v83, v83
	v_mul_f32_e32 v85, v85, v85
	v_add_f32_e32 v94, v102, v94
	v_add_f32_e32 v90, v90, v91
	v_fmac_f32_e32 v88, v82, v82
	v_fmac_f32_e32 v85, v84, v84
	v_add_f32_e32 v90, v94, v90
	v_add_f32_e32 v84, v88, v85
	v_add_f32_e32 v84, v90, v84
	ds_swizzle_b32 v85, v84 offset:swizzle(SWAP,16)
	v_mul_f32_e32 v82, v46, v82
	v_mul_f32_e32 v83, v47, v83
	s_nop 0
	v_cvt_pk_bf16_f32 v82, v82, v83
	v_cvt_pk_bf16_f32 v83, v86, v87
	global_store_dwordx2 v[96:97], v[82:83], off offset:288
	s_waitcnt lgkmcnt(0)
	v_add_f32_e32 v82, v84, v85
	v_mov_b32_e32 v83, v82
	s_nop 1
	v_permlane32_swap_b32_e32 v82, v83
	s_and_saveexec_b64 s[26:27], vcc
	s_cbranch_execz .LBB0_633
	v_add_f32_e32 v82, v82, v83
	s_mov_b32 s28, 0x49800000
	v_fma_f32 v82, v82, s28, 0.5
	v_trunc_f32_e32 v82, v82
	v_mul_f32_e32 v83, 0x2f800000, v82
	v_floor_f32_e32 v83, v83
	v_fmac_f32_e32 v82, 0xcf800000, v83
	v_cvt_u32_f32_e32 v82, v82
	v_cvt_u32_f32_e32 v83, v83
	v_lshl_add_u64 v[84:85], v[134:135], 3, s[10:11]
	global_atomic_add_x2 v[84:85], v[82:83], off
; #define GAS __attribute__((address_space(1)))
; __device__ __forceinline__ unsigned cvt_pk_bf16(float lo, float hi) { unsigned r; asm("v_cvt_pk_bf16_f32 %0, %1, %2" : "=v"(r) : "v"(lo), "v"(hi)); return r; }
; template <int M> __device__ __forceinline__ float swz_xor(float v) { return __int_as_float(__builtin_amdgcn_ds_swizzle(__float_as_int(v), 0x1f | (M << 10))); }
; __device__ __forceinline__ float sum_x32(float v) { auto rr = __builtin_amdgcn_permlane32_swap(__float_as_uint(v), __float_as_uint(v), false, false); return __uint_as_float(rr[0]) + __uint_as_float(rr[1]); }
;     __device__ __forceinline__ void operator()(const f32x4 (&acc)[2][2][4][2], const Unit& u, int wr, int wc, int fr, int fq) const {
;     ...
;         for (int ai = 0; ai < 2; ++ai)
; #pragma unroll
;             for (int mh = 0; mh < 2; ++mh) {
;                 f32x4 bsv[2][2][2];
; #pragma unroll
;                 for (int mm = 0; mm < 2; ++mm) { const size_t off = (size_t)(row0 + ai * HALF + (2 * mh + mm) * 16) * ldc + col0;
; #pragma unroll
;                     for (int bj = 0; bj < 2; ++bj)
; #pragma unroll
;                         for (int n = 0; n < 2; ++n) bsv[mm][bj][n] = *(const GAS f32x4*)(base + off + bj * HALF + n * 16); }
; #pragma unroll
;                 for (int mm = 0; mm < 2; ++mm) { const int m = 2 * mh + mm, row = row0 + ai * HALF + m * 16; const size_t off = (size_t)row * ldc + col0; float sq = 0.f;
; #pragma unroll
;                     for (int bj = 0; bj < 2; ++bj)
; #pragma unroll
;                         for (int n = 0; n < 2; ++n) { const f32x4 v = bsv[mm][bj][n] + acc[ai][bj][m][n]; *(GAS f32x4*)(out + off + bj * HALF + n * 16) = v;
;                             if (do_norm) { sq += (v[0] * v[0] + v[1] * v[1]) + (v[2] * v[2] + v[3] * v[3]); const f32x4 w = v * gv[bj][n];
;                                 u32x2 pk; pk.x = cvt_pk_bf16(w[0], w[1]); pk.y = cvt_pk_bf16(w[2], w[3]); *(GAS u32x2*)(xb + off + bj * HALF + n * 16) = pk; } }
;                     if (do_norm) { sq += swz_xor<16>(sq); sq = sum_x32(sq); if (fq == 0) (void)__hip_atomic_fetch_add(ssq + row, (unsigned long long)(sq * 1048576.f + 0.5f), __ATOMIC_RELAXED, __HIP_MEMORY_SCOPE_AGENT); } }
.LBB0_633:
	s_or_b64 exec, exec, s[26:27]
	v_add_u32_e32 v104, 0x80, v174
	v_ashrrev_i32_e32 v105, 31, v104
	v_lshlrev_b64 v[82:83], 12, v[104:105]
	v_lshl_add_u64 v[82:83], v[176:177], 0, v[82:83]
	global_load_dwordx4 v[106:109], v[82:83], off
	global_load_dwordx4 v[110:113], v[82:83], off offset:64
	global_load_dwordx4 v[114:117], v[82:83], off offset:512
	global_load_dwordx4 v[98:101], v[82:83], off offset:576
	v_add_u32_e32 v102, 0x90, v174
	v_ashrrev_i32_e32 v103, 31, v102
	v_lshlrev_b64 v[82:83], 12, v[102:103]
	v_lshl_add_u64 v[82:83], v[176:177], 0, v[82:83]
	global_load_dwordx4 v[94:97], v[82:83], off
	global_load_dwordx4 v[90:93], v[82:83], off offset:64
	global_load_dwordx4 v[86:89], v[82:83], off offset:512
	s_nop 0
	global_load_dwordx4 v[82:85], v[82:83], off offset:576
	v_lshlrev_b64 v[118:119], 10, v[104:105]
	v_lshl_add_u64 v[118:119], v[118:119], 0, v[172:173]
	s_waitcnt vmcnt(7)
	v_add_f32_e32 v80, v80, v108
	v_add_f32_e32 v81, v81, v109
	v_add_f32_e32 v78, v78, v106
	v_add_f32_e32 v79, v79, v107
	v_lshl_add_u64 v[106:107], v[118:119], 2, s[12:13]
	v_mul_f32_e32 v108, v79, v79
	v_mul_f32_e32 v109, v81, v81
	global_store_dwordx4 v[106:107], v[78:81], off
	v_fmac_f32_e32 v108, v78, v78
	v_fmac_f32_e32 v109, v80, v80
	v_mul_f32_e32 v80, v64, v80
	v_mul_f32_e32 v81, v65, v81
	v_mul_f32_e32 v78, v62, v78
	v_mul_f32_e32 v79, v63, v79
	s_waitcnt vmcnt(7)
	v_add_f32_e32 v74, v74, v110
	v_add_f32_e32 v75, v75, v111
	v_cvt_pk_bf16_f32 v78, v78, v79
	v_cvt_pk_bf16_f32 v79, v80, v81
	v_lshl_add_u64 v[80:81], v[118:119], 1, s[22:23]
	global_store_dwordx2 v[80:81], v[78:79], off
	v_add_f32_e32 v76, v76, v112
	v_add_f32_e32 v77, v77, v113
	v_mul_f32_e32 v78, v75, v75
	global_store_dwordx4 v[106:107], v[74:77], off offset:64
	v_fmac_f32_e32 v78, v74, v74
	v_mul_f32_e32 v79, v77, v77
	v_mul_f32_e32 v74, v58, v74
	v_mul_f32_e32 v75, v59, v75
	v_fmac_f32_e32 v79, v76, v76
	v_mul_f32_e32 v76, v60, v76
	v_mul_f32_e32 v77, v61, v77
	v_cvt_pk_bf16_f32 v74, v74, v75
	s_waitcnt vmcnt(8)
	v_add_f32_e32 v72, v72, v116
	v_add_f32_e32 v73, v73, v117
	v_cvt_pk_bf16_f32 v75, v76, v77
	v_add_f32_e32 v70, v70, v114
	v_add_f32_e32 v71, v71, v115
	global_store_dwordx2 v[80:81], v[74:75], off offset:32
	v_mul_f32_e32 v74, v71, v71
	v_mul_f32_e32 v75, v73, v73
	global_store_dwordx4 v[106:107], v[70:73], off offset:512
	v_fmac_f32_e32 v74, v70, v70
	v_fmac_f32_e32 v75, v72, v72
	v_mul_f32_e32 v72, v56, v72
	v_mul_f32_e32 v73, v57, v73
	v_mul_f32_e32 v70, v54, v70
	v_mul_f32_e32 v71, v55, v71
	s_waitcnt vmcnt(9)
	v_add_f32_e32 v68, v68, v100
	v_add_f32_e32 v69, v69, v101
	v_add_f32_e32 v66, v66, v98
	v_add_f32_e32 v67, v67, v99
	v_cvt_pk_bf16_f32 v70, v70, v71
	v_cvt_pk_bf16_f32 v71, v72, v73
	global_store_dwordx2 v[80:81], v[70:71], off offset:256
	global_store_dwordx4 v[106:107], v[66:69], off offset:576
	v_mul_f32_e32 v72, v46, v66
	v_mul_f32_e32 v73, v47, v67
	v_add_f32_e32 v108, v108, v109
	v_mul_f32_e32 v67, v67, v67
	v_add_f32_e32 v78, v78, v79
	v_fmac_f32_e32 v67, v66, v66
	v_mul_f32_e32 v66, v69, v69
	v_add_f32_e32 v78, v108, v78
	v_add_f32_e32 v74, v74, v75
	v_fmac_f32_e32 v66, v68, v68
	v_add_f32_e32 v74, v78, v74
	v_add_f32_e32 v66, v67, v66
	v_add_f32_e32 v66, v74, v66
	ds_swizzle_b32 v67, v66 offset:swizzle(SWAP,16)
	v_mul_f32_e32 v70, v48, v68
	v_mul_f32_e32 v71, v49, v69
	v_cvt_pk_bf16_f32 v72, v72, v73
	s_waitcnt lgkmcnt(0)
	v_add_f32_e32 v66, v66, v67
	v_mov_b32_e32 v67, v66
	s_nop 1
	v_permlane32_swap_b32_e32 v66, v67
	v_cvt_pk_bf16_f32 v73, v70, v71
	global_store_dwordx2 v[80:81], v[72:73], off offset:288
	s_and_saveexec_b64 s[26:27], vcc
	s_cbranch_execz .LBB0_635
	v_add_f32_e32 v66, v66, v67
	s_mov_b32 s28, 0x49800000
	v_fma_f32 v66, v66, s28, 0.5
	v_trunc_f32_e32 v66, v66
	v_mul_f32_e32 v67, 0x2f800000, v66
	v_floor_f32_e32 v67, v67
	v_fmac_f32_e32 v66, 0xcf800000, v67
	v_cvt_u32_f32_e32 v66, v66
	v_cvt_u32_f32_e32 v67, v67
	v_lshl_add_u64 v[68:69], v[104:105], 3, s[10:11]
	global_atomic_add_x2 v[68:69], v[66:67], off
.LBB0_635:
	s_or_b64 exec, exec, s[26:27]
	v_lshlrev_b64 v[66:67], 10, v[102:103]
	v_lshl_add_u64 v[66:67], v[66:67], 0, v[172:173]
	s_waitcnt vmcnt(11)
	v_add_f32_e32 v52, v52, v96
	v_add_f32_e32 v53, v53, v97
	v_add_f32_e32 v50, v50, v94
	v_add_f32_e32 v51, v51, v95
	v_lshl_add_u64 v[68:69], v[66:67], 2, s[12:13]
	v_mul_f32_e32 v70, v51, v51
	v_mul_f32_e32 v71, v53, v53
	global_store_dwordx4 v[68:69], v[50:53], off
	v_fmac_f32_e32 v70, v50, v50
	v_fmac_f32_e32 v71, v52, v52
	v_mul_f32_e32 v52, v64, v52
	v_mul_f32_e32 v53, v65, v53
	v_mul_f32_e32 v50, v62, v50
	v_mul_f32_e32 v51, v63, v51
	s_waitcnt vmcnt(11)
	v_add_f32_e32 v42, v42, v90
	v_add_f32_e32 v43, v43, v91
	v_cvt_pk_bf16_f32 v50, v50, v51
	v_cvt_pk_bf16_f32 v51, v52, v53
	v_lshl_add_u64 v[52:53], v[66:67], 1, s[22:23]
	global_store_dwordx2 v[52:53], v[50:51], off
	v_add_f32_e32 v44, v44, v92
	v_add_f32_e32 v45, v45, v93
	v_mul_f32_e32 v50, v43, v43
	global_store_dwordx4 v[68:69], v[42:45], off offset:64
	v_fmac_f32_e32 v50, v42, v42
	v_mul_f32_e32 v51, v45, v45
	v_mul_f32_e32 v42, v58, v42
	v_mul_f32_e32 v43, v59, v43
	s_waitcnt vmcnt(12)
	v_add_f32_e32 v38, v38, v86
	v_add_f32_e32 v39, v39, v87
	v_cvt_pk_bf16_f32 v42, v42, v43
	v_fmac_f32_e32 v51, v44, v44
	v_mul_f32_e32 v44, v60, v44
	v_mul_f32_e32 v45, v61, v45
	v_add_f32_e32 v40, v40, v88
	v_add_f32_e32 v41, v41, v89
	v_cvt_pk_bf16_f32 v43, v44, v45
	global_store_dwordx2 v[52:53], v[42:43], off offset:32
	v_mul_f32_e32 v42, v39, v39
	global_store_dwordx4 v[68:69], v[38:41], off offset:512
	v_fmac_f32_e32 v42, v38, v38
	v_mul_f32_e32 v43, v41, v41
	v_mul_f32_e32 v38, v54, v38
	v_mul_f32_e32 v39, v55, v39
	v_fmac_f32_e32 v43, v40, v40
	v_mul_f32_e32 v40, v56, v40
	v_mul_f32_e32 v41, v57, v41
	v_cvt_pk_bf16_f32 v38, v38, v39
	s_waitcnt vmcnt(13)
	v_add_f32_e32 v36, v36, v84
	v_add_f32_e32 v37, v37, v85
	v_cvt_pk_bf16_f32 v39, v40, v41
	v_add_f32_e32 v34, v34, v82
	v_add_f32_e32 v35, v35, v83
	v_add_f32_e32 v70, v70, v71
	v_add_f32_e32 v50, v50, v51
	global_store_dwordx2 v[52:53], v[38:39], off offset:256
	global_store_dwordx4 v[68:69], v[34:37], off offset:576
	v_mul_f32_e32 v38, v48, v36
	v_mul_f32_e32 v39, v49, v37
	v_mul_f32_e32 v40, v35, v35
	v_mul_f32_e32 v37, v37, v37
	v_add_f32_e32 v50, v70, v50
	v_add_f32_e32 v42, v42, v43
	v_fmac_f32_e32 v40, v34, v34
	v_fmac_f32_e32 v37, v36, v36
	v_add_f32_e32 v42, v50, v42
	v_add_f32_e32 v36, v40, v37
	v_add_f32_e32 v36, v42, v36
	ds_swizzle_b32 v37, v36 offset:swizzle(SWAP,16)
	v_mul_f32_e32 v34, v46, v34
	v_mul_f32_e32 v35, v47, v35
	s_nop 0
	v_cvt_pk_bf16_f32 v34, v34, v35
	v_cvt_pk_bf16_f32 v35, v38, v39
	global_store_dwordx2 v[52:53], v[34:35], off offset:288
	s_waitcnt lgkmcnt(0)
	v_add_f32_e32 v34, v36, v37
	v_mov_b32_e32 v35, v34
	s_nop 1
	v_permlane32_swap_b32_e32 v34, v35
	s_and_saveexec_b64 s[26:27], vcc
	s_cbranch_execz .LBB0_637
; #define GAS __attribute__((address_space(1)))
; __device__ __forceinline__ unsigned cvt_pk_bf16(float lo, float hi) { unsigned r; asm("v_cvt_pk_bf16_f32 %0, %1, %2" : "=v"(r) : "v"(lo), "v"(hi)); return r; }
; template <int M> __device__ __forceinline__ float swz_xor(float v) { return __int_as_float(__builtin_amdgcn_ds_swizzle(__float_as_int(v), 0x1f | (M << 10))); }
; __device__ __forceinline__ float sum_x32(float v) { auto rr = __builtin_amdgcn_permlane32_swap(__float_as_uint(v), __float_as_uint(v), false, false); return __uint_as_float(rr[0]) + __uint_as_float(rr[1]); }
;     __device__ __forceinline__ void operator()(const f32x4 (&acc)[2][2][4][2], const Unit& u, int wr, int wc, int fr, int fq) const {
;     ...
;         for (int ai = 0; ai < 2; ++ai)
; #pragma unroll
;             for (int mh = 0; mh < 2; ++mh) {
;                 f32x4 bsv[2][2][2];
; #pragma unroll
;                 for (int mm = 0; mm < 2; ++mm) { const size_t off = (size_t)(row0 + ai * HALF + (2 * mh + mm) * 16) * ldc + col0;
; #pragma unroll
;                     for (int bj = 0; bj < 2; ++bj)
; #pragma unroll
;                         for (int n = 0; n < 2; ++n) bsv[mm][bj][n] = *(const GAS f32x4*)(base + off + bj * HALF + n * 16); }
; #pragma unroll
;                 for (int mm = 0; mm < 2; ++mm) { const int m = 2 * mh + mm, row = row0 + ai * HALF + m * 16; const size_t off = (size_t)row * ldc + col0; float sq = 0.f;
; #pragma unroll
;                     for (int bj = 0; bj < 2; ++bj)
; #pragma unroll
;                         for (int n = 0; n < 2; ++n) { const f32x4 v = bsv[mm][bj][n] + acc[ai][bj][m][n]; *(GAS f32x4*)(out + off + bj * HALF + n * 16) = v;
;                             if (do_norm) { sq += (v[0] * v[0] + v[1] * v[1]) + (v[2] * v[2] + v[3] * v[3]); const f32x4 w = v * gv[bj][n];
;                                 u32x2 pk; pk.x = cvt_pk_bf16(w[0], w[1]); pk.y = cvt_pk_bf16(w[2], w[3]); *(GAS u32x2*)(xb + off + bj * HALF + n * 16) = pk; } }
;                     if (do_norm) { sq += swz_xor<16>(sq); sq = sum_x32(sq); if (fq == 0) (void)__hip_atomic_fetch_add(ssq + row, (unsigned long long)(sq * 1048576.f + 0.5f), __ATOMIC_RELAXED, __HIP_MEMORY_SCOPE_AGENT); } }
	v_add_f32_e32 v34, v34, v35
	s_mov_b32 s28, 0x49800000
	v_fma_f32 v34, v34, s28, 0.5
	v_trunc_f32_e32 v34, v34
	v_mul_f32_e32 v35, 0x2f800000, v34
	v_floor_f32_e32 v35, v35
	v_fmac_f32_e32 v34, 0xcf800000, v35
	v_cvt_u32_f32_e32 v34, v34
	v_cvt_u32_f32_e32 v35, v35
	v_lshl_add_u64 v[36:37], v[102:103], 3, s[10:11]
	global_atomic_add_x2 v[36:37], v[34:35], off
.LBB0_637:
	s_or_b64 exec, exec, s[26:27]
	v_add_u32_e32 v72, 0xa0, v174
	v_ashrrev_i32_e32 v73, 31, v72
	v_lshlrev_b64 v[34:35], 12, v[72:73]
	v_lshl_add_u64 v[34:35], v[176:177], 0, v[34:35]
	global_load_dwordx4 v[74:77], v[34:35], off
	global_load_dwordx4 v[78:81], v[34:35], off offset:64
	global_load_dwordx4 v[82:85], v[34:35], off offset:512
	global_load_dwordx4 v[66:69], v[34:35], off offset:576
	v_add_u32_e32 v70, 0xb0, v174
	v_ashrrev_i32_e32 v71, 31, v70
	v_lshlrev_b64 v[34:35], 12, v[70:71]
	v_lshl_add_u64 v[34:35], v[176:177], 0, v[34:35]
	global_load_dwordx4 v[50:53], v[34:35], off
	global_load_dwordx4 v[42:45], v[34:35], off offset:64
	global_load_dwordx4 v[38:41], v[34:35], off offset:512
	s_nop 0
	global_load_dwordx4 v[34:37], v[34:35], off offset:576
	v_lshlrev_b64 v[86:87], 10, v[72:73]
	v_lshl_add_u64 v[86:87], v[86:87], 0, v[172:173]
	s_waitcnt vmcnt(7)
	v_add_f32_e32 v32, v32, v76
	v_add_f32_e32 v33, v33, v77
	v_add_f32_e32 v30, v30, v74
	v_add_f32_e32 v31, v31, v75
	v_lshl_add_u64 v[74:75], v[86:87], 2, s[12:13]
	v_mul_f32_e32 v76, v31, v31
	v_mul_f32_e32 v77, v33, v33
	global_store_dwordx4 v[74:75], v[30:33], off
	v_fmac_f32_e32 v76, v30, v30
	v_fmac_f32_e32 v77, v32, v32
	v_mul_f32_e32 v32, v64, v32
	v_mul_f32_e32 v33, v65, v33
	v_mul_f32_e32 v30, v62, v30
	v_mul_f32_e32 v31, v63, v31
	s_waitcnt vmcnt(7)
	v_add_f32_e32 v26, v26, v78
	v_add_f32_e32 v27, v27, v79
	v_cvt_pk_bf16_f32 v30, v30, v31
	v_cvt_pk_bf16_f32 v31, v32, v33
	v_lshl_add_u64 v[32:33], v[86:87], 1, s[22:23]
	global_store_dwordx2 v[32:33], v[30:31], off
	v_add_f32_e32 v28, v28, v80
	v_add_f32_e32 v29, v29, v81
	v_mul_f32_e32 v30, v27, v27
	global_store_dwordx4 v[74:75], v[26:29], off offset:64
	v_fmac_f32_e32 v30, v26, v26
	v_mul_f32_e32 v31, v29, v29
	v_mul_f32_e32 v26, v58, v26
	v_mul_f32_e32 v27, v59, v27
	v_fmac_f32_e32 v31, v28, v28
	v_mul_f32_e32 v28, v60, v28
	v_mul_f32_e32 v29, v61, v29
	v_cvt_pk_bf16_f32 v26, v26, v27
	s_waitcnt vmcnt(8)
	v_add_f32_e32 v24, v24, v84
	v_add_f32_e32 v25, v25, v85
	v_cvt_pk_bf16_f32 v27, v28, v29
	v_add_f32_e32 v22, v22, v82
	v_add_f32_e32 v23, v23, v83
	global_store_dwordx2 v[32:33], v[26:27], off offset:32
	v_mul_f32_e32 v26, v23, v23
	v_mul_f32_e32 v27, v25, v25
	global_store_dwordx4 v[74:75], v[22:25], off offset:512
	v_fmac_f32_e32 v26, v22, v22
	v_fmac_f32_e32 v27, v24, v24
	v_mul_f32_e32 v24, v56, v24
	v_mul_f32_e32 v25, v57, v25
	v_mul_f32_e32 v22, v54, v22
	v_mul_f32_e32 v23, v55, v23
	s_waitcnt vmcnt(9)
	v_add_f32_e32 v20, v20, v68
	v_add_f32_e32 v21, v21, v69
	v_add_f32_e32 v18, v18, v66
	v_add_f32_e32 v19, v19, v67
	v_cvt_pk_bf16_f32 v22, v22, v23
	v_cvt_pk_bf16_f32 v23, v24, v25
	global_store_dwordx2 v[32:33], v[22:23], off offset:256
	global_store_dwordx4 v[74:75], v[18:21], off offset:576
	v_mul_f32_e32 v24, v46, v18
	v_mul_f32_e32 v25, v47, v19
	v_add_f32_e32 v76, v76, v77
	v_mul_f32_e32 v19, v19, v19
	v_add_f32_e32 v30, v30, v31
	v_fmac_f32_e32 v19, v18, v18
	v_mul_f32_e32 v18, v21, v21
	v_add_f32_e32 v30, v76, v30
	v_add_f32_e32 v26, v26, v27
	v_fmac_f32_e32 v18, v20, v20
	v_add_f32_e32 v26, v30, v26
	v_add_f32_e32 v18, v19, v18
	v_add_f32_e32 v18, v26, v18
	ds_swizzle_b32 v19, v18 offset:swizzle(SWAP,16)
	v_mul_f32_e32 v22, v48, v20
	v_mul_f32_e32 v23, v49, v21
	v_cvt_pk_bf16_f32 v24, v24, v25
	s_waitcnt lgkmcnt(0)
	v_add_f32_e32 v18, v18, v19
	v_mov_b32_e32 v19, v18
	s_nop 1
	v_permlane32_swap_b32_e32 v18, v19
	v_cvt_pk_bf16_f32 v25, v22, v23
	global_store_dwordx2 v[32:33], v[24:25], off offset:288
	s_and_saveexec_b64 s[26:27], vcc
	s_cbranch_execz .LBB0_639
	v_add_f32_e32 v18, v18, v19
	s_mov_b32 s28, 0x49800000
	v_fma_f32 v18, v18, s28, 0.5
	v_trunc_f32_e32 v18, v18
	v_mul_f32_e32 v19, 0x2f800000, v18
	v_floor_f32_e32 v19, v19
	v_fmac_f32_e32 v18, 0xcf800000, v19
	v_cvt_u32_f32_e32 v18, v18
	v_cvt_u32_f32_e32 v19, v19
	v_lshl_add_u64 v[20:21], v[72:73], 3, s[10:11]
	global_atomic_add_x2 v[20:21], v[18:19], off
; #define GAS __attribute__((address_space(1)))
; __device__ __forceinline__ unsigned cvt_pk_bf16(float lo, float hi) { unsigned r; asm("v_cvt_pk_bf16_f32 %0, %1, %2" : "=v"(r) : "v"(lo), "v"(hi)); return r; }
; template <int M> __device__ __forceinline__ float swz_xor(float v) { return __int_as_float(__builtin_amdgcn_ds_swizzle(__float_as_int(v), 0x1f | (M << 10))); }
; __device__ __forceinline__ float sum_x32(float v) { auto rr = __builtin_amdgcn_permlane32_swap(__float_as_uint(v), __float_as_uint(v), false, false); return __uint_as_float(rr[0]) + __uint_as_float(rr[1]); }
;     __device__ __forceinline__ void operator()(const f32x4 (&acc)[2][2][4][2], const Unit& u, int wr, int wc, int fr, int fq) const {
;     ...
;         for (int ai = 0; ai < 2; ++ai)
; #pragma unroll
;             for (int mh = 0; mh < 2; ++mh) {
;                 f32x4 bsv[2][2][2];
; #pragma unroll
;                 for (int mm = 0; mm < 2; ++mm) { const size_t off = (size_t)(row0 + ai * HALF + (2 * mh + mm) * 16) * ldc + col0;
; #pragma unroll
;                     for (int bj = 0; bj < 2; ++bj)
; #pragma unroll
;                         for (int n = 0; n < 2; ++n) bsv[mm][bj][n] = *(const GAS f32x4*)(base + off + bj * HALF + n * 16); }
; #pragma unroll
;                 for (int mm = 0; mm < 2; ++mm) { const int m = 2 * mh + mm, row = row0 + ai * HALF + m * 16; const size_t off = (size_t)row * ldc + col0; float sq = 0.f;
; #pragma unroll
;                     for (int bj = 0; bj < 2; ++bj)
; #pragma unroll
;                         for (int n = 0; n < 2; ++n) { const f32x4 v = bsv[mm][bj][n] + acc[ai][bj][m][n]; *(GAS f32x4*)(out + off + bj * HALF + n * 16) = v;
;                             if (do_norm) { sq += (v[0] * v[0] + v[1] * v[1]) + (v[2] * v[2] + v[3] * v[3]); const f32x4 w = v * gv[bj][n];
;                                 u32x2 pk; pk.x = cvt_pk_bf16(w[0], w[1]); pk.y = cvt_pk_bf16(w[2], w[3]); *(GAS u32x2*)(xb + off + bj * HALF + n * 16) = pk; } }
;                     if (do_norm) { sq += swz_xor<16>(sq); sq = sum_x32(sq); if (fq == 0) (void)__hip_atomic_fetch_add(ssq + row, (unsigned long long)(sq * 1048576.f + 0.5f), __ATOMIC_RELAXED, __HIP_MEMORY_SCOPE_AGENT); } }
.LBB0_639:
	s_or_b64 exec, exec, s[26:27]
	v_lshlrev_b64 v[18:19], 10, v[70:71]
	v_lshl_add_u64 v[18:19], v[18:19], 0, v[172:173]
	s_waitcnt vmcnt(11)
	v_add_f32_e32 v16, v16, v52
	v_add_f32_e32 v17, v17, v53
	v_add_f32_e32 v14, v14, v50
	v_add_f32_e32 v15, v15, v51
	v_lshl_add_u64 v[20:21], v[18:19], 2, s[12:13]
	v_mul_f32_e32 v22, v15, v15
	v_mul_f32_e32 v23, v17, v17
	global_store_dwordx4 v[20:21], v[14:17], off
	v_fmac_f32_e32 v22, v14, v14
	v_fmac_f32_e32 v23, v16, v16
	v_mul_f32_e32 v16, v64, v16
	v_mul_f32_e32 v17, v65, v17
	v_mul_f32_e32 v14, v62, v14
	v_mul_f32_e32 v15, v63, v15
	s_waitcnt vmcnt(11)
	v_add_f32_e32 v10, v10, v42
	v_add_f32_e32 v11, v11, v43
	v_cvt_pk_bf16_f32 v14, v14, v15
	v_cvt_pk_bf16_f32 v15, v16, v17
	v_lshl_add_u64 v[16:17], v[18:19], 1, s[22:23]
	global_store_dwordx2 v[16:17], v[14:15], off
	v_add_f32_e32 v12, v12, v44
	v_add_f32_e32 v13, v13, v45
	v_mul_f32_e32 v14, v11, v11
	global_store_dwordx4 v[20:21], v[10:13], off offset:64
	v_fmac_f32_e32 v14, v10, v10
	v_mul_f32_e32 v15, v13, v13
	v_mul_f32_e32 v10, v58, v10
	v_mul_f32_e32 v11, v59, v11
	s_waitcnt vmcnt(12)
	v_add_f32_e32 v6, v6, v38
	v_add_f32_e32 v7, v7, v39
	v_cvt_pk_bf16_f32 v10, v10, v11
	v_fmac_f32_e32 v15, v12, v12
	v_mul_f32_e32 v12, v60, v12
	v_mul_f32_e32 v13, v61, v13
	v_add_f32_e32 v8, v8, v40
	v_add_f32_e32 v9, v9, v41
	v_cvt_pk_bf16_f32 v11, v12, v13
	global_store_dwordx2 v[16:17], v[10:11], off offset:32
	v_mul_f32_e32 v10, v7, v7
	global_store_dwordx4 v[20:21], v[6:9], off offset:512
	v_fmac_f32_e32 v10, v6, v6
	v_mul_f32_e32 v11, v9, v9
	v_mul_f32_e32 v6, v54, v6
	v_mul_f32_e32 v7, v55, v7
	v_fmac_f32_e32 v11, v8, v8
	v_mul_f32_e32 v8, v56, v8
	v_mul_f32_e32 v9, v57, v9
	v_cvt_pk_bf16_f32 v6, v6, v7
	s_waitcnt vmcnt(13)
	v_add_f32_e32 v4, v4, v36
	v_add_f32_e32 v5, v5, v37
	v_cvt_pk_bf16_f32 v7, v8, v9
	v_add_f32_e32 v2, v2, v34
	v_add_f32_e32 v3, v3, v35
	v_add_f32_e32 v22, v22, v23
	v_add_f32_e32 v14, v14, v15
	global_store_dwordx2 v[16:17], v[6:7], off offset:256
	global_store_dwordx4 v[20:21], v[2:5], off offset:576
	v_mul_f32_e32 v6, v48, v4
	v_mul_f32_e32 v7, v49, v5
	v_mul_f32_e32 v8, v3, v3
	v_mul_f32_e32 v5, v5, v5
	v_add_f32_e32 v14, v22, v14
	v_add_f32_e32 v10, v10, v11
	v_fmac_f32_e32 v8, v2, v2
	v_fmac_f32_e32 v5, v4, v4
	v_add_f32_e32 v10, v14, v10
	v_add_f32_e32 v4, v8, v5
	v_add_f32_e32 v4, v10, v4
	ds_swizzle_b32 v5, v4 offset:swizzle(SWAP,16)
	v_mul_f32_e32 v2, v46, v2
	v_mul_f32_e32 v3, v47, v3
	s_nop 0
	v_cvt_pk_bf16_f32 v2, v2, v3
	v_cvt_pk_bf16_f32 v3, v6, v7
	global_store_dwordx2 v[16:17], v[2:3], off offset:288
	s_waitcnt lgkmcnt(0)
	v_add_f32_e32 v2, v4, v5
	v_mov_b32_e32 v3, v2
	s_nop 1
	v_permlane32_swap_b32_e32 v2, v3
	s_and_saveexec_b64 s[26:27], vcc
	s_cbranch_execz .LBB0_641
	v_add_f32_e32 v2, v2, v3
	s_mov_b32 s28, 0x49800000
	v_fma_f32 v2, v2, s28, 0.5
	v_trunc_f32_e32 v2, v2
	v_mul_f32_e32 v3, 0x2f800000, v2
	v_floor_f32_e32 v3, v3
	v_fmac_f32_e32 v2, 0xcf800000, v3
	v_cvt_u32_f32_e32 v2, v2
	v_cvt_u32_f32_e32 v3, v3
	v_lshl_add_u64 v[4:5], v[70:71], 3, s[10:11]
	global_atomic_add_x2 v[4:5], v[2:3], off

; #define GAS __attribute__((address_space(1)))
; __device__ __forceinline__ unsigned cvt_pk_bf16(float lo, float hi) { unsigned r; asm("v_cvt_pk_bf16_f32 %0, %1, %2" : "=v"(r) : "v"(lo), "v"(hi)); return r; }
; template <int CTRL> __device__ __forceinline__ float dpp_mov(float v) { return __int_as_float(__builtin_amdgcn_update_dpp(0, __float_as_int(v), CTRL, 0xf, 0xf, false)); }
;     __device__ __forceinline__ void operator()(const f32x4 (&acc)[2][2][4][2], const Unit& u, int wr, int wc, int fr, int fq) const {
;     ...
;                 for (int k = 0; k < 8; ++k) {
;                     const float am = acc[ai][0][m][k >> 2][k & 3] * rs[ai][m];
;                     float sp, sn;
;                     if (m > 0) sp = fr == 15 ? acc[ai][0][m - 1][k >> 2][k & 3] * rs[ai][m - 1] : am; else sp = am;
;                     if (m < 3) sn = fr == 0 ? acc[ai][0][m + 1][k >> 2][k & 3] * rs[ai][m + 1] : am; else sn = am;
;                     float pv = dpp_mov<0x121>(sp), nv = dpp_mov<0x12F>(sn);
;                     if (m == 0) { const float e = chunk > 0 ? xch[((chunk - 1) * 2 + 1) * 128 + colh + k] : 0.f; pv = fr == 0 ? e : pv; }
;                     if (m == 3) { const float e = chunk < 3 ? xch[((chunk + 1) * 2 + 0) * 128 + colh + k] : 0.f; nv = fr == 15 ? e : nv; }
;                     pv = pos == 0 ? 0.f : pv; nv = pos == S - 1 ? 0.f : nv;
;                     const float c = pv * w0[k] + am * w1[k] + nv * w2[k] + bb[k];
;                     const float ge = c * __builtin_amdgcn_rcpf(1.f + __builtin_amdgcn_exp2f(c * __builtin_fmaf(-0.10294324f, c * c, -2.3022082f)));
;                     gsv[k] = ge * (acc[ai][1][m][k >> 2][k & 3] * rs[ai][m]);
;                 }
;                 if (row >= out_lo && row < out_hi) {
;                     u32x4 w; w.x = cvt_pk_bf16(gsv[0], gsv[1]); w.y = cvt_pk_bf16(gsv[2], gsv[3]); w.z = cvt_pk_bf16(gsv[4], gsv[5]); w.w = cvt_pk_bf16(gsv[6], gsv[7]);
;                     *(GAS u32x4*)(Gout + (size_t)row * DFF + f0) = w; }
.LBB0_799:
	s_min_i32 s76, s41, 0xff02
	s_addk_i32 s76, 0xfe
	v_cmp_le_i32_e32 vcc, s41, v174
	v_cmp_gt_i32_e64 s[10:11], s76, v174
	s_and_b64 s[10:11], vcc, s[10:11]
	s_and_saveexec_b64 s[12:13], s[10:11]
	s_cbranch_execz .LBB0_801
	v_and_b32_e32 v184, s7, v174
	v_cmp_eq_u32_e64 s[10:11], 0, v184
	v_cmp_eq_u32_e32 vcc, s7, v184
	s_waitcnt lgkmcnt(0)
	v_cndmask_b32_e64 v184, v240, v241, s[26:27]
	v_cndmask_b32_e64 v184, v184, 0, s[10:11]
	v_mul_f32_e32 v184, v28, v184
	v_cndmask_b32_e64 v185, v239, 0, vcc
	v_fmac_f32_e32 v184, v40, v233
	v_fmac_f32_e32 v184, v32, v185
	v_add_f32_e32 v184, v36, v184
	v_mul_f32_e32 v185, v184, v184
	v_fmamk_f32 v185, v185, 0xbdd2d3e8, v225
	v_mul_f32_e32 v185, v184, v185
	v_exp_f32_e32 v185, v185
	v_mul_f32_e32 v116, v116, v182
	v_mul_f32_e32 v115, v115, v182
	v_mul_f32_e32 v114, v114, v182
	v_add_f32_e32 v185, 1.0, v185
	v_rcp_f32_e32 v185, v185
	s_nop 0
	v_mul_f32_e32 v184, v184, v185
	v_mul_f32_e32 v184, v116, v184
	v_cndmask_b32_e64 v116, v237, v236, s[26:27]
	v_cndmask_b32_e64 v116, v116, 0, s[10:11]
	v_mul_f32_e32 v116, v27, v116
	v_cndmask_b32_e64 v185, v238, 0, vcc
	v_fmac_f32_e32 v116, v39, v232
	v_fmac_f32_e32 v116, v31, v185
	v_add_f32_e32 v116, v35, v116
	v_mul_f32_e32 v185, v116, v116
	v_fmamk_f32 v185, v185, 0xbdd2d3e8, v225
	v_mul_f32_e32 v185, v116, v185
	v_exp_f32_e32 v185, v185
	s_nop 0
	v_add_f32_e32 v185, 1.0, v185
	v_rcp_f32_e32 v185, v185
	s_nop 0
	v_mul_f32_e32 v116, v116, v185
	v_mul_f32_e32 v116, v115, v116
	v_cndmask_b32_e64 v115, v202, v234, s[26:27]
	v_cndmask_b32_e64 v115, v115, 0, s[10:11]
	v_mul_f32_e32 v115, v26, v115
	v_cndmask_b32_e64 v185, v203, 0, vcc
	v_fmac_f32_e32 v115, v38, v231
	v_fmac_f32_e32 v115, v30, v185
	v_add_f32_e32 v115, v34, v115
	v_mul_f32_e32 v185, v115, v115
	v_fmamk_f32 v185, v185, 0xbdd2d3e8, v225
	v_mul_f32_e32 v185, v115, v185
	v_exp_f32_e32 v185, v185
	s_nop 0
	v_add_f32_e32 v185, 1.0, v185
	v_rcp_f32_e32 v185, v185
	s_nop 0
	v_mul_f32_e32 v115, v115, v185
	v_mul_f32_e32 v185, v114, v115
	v_cndmask_b32_e64 v114, v198, v183, s[26:27]
	v_cndmask_b32_e64 v114, v114, 0, s[10:11]
	v_mul_f32_e32 v114, v45, v114
	v_cndmask_b32_e64 v115, v199, 0, vcc
	v_fmac_f32_e32 v114, v49, v217
	v_fmac_f32_e32 v114, v53, v115
	v_add_f32_e32 v114, v57, v114
	v_mul_f32_e32 v115, v114, v114
	v_fmamk_f32 v115, v115, 0xbdd2d3e8, v225
	v_mul_f32_e32 v115, v114, v115
	v_exp_f32_e32 v115, v115
	v_cvt_pk_bf16_f32 v116, v185, v116
	s_nop 0
	v_add_f32_e32 v115, 1.0, v115
	v_rcp_f32_e32 v115, v115
	s_nop 0
	v_mul_f32_e32 v114, v114, v115
	v_mul_f32_e32 v115, v121, v182
	v_mul_f32_e32 v121, v115, v114
	v_cndmask_b32_e64 v114, v143, v153, s[26:27]
	v_cndmask_b32_e64 v114, v114, 0, s[10:11]
	v_mul_f32_e32 v114, v44, v114
	v_cndmask_b32_e64 v115, v149, 0, vcc
	v_fmac_f32_e32 v114, v48, v216
	v_fmac_f32_e32 v114, v52, v115
	v_add_f32_e32 v114, v56, v114
	v_mul_f32_e32 v115, v114, v114
	v_fmamk_f32 v115, v115, 0xbdd2d3e8, v225
	v_mul_f32_e32 v115, v114, v115
	v_exp_f32_e32 v115, v115
	s_nop 0
	v_add_f32_e32 v115, 1.0, v115
	v_rcp_f32_e32 v115, v115
	s_nop 0
	v_mul_f32_e32 v114, v114, v115
	v_mul_f32_e32 v115, v120, v182
	v_mul_f32_e32 v120, v115, v114
	v_cndmask_b32_e64 v114, v127, v141, s[26:27]
	v_cndmask_b32_e64 v114, v114, 0, s[10:11]
	v_mul_f32_e32 v114, v43, v114
	v_cndmask_b32_e64 v115, v142, 0, vcc
	v_fmac_f32_e32 v114, v47, v215
	v_fmac_f32_e32 v114, v51, v115
	v_add_f32_e32 v114, v55, v114
	v_mul_f32_e32 v115, v114, v114
	v_fmamk_f32 v115, v115, 0xbdd2d3e8, v225
	v_mul_f32_e32 v115, v114, v115
	v_exp_f32_e32 v115, v115
	s_nop 0
	v_add_f32_e32 v115, 1.0, v115
	v_rcp_f32_e32 v115, v115
	s_nop 0
	v_mul_f32_e32 v114, v114, v115
	v_mul_f32_e32 v115, v119, v182
	v_mul_f32_e32 v119, v115, v114
	v_cndmask_b32_e64 v114, v135, v139, s[26:27]
	v_cndmask_b32_e64 v114, v114, 0, s[10:11]
	v_mul_f32_e32 v114, v42, v114
	v_cndmask_b32_e64 v115, v137, 0, vcc
	v_fmac_f32_e32 v114, v46, v214
	v_fmac_f32_e32 v114, v50, v115
	v_add_f32_e32 v114, v54, v114
	v_mul_f32_e32 v115, v114, v114
	v_fmamk_f32 v115, v115, 0xbdd2d3e8, v225
	v_mul_f32_e32 v115, v114, v115
	v_exp_f32_e32 v115, v115
	s_nop 0
	v_add_f32_e32 v115, 1.0, v115
	v_rcp_f32_e32 v115, v115
	s_nop 0
	v_mul_f32_e32 v114, v114, v115
	v_mul_f32_e32 v115, v118, v182
	v_mul_f32_e32 v118, v115, v114
	v_cndmask_b32_e64 v114, v129, v123, s[26:27]
	v_cndmask_b32_e64 v153, v114, 0, s[10:11]
	v_mov_b32_e32 v114, v41
	v_mov_b32_e32 v115, v29
	v_mul_f32_e32 v114, v114, v152
	v_mul_f32_e32 v115, v115, v153
	s_nop 0
	v_add_f32_e32 v114, v114, v115
	v_cndmask_b32_e64 v115, v125, 0, vcc
	v_fmac_f32_e32 v114, v33, v115
	v_add_f32_e32 v115, v37, v114
	v_mul_f32_e32 v114, v115, v115
	v_fmamk_f32 v114, v114, 0xbdd2d3e8, v225
	v_mul_f32_e32 v114, v115, v114
	v_exp_f32_e32 v114, v114
	s_nop 0
	v_add_f32_e32 v114, 1.0, v114
	v_rcp_f32_e32 v183, v114
	v_mov_b32_e32 v114, v117
	v_mul_f32_e32 v114, v114, v182
	v_mul_f32_e32 v115, v115, v183
	s_nop 0
	v_mul_f32_e32 v117, v114, v115
	v_cvt_pk_bf16_f32 v114, v118, v119
	v_mov_b64_e32 v[118:119], s[4:5]
	v_mad_i64_i32 v[118:119], s[10:11], v174, s1, v[118:119]
	v_lshl_add_u64 v[118:119], v[172:173], 1, v[118:119]
	v_cvt_pk_bf16_f32 v115, v120, v121
	v_cvt_pk_bf16_f32 v117, v184, v117
	global_store_dwordx4 v[118:119], v[114:117], off
; #define GAS __attribute__((address_space(1)))
; __device__ __forceinline__ unsigned cvt_pk_bf16(float lo, float hi) { unsigned r; asm("v_cvt_pk_bf16_f32 %0, %1, %2" : "=v"(r) : "v"(lo), "v"(hi)); return r; }
; template <int CTRL> __device__ __forceinline__ float dpp_mov(float v) { return __int_as_float(__builtin_amdgcn_update_dpp(0, __float_as_int(v), CTRL, 0xf, 0xf, false)); }
; __device__ __forceinline__ float rstd_of(unsigned long long ssq) { return __builtin_amdgcn_rsqf((float)ssq * (1.f / (1024.f * 1048576.f)) + EPS); }
;     __device__ __forceinline__ void operator()(const f32x4 (&acc)[2][2][4][2], const Unit& u, int wr, int wc, int fr, int fq) const {
;     ...
;               for (int m = 0; m < 4; ++m) rs[ai][m] = rstd_of(q[ai][m]); }
;     ...
;                 const int chunk = ai * 2 + wr, row = base + ai * HALF + wr * 64 + m * 16 + fr, pos = row & (S - 1);
;                 float gsv[8];
; #pragma unroll
;                 for (int k = 0; k < 8; ++k) {
;                     const float am = acc[ai][0][m][k >> 2][k & 3] * rs[ai][m];
;                     float sp, sn;
;                     if (m > 0) sp = fr == 15 ? acc[ai][0][m - 1][k >> 2][k & 3] * rs[ai][m - 1] : am; else sp = am;
;                     if (m < 3) sn = fr == 0 ? acc[ai][0][m + 1][k >> 2][k & 3] * rs[ai][m + 1] : am; else sn = am;
;                     float pv = dpp_mov<0x121>(sp), nv = dpp_mov<0x12F>(sn);
;                     if (m == 0) { const float e = chunk > 0 ? xch[((chunk - 1) * 2 + 1) * 128 + colh + k] : 0.f; pv = fr == 0 ? e : pv; }
;                     if (m == 3) { const float e = chunk < 3 ? xch[((chunk + 1) * 2 + 0) * 128 + colh + k] : 0.f; nv = fr == 15 ? e : nv; }
;                     pv = pos == 0 ? 0.f : pv; nv = pos == S - 1 ? 0.f : nv;
;                     const float c = pv * w0[k] + am * w1[k] + nv * w2[k] + bb[k];
;                     const float ge = c * __builtin_amdgcn_rcpf(1.f + __builtin_amdgcn_exp2f(c * __builtin_fmaf(-0.10294324f, c * c, -2.3022082f)));
;                     gsv[k] = ge * (acc[ai][1][m][k >> 2][k & 3] * rs[ai][m]);
;                 }
;                 if (row >= out_lo && row < out_hi) {
;                     u32x4 w; w.x = cvt_pk_bf16(gsv[0], gsv[1]); w.y = cvt_pk_bf16(gsv[2], gsv[3]); w.z = cvt_pk_bf16(gsv[4], gsv[5]); w.w = cvt_pk_bf16(gsv[6], gsv[7]);
;                     *(GAS u32x4*)(Gout + (size_t)row * DFF + f0) = w; }
.LBB0_801:
	s_or_b64 exec, exec, s[12:13]
	s_nop 0
	v_ffbh_u32_e32 v114, v197
	v_min_u32_e32 v116, 32, v114
	v_lshlrev_b64 v[114:115], v116, v[196:197]
	v_min_u32_e32 v114, 1, v114
	v_or_b32_e32 v114, v115, v114
	v_cvt_f32_u32_e32 v114, v114
	v_sub_u32_e32 v116, 32, v116
	v_cmp_eq_u32_e64 s[10:11], 15, v213
	v_mov_b32_e32 v119, v1
	v_ldexp_f32 v114, v114, v116
	v_fmamk_f32 v114, v114, 0x30800000, v218
	v_rsq_f32_e32 v120, v114
	v_cndmask_b32_e64 v114, v126, v214, s[10:11]
	v_mov_b32_e32 v117, v1
	v_mov_b32_e32 v121, v1
	v_mul_f32_e32 v142, v110, v120
	v_cndmask_b32_e64 v110, v126, v142, s[26:27]
	v_mul_f32_e32 v118, v111, v120
	v_mov_b32_dpp v119, v114 row_ror:1 row_mask:0xf bank_mask:0xf
	v_mov_b32_dpp v117, v110 row_ror:15 row_mask:0xf bank_mask:0xf
	v_cndmask_b32_e64 v110, v136, v215, s[10:11]
	v_cndmask_b32_e64 v114, v136, v118, s[26:27]
	v_mov_b32_e32 v111, v1
	v_mul_f32_e32 v116, v112, v120
	v_mov_b32_dpp v121, v110 row_ror:1 row_mask:0xf bank_mask:0xf
	v_mov_b32_dpp v111, v114 row_ror:15 row_mask:0xf bank_mask:0xf
	v_cndmask_b32_e64 v110, v128, v216, s[10:11]
	v_cndmask_b32_e64 v112, v128, v116, s[26:27]
	v_mov_b32_e32 v127, v1
	v_mov_b32_e32 v125, v1
	v_mul_f32_e32 v114, v113, v120
	v_mov_b32_dpp v127, v110 row_ror:1 row_mask:0xf bank_mask:0xf
	v_mov_b32_dpp v125, v112 row_ror:15 row_mask:0xf bank_mask:0xf
	v_cndmask_b32_e64 v110, v138, v217, s[10:11]
	v_cndmask_b32_e64 v112, v138, v114, s[26:27]
	v_mov_b32_e32 v129, v1
	v_mov_b32_e32 v113, v1
	s_waitcnt lgkmcnt(0)
	v_mov_b32_e32 v123, v1
	v_mov_b32_dpp v129, v110 row_ror:1 row_mask:0xf bank_mask:0xf
	v_mov_b32_dpp v113, v112 row_ror:15 row_mask:0xf bank_mask:0xf
	v_cndmask_b32_e64 v110, v122, v231, s[10:11]
	v_mul_f32_e32 v112, v106, v120
	v_cndmask_b32_e64 v106, v122, v112, s[26:27]
	v_mov_b32_dpp v123, v110 row_ror:1 row_mask:0xf bank_mask:0xf
	v_mov_b32_e32 v137, v1
	v_mul_f32_e32 v110, v107, v120
	v_cndmask_b32_e64 v107, v140, v110, s[26:27]
	v_mov_b32_dpp v137, v106 row_ror:15 row_mask:0xf bank_mask:0xf
	v_cndmask_b32_e64 v106, v140, v232, s[10:11]
	v_mov_b32_e32 v141, v1
	v_mov_b32_e32 v139, v1
	v_mul_f32_e32 v108, v108, v120
	v_mov_b32_dpp v141, v106 row_ror:1 row_mask:0xf bank_mask:0xf
	v_mov_b32_dpp v139, v107 row_ror:15 row_mask:0xf bank_mask:0xf
	v_cndmask_b32_e64 v106, v133, v233, s[10:11]
	v_cndmask_b32_e64 v107, v133, v108, s[26:27]
	v_mov_b32_e32 v135, v1
	v_mov_b32_e32 v143, v1
	v_add_u32_e32 v115, 16, v174
	v_mov_b32_dpp v135, v106 row_ror:1 row_mask:0xf bank_mask:0xf
	v_mov_b32_dpp v143, v107 row_ror:15 row_mask:0xf bank_mask:0xf
	v_cndmask_b32_e64 v107, v124, v152, s[10:11]
	v_mul_f32_e32 v106, v109, v120
	v_mov_b32_e32 v109, v1
	v_cndmask_b32_e64 v149, v124, v106, s[26:27]
	v_cmp_le_i32_e32 vcc, s41, v115
	v_mov_b32_dpp v109, v107 row_ror:1 row_mask:0xf bank_mask:0xf
	v_mov_b32_e32 v107, v1
	v_cmp_gt_i32_e64 s[12:13], s76, v115
	s_and_b64 s[12:13], vcc, s[12:13]
	v_mov_b32_dpp v107, v149 row_ror:15 row_mask:0xf bank_mask:0xf
	s_and_saveexec_b64 s[28:29], s[12:13]
	s_cbranch_execz .LBB0_803
	v_and_b32_e32 v149, s7, v115
	v_cmp_eq_u32_e64 s[12:13], 0, v149
	v_cmp_eq_u32_e32 vcc, s7, v149
	v_mov_b32_e32 v182, v28
	v_cndmask_b32_e64 v152, v135, 0, s[12:13]
	v_cndmask_b32_e64 v153, v143, 0, vcc
	v_mov_b32_e32 v183, v32
	v_mul_f32_e32 v152, v182, v152
	v_mul_f32_e32 v153, v183, v153
	v_cndmask_b32_e64 v141, v141, 0, s[12:13]
	v_fma_f32 v135, v40, v133, v152
	v_add_f32_e32 v135, v135, v153
	v_add_f32_e32 v153, v36, v135
	v_mul_f32_e32 v135, v153, v153
	v_fmamk_f32 v135, v135, 0xbdd2d3e8, v225
	v_mul_f32_e32 v135, v153, v135
	v_exp_f32_e32 v135, v135
	v_mov_b32_e32 v152, v100
	v_cndmask_b32_e64 v123, v123, 0, s[12:13]
	v_add_f32_e32 v135, 1.0, v135
	v_rcp_f32_e32 v135, v135
	s_nop 0
	v_mul_f32_e32 v152, v152, v134
	v_mul_f32_e32 v153, v153, v135
	s_nop 0
	v_mul_f32_e32 v143, v152, v153
	v_mov_b32_e32 v152, v39
	v_mov_b32_e32 v153, v27
	v_mul_f32_e32 v152, v152, v140
	v_mul_f32_e32 v153, v153, v141
	v_cndmask_b32_e64 v135, v139, 0, vcc
	v_add_f32_e32 v100, v152, v153
	v_fmac_f32_e32 v100, v31, v135
	v_add_f32_e32 v153, v35, v100
	v_mul_f32_e32 v100, v153, v153
	v_fmamk_f32 v100, v100, 0xbdd2d3e8, v225
	v_mul_f32_e32 v100, v153, v100
	v_exp_f32_e32 v100, v100
	v_mov_b32_e32 v152, v99
	v_cndmask_b32_e64 v139, v129, 0, s[12:13]
	v_cndmask_b32_e64 v129, v127, 0, s[12:13]
	v_add_f32_e32 v100, 1.0, v100
	v_rcp_f32_e32 v135, v100
	v_cndmask_b32_e64 v127, v119, 0, s[12:13]
	v_mul_f32_e32 v152, v152, v134
	v_mul_f32_e32 v153, v153, v135
	s_nop 0
	v_mul_f32_e32 v100, v152, v153
	v_mov_b32_e32 v152, v38
	v_mov_b32_e32 v153, v26
	v_mul_f32_e32 v152, v152, v122
	v_mul_f32_e32 v153, v153, v123
	v_cndmask_b32_e64 v123, v137, 0, vcc
	v_add_f32_e32 v99, v152, v153
	v_fmac_f32_e32 v99, v30, v123
	v_add_f32_e32 v99, v34, v99
	v_mul_f32_e32 v123, v99, v99
	v_fmamk_f32 v123, v123, 0xbdd2d3e8, v225
	v_mul_f32_e32 v123, v99, v123
	v_exp_f32_e32 v123, v123
	v_cndmask_b32_e64 v137, v121, 0, s[12:13]
	v_add_f32_e32 v123, 1.0, v123
	v_rcp_f32_e32 v135, v123
	s_nop 0
	v_mul_f32_e32 v98, v98, v134
	v_mul_f32_e32 v99, v99, v135
	s_nop 0
	v_mul_f32_e32 v123, v98, v99
	v_mov_b32_e32 v98, v49
	v_mov_b32_e32 v99, v45
	v_mul_f32_e32 v98, v98, v138
	v_mul_f32_e32 v99, v99, v139
	v_cvt_pk_bf16_f32 v100, v123, v100
	s_nop 0
	v_add_f32_e32 v98, v98, v99
	v_cndmask_b32_e64 v99, v113, 0, vcc
	v_fmac_f32_e32 v98, v53, v99
	v_add_f32_e32 v99, v57, v98
	v_mul_f32_e32 v98, v99, v99
	v_fmamk_f32 v98, v98, 0xbdd2d3e8, v225
	v_mul_f32_e32 v98, v99, v98
	v_exp_f32_e32 v98, v98
	s_nop 0
	v_add_f32_e32 v98, 1.0, v98
	v_rcp_f32_e32 v135, v98
	v_mov_b32_e32 v98, v105
	v_mul_f32_e32 v98, v98, v134
	v_mul_f32_e32 v99, v99, v135
; #define GAS __attribute__((address_space(1)))
; __device__ __forceinline__ unsigned cvt_pk_bf16(float lo, float hi) { unsigned r; asm("v_cvt_pk_bf16_f32 %0, %1, %2" : "=v"(r) : "v"(lo), "v"(hi)); return r; }
; template <int CTRL> __device__ __forceinline__ float dpp_mov(float v) { return __int_as_float(__builtin_amdgcn_update_dpp(0, __float_as_int(v), CTRL, 0xf, 0xf, false)); }
;     __device__ __forceinline__ void operator()(const f32x4 (&acc)[2][2][4][2], const Unit& u, int wr, int wc, int fr, int fq) const {
;     ...
;                 for (int k = 0; k < 8; ++k) {
;                     const float am = acc[ai][0][m][k >> 2][k & 3] * rs[ai][m];
;                     float sp, sn;
;                     if (m > 0) sp = fr == 15 ? acc[ai][0][m - 1][k >> 2][k & 3] * rs[ai][m - 1] : am; else sp = am;
;                     if (m < 3) sn = fr == 0 ? acc[ai][0][m + 1][k >> 2][k & 3] * rs[ai][m + 1] : am; else sn = am;
;                     float pv = dpp_mov<0x121>(sp), nv = dpp_mov<0x12F>(sn);
;                     if (m == 0) { const float e = chunk > 0 ? xch[((chunk - 1) * 2 + 1) * 128 + colh + k] : 0.f; pv = fr == 0 ? e : pv; }
;                     if (m == 3) { const float e = chunk < 3 ? xch[((chunk + 1) * 2 + 0) * 128 + colh + k] : 0.f; nv = fr == 15 ? e : nv; }
;                     pv = pos == 0 ? 0.f : pv; nv = pos == S - 1 ? 0.f : nv;
;                     const float c = pv * w0[k] + am * w1[k] + nv * w2[k] + bb[k];
;                     const float ge = c * __builtin_amdgcn_rcpf(1.f + __builtin_amdgcn_exp2f(c * __builtin_fmaf(-0.10294324f, c * c, -2.3022082f)));
;                     gsv[k] = ge * (acc[ai][1][m][k >> 2][k & 3] * rs[ai][m]);
;                 }
;                 if (row >= out_lo && row < out_hi) {
;                     u32x4 w; w.x = cvt_pk_bf16(gsv[0], gsv[1]); w.y = cvt_pk_bf16(gsv[2], gsv[3]); w.z = cvt_pk_bf16(gsv[4], gsv[5]); w.w = cvt_pk_bf16(gsv[6], gsv[7]);
;                     *(GAS u32x4*)(Gout + (size_t)row * DFF + f0) = w; }
	s_nop 0
	v_mul_f32_e32 v113, v98, v99
	v_mov_b32_e32 v98, v48
	v_mov_b32_e32 v99, v44
	v_mul_f32_e32 v98, v98, v128
	v_mul_f32_e32 v99, v99, v129
	s_nop 0
	v_add_f32_e32 v98, v98, v99
	v_cndmask_b32_e64 v99, v125, 0, vcc
	v_fmac_f32_e32 v98, v52, v99
	v_add_f32_e32 v105, v56, v98
	v_mul_f32_e32 v98, v105, v105
	v_fmamk_f32 v98, v98, 0xbdd2d3e8, v225
	v_mul_f32_e32 v98, v105, v98
	v_exp_f32_e32 v98, v98
	v_cndmask_b32_e64 v125, v109, 0, s[12:13]
	v_add_f32_e32 v98, 1.0, v98
	v_rcp_f32_e32 v135, v98
	s_nop 0
	v_mul_f32_e32 v98, v104, v134
	v_mul_f32_e32 v99, v105, v135
	s_nop 0
	v_mul_f32_e32 v104, v98, v99
	v_mov_b32_e32 v98, v47
	v_mov_b32_e32 v99, v43
	v_mul_f32_e32 v98, v98, v136
	v_mul_f32_e32 v99, v99, v137
	s_nop 0
	v_add_f32_e32 v98, v98, v99
	v_cndmask_b32_e64 v99, v111, 0, vcc
	v_fmac_f32_e32 v98, v51, v99
	v_add_f32_e32 v99, v55, v98
	v_mul_f32_e32 v98, v99, v99
	v_fmamk_f32 v98, v98, 0xbdd2d3e8, v225
	v_mul_f32_e32 v98, v99, v98
	v_exp_f32_e32 v98, v98
	s_nop 0
	v_add_f32_e32 v98, 1.0, v98
	v_rcp_f32_e32 v135, v98
	v_mov_b32_e32 v98, v103
	v_mul_f32_e32 v98, v98, v134
	v_mul_f32_e32 v99, v99, v135
	s_nop 0
	v_mul_f32_e32 v105, v98, v99
	v_mov_b32_e32 v98, v46
	v_mov_b32_e32 v99, v42
	v_mul_f32_e32 v98, v98, v126
	v_mul_f32_e32 v99, v99, v127
	s_nop 0
	v_add_f32_e32 v98, v98, v99
	v_cndmask_b32_e64 v99, v117, 0, vcc
	v_fmac_f32_e32 v98, v50, v99
	v_add_f32_e32 v103, v54, v98
	v_mul_f32_e32 v98, v103, v103
	v_fmamk_f32 v98, v98, 0xbdd2d3e8, v225
	v_mul_f32_e32 v98, v103, v98
	v_exp_f32_e32 v98, v98
	s_nop 0
	v_add_f32_e32 v98, 1.0, v98
	v_rcp_f32_e32 v135, v98
	s_nop 0
	v_mul_f32_e32 v98, v102, v134
	v_mul_f32_e32 v99, v103, v135
	s_nop 0
	v_mul_f32_e32 v102, v98, v99
	v_mov_b32_e32 v98, v41
	v_mov_b32_e32 v99, v29
	v_mul_f32_e32 v98, v98, v124
	v_mul_f32_e32 v99, v99, v125
	s_nop 0
	v_add_f32_e32 v98, v98, v99
	v_cndmask_b32_e64 v99, v107, 0, vcc
	v_fmac_f32_e32 v98, v33, v99
	v_add_f32_e32 v99, v37, v98
	v_mul_f32_e32 v98, v99, v99
	v_fmamk_f32 v98, v98, 0xbdd2d3e8, v225
	v_mul_f32_e32 v98, v99, v98
	v_exp_f32_e32 v98, v98
	s_nop 0
	v_add_f32_e32 v98, 1.0, v98
	v_rcp_f32_e32 v135, v98
	v_mov_b32_e32 v98, v101
	v_mul_f32_e32 v98, v98, v134
	v_mul_f32_e32 v99, v99, v135
	s_nop 0
	v_mul_f32_e32 v101, v98, v99
	v_cvt_pk_bf16_f32 v98, v102, v105
	v_mov_b64_e32 v[102:103], s[4:5]
	v_mad_i64_i32 v[102:103], s[12:13], v115, s1, v[102:103]
	v_lshl_add_u64 v[102:103], v[172:173], 1, v[102:103]
	v_cvt_pk_bf16_f32 v99, v104, v113
	v_cvt_pk_bf16_f32 v101, v143, v101
	global_store_dwordx4 v[102:103], v[98:101], off
.LBB0_803:
	s_or_b64 exec, exec, s[28:29]
	s_nop 0
	v_cndmask_b32_e64 v99, v142, v126, s[10:11]
	v_cndmask_b32_e64 v101, v142, v179, s[26:27]
	v_mov_b32_e32 v102, v1
	v_mov_b32_e32 v100, v1
	v_mov_b32_e32 v104, v1
	v_mov_b32_dpp v102, v99 row_ror:1 row_mask:0xf bank_mask:0xf
	v_mov_b32_dpp v100, v101 row_ror:15 row_mask:0xf bank_mask:0xf
	v_cndmask_b32_e64 v99, v118, v136, s[10:11]
	v_cndmask_b32_e64 v101, v118, v208, s[26:27]
	v_mov_b32_e32 v103, v1
	v_mov_b32_dpp v104, v99 row_ror:1 row_mask:0xf bank_mask:0xf
	v_cndmask_b32_e64 v99, v116, v128, s[10:11]
	v_mov_b32_dpp v103, v101 row_ror:15 row_mask:0xf bank_mask:0xf
	v_cndmask_b32_e64 v101, v116, v209, s[26:27]
	v_mov_b32_e32 v107, v1
	v_mov_b32_e32 v105, v1
	v_mov_b32_e32 v115, v1
	v_mov_b32_dpp v107, v99 row_ror:1 row_mask:0xf bank_mask:0xf
	v_mov_b32_dpp v105, v101 row_ror:15 row_mask:0xf bank_mask:0xf
	v_cndmask_b32_e64 v99, v114, v138, s[10:11]
	v_cndmask_b32_e64 v101, v114, v210, s[26:27]
	v_mov_b32_e32 v109, v1
	v_mov_b32_dpp v115, v99 row_ror:1 row_mask:0xf bank_mask:0xf
	v_cndmask_b32_e64 v99, v112, v122, s[10:11]
	v_mov_b32_dpp v109, v101 row_ror:15 row_mask:0xf bank_mask:0xf
	v_cndmask_b32_e64 v101, v112, v211, s[26:27]
	v_mov_b32_e32 v113, v1
	v_mov_b32_e32 v117, v1
	v_mov_b32_e32 v111, v1
	v_mov_b32_dpp v113, v99 row_ror:1 row_mask:0xf bank_mask:0xf
	v_mov_b32_dpp v117, v101 row_ror:15 row_mask:0xf bank_mask:0xf
	v_cndmask_b32_e64 v99, v110, v140, s[10:11]
	v_cndmask_b32_e64 v101, v110, v151, s[26:27]
	v_mov_b32_e32 v119, v1
	v_mov_b32_dpp v111, v99 row_ror:1 row_mask:0xf bank_mask:0xf
	v_cndmask_b32_e64 v99, v108, v133, s[10:11]
	v_mov_b32_dpp v119, v101 row_ror:15 row_mask:0xf bank_mask:0xf
	v_cndmask_b32_e64 v101, v108, v212, s[26:27]
	v_mov_b32_e32 v121, v1
	v_mov_b32_e32 v122, v1
	v_add_u32_e32 v98, 32, v174
	v_mov_b32_dpp v121, v99 row_ror:1 row_mask:0xf bank_mask:0xf
	v_mov_b32_dpp v122, v101 row_ror:15 row_mask:0xf bank_mask:0xf
	v_cndmask_b32_e64 v99, v106, v124, s[10:11]
	v_mov_b32_e32 v101, v1
	v_cndmask_b32_e64 v123, v106, v150, s[26:27]
	v_cmp_le_i32_e32 vcc, s41, v98
	v_mov_b32_dpp v101, v99 row_ror:1 row_mask:0xf bank_mask:0xf
	v_mov_b32_e32 v99, v1
	v_cmp_gt_i32_e64 s[12:13], s76, v98
	s_and_b64 s[12:13], vcc, s[12:13]
	v_mov_b32_dpp v99, v123 row_ror:15 row_mask:0xf bank_mask:0xf
	s_and_saveexec_b64 s[28:29], s[12:13]
	s_cbranch_execz .LBB0_805
; #define GAS __attribute__((address_space(1)))
; __device__ __forceinline__ unsigned cvt_pk_bf16(float lo, float hi) { unsigned r; asm("v_cvt_pk_bf16_f32 %0, %1, %2" : "=v"(r) : "v"(lo), "v"(hi)); return r; }
; template <int CTRL> __device__ __forceinline__ float dpp_mov(float v) { return __int_as_float(__builtin_amdgcn_update_dpp(0, __float_as_int(v), CTRL, 0xf, 0xf, false)); }
;     __device__ __forceinline__ void operator()(const f32x4 (&acc)[2][2][4][2], const Unit& u, int wr, int wc, int fr, int fq) const {
;     ...
;                 for (int k = 0; k < 8; ++k) {
;                     const float am = acc[ai][0][m][k >> 2][k & 3] * rs[ai][m];
;                     float sp, sn;
;                     if (m > 0) sp = fr == 15 ? acc[ai][0][m - 1][k >> 2][k & 3] * rs[ai][m - 1] : am; else sp = am;
;                     if (m < 3) sn = fr == 0 ? acc[ai][0][m + 1][k >> 2][k & 3] * rs[ai][m + 1] : am; else sn = am;
;                     float pv = dpp_mov<0x121>(sp), nv = dpp_mov<0x12F>(sn);
;                     if (m == 0) { const float e = chunk > 0 ? xch[((chunk - 1) * 2 + 1) * 128 + colh + k] : 0.f; pv = fr == 0 ? e : pv; }
;                     if (m == 3) { const float e = chunk < 3 ? xch[((chunk + 1) * 2 + 0) * 128 + colh + k] : 0.f; nv = fr == 15 ? e : nv; }
;                     pv = pos == 0 ? 0.f : pv; nv = pos == S - 1 ? 0.f : nv;
;                     const float c = pv * w0[k] + am * w1[k] + nv * w2[k] + bb[k];
;                     const float ge = c * __builtin_amdgcn_rcpf(1.f + __builtin_amdgcn_exp2f(c * __builtin_fmaf(-0.10294324f, c * c, -2.3022082f)));
;                     gsv[k] = ge * (acc[ai][1][m][k >> 2][k & 3] * rs[ai][m]);
;                 }
;                 if (row >= out_lo && row < out_hi) {
;                     u32x4 w; w.x = cvt_pk_bf16(gsv[0], gsv[1]); w.y = cvt_pk_bf16(gsv[2], gsv[3]); w.z = cvt_pk_bf16(gsv[4], gsv[5]); w.w = cvt_pk_bf16(gsv[6], gsv[7]);
;                     *(GAS u32x4*)(Gout + (size_t)row * DFF + f0) = w; }
	v_and_b32_e32 v123, s7, v98
	v_cmp_eq_u32_e64 s[12:13], 0, v123
	v_cmp_eq_u32_e32 vcc, s7, v123
	v_mov_b32_e32 v124, v28
	v_mov_b32_e32 v125, v32
	v_cndmask_b32_e64 v123, v122, 0, vcc
	v_cndmask_b32_e64 v122, v121, 0, s[12:13]
	v_mul_f32_e32 v122, v124, v122
	v_mul_f32_e32 v123, v125, v123
	v_cndmask_b32_e64 v111, v111, 0, s[12:13]
	v_fma_f32 v121, v40, v108, v122
	v_add_f32_e32 v121, v121, v123
	v_add_f32_e32 v123, v36, v121
	v_mul_f32_e32 v121, v123, v123
	v_fmamk_f32 v121, v121, 0xbdd2d3e8, v225
	v_mul_f32_e32 v121, v123, v121
	v_exp_f32_e32 v121, v121
	v_mov_b32_e32 v122, v92
	v_cndmask_b32_e64 v113, v113, 0, s[12:13]
	v_cndmask_b32_e64 v115, v115, 0, s[12:13]
	v_add_f32_e32 v121, 1.0, v121
	v_rcp_f32_e32 v121, v121
	v_cndmask_b32_e64 v143, v102, 0, s[12:13]
	v_mul_f32_e32 v122, v122, v120
	v_mul_f32_e32 v123, v123, v121
	s_nop 0
	v_mul_f32_e32 v124, v122, v123
	v_mov_b32_e32 v122, v39
	v_mov_b32_e32 v123, v27
	v_mul_f32_e32 v122, v122, v110
	v_mul_f32_e32 v123, v123, v111
	v_cndmask_b32_e64 v111, v119, 0, vcc
	v_add_f32_e32 v92, v122, v123
	v_fmac_f32_e32 v92, v31, v111
	v_add_f32_e32 v123, v35, v92
	v_mul_f32_e32 v92, v123, v123
	v_fmamk_f32 v92, v92, 0xbdd2d3e8, v225
	v_mul_f32_e32 v92, v123, v92
	v_exp_f32_e32 v92, v92
	v_mov_b32_e32 v122, v91
	v_cndmask_b32_e64 v111, v117, 0, vcc
	v_cndmask_b32_e64 v117, v107, 0, s[12:13]
	v_add_f32_e32 v92, 1.0, v92
	v_rcp_f32_e32 v121, v92
	v_cndmask_b32_e64 v119, v104, 0, s[12:13]
	v_cndmask_b32_e64 v107, v101, 0, s[12:13]
	v_mul_f32_e32 v122, v122, v120
	v_mul_f32_e32 v123, v123, v121
	s_nop 0
	v_mul_f32_e32 v92, v122, v123
	v_mov_b32_e32 v122, v38
	v_mov_b32_e32 v123, v26
	v_mul_f32_e32 v122, v122, v112
	v_mul_f32_e32 v123, v123, v113
	s_nop 0
	v_add_f32_e32 v91, v122, v123
	v_fmac_f32_e32 v91, v30, v111
	v_add_f32_e32 v91, v34, v91
	v_mul_f32_e32 v111, v91, v91
	v_fmamk_f32 v111, v111, 0xbdd2d3e8, v225
	v_mul_f32_e32 v111, v91, v111
	v_exp_f32_e32 v111, v111
	s_nop 0
	v_add_f32_e32 v111, 1.0, v111
	v_rcp_f32_e32 v121, v111
	s_nop 0
	v_mul_f32_e32 v90, v90, v120
	v_mul_f32_e32 v91, v91, v121
	s_nop 0
	v_mul_f32_e32 v111, v90, v91
	v_mov_b32_e32 v90, v49
	v_mov_b32_e32 v91, v45
	v_mul_f32_e32 v90, v90, v114
	v_mul_f32_e32 v91, v91, v115
	v_cvt_pk_bf16_f32 v92, v111, v92
	s_nop 0
	v_add_f32_e32 v90, v90, v91
	v_cndmask_b32_e64 v91, v109, 0, vcc
	v_fmac_f32_e32 v90, v53, v91
	v_add_f32_e32 v91, v57, v90
	v_mul_f32_e32 v90, v91, v91
	v_fmamk_f32 v90, v90, 0xbdd2d3e8, v225
	v_mul_f32_e32 v90, v91, v90
	v_exp_f32_e32 v90, v90
	s_nop 0
	v_add_f32_e32 v90, 1.0, v90
	v_rcp_f32_e32 v121, v90
	v_mov_b32_e32 v90, v97
	v_mul_f32_e32 v90, v90, v120
	v_mul_f32_e32 v91, v91, v121
	s_nop 0
	v_mul_f32_e32 v109, v90, v91
	v_mov_b32_e32 v90, v48
	v_mov_b32_e32 v91, v44
	v_mul_f32_e32 v90, v90, v116
	v_mul_f32_e32 v91, v91, v117
	s_nop 0
	v_add_f32_e32 v90, v90, v91
	v_cndmask_b32_e64 v91, v105, 0, vcc
	v_fmac_f32_e32 v90, v52, v91
	v_add_f32_e32 v97, v56, v90
	v_mul_f32_e32 v90, v97, v97
	v_fmamk_f32 v90, v90, 0xbdd2d3e8, v225
	v_mul_f32_e32 v90, v97, v90
	v_exp_f32_e32 v90, v90
	s_nop 0
	v_add_f32_e32 v90, 1.0, v90
	v_rcp_f32_e32 v121, v90
	s_nop 0
	v_mul_f32_e32 v90, v96, v120
	v_mul_f32_e32 v91, v97, v121
	s_nop 0
	v_mul_f32_e32 v96, v90, v91
	v_mov_b32_e32 v90, v47
	v_mov_b32_e32 v91, v43
	v_mul_f32_e32 v90, v90, v118
	v_mul_f32_e32 v91, v91, v119
	s_nop 0
	v_add_f32_e32 v90, v90, v91
	v_cndmask_b32_e64 v91, v103, 0, vcc
	v_fmac_f32_e32 v90, v51, v91
	v_add_f32_e32 v91, v55, v90
	v_mul_f32_e32 v90, v91, v91
	v_fmamk_f32 v90, v90, 0xbdd2d3e8, v225
	v_mul_f32_e32 v90, v91, v90
	v_exp_f32_e32 v90, v90
	s_nop 0
	v_add_f32_e32 v90, 1.0, v90
	v_rcp_f32_e32 v121, v90
	v_mov_b32_e32 v90, v95
	v_mul_f32_e32 v90, v90, v120
	v_mul_f32_e32 v91, v91, v121
	s_nop 0
	v_mul_f32_e32 v97, v90, v91
	v_mov_b32_e32 v90, v46
	v_mov_b32_e32 v91, v42
	v_mul_f32_e32 v90, v90, v142
	v_mul_f32_e32 v91, v91, v143
	s_nop 0
	v_add_f32_e32 v90, v90, v91
	v_cndmask_b32_e64 v91, v100, 0, vcc
	v_fmac_f32_e32 v90, v50, v91
	v_add_f32_e32 v95, v54, v90
	v_mul_f32_e32 v90, v95, v95
	v_fmamk_f32 v90, v90, 0xbdd2d3e8, v225
	v_mul_f32_e32 v90, v95, v90
	v_exp_f32_e32 v90, v90
	s_nop 0
	v_add_f32_e32 v90, 1.0, v90
	v_rcp_f32_e32 v121, v90
	s_nop 0
	v_mul_f32_e32 v90, v94, v120
	v_mul_f32_e32 v91, v95, v121
	s_nop 0
	v_mul_f32_e32 v94, v90, v91
	v_mov_b32_e32 v90, v41
	v_mov_b32_e32 v91, v29
	v_mul_f32_e32 v90, v90, v106
	v_mul_f32_e32 v91, v91, v107
	s_nop 0
	v_add_f32_e32 v90, v90, v91
	v_cndmask_b32_e64 v91, v99, 0, vcc
	v_fmac_f32_e32 v90, v33, v91
	v_add_f32_e32 v91, v37, v90
	v_mul_f32_e32 v90, v91, v91
	v_fmamk_f32 v90, v90, 0xbdd2d3e8, v225
	v_mul_f32_e32 v90, v91, v90
	v_exp_f32_e32 v90, v90
	s_nop 0
	v_add_f32_e32 v90, 1.0, v90
	v_rcp_f32_e32 v121, v90
	v_mov_b32_e32 v90, v93
	v_mul_f32_e32 v90, v90, v120
	v_mul_f32_e32 v91, v91, v121
	s_nop 0
	v_mul_f32_e32 v93, v90, v91
	v_cvt_pk_bf16_f32 v90, v94, v97
	v_mov_b64_e32 v[94:95], s[4:5]
	v_mad_i64_i32 v[94:95], s[12:13], v98, s1, v[94:95]
	v_lshl_add_u64 v[94:95], v[172:173], 1, v[94:95]
	v_cvt_pk_bf16_f32 v91, v96, v109
	v_cvt_pk_bf16_f32 v93, v124, v93
	global_store_dwordx4 v[94:95], v[90:93], off

; #define GAS __attribute__((address_space(1)))
; __device__ __forceinline__ unsigned cvt_pk_bf16(float lo, float hi) { unsigned r; asm("v_cvt_pk_bf16_f32 %0, %1, %2" : "=v"(r) : "v"(lo), "v"(hi)); return r; }
; template <int CTRL> __device__ __forceinline__ float dpp_mov(float v) { return __int_as_float(__builtin_amdgcn_update_dpp(0, __float_as_int(v), CTRL, 0xf, 0xf, false)); }
;     __device__ __forceinline__ void operator()(const f32x4 (&acc)[2][2][4][2], const Unit& u, int wr, int wc, int fr, int fq) const {
;     ...
;                 for (int k = 0; k < 8; ++k) {
;                     const float am = acc[ai][0][m][k >> 2][k & 3] * rs[ai][m];
;                     float sp, sn;
;                     if (m > 0) sp = fr == 15 ? acc[ai][0][m - 1][k >> 2][k & 3] * rs[ai][m - 1] : am; else sp = am;
;                     if (m < 3) sn = fr == 0 ? acc[ai][0][m + 1][k >> 2][k & 3] * rs[ai][m + 1] : am; else sn = am;
;                     float pv = dpp_mov<0x121>(sp), nv = dpp_mov<0x12F>(sn);
;                     if (m == 0) { const float e = chunk > 0 ? xch[((chunk - 1) * 2 + 1) * 128 + colh + k] : 0.f; pv = fr == 0 ? e : pv; }
;                     if (m == 3) { const float e = chunk < 3 ? xch[((chunk + 1) * 2 + 0) * 128 + colh + k] : 0.f; nv = fr == 15 ? e : nv; }
;                     pv = pos == 0 ? 0.f : pv; nv = pos == S - 1 ? 0.f : nv;
;                     const float c = pv * w0[k] + am * w1[k] + nv * w2[k] + bb[k];
;                     const float ge = c * __builtin_amdgcn_rcpf(1.f + __builtin_amdgcn_exp2f(c * __builtin_fmaf(-0.10294324f, c * c, -2.3022082f)));
;                     gsv[k] = ge * (acc[ai][1][m][k >> 2][k & 3] * rs[ai][m]);
;                 }
;                 if (row >= out_lo && row < out_hi) {
;                     u32x4 w; w.x = cvt_pk_bf16(gsv[0], gsv[1]); w.y = cvt_pk_bf16(gsv[2], gsv[3]); w.z = cvt_pk_bf16(gsv[4], gsv[5]); w.w = cvt_pk_bf16(gsv[6], gsv[7]);
;                     *(GAS u32x4*)(Gout + (size_t)row * DFF + f0) = w; }
.LBB0_821:
	v_add_u32_e32 v93, 48, v174
	v_cmp_le_i32_e32 vcc, s41, v93
	v_cmp_gt_i32_e64 s[12:13], s76, v93
	s_and_b64 s[12:13], vcc, s[12:13]
	s_and_saveexec_b64 s[28:29], s[12:13]
	s_cbranch_execz .LBB0_823
	v_and_b32_e32 v106, s7, v93
	v_cmp_eq_u32_e64 s[12:13], 0, v106
	v_cmp_eq_u32_e32 vcc, s7, v106
	s_waitcnt lgkmcnt(0)
	v_cndmask_b32_e64 v106, v114, v115, s[10:11]
	v_cndmask_b32_e64 v108, v108, 0, s[12:13]
	v_mul_f32_e32 v108, v28, v108
	v_cndmask_b32_e64 v106, v106, 0, vcc
	v_fmac_f32_e32 v108, v40, v212
	v_fmac_f32_e32 v108, v32, v106
	v_add_f32_e32 v106, v36, v108
	v_mul_f32_e32 v108, v106, v106
	v_fmamk_f32 v108, v108, 0xbdd2d3e8, v225
	v_mul_f32_e32 v108, v106, v108
	v_exp_f32_e32 v108, v108
	v_mul_f32_e32 v84, v84, v178
	v_mul_f32_e32 v83, v83, v178
	v_cndmask_b32_e64 v107, v107, 0, s[12:13]
	v_add_f32_e32 v108, 1.0, v108
	v_rcp_f32_e32 v108, v108
	v_mul_f32_e32 v107, v26, v107
	v_fmac_f32_e32 v107, v38, v211
	v_mul_f32_e32 v82, v82, v178
	v_mul_f32_e32 v106, v106, v108
	v_cndmask_b32_e64 v108, v110, 0, s[12:13]
	v_mul_f32_e32 v106, v84, v106
	v_cndmask_b32_e64 v84, v113, v112, s[10:11]
	v_mul_f32_e32 v108, v27, v108
	v_cndmask_b32_e64 v84, v84, 0, vcc
	v_fmac_f32_e32 v108, v39, v151
	v_fmac_f32_e32 v108, v31, v84
	v_add_f32_e32 v84, v35, v108
	v_mul_f32_e32 v108, v84, v84
	v_fmamk_f32 v108, v108, 0xbdd2d3e8, v225
	v_mul_f32_e32 v108, v84, v108
	v_exp_f32_e32 v108, v108
	v_cndmask_b32_e64 v151, v99, 0, s[12:13]
	v_add_f32_e32 v108, 1.0, v108
	v_rcp_f32_e32 v108, v108
	s_nop 0
	v_mul_f32_e32 v84, v84, v108
	v_mul_f32_e32 v84, v83, v84
	v_cndmask_b32_e64 v83, v109, v111, s[10:11]
	v_cndmask_b32_e64 v83, v83, 0, vcc
	v_fmac_f32_e32 v107, v30, v83
	v_add_f32_e32 v83, v34, v107
	v_mul_f32_e32 v107, v83, v83
	v_fmamk_f32 v107, v107, 0xbdd2d3e8, v225
	v_mul_f32_e32 v107, v83, v107
	v_exp_f32_e32 v107, v107
	s_nop 0
	v_add_f32_e32 v107, 1.0, v107
	v_rcp_f32_e32 v107, v107
	s_nop 0
	v_mul_f32_e32 v83, v83, v107
	v_mul_f32_e32 v107, v82, v83
	v_cndmask_b32_e64 v83, v104, 0, s[12:13]
	v_cndmask_b32_e64 v82, v105, v103, s[10:11]
	v_mul_f32_e32 v83, v45, v83
	v_cndmask_b32_e64 v82, v82, 0, vcc
	v_fmac_f32_e32 v83, v49, v210
	v_fmac_f32_e32 v83, v53, v82
	v_add_f32_e32 v82, v57, v83
	v_mul_f32_e32 v83, v82, v82
	v_fmamk_f32 v83, v83, 0xbdd2d3e8, v225
	v_mul_f32_e32 v83, v82, v83
	v_exp_f32_e32 v83, v83
	v_cvt_pk_bf16_f32 v84, v107, v84
	s_nop 0
	v_add_f32_e32 v83, 1.0, v83
	v_rcp_f32_e32 v83, v83
	s_nop 0
	v_mul_f32_e32 v82, v82, v83
	v_mul_f32_e32 v83, v89, v178
	v_mul_f32_e32 v89, v83, v82
	v_cndmask_b32_e64 v83, v100, 0, s[12:13]
	v_cndmask_b32_e64 v82, v101, v102, s[10:11]
	v_mul_f32_e32 v83, v44, v83
	v_cndmask_b32_e64 v82, v82, 0, vcc
	v_fmac_f32_e32 v83, v48, v209
	v_fmac_f32_e32 v83, v52, v82
	v_add_f32_e32 v82, v56, v83
	v_mul_f32_e32 v83, v82, v82
	v_fmamk_f32 v83, v83, 0xbdd2d3e8, v225
	v_mul_f32_e32 v83, v82, v83
	v_exp_f32_e32 v83, v83
	s_nop 0
	v_add_f32_e32 v83, 1.0, v83
	v_rcp_f32_e32 v83, v83
	s_nop 0
	v_mul_f32_e32 v82, v82, v83
	v_mul_f32_e32 v83, v88, v178
	v_mul_f32_e32 v88, v83, v82
	v_cndmask_b32_e64 v83, v96, 0, s[12:13]
	v_cndmask_b32_e64 v82, v98, v94, s[10:11]
	v_mul_f32_e32 v83, v43, v83
	v_cndmask_b32_e64 v82, v82, 0, vcc
	v_fmac_f32_e32 v83, v47, v208
	v_fmac_f32_e32 v83, v51, v82
	v_add_f32_e32 v82, v55, v83
	v_mul_f32_e32 v83, v82, v82
	v_fmamk_f32 v83, v83, 0xbdd2d3e8, v225
	v_mul_f32_e32 v83, v82, v83
	v_exp_f32_e32 v83, v83
	s_nop 0
	v_add_f32_e32 v83, 1.0, v83
	v_rcp_f32_e32 v83, v83
	s_nop 0
	v_mul_f32_e32 v82, v82, v83
	v_mul_f32_e32 v83, v87, v178
	v_mul_f32_e32 v87, v83, v82
	v_cndmask_b32_e64 v83, v90, 0, s[12:13]
	v_cndmask_b32_e64 v82, v91, v92, s[10:11]
	v_mul_f32_e32 v83, v42, v83
	v_cndmask_b32_e64 v82, v82, 0, vcc
	v_fmac_f32_e32 v83, v46, v179
	v_fmac_f32_e32 v83, v50, v82
	v_add_f32_e32 v82, v54, v83
	v_mul_f32_e32 v83, v82, v82
	v_fmamk_f32 v83, v83, 0xbdd2d3e8, v225
	v_mul_f32_e32 v83, v82, v83
	v_exp_f32_e32 v83, v83
	s_nop 0
	v_add_f32_e32 v83, 1.0, v83
	v_rcp_f32_e32 v83, v83
	s_nop 0
	v_mul_f32_e32 v82, v82, v83
	v_mul_f32_e32 v83, v86, v178
	v_mul_f32_e32 v86, v83, v82
	v_mov_b32_e32 v82, v41
	v_mov_b32_e32 v83, v29
	v_mul_f32_e32 v82, v82, v150
	v_mul_f32_e32 v83, v83, v151
	s_nop 0
	v_add_f32_e32 v82, v82, v83
	v_cndmask_b32_e64 v83, v97, v95, s[10:11]
	v_cndmask_b32_e64 v83, v83, 0, vcc
	v_fmac_f32_e32 v82, v33, v83
	v_add_f32_e32 v83, v37, v82
	v_mul_f32_e32 v82, v83, v83
	v_fmamk_f32 v82, v82, 0xbdd2d3e8, v225
	v_mul_f32_e32 v82, v83, v82
	v_exp_f32_e32 v82, v82
	s_nop 0
	v_add_f32_e32 v82, 1.0, v82
	v_rcp_f32_e32 v179, v82
	v_mov_b32_e32 v82, v85
	v_mul_f32_e32 v82, v82, v178
	v_mul_f32_e32 v83, v83, v179
	s_nop 0
	v_mul_f32_e32 v85, v82, v83
	v_cvt_pk_bf16_f32 v82, v86, v87
	v_mov_b64_e32 v[86:87], s[4:5]
	v_mad_i64_i32 v[86:87], s[12:13], v93, s1, v[86:87]
	v_lshl_add_u64 v[86:87], v[172:173], 1, v[86:87]
	v_cvt_pk_bf16_f32 v83, v88, v89
	v_cvt_pk_bf16_f32 v85, v106, v85
	global_store_dwordx4 v[86:87], v[82:85], off

; #define GAS __attribute__((address_space(1)))
; __device__ __forceinline__ unsigned cvt_pk_bf16(float lo, float hi) { unsigned r; asm("v_cvt_pk_bf16_f32 %0, %1, %2" : "=v"(r) : "v"(lo), "v"(hi)); return r; }
; template <int CTRL> __device__ __forceinline__ float dpp_mov(float v) { return __int_as_float(__builtin_amdgcn_update_dpp(0, __float_as_int(v), CTRL, 0xf, 0xf, false)); }
;     __device__ __forceinline__ void operator()(const f32x4 (&acc)[2][2][4][2], const Unit& u, int wr, int wc, int fr, int fq) const {
;     ...
;                 for (int k = 0; k < 8; ++k) {
;                     const float am = acc[ai][0][m][k >> 2][k & 3] * rs[ai][m];
;                     float sp, sn;
;                     if (m > 0) sp = fr == 15 ? acc[ai][0][m - 1][k >> 2][k & 3] * rs[ai][m - 1] : am; else sp = am;
;                     if (m < 3) sn = fr == 0 ? acc[ai][0][m + 1][k >> 2][k & 3] * rs[ai][m + 1] : am; else sn = am;
;                     float pv = dpp_mov<0x121>(sp), nv = dpp_mov<0x12F>(sn);
;                     if (m == 0) { const float e = chunk > 0 ? xch[((chunk - 1) * 2 + 1) * 128 + colh + k] : 0.f; pv = fr == 0 ? e : pv; }
;                     if (m == 3) { const float e = chunk < 3 ? xch[((chunk + 1) * 2 + 0) * 128 + colh + k] : 0.f; nv = fr == 15 ? e : nv; }
;                     pv = pos == 0 ? 0.f : pv; nv = pos == S - 1 ? 0.f : nv;
;                     const float c = pv * w0[k] + am * w1[k] + nv * w2[k] + bb[k];
;                     const float ge = c * __builtin_amdgcn_rcpf(1.f + __builtin_amdgcn_exp2f(c * __builtin_fmaf(-0.10294324f, c * c, -2.3022082f)));
;                     gsv[k] = ge * (acc[ai][1][m][k >> 2][k & 3] * rs[ai][m]);
;                 }
;                 if (row >= out_lo && row < out_hi) {
;                     u32x4 w; w.x = cvt_pk_bf16(gsv[0], gsv[1]); w.y = cvt_pk_bf16(gsv[2], gsv[3]); w.z = cvt_pk_bf16(gsv[4], gsv[5]); w.w = cvt_pk_bf16(gsv[6], gsv[7]);
;                     *(GAS u32x4*)(Gout + (size_t)row * DFF + f0) = w; }
.LBB0_839:
	v_add_u32_e32 v75, 0x80, v174
	v_cmp_le_i32_e32 vcc, s41, v75
	v_cmp_gt_i32_e64 s[12:13], s76, v75
	s_and_b64 s[12:13], vcc, s[12:13]
	s_and_saveexec_b64 s[28:29], s[12:13]
	s_cbranch_execz .LBB0_841
	v_and_b32_e32 v108, s7, v75
	v_cmp_eq_u32_e64 s[12:13], 0, v108
	s_waitcnt lgkmcnt(0)
	v_cndmask_b32_e64 v106, v106, v107, s[26:27]
	v_cmp_eq_u32_e32 vcc, s7, v108
	v_cndmask_b32_e64 v106, v106, 0, s[12:13]
	v_mul_f32_e32 v106, v28, v106
	v_cndmask_b32_e64 v105, v105, 0, vcc
	v_fmac_f32_e32 v106, v40, v201
	v_fmac_f32_e32 v106, v32, v105
	v_add_f32_e32 v105, v36, v106
	v_mul_f32_e32 v106, v105, v105
	v_fmamk_f32 v106, v106, 0xbdd2d3e8, v225
	v_mul_f32_e32 v106, v105, v106
	v_exp_f32_e32 v106, v106
	v_mul_f32_e32 v68, v68, v148
	v_mul_f32_e32 v67, v67, v148
	v_mul_f32_e32 v66, v66, v148
	v_add_f32_e32 v106, 1.0, v106
	v_rcp_f32_e32 v106, v106
	s_nop 0
	v_mul_f32_e32 v105, v105, v106
	v_mul_f32_e32 v105, v68, v105
	v_cndmask_b32_e64 v68, v103, v102, s[26:27]
	v_cndmask_b32_e64 v68, v68, 0, s[12:13]
	v_mul_f32_e32 v68, v27, v68
	v_cndmask_b32_e64 v102, v104, 0, vcc
	v_fmac_f32_e32 v68, v39, v200
	v_fmac_f32_e32 v68, v31, v102
	v_add_f32_e32 v68, v35, v68
	v_mul_f32_e32 v102, v68, v68
	v_fmamk_f32 v102, v102, 0xbdd2d3e8, v225
	v_mul_f32_e32 v102, v68, v102
	v_exp_f32_e32 v102, v102
	s_nop 0
	v_add_f32_e32 v102, 1.0, v102
	v_rcp_f32_e32 v102, v102
	s_nop 0
	v_mul_f32_e32 v68, v68, v102
	v_mul_f32_e32 v68, v67, v68
	v_cndmask_b32_e64 v67, v99, v101, s[26:27]
	v_cndmask_b32_e64 v67, v67, 0, s[12:13]
	v_mul_f32_e32 v67, v26, v67
	v_cndmask_b32_e64 v99, v100, 0, vcc
	v_fmac_f32_e32 v67, v38, v175
	v_fmac_f32_e32 v67, v30, v99
	v_add_f32_e32 v67, v34, v67
	v_mul_f32_e32 v99, v67, v67
	v_fmamk_f32 v99, v99, 0xbdd2d3e8, v225
	v_mul_f32_e32 v99, v67, v99
	v_exp_f32_e32 v99, v99
	s_nop 0
	v_add_f32_e32 v99, 1.0, v99
	v_rcp_f32_e32 v99, v99
	s_nop 0
	v_mul_f32_e32 v67, v67, v99
	v_mul_f32_e32 v99, v66, v67
	v_cndmask_b32_e64 v66, v97, v96, s[26:27]
	v_cndmask_b32_e64 v66, v66, 0, s[12:13]
	v_mul_f32_e32 v66, v45, v66
	v_cndmask_b32_e64 v67, v98, 0, vcc
	v_fmac_f32_e32 v66, v49, v161
	v_fmac_f32_e32 v66, v53, v67
	v_add_f32_e32 v66, v57, v66
	v_mul_f32_e32 v67, v66, v66
	v_fmamk_f32 v67, v67, 0xbdd2d3e8, v225
	v_mul_f32_e32 v67, v66, v67
	v_exp_f32_e32 v67, v67
	v_cvt_pk_bf16_f32 v68, v99, v68
	s_nop 0
	v_add_f32_e32 v67, 1.0, v67
	v_rcp_f32_e32 v67, v67
	s_nop 0
	v_mul_f32_e32 v66, v66, v67
	v_mul_f32_e32 v67, v73, v148
	v_mul_f32_e32 v73, v67, v66
	v_cndmask_b32_e64 v66, v93, v95, s[26:27]
	v_cndmask_b32_e64 v66, v66, 0, s[12:13]
	v_mul_f32_e32 v66, v44, v66
	v_cndmask_b32_e64 v67, v94, 0, vcc
	v_fmac_f32_e32 v66, v48, v160
	v_fmac_f32_e32 v66, v52, v67
	v_add_f32_e32 v66, v56, v66
	v_mul_f32_e32 v67, v66, v66
	v_fmamk_f32 v67, v67, 0xbdd2d3e8, v225
	v_mul_f32_e32 v67, v66, v67
	v_exp_f32_e32 v67, v67
	s_nop 0
	v_add_f32_e32 v67, 1.0, v67
	v_rcp_f32_e32 v67, v67
	s_nop 0
	v_mul_f32_e32 v66, v66, v67
	v_mul_f32_e32 v67, v72, v148
	v_mul_f32_e32 v72, v67, v66
	v_cndmask_b32_e64 v66, v79, v89, s[26:27]
	v_cndmask_b32_e64 v66, v66, 0, s[12:13]
	v_mul_f32_e32 v66, v43, v66
	v_cndmask_b32_e64 v67, v90, 0, vcc
	v_fmac_f32_e32 v66, v47, v159
	v_fmac_f32_e32 v66, v51, v67
	v_add_f32_e32 v66, v55, v66
	v_mul_f32_e32 v67, v66, v66
	v_fmamk_f32 v67, v67, 0xbdd2d3e8, v225
	v_mul_f32_e32 v67, v66, v67
	v_exp_f32_e32 v67, v67
	s_nop 0
	v_add_f32_e32 v67, 1.0, v67
	v_rcp_f32_e32 v67, v67
	s_nop 0
	v_mul_f32_e32 v66, v66, v67
	v_mul_f32_e32 v67, v71, v148
	v_mul_f32_e32 v71, v67, v66
	v_cndmask_b32_e64 v66, v83, v87, s[26:27]
	v_cndmask_b32_e64 v66, v66, 0, s[12:13]
	v_mul_f32_e32 v66, v42, v66
	v_cndmask_b32_e64 v67, v85, 0, vcc
	v_fmac_f32_e32 v66, v46, v158
	v_fmac_f32_e32 v66, v50, v67
	v_add_f32_e32 v66, v54, v66
	v_mul_f32_e32 v67, v66, v66
	v_fmamk_f32 v67, v67, 0xbdd2d3e8, v225
	v_mul_f32_e32 v67, v66, v67
	v_exp_f32_e32 v67, v67
	s_nop 0
	v_add_f32_e32 v67, 1.0, v67
	v_rcp_f32_e32 v67, v67
	s_nop 0
	v_mul_f32_e32 v66, v66, v67
	v_mul_f32_e32 v67, v70, v148
	v_mul_f32_e32 v70, v67, v66
	v_cndmask_b32_e64 v66, v92, v81, s[26:27]
	v_cndmask_b32_e64 v133, v66, 0, s[12:13]
	v_mov_b32_e32 v66, v41
	v_mov_b32_e32 v67, v29
	v_mul_f32_e32 v66, v66, v132
	v_mul_f32_e32 v67, v67, v133
	s_nop 0
	v_add_f32_e32 v66, v66, v67
	v_cndmask_b32_e64 v67, v77, 0, vcc
	v_fmac_f32_e32 v66, v33, v67
	v_add_f32_e32 v67, v37, v66
	v_mul_f32_e32 v66, v67, v67
	v_fmamk_f32 v66, v66, 0xbdd2d3e8, v225
	v_mul_f32_e32 v66, v67, v66
	v_exp_f32_e32 v66, v66
	s_nop 0
	v_add_f32_e32 v66, 1.0, v66
	v_rcp_f32_e32 v149, v66
	v_mov_b32_e32 v66, v69
	v_mul_f32_e32 v66, v66, v148
	v_mul_f32_e32 v67, v67, v149
	s_nop 0
	v_mul_f32_e32 v69, v66, v67
	v_cvt_pk_bf16_f32 v66, v70, v71
	v_mov_b64_e32 v[70:71], s[4:5]
	v_mad_i64_i32 v[70:71], s[12:13], v75, s1, v[70:71]
	v_lshl_add_u64 v[70:71], v[172:173], 1, v[70:71]
	v_cvt_pk_bf16_f32 v67, v72, v73
	v_cvt_pk_bf16_f32 v69, v105, v69
	global_store_dwordx4 v[70:71], v[66:69], off
; #define GAS __attribute__((address_space(1)))
; __device__ __forceinline__ unsigned cvt_pk_bf16(float lo, float hi) { unsigned r; asm("v_cvt_pk_bf16_f32 %0, %1, %2" : "=v"(r) : "v"(lo), "v"(hi)); return r; }
; template <int CTRL> __device__ __forceinline__ float dpp_mov(float v) { return __int_as_float(__builtin_amdgcn_update_dpp(0, __float_as_int(v), CTRL, 0xf, 0xf, false)); }
; __device__ __forceinline__ float rstd_of(unsigned long long ssq) { return __builtin_amdgcn_rsqf((float)ssq * (1.f / (1024.f * 1048576.f)) + EPS); }
;     __device__ __forceinline__ void operator()(const f32x4 (&acc)[2][2][4][2], const Unit& u, int wr, int wc, int fr, int fq) const {
;     ...
;               for (int m = 0; m < 4; ++m) rs[ai][m] = rstd_of(q[ai][m]); }
;     ...
;                 const int chunk = ai * 2 + wr, row = base + ai * HALF + wr * 64 + m * 16 + fr, pos = row & (S - 1);
;                 float gsv[8];
; #pragma unroll
;                 for (int k = 0; k < 8; ++k) {
;                     const float am = acc[ai][0][m][k >> 2][k & 3] * rs[ai][m];
;                     float sp, sn;
;                     if (m > 0) sp = fr == 15 ? acc[ai][0][m - 1][k >> 2][k & 3] * rs[ai][m - 1] : am; else sp = am;
;                     if (m < 3) sn = fr == 0 ? acc[ai][0][m + 1][k >> 2][k & 3] * rs[ai][m + 1] : am; else sn = am;
;                     float pv = dpp_mov<0x121>(sp), nv = dpp_mov<0x12F>(sn);
;                     if (m == 0) { const float e = chunk > 0 ? xch[((chunk - 1) * 2 + 1) * 128 + colh + k] : 0.f; pv = fr == 0 ? e : pv; }
;                     if (m == 3) { const float e = chunk < 3 ? xch[((chunk + 1) * 2 + 0) * 128 + colh + k] : 0.f; nv = fr == 15 ? e : nv; }
;                     pv = pos == 0 ? 0.f : pv; nv = pos == S - 1 ? 0.f : nv;
;                     const float c = pv * w0[k] + am * w1[k] + nv * w2[k] + bb[k];
;                     const float ge = c * __builtin_amdgcn_rcpf(1.f + __builtin_amdgcn_exp2f(c * __builtin_fmaf(-0.10294324f, c * c, -2.3022082f)));
;                     gsv[k] = ge * (acc[ai][1][m][k >> 2][k & 3] * rs[ai][m]);
;                 }
;                 if (row >= out_lo && row < out_hi) {
;                     u32x4 w; w.x = cvt_pk_bf16(gsv[0], gsv[1]); w.y = cvt_pk_bf16(gsv[2], gsv[3]); w.z = cvt_pk_bf16(gsv[4], gsv[5]); w.w = cvt_pk_bf16(gsv[6], gsv[7]);
;                     *(GAS u32x4*)(Gout + (size_t)row * DFF + f0) = w; }
.LBB0_841:
	s_or_b64 exec, exec, s[28:29]
	s_nop 0
	v_ffbh_u32_e32 v66, v177
	v_min_u32_e32 v68, 32, v66
	v_lshlrev_b64 v[66:67], v68, v[176:177]
	v_min_u32_e32 v66, 1, v66
	v_or_b32_e32 v66, v67, v66
	v_cvt_f32_u32_e32 v66, v66
	v_sub_u32_e32 v68, 32, v68
	v_cndmask_b32_e64 v70, v78, v158, s[10:11]
	v_mov_b32_e32 v71, v1
	v_ldexp_f32 v66, v66, v68
	v_fmamk_f32 v66, v66, 0x30800000, v218
	v_rsq_f32_e32 v90, v66
	v_mov_b32_e32 v69, v1
	v_mov_b32_dpp v71, v70 row_ror:1 row_mask:0xf bank_mask:0xf
	v_mov_b32_e32 v73, v1
	v_mul_f32_e32 v72, v62, v90
	v_cndmask_b32_e64 v62, v78, v72, s[26:27]
	v_mul_f32_e32 v70, v63, v90
	v_cndmask_b32_e64 v66, v84, v70, s[26:27]
	v_mov_b32_dpp v69, v62 row_ror:15 row_mask:0xf bank_mask:0xf
	v_cndmask_b32_e64 v62, v84, v159, s[10:11]
	v_mov_b32_e32 v63, v1
	v_mul_f32_e32 v68, v64, v90
	v_mov_b32_dpp v73, v62 row_ror:1 row_mask:0xf bank_mask:0xf
	v_mov_b32_dpp v63, v66 row_ror:15 row_mask:0xf bank_mask:0xf
	v_cndmask_b32_e64 v62, v80, v160, s[10:11]
	v_cndmask_b32_e64 v64, v80, v68, s[26:27]
	v_mov_b32_e32 v79, v1
	v_mov_b32_e32 v77, v1
	v_mul_f32_e32 v66, v65, v90
	v_mov_b32_dpp v79, v62 row_ror:1 row_mask:0xf bank_mask:0xf
	v_mov_b32_dpp v77, v64 row_ror:15 row_mask:0xf bank_mask:0xf
	v_cndmask_b32_e64 v62, v86, v161, s[10:11]
	v_cndmask_b32_e64 v64, v86, v66, s[26:27]
	s_waitcnt lgkmcnt(0)
	v_mov_b32_e32 v81, v1
	v_mov_b32_e32 v65, v1
	v_mov_b32_e32 v75, v1
	v_mov_b32_dpp v81, v62 row_ror:1 row_mask:0xf bank_mask:0xf
	v_mov_b32_dpp v65, v64 row_ror:15 row_mask:0xf bank_mask:0xf
	v_cndmask_b32_e64 v62, v74, v175, s[10:11]
	v_mul_f32_e32 v64, v58, v90
	v_cndmask_b32_e64 v58, v74, v64, s[26:27]
	v_mov_b32_dpp v75, v62 row_ror:1 row_mask:0xf bank_mask:0xf
	v_mov_b32_e32 v85, v1
	v_mul_f32_e32 v62, v59, v90
	v_cndmask_b32_e64 v59, v88, v62, s[26:27]
	v_mov_b32_dpp v85, v58 row_ror:15 row_mask:0xf bank_mask:0xf
	v_cndmask_b32_e64 v58, v88, v200, s[10:11]
	v_mov_b32_e32 v89, v1
	v_mov_b32_e32 v87, v1
	v_mul_f32_e32 v60, v60, v90
	v_mov_b32_dpp v89, v58 row_ror:1 row_mask:0xf bank_mask:0xf
	v_mov_b32_dpp v87, v59 row_ror:15 row_mask:0xf bank_mask:0xf
	v_cndmask_b32_e64 v58, v91, v201, s[10:11]
	v_cndmask_b32_e64 v59, v91, v60, s[26:27]
	v_mov_b32_e32 v83, v1
	v_mov_b32_e32 v92, v1
	v_add_u32_e32 v67, 0x90, v174
	v_mov_b32_dpp v83, v58 row_ror:1 row_mask:0xf bank_mask:0xf
	v_mov_b32_dpp v92, v59 row_ror:15 row_mask:0xf bank_mask:0xf
	v_cndmask_b32_e64 v59, v76, v132, s[10:11]
	v_mul_f32_e32 v58, v61, v90
	v_mov_b32_e32 v61, v1
	v_cndmask_b32_e64 v93, v76, v58, s[26:27]
	v_cmp_le_i32_e32 vcc, s41, v67
	v_mov_b32_dpp v61, v59 row_ror:1 row_mask:0xf bank_mask:0xf
	v_mov_b32_e32 v59, v1
	v_cmp_gt_i32_e64 s[12:13], s76, v67
	s_and_b64 s[12:13], vcc, s[12:13]
	v_mov_b32_dpp v59, v93 row_ror:15 row_mask:0xf bank_mask:0xf
	s_and_saveexec_b64 s[28:29], s[12:13]
	s_cbranch_execz .LBB0_843
	v_and_b32_e32 v93, s7, v67
	v_cmp_eq_u32_e64 s[12:13], 0, v93
	v_cmp_eq_u32_e32 vcc, s7, v93
	v_mov_b32_e32 v94, v28
	v_mov_b32_e32 v95, v32
	v_cndmask_b32_e64 v93, v92, 0, vcc
	v_cndmask_b32_e64 v92, v83, 0, s[12:13]
	v_mul_f32_e32 v92, v94, v92
	v_mul_f32_e32 v93, v95, v93
	v_cndmask_b32_e64 v89, v89, 0, s[12:13]
	v_fma_f32 v83, v40, v91, v92
	v_add_f32_e32 v83, v83, v93
	v_add_f32_e32 v93, v36, v83
	v_mul_f32_e32 v83, v93, v93
	v_fmamk_f32 v83, v83, 0xbdd2d3e8, v225
	v_mul_f32_e32 v83, v93, v83
	v_exp_f32_e32 v83, v83
	v_mov_b32_e32 v92, v20
	v_cndmask_b32_e64 v75, v75, 0, s[12:13]
	v_add_f32_e32 v83, 1.0, v83
	v_rcp_f32_e32 v83, v83
	s_nop 0
	v_mul_f32_e32 v92, v92, v82
	v_mul_f32_e32 v93, v93, v83
	s_nop 0
	v_mul_f32_e32 v94, v92, v93
	v_mov_b32_e32 v92, v39
	v_mov_b32_e32 v93, v27
	v_mul_f32_e32 v92, v92, v88
	v_mul_f32_e32 v93, v93, v89
	v_cndmask_b32_e64 v83, v87, 0, vcc
	v_add_f32_e32 v20, v92, v93
	v_fmac_f32_e32 v20, v31, v83
	v_add_f32_e32 v93, v35, v20
	v_mul_f32_e32 v20, v93, v93
	v_fmamk_f32 v20, v20, 0xbdd2d3e8, v225
	v_mul_f32_e32 v20, v93, v20
	v_exp_f32_e32 v20, v20
	v_mov_b32_e32 v92, v19
	v_cndmask_b32_e64 v87, v81, 0, s[12:13]
	v_cndmask_b32_e64 v81, v79, 0, s[12:13]
	v_add_f32_e32 v20, 1.0, v20
	v_rcp_f32_e32 v83, v20
	v_cndmask_b32_e64 v79, v71, 0, s[12:13]
	v_mul_f32_e32 v92, v92, v82
	v_mul_f32_e32 v93, v93, v83
	s_nop 0
	v_mul_f32_e32 v20, v92, v93
	v_mov_b32_e32 v92, v38
	v_mov_b32_e32 v93, v26
	v_mul_f32_e32 v92, v92, v74
	v_mul_f32_e32 v93, v93, v75
	v_cndmask_b32_e64 v75, v85, 0, vcc
	v_add_f32_e32 v19, v92, v93
	v_fmac_f32_e32 v19, v30, v75
	v_add_f32_e32 v19, v34, v19
	v_mul_f32_e32 v75, v19, v19
	v_fmamk_f32 v75, v75, 0xbdd2d3e8, v225
	v_mul_f32_e32 v75, v19, v75
	v_exp_f32_e32 v75, v75
	v_cndmask_b32_e64 v85, v73, 0, s[12:13]
	v_add_f32_e32 v75, 1.0, v75
	v_rcp_f32_e32 v83, v75
	s_nop 0
	v_mul_f32_e32 v18, v18, v82
	v_mul_f32_e32 v19, v19, v83
	s_nop 0
	v_mul_f32_e32 v75, v18, v19
	v_mov_b32_e32 v18, v49
	v_mov_b32_e32 v19, v45
	v_mul_f32_e32 v18, v18, v86
	v_mul_f32_e32 v19, v19, v87
	v_cvt_pk_bf16_f32 v20, v75, v20
	s_nop 0
	v_add_f32_e32 v18, v18, v19
	v_cndmask_b32_e64 v19, v65, 0, vcc
	v_fmac_f32_e32 v18, v53, v19
	v_add_f32_e32 v19, v57, v18
	v_mul_f32_e32 v18, v19, v19
	v_fmamk_f32 v18, v18, 0xbdd2d3e8, v225
	v_mul_f32_e32 v18, v19, v18
	v_exp_f32_e32 v18, v18
	s_nop 0
	v_add_f32_e32 v18, 1.0, v18
	v_rcp_f32_e32 v83, v18
	v_mov_b32_e32 v18, v25
	v_mul_f32_e32 v18, v18, v82
	v_mul_f32_e32 v19, v19, v83
	s_nop 0
	v_mul_f32_e32 v65, v18, v19
	v_mov_b32_e32 v18, v48
	v_mov_b32_e32 v19, v44
	v_mul_f32_e32 v18, v18, v80
	v_mul_f32_e32 v19, v19, v81
	s_nop 0
	v_add_f32_e32 v18, v18, v19
	v_cndmask_b32_e64 v19, v77, 0, vcc
	v_fmac_f32_e32 v18, v52, v19
	v_add_f32_e32 v25, v56, v18
	v_mul_f32_e32 v18, v25, v25
; #define GAS __attribute__((address_space(1)))
; __device__ __forceinline__ unsigned cvt_pk_bf16(float lo, float hi) { unsigned r; asm("v_cvt_pk_bf16_f32 %0, %1, %2" : "=v"(r) : "v"(lo), "v"(hi)); return r; }
; template <int CTRL> __device__ __forceinline__ float dpp_mov(float v) { return __int_as_float(__builtin_amdgcn_update_dpp(0, __float_as_int(v), CTRL, 0xf, 0xf, false)); }
;     __device__ __forceinline__ void operator()(const f32x4 (&acc)[2][2][4][2], const Unit& u, int wr, int wc, int fr, int fq) const {
;     ...
;                 for (int k = 0; k < 8; ++k) {
;                     const float am = acc[ai][0][m][k >> 2][k & 3] * rs[ai][m];
;                     float sp, sn;
;                     if (m > 0) sp = fr == 15 ? acc[ai][0][m - 1][k >> 2][k & 3] * rs[ai][m - 1] : am; else sp = am;
;                     if (m < 3) sn = fr == 0 ? acc[ai][0][m + 1][k >> 2][k & 3] * rs[ai][m + 1] : am; else sn = am;
;                     float pv = dpp_mov<0x121>(sp), nv = dpp_mov<0x12F>(sn);
;                     if (m == 0) { const float e = chunk > 0 ? xch[((chunk - 1) * 2 + 1) * 128 + colh + k] : 0.f; pv = fr == 0 ? e : pv; }
;                     if (m == 3) { const float e = chunk < 3 ? xch[((chunk + 1) * 2 + 0) * 128 + colh + k] : 0.f; nv = fr == 15 ? e : nv; }
;                     pv = pos == 0 ? 0.f : pv; nv = pos == S - 1 ? 0.f : nv;
;                     const float c = pv * w0[k] + am * w1[k] + nv * w2[k] + bb[k];
;                     const float ge = c * __builtin_amdgcn_rcpf(1.f + __builtin_amdgcn_exp2f(c * __builtin_fmaf(-0.10294324f, c * c, -2.3022082f)));
;                     gsv[k] = ge * (acc[ai][1][m][k >> 2][k & 3] * rs[ai][m]);
;                 }
;                 if (row >= out_lo && row < out_hi) {
;                     u32x4 w; w.x = cvt_pk_bf16(gsv[0], gsv[1]); w.y = cvt_pk_bf16(gsv[2], gsv[3]); w.z = cvt_pk_bf16(gsv[4], gsv[5]); w.w = cvt_pk_bf16(gsv[6], gsv[7]);
;                     *(GAS u32x4*)(Gout + (size_t)row * DFF + f0) = w; }
	v_fmamk_f32 v18, v18, 0xbdd2d3e8, v225
	v_mul_f32_e32 v18, v25, v18
	v_exp_f32_e32 v18, v18
	v_cndmask_b32_e64 v77, v61, 0, s[12:13]
	v_add_f32_e32 v18, 1.0, v18
	v_rcp_f32_e32 v83, v18
	s_nop 0
	v_mul_f32_e32 v18, v24, v82
	v_mul_f32_e32 v19, v25, v83
	s_nop 0
	v_mul_f32_e32 v24, v18, v19
	v_mov_b32_e32 v18, v47
	v_mov_b32_e32 v19, v43
	v_mul_f32_e32 v18, v18, v84
	v_mul_f32_e32 v19, v19, v85
	s_nop 0
	v_add_f32_e32 v18, v18, v19
	v_cndmask_b32_e64 v19, v63, 0, vcc
	v_fmac_f32_e32 v18, v51, v19
	v_add_f32_e32 v19, v55, v18
	v_mul_f32_e32 v18, v19, v19
	v_fmamk_f32 v18, v18, 0xbdd2d3e8, v225
	v_mul_f32_e32 v18, v19, v18
	v_exp_f32_e32 v18, v18
	s_nop 0
	v_add_f32_e32 v18, 1.0, v18
	v_rcp_f32_e32 v83, v18
	v_mov_b32_e32 v18, v23
	v_mul_f32_e32 v18, v18, v82
	v_mul_f32_e32 v19, v19, v83
	s_nop 0
	v_mul_f32_e32 v25, v18, v19
	v_mov_b32_e32 v18, v46
	v_mov_b32_e32 v19, v42
	v_mul_f32_e32 v18, v18, v78
	v_mul_f32_e32 v19, v19, v79
	s_nop 0
	v_add_f32_e32 v18, v18, v19
	v_cndmask_b32_e64 v19, v69, 0, vcc
	v_fmac_f32_e32 v18, v50, v19
	v_add_f32_e32 v23, v54, v18
	v_mul_f32_e32 v18, v23, v23
	v_fmamk_f32 v18, v18, 0xbdd2d3e8, v225
	v_mul_f32_e32 v18, v23, v18
	v_exp_f32_e32 v18, v18
	s_nop 0
	v_add_f32_e32 v18, 1.0, v18
	v_rcp_f32_e32 v83, v18
	s_nop 0
	v_mul_f32_e32 v18, v22, v82
	v_mul_f32_e32 v19, v23, v83
	s_nop 0
	v_mul_f32_e32 v22, v18, v19
	v_mov_b32_e32 v18, v41
	v_mov_b32_e32 v19, v29
	v_mul_f32_e32 v18, v18, v76
	v_mul_f32_e32 v19, v19, v77
	s_nop 0
	v_add_f32_e32 v18, v18, v19
	v_cndmask_b32_e64 v19, v59, 0, vcc
	v_fmac_f32_e32 v18, v33, v19
	v_add_f32_e32 v19, v37, v18
	v_mul_f32_e32 v18, v19, v19
	v_fmamk_f32 v18, v18, 0xbdd2d3e8, v225
	v_mul_f32_e32 v18, v19, v18
	v_exp_f32_e32 v18, v18
	s_nop 0
	v_add_f32_e32 v18, 1.0, v18
	v_rcp_f32_e32 v83, v18
	v_mov_b32_e32 v18, v21
	v_mul_f32_e32 v18, v18, v82
	v_mul_f32_e32 v19, v19, v83
	s_nop 0
	v_mul_f32_e32 v21, v18, v19
	v_cvt_pk_bf16_f32 v18, v22, v25
	v_mov_b64_e32 v[22:23], s[4:5]
	v_mad_i64_i32 v[22:23], s[12:13], v67, s1, v[22:23]
	v_lshl_add_u64 v[22:23], v[172:173], 1, v[22:23]
	v_cvt_pk_bf16_f32 v19, v24, v65
	v_cvt_pk_bf16_f32 v21, v94, v21
	global_store_dwordx4 v[22:23], v[18:21], off
.LBB0_843:
	s_or_b64 exec, exec, s[28:29]
	s_nop 0
	v_cndmask_b32_e64 v19, v72, v78, s[10:11]
	v_cndmask_b32_e64 v21, v72, v147, s[26:27]
	v_mov_b32_e32 v22, v1
	v_mov_b32_e32 v20, v1
	v_mov_b32_e32 v24, v1
	v_mov_b32_dpp v22, v19 row_ror:1 row_mask:0xf bank_mask:0xf
	v_mov_b32_dpp v20, v21 row_ror:15 row_mask:0xf bank_mask:0xf
	v_cndmask_b32_e64 v19, v70, v84, s[10:11]
	v_cndmask_b32_e64 v21, v70, v155, s[26:27]
	v_mov_b32_e32 v23, v1
	v_mov_b32_dpp v24, v19 row_ror:1 row_mask:0xf bank_mask:0xf
	v_cndmask_b32_e64 v19, v68, v80, s[10:11]
	v_mov_b32_dpp v23, v21 row_ror:15 row_mask:0xf bank_mask:0xf
	v_cndmask_b32_e64 v21, v68, v144, s[26:27]
	v_mov_b32_e32 v59, v1
	v_mov_b32_e32 v25, v1
	v_mov_b32_e32 v67, v1
	v_mov_b32_dpp v59, v19 row_ror:1 row_mask:0xf bank_mask:0xf
	v_mov_b32_dpp v25, v21 row_ror:15 row_mask:0xf bank_mask:0xf
	v_cndmask_b32_e64 v19, v66, v86, s[10:11]
	v_cndmask_b32_e64 v21, v66, v145, s[26:27]
	v_mov_b32_e32 v61, v1
	v_mov_b32_dpp v67, v19 row_ror:1 row_mask:0xf bank_mask:0xf
	v_cndmask_b32_e64 v19, v64, v74, s[10:11]
	v_mov_b32_dpp v61, v21 row_ror:15 row_mask:0xf bank_mask:0xf
	v_cndmask_b32_e64 v21, v64, v156, s[26:27]
	v_mov_b32_e32 v65, v1
	v_mov_b32_e32 v69, v1
	v_mov_b32_e32 v63, v1
	v_mov_b32_dpp v65, v19 row_ror:1 row_mask:0xf bank_mask:0xf
	v_mov_b32_dpp v69, v21 row_ror:15 row_mask:0xf bank_mask:0xf
	v_cndmask_b32_e64 v19, v62, v88, s[10:11]
	v_cndmask_b32_e64 v21, v62, v131, s[26:27]
	v_mov_b32_e32 v71, v1
	v_mov_b32_dpp v63, v19 row_ror:1 row_mask:0xf bank_mask:0xf
	v_cndmask_b32_e64 v19, v60, v91, s[10:11]
	v_mov_b32_dpp v71, v21 row_ror:15 row_mask:0xf bank_mask:0xf
	v_cndmask_b32_e64 v21, v60, v157, s[26:27]
	v_mov_b32_e32 v73, v1
	v_mov_b32_e32 v74, v1
	v_add_u32_e32 v18, 0xa0, v174
	v_mov_b32_dpp v73, v19 row_ror:1 row_mask:0xf bank_mask:0xf
	v_mov_b32_dpp v74, v21 row_ror:15 row_mask:0xf bank_mask:0xf
	v_cndmask_b32_e64 v19, v58, v76, s[10:11]
	v_mov_b32_e32 v21, v1
	v_cndmask_b32_e64 v75, v58, v130, s[26:27]
	v_cmp_le_i32_e32 vcc, s41, v18
	v_mov_b32_dpp v21, v19 row_ror:1 row_mask:0xf bank_mask:0xf
	v_mov_b32_e32 v19, v1
	v_cmp_gt_i32_e64 s[12:13], s76, v18
	s_and_b64 s[12:13], vcc, s[12:13]
	v_mov_b32_dpp v19, v75 row_ror:15 row_mask:0xf bank_mask:0xf
	s_and_saveexec_b64 s[26:27], s[12:13]
	s_cbranch_execz .LBB0_845
; #define GAS __attribute__((address_space(1)))
; __device__ __forceinline__ unsigned cvt_pk_bf16(float lo, float hi) { unsigned r; asm("v_cvt_pk_bf16_f32 %0, %1, %2" : "=v"(r) : "v"(lo), "v"(hi)); return r; }
; template <int CTRL> __device__ __forceinline__ float dpp_mov(float v) { return __int_as_float(__builtin_amdgcn_update_dpp(0, __float_as_int(v), CTRL, 0xf, 0xf, false)); }
;     __device__ __forceinline__ void operator()(const f32x4 (&acc)[2][2][4][2], const Unit& u, int wr, int wc, int fr, int fq) const {
;     ...
;                 for (int k = 0; k < 8; ++k) {
;                     const float am = acc[ai][0][m][k >> 2][k & 3] * rs[ai][m];
;                     float sp, sn;
;                     if (m > 0) sp = fr == 15 ? acc[ai][0][m - 1][k >> 2][k & 3] * rs[ai][m - 1] : am; else sp = am;
;                     if (m < 3) sn = fr == 0 ? acc[ai][0][m + 1][k >> 2][k & 3] * rs[ai][m + 1] : am; else sn = am;
;                     float pv = dpp_mov<0x121>(sp), nv = dpp_mov<0x12F>(sn);
;                     if (m == 0) { const float e = chunk > 0 ? xch[((chunk - 1) * 2 + 1) * 128 + colh + k] : 0.f; pv = fr == 0 ? e : pv; }
;                     if (m == 3) { const float e = chunk < 3 ? xch[((chunk + 1) * 2 + 0) * 128 + colh + k] : 0.f; nv = fr == 15 ? e : nv; }
;                     pv = pos == 0 ? 0.f : pv; nv = pos == S - 1 ? 0.f : nv;
;                     const float c = pv * w0[k] + am * w1[k] + nv * w2[k] + bb[k];
;                     const float ge = c * __builtin_amdgcn_rcpf(1.f + __builtin_amdgcn_exp2f(c * __builtin_fmaf(-0.10294324f, c * c, -2.3022082f)));
;                     gsv[k] = ge * (acc[ai][1][m][k >> 2][k & 3] * rs[ai][m]);
;                 }
;                 if (row >= out_lo && row < out_hi) {
;                     u32x4 w; w.x = cvt_pk_bf16(gsv[0], gsv[1]); w.y = cvt_pk_bf16(gsv[2], gsv[3]); w.z = cvt_pk_bf16(gsv[4], gsv[5]); w.w = cvt_pk_bf16(gsv[6], gsv[7]);
;                     *(GAS u32x4*)(Gout + (size_t)row * DFF + f0) = w; }
	v_and_b32_e32 v75, s7, v18
	v_cmp_eq_u32_e64 s[12:13], 0, v75
	v_cmp_eq_u32_e32 vcc, s7, v75
	v_mov_b32_e32 v76, v28
	v_mov_b32_e32 v77, v32
	v_cndmask_b32_e64 v75, v74, 0, vcc
	v_cndmask_b32_e64 v74, v73, 0, s[12:13]
	v_mul_f32_e32 v74, v76, v74
	v_mul_f32_e32 v75, v77, v75
	v_cndmask_b32_e64 v63, v63, 0, s[12:13]
	v_fma_f32 v73, v40, v60, v74
	v_add_f32_e32 v73, v73, v75
	v_add_f32_e32 v75, v36, v73
	v_mul_f32_e32 v73, v75, v75
	v_fmamk_f32 v73, v73, 0xbdd2d3e8, v225
	v_mul_f32_e32 v73, v75, v73
	v_exp_f32_e32 v73, v73
	v_mov_b32_e32 v74, v12
	v_cndmask_b32_e64 v65, v65, 0, s[12:13]
	v_cndmask_b32_e64 v67, v67, 0, s[12:13]
	v_add_f32_e32 v73, 1.0, v73
	v_rcp_f32_e32 v91, v73
	v_cndmask_b32_e64 v73, v22, 0, s[12:13]
	v_mul_f32_e32 v74, v74, v90
	v_mul_f32_e32 v75, v75, v91
	s_nop 0
	v_mul_f32_e32 v76, v74, v75
	v_mov_b32_e32 v74, v39
	v_mov_b32_e32 v75, v27
	v_mul_f32_e32 v74, v74, v62
	v_mul_f32_e32 v75, v75, v63
	v_cndmask_b32_e64 v63, v71, 0, vcc
	v_add_f32_e32 v12, v74, v75
	v_fmac_f32_e32 v12, v31, v63
	v_add_f32_e32 v75, v35, v12
	v_mul_f32_e32 v12, v75, v75
	v_fmamk_f32 v12, v12, 0xbdd2d3e8, v225
	v_mul_f32_e32 v12, v75, v12
	v_exp_f32_e32 v12, v12
	v_mov_b32_e32 v74, v11
	v_cndmask_b32_e64 v63, v69, 0, vcc
	v_cndmask_b32_e64 v69, v59, 0, s[12:13]
	v_add_f32_e32 v12, 1.0, v12
	v_rcp_f32_e32 v91, v12
	v_cndmask_b32_e64 v71, v24, 0, s[12:13]
	v_cndmask_b32_e64 v59, v21, 0, s[12:13]
	v_mul_f32_e32 v74, v74, v90
	v_mul_f32_e32 v75, v75, v91
	s_nop 0
	v_mul_f32_e32 v12, v74, v75
	v_mov_b32_e32 v74, v38
	v_mov_b32_e32 v75, v26
	v_mul_f32_e32 v74, v74, v64
	v_mul_f32_e32 v75, v75, v65
	s_nop 0
	v_add_f32_e32 v11, v74, v75
	v_fmac_f32_e32 v11, v30, v63
	v_add_f32_e32 v11, v34, v11
	v_mul_f32_e32 v63, v11, v11
	v_fmamk_f32 v63, v63, 0xbdd2d3e8, v225
	v_mul_f32_e32 v63, v11, v63
	v_exp_f32_e32 v63, v63
	s_nop 0
	v_add_f32_e32 v63, 1.0, v63
	v_rcp_f32_e32 v91, v63
	s_nop 0
	v_mul_f32_e32 v10, v10, v90
	v_mul_f32_e32 v11, v11, v91
	s_nop 0
	v_mul_f32_e32 v63, v10, v11
	v_mov_b32_e32 v10, v49
	v_mov_b32_e32 v11, v45
	v_mul_f32_e32 v10, v10, v66
	v_mul_f32_e32 v11, v11, v67
	v_cvt_pk_bf16_f32 v12, v63, v12
	s_nop 0
	v_add_f32_e32 v10, v10, v11
	v_cndmask_b32_e64 v11, v61, 0, vcc
	v_fmac_f32_e32 v10, v53, v11
	v_add_f32_e32 v11, v57, v10
	v_mul_f32_e32 v10, v11, v11
	v_fmamk_f32 v10, v10, 0xbdd2d3e8, v225
	v_mul_f32_e32 v10, v11, v10
	v_exp_f32_e32 v10, v10
	s_nop 0
	v_add_f32_e32 v10, 1.0, v10
	v_rcp_f32_e32 v91, v10
	v_mov_b32_e32 v10, v17
	v_mul_f32_e32 v10, v10, v90
	v_mul_f32_e32 v11, v11, v91
	s_nop 0
	v_mul_f32_e32 v61, v10, v11
	v_mov_b32_e32 v10, v48
	v_mov_b32_e32 v11, v44
	v_mul_f32_e32 v10, v10, v68
	v_mul_f32_e32 v11, v11, v69
	s_nop 0
	v_add_f32_e32 v10, v10, v11
	v_cndmask_b32_e64 v11, v25, 0, vcc
	v_fmac_f32_e32 v10, v52, v11
	v_add_f32_e32 v17, v56, v10
	v_mul_f32_e32 v10, v17, v17
	v_fmamk_f32 v10, v10, 0xbdd2d3e8, v225
	v_mul_f32_e32 v10, v17, v10
	v_exp_f32_e32 v10, v10
	s_nop 0
	v_add_f32_e32 v10, 1.0, v10
	v_rcp_f32_e32 v91, v10
	s_nop 0
	v_mul_f32_e32 v10, v16, v90
	v_mul_f32_e32 v11, v17, v91
	s_nop 0
	v_mul_f32_e32 v16, v10, v11
	v_mov_b32_e32 v10, v47
	v_mov_b32_e32 v11, v43
	v_mul_f32_e32 v10, v10, v70
	v_mul_f32_e32 v11, v11, v71
	s_nop 0
	v_add_f32_e32 v10, v10, v11
	v_cndmask_b32_e64 v11, v23, 0, vcc
	v_fmac_f32_e32 v10, v51, v11
	v_add_f32_e32 v11, v55, v10
	v_mul_f32_e32 v10, v11, v11
	v_fmamk_f32 v10, v10, 0xbdd2d3e8, v225
	v_mul_f32_e32 v10, v11, v10
	v_exp_f32_e32 v10, v10
	s_nop 0
	v_add_f32_e32 v10, 1.0, v10
	v_rcp_f32_e32 v91, v10
	v_mov_b32_e32 v10, v15
	v_mul_f32_e32 v10, v10, v90
	v_mul_f32_e32 v11, v11, v91
	s_nop 0
	v_mul_f32_e32 v17, v10, v11
	v_mov_b32_e32 v10, v46
	v_mov_b32_e32 v11, v42
	v_mul_f32_e32 v10, v10, v72
	v_mul_f32_e32 v11, v11, v73
	s_nop 0
	v_add_f32_e32 v10, v10, v11
	v_cndmask_b32_e64 v11, v20, 0, vcc
	v_fmac_f32_e32 v10, v50, v11
	v_add_f32_e32 v15, v54, v10
	v_mul_f32_e32 v10, v15, v15
	v_fmamk_f32 v10, v10, 0xbdd2d3e8, v225
	v_mul_f32_e32 v10, v15, v10
	v_exp_f32_e32 v10, v10
	s_nop 0
	v_add_f32_e32 v10, 1.0, v10
	v_rcp_f32_e32 v91, v10
	s_nop 0
	v_mul_f32_e32 v10, v14, v90
	v_mul_f32_e32 v11, v15, v91
	s_nop 0
	v_mul_f32_e32 v14, v10, v11
	v_mov_b32_e32 v10, v41
	v_mov_b32_e32 v11, v29
	v_mul_f32_e32 v10, v10, v58
	v_mul_f32_e32 v11, v11, v59
	s_nop 0
	v_add_f32_e32 v10, v10, v11
	v_cndmask_b32_e64 v11, v19, 0, vcc
	v_fmac_f32_e32 v10, v33, v11
	v_add_f32_e32 v11, v37, v10
	v_mul_f32_e32 v10, v11, v11
	v_fmamk_f32 v10, v10, 0xbdd2d3e8, v225
	v_mul_f32_e32 v10, v11, v10
	v_exp_f32_e32 v10, v10
	s_nop 0
	v_add_f32_e32 v10, 1.0, v10
	v_rcp_f32_e32 v91, v10
	v_mov_b32_e32 v10, v13
	v_mul_f32_e32 v10, v10, v90
	v_mul_f32_e32 v11, v11, v91
	s_nop 0
	v_mul_f32_e32 v13, v10, v11
	v_cvt_pk_bf16_f32 v10, v14, v17
	v_mov_b64_e32 v[14:15], s[4:5]
	v_mad_i64_i32 v[14:15], s[12:13], v18, s1, v[14:15]
	v_lshl_add_u64 v[14:15], v[172:173], 1, v[14:15]
	v_cvt_pk_bf16_f32 v11, v16, v61
	v_cvt_pk_bf16_f32 v13, v76, v13
	global_store_dwordx4 v[14:15], v[10:13], off

; #define GAS __attribute__((address_space(1)))
; __device__ __forceinline__ unsigned cvt_pk_bf16(float lo, float hi) { unsigned r; asm("v_cvt_pk_bf16_f32 %0, %1, %2" : "=v"(r) : "v"(lo), "v"(hi)); return r; }
; template <int CTRL> __device__ __forceinline__ float dpp_mov(float v) { return __int_as_float(__builtin_amdgcn_update_dpp(0, __float_as_int(v), CTRL, 0xf, 0xf, false)); }
;     __device__ __forceinline__ void operator()(const f32x4 (&acc)[2][2][4][2], const Unit& u, int wr, int wc, int fr, int fq) const {
;     ...
;                 for (int k = 0; k < 8; ++k) {
;                     const float am = acc[ai][0][m][k >> 2][k & 3] * rs[ai][m];
;                     float sp, sn;
;                     if (m > 0) sp = fr == 15 ? acc[ai][0][m - 1][k >> 2][k & 3] * rs[ai][m - 1] : am; else sp = am;
;                     if (m < 3) sn = fr == 0 ? acc[ai][0][m + 1][k >> 2][k & 3] * rs[ai][m + 1] : am; else sn = am;
;                     float pv = dpp_mov<0x121>(sp), nv = dpp_mov<0x12F>(sn);
;                     if (m == 0) { const float e = chunk > 0 ? xch[((chunk - 1) * 2 + 1) * 128 + colh + k] : 0.f; pv = fr == 0 ? e : pv; }
;                     if (m == 3) { const float e = chunk < 3 ? xch[((chunk + 1) * 2 + 0) * 128 + colh + k] : 0.f; nv = fr == 15 ? e : nv; }
;                     pv = pos == 0 ? 0.f : pv; nv = pos == S - 1 ? 0.f : nv;
;                     const float c = pv * w0[k] + am * w1[k] + nv * w2[k] + bb[k];
;                     const float ge = c * __builtin_amdgcn_rcpf(1.f + __builtin_amdgcn_exp2f(c * __builtin_fmaf(-0.10294324f, c * c, -2.3022082f)));
;                     gsv[k] = ge * (acc[ai][1][m][k >> 2][k & 3] * rs[ai][m]);
;                 }
;                 if (row >= out_lo && row < out_hi) {
;                     u32x4 w; w.x = cvt_pk_bf16(gsv[0], gsv[1]); w.y = cvt_pk_bf16(gsv[2], gsv[3]); w.z = cvt_pk_bf16(gsv[4], gsv[5]); w.w = cvt_pk_bf16(gsv[6], gsv[7]);
;                     *(GAS u32x4*)(Gout + (size_t)row * DFF + f0) = w; }
.LBB0_861:
	v_add_u32_e32 v13, 0xb0, v174
	v_cmp_le_i32_e32 vcc, s41, v13
	v_cmp_gt_i32_e64 s[12:13], s76, v13
	s_and_b64 s[12:13], vcc, s[12:13]
	s_and_saveexec_b64 s[26:27], s[12:13]
	s_cbranch_execz .LBB0_863
	v_and_b32_e32 v58, s7, v13
	v_cmp_eq_u32_e64 s[12:13], 0, v58
	v_cmp_eq_u32_e32 vcc, s7, v58
	s_waitcnt lgkmcnt(0)
	v_cndmask_b32_e64 v58, v66, v67, s[10:11]
	v_cndmask_b32_e64 v60, v60, 0, s[12:13]
	v_mul_f32_e32 v28, v28, v60
	v_cndmask_b32_e64 v58, v58, 0, vcc
	v_fmac_f32_e32 v28, v40, v157
	v_fmac_f32_e32 v28, v32, v58
	v_add_f32_e32 v28, v36, v28
	v_mul_f32_e32 v32, v28, v28
	v_fmamk_f32 v32, v32, 0xbdd2d3e8, v225
	v_mul_f32_e32 v32, v28, v32
	v_exp_f32_e32 v32, v32
	v_mul_f32_e32 v4, v4, v146
	v_mul_f32_e32 v3, v3, v146
	v_mul_f32_e32 v2, v2, v146
	v_add_f32_e32 v32, 1.0, v32
	v_rcp_f32_e32 v32, v32
	s_nop 0
	v_mul_f32_e32 v28, v28, v32
	v_mul_f32_e32 v32, v4, v28
	v_cndmask_b32_e64 v28, v62, 0, s[12:13]
	v_cndmask_b32_e64 v4, v65, v64, s[10:11]
	v_mul_f32_e32 v27, v27, v28
	v_cndmask_b32_e64 v4, v4, 0, vcc
	v_fmac_f32_e32 v27, v39, v131
	v_fmac_f32_e32 v27, v31, v4
	v_add_f32_e32 v4, v35, v27
	v_mul_f32_e32 v27, v4, v4
	v_fmamk_f32 v27, v27, 0xbdd2d3e8, v225
	v_mul_f32_e32 v27, v4, v27
	v_exp_f32_e32 v27, v27
	v_cndmask_b32_e64 v131, v19, 0, s[12:13]
	v_mov_b32_e32 v28, v41
	v_add_f32_e32 v27, 1.0, v27
	v_rcp_f32_e32 v27, v27
	s_nop 0
	v_mul_f32_e32 v4, v4, v27
	v_cndmask_b32_e64 v27, v59, 0, s[12:13]
	v_mul_f32_e32 v4, v3, v4
	v_cndmask_b32_e64 v3, v61, v63, s[10:11]
	v_mul_f32_e32 v26, v26, v27
	v_cndmask_b32_e64 v3, v3, 0, vcc
	v_fmac_f32_e32 v26, v38, v156
	v_fmac_f32_e32 v26, v30, v3
	v_add_f32_e32 v3, v34, v26
	v_mul_f32_e32 v26, v3, v3
	v_fmamk_f32 v26, v26, 0xbdd2d3e8, v225
	v_mul_f32_e32 v26, v3, v26
	v_exp_f32_e32 v26, v26
	s_nop 0
	v_add_f32_e32 v26, 1.0, v26
	v_rcp_f32_e32 v26, v26
	s_nop 0
	v_mul_f32_e32 v3, v3, v26
	v_mul_f32_e32 v26, v2, v3
	v_cndmask_b32_e64 v3, v24, 0, s[12:13]
	v_cndmask_b32_e64 v2, v25, v23, s[10:11]
	v_mul_f32_e32 v3, v45, v3
	v_cndmask_b32_e64 v2, v2, 0, vcc
	v_fmac_f32_e32 v3, v49, v145
	v_fmac_f32_e32 v3, v53, v2
	v_add_f32_e32 v2, v57, v3
	v_mul_f32_e32 v3, v2, v2
	v_fmamk_f32 v3, v3, 0xbdd2d3e8, v225
	v_mul_f32_e32 v3, v2, v3
	v_exp_f32_e32 v3, v3
	v_cvt_pk_bf16_f32 v4, v26, v4
	s_nop 0
	v_add_f32_e32 v3, 1.0, v3
	v_rcp_f32_e32 v3, v3
	s_nop 0
	v_mul_f32_e32 v2, v2, v3
	v_mul_f32_e32 v3, v9, v146
	v_mul_f32_e32 v9, v3, v2
	v_cndmask_b32_e64 v3, v20, 0, s[12:13]
	v_cndmask_b32_e64 v2, v21, v22, s[10:11]
	v_mul_f32_e32 v3, v44, v3
	v_cndmask_b32_e64 v2, v2, 0, vcc
	v_fmac_f32_e32 v3, v48, v144
	v_fmac_f32_e32 v3, v52, v2
	v_add_f32_e32 v2, v56, v3
	v_mul_f32_e32 v3, v2, v2
	v_fmamk_f32 v3, v3, 0xbdd2d3e8, v225
	v_mul_f32_e32 v3, v2, v3
	v_exp_f32_e32 v3, v3
	s_nop 0
	v_add_f32_e32 v3, 1.0, v3
	v_rcp_f32_e32 v3, v3
	s_nop 0
	v_mul_f32_e32 v2, v2, v3
	v_mul_f32_e32 v3, v8, v146
	v_mul_f32_e32 v8, v3, v2
	v_cndmask_b32_e64 v3, v16, 0, s[12:13]
	v_cndmask_b32_e64 v2, v18, v14, s[10:11]
	v_mul_f32_e32 v3, v43, v3
	v_cndmask_b32_e64 v2, v2, 0, vcc
	v_fmac_f32_e32 v3, v47, v155
	v_fmac_f32_e32 v3, v51, v2
	v_add_f32_e32 v2, v55, v3
	v_mul_f32_e32 v3, v2, v2
	v_fmamk_f32 v3, v3, 0xbdd2d3e8, v225
	v_mul_f32_e32 v3, v2, v3
	v_exp_f32_e32 v3, v3
	s_nop 0
	v_add_f32_e32 v3, 1.0, v3
	v_rcp_f32_e32 v3, v3
	s_nop 0
	v_mul_f32_e32 v2, v2, v3
	v_mul_f32_e32 v3, v7, v146
	v_mul_f32_e32 v7, v3, v2
	v_cndmask_b32_e64 v3, v10, 0, s[12:13]
	v_cndmask_b32_e64 v2, v11, v12, s[10:11]
	v_mul_f32_e32 v3, v42, v3
	v_cndmask_b32_e64 v2, v2, 0, vcc
	v_fmac_f32_e32 v3, v46, v147
	v_fmac_f32_e32 v3, v50, v2
	v_add_f32_e32 v2, v54, v3
	v_mul_f32_e32 v3, v2, v2
	v_fmamk_f32 v3, v3, 0xbdd2d3e8, v225
	v_mul_f32_e32 v3, v2, v3
	v_exp_f32_e32 v3, v3
	s_nop 0
	v_add_f32_e32 v3, 1.0, v3
	v_rcp_f32_e32 v3, v3
	s_nop 0
	v_mul_f32_e32 v2, v2, v3
	v_mul_f32_e32 v3, v6, v146
	v_mul_f32_e32 v6, v3, v2
	v_mul_f32_e32 v2, v28, v130
	v_mul_f32_e32 v3, v29, v131
	s_nop 0
	v_add_f32_e32 v2, v2, v3
	v_cndmask_b32_e64 v3, v17, v15, s[10:11]
	v_cndmask_b32_e64 v3, v3, 0, vcc
	v_fmac_f32_e32 v2, v33, v3
	v_add_f32_e32 v3, v37, v2
	v_mul_f32_e32 v2, v3, v3
	v_fmamk_f32 v2, v2, 0xbdd2d3e8, v225
	v_mul_f32_e32 v2, v3, v2
	v_exp_f32_e32 v2, v2
	s_nop 0
	v_add_f32_e32 v2, 1.0, v2
	v_rcp_f32_e32 v147, v2
	v_mov_b32_e32 v2, v5
	v_mul_f32_e32 v2, v2, v146
	v_mul_f32_e32 v3, v3, v147
	s_nop 0
	v_mul_f32_e32 v5, v2, v3
	v_cvt_pk_bf16_f32 v2, v6, v7
	v_mov_b64_e32 v[6:7], s[4:5]
	v_mad_i64_i32 v[6:7], s[10:11], v13, s1, v[6:7]
	v_lshl_add_u64 v[6:7], v[172:173], 1, v[6:7]
	v_cvt_pk_bf16_f32 v3, v8, v9
	v_cvt_pk_bf16_f32 v5, v32, v5
	global_store_dwordx4 v[6:7], v[2:5], off

; #define GAS __attribute__((address_space(1)))
; __device__ __forceinline__ unsigned cvt_pk_bf16(float lo, float hi) { unsigned r; asm("v_cvt_pk_bf16_f32 %0, %1, %2" : "=v"(r) : "v"(lo), "v"(hi)); return r; }
; template <int M> __device__ __forceinline__ float swz_xor(float v) { return __int_as_float(__builtin_amdgcn_ds_swizzle(__float_as_int(v), 0x1f | (M << 10))); }
; __device__ __forceinline__ float sum_x32(float v) { auto rr = __builtin_amdgcn_permlane32_swap(__float_as_uint(v), __float_as_uint(v), false, false); return __uint_as_float(rr[0]) + __uint_as_float(rr[1]); }
;     __device__ __forceinline__ void operator()(const f32x4 (&acc)[2][2][4][2], const Unit& u, int wr, int wc, int fr, int fq) const {
;     ...
;                 f32x4 bsv[2][2][2];
; #pragma unroll
;                 for (int mm = 0; mm < 2; ++mm) { const size_t off = (size_t)(row0 + ai * HALF + (2 * mh + mm) * 16) * ldc + col0;
; #pragma unroll
;                     for (int bj = 0; bj < 2; ++bj)
; #pragma unroll
;                         for (int n = 0; n < 2; ++n) bsv[mm][bj][n] = *(const GAS f32x4*)(base + off + bj * HALF + n * 16); }
; #pragma unroll
;                 for (int mm = 0; mm < 2; ++mm) { const int m = 2 * mh + mm, row = row0 + ai * HALF + m * 16; const size_t off = (size_t)row * ldc + col0; float sq = 0.f;
; #pragma unroll
;                     for (int bj = 0; bj < 2; ++bj)
; #pragma unroll
;                         for (int n = 0; n < 2; ++n) { const f32x4 v = bsv[mm][bj][n] + acc[ai][bj][m][n]; *(GAS f32x4*)(out + off + bj * HALF + n * 16) = v;
;                             if (do_norm) { sq += (v[0] * v[0] + v[1] * v[1]) + (v[2] * v[2] + v[3] * v[3]); const f32x4 w = v * gv[bj][n];
;                                 u32x2 pk; pk.x = cvt_pk_bf16(w[0], w[1]); pk.y = cvt_pk_bf16(w[2], w[3]); *(GAS u32x2*)(xb + off + bj * HALF + n * 16) = pk; } }
;                     if (do_norm) { sq += swz_xor<16>(sq); sq = sum_x32(sq); if (fq == 0) (void)__hip_atomic_fetch_add(ssq + row, (unsigned long long)(sq * 1048576.f + 0.5f), __ATOMIC_RELAXED, __HIP_MEMORY_SCOPE_AGENT); } }
.LBB0_977:
	s_lshl_b32 s8, s88, 8
	s_add_i32 s8, s8, s76
	v_add_u32_e32 v206, s8, v148
	v_ashrrev_i32_e32 v207, 31, v206
	v_add_u32_e32 v208, 16, v206
	v_lshl_add_u64 v[204:205], v[202:203], 2, s[16:17]
	v_lshlrev_b64 v[146:147], 12, v[206:207]
	v_ashrrev_i32_e32 v209, 31, v208
	v_lshl_add_u64 v[212:213], v[204:205], 0, v[146:147]
	v_lshlrev_b64 v[146:147], 12, v[208:209]
	v_lshl_add_u64 v[210:211], v[204:205], 0, v[146:147]
	global_load_dwordx4 v[176:179], v[212:213], off
	global_load_dwordx4 v[172:175], v[212:213], off offset:64
	global_load_dwordx4 v[166:169], v[212:213], off offset:512
	global_load_dwordx4 v[162:165], v[212:213], off offset:576
	global_load_dwordx4 v[158:161], v[210:211], off
	global_load_dwordx4 v[154:157], v[210:211], off offset:64
	global_load_dwordx4 v[150:153], v[210:211], off offset:512
	global_load_dwordx4 v[146:149], v[210:211], off offset:576
	v_cmp_eq_u32_e64 s[8:9], 0, v170
	s_mov_b64 s[28:29], -1
	s_and_b64 vcc, exec, s[24:25]
	s_waitcnt vmcnt(0)
	v_add_f32_e32 v182, v144, v178
	v_add_f32_e32 v183, v145, v179
	v_add_f32_e32 v180, v142, v176
	v_add_f32_e32 v181, v143, v177
	v_add_f32_e32 v176, v138, v172
	v_add_f32_e32 v177, v139, v173
	v_add_f32_e32 v170, v134, v166
	v_add_f32_e32 v171, v135, v167
	v_add_f32_e32 v142, v130, v162
	v_add_f32_e32 v143, v131, v163
	global_store_dwordx4 v[212:213], v[180:183], off
	s_cbranch_vccz .LBB0_979
	v_add_f32_e32 v178, v140, v174
	v_add_f32_e32 v179, v141, v175
	v_add_f32_e32 v172, v136, v168
	v_add_f32_e32 v173, v137, v169
	v_add_f32_e32 v144, v132, v164
	v_add_f32_e32 v145, v133, v165
	global_store_dwordx4 v[212:213], v[176:179], off offset:64
	global_store_dwordx4 v[212:213], v[170:173], off offset:512
	global_store_dwordx4 v[212:213], v[142:145], off offset:576
	s_mov_b64 s[28:29], 0
.LBB0_979:
	s_andn2_b64 vcc, exec, s[28:29]
	s_cbranch_vccnz .LBB0_983
	v_mul_f32_e32 v134, v181, v181
	v_mul_f32_e32 v135, v183, v183
	v_fmac_f32_e32 v134, v180, v180
	v_fmac_f32_e32 v135, v182, v182
	v_add_f32_e32 v144, v134, v135
	v_mul_f32_e32 v134, v80, v182
	v_mul_f32_e32 v135, v81, v183
	v_mul_f32_e32 v138, v78, v180
	v_mul_f32_e32 v139, v79, v181
	v_add_f32_e32 v178, v140, v174
	v_add_f32_e32 v179, v141, v175
	v_lshlrev_b64 v[130:131], 10, v[206:207]
	v_cvt_pk_bf16_f32 v138, v138, v139
	v_cvt_pk_bf16_f32 v139, v134, v135
	v_mul_f32_e32 v134, v177, v177
	v_mul_f32_e32 v135, v179, v179
	v_lshl_add_u64 v[130:131], v[130:131], 0, v[202:203]
	v_fmac_f32_e32 v134, v176, v176
	v_fmac_f32_e32 v135, v178, v178
	v_lshl_add_u64 v[130:131], v[130:131], 1, s[12:13]
	v_add_f32_e32 v134, v134, v135
	global_store_dwordx2 v[130:131], v[138:139], off
	v_add_f32_e32 v140, v144, v134
	v_mul_f32_e32 v134, v68, v178
	v_mul_f32_e32 v135, v69, v179
	v_mul_f32_e32 v138, v66, v176
	v_mul_f32_e32 v139, v67, v177
	v_add_f32_e32 v172, v136, v168
	v_add_f32_e32 v173, v137, v169
	v_cvt_pk_bf16_f32 v138, v138, v139
	v_cvt_pk_bf16_f32 v139, v134, v135
	v_mul_f32_e32 v134, v171, v171
	v_mul_f32_e32 v135, v173, v173
	v_fmac_f32_e32 v134, v170, v170
	v_fmac_f32_e32 v135, v172, v172
	v_add_f32_e32 v134, v134, v135
	global_store_dwordx4 v[212:213], v[176:179], off offset:64
	global_store_dwordx2 v[130:131], v[138:139], off offset:32
	v_add_f32_e32 v138, v140, v134
	v_mul_f32_e32 v134, v76, v172
	v_mul_f32_e32 v135, v77, v173
	v_mul_f32_e32 v136, v74, v170
	v_mul_f32_e32 v137, v75, v171
	v_add_f32_e32 v144, v132, v164
	v_add_f32_e32 v145, v133, v165
	v_cvt_pk_bf16_f32 v136, v136, v137
	v_cvt_pk_bf16_f32 v137, v134, v135
	v_mul_f32_e32 v134, v143, v143
	v_mul_f32_e32 v135, v145, v145
	v_fmac_f32_e32 v134, v142, v142
	v_fmac_f32_e32 v135, v144, v144
	v_add_f32_e32 v134, v134, v135
	global_store_dwordx4 v[212:213], v[170:173], off offset:512
	global_store_dwordx2 v[130:131], v[136:137], off offset:256
	v_add_f32_e32 v136, v138, v134
	ds_swizzle_b32 v137, v136 offset:swizzle(SWAP,16)
	v_mul_f32_e32 v134, v62, v142
	v_mul_f32_e32 v135, v63, v143
	global_store_dwordx4 v[212:213], v[142:145], off offset:576
	v_mul_f32_e32 v132, v64, v144
	v_mul_f32_e32 v133, v65, v145
	v_cvt_pk_bf16_f32 v134, v134, v135
	s_nop 0
	v_cvt_pk_bf16_f32 v135, v132, v133
	global_store_dwordx2 v[130:131], v[134:135], off offset:288
	s_waitcnt lgkmcnt(0)
	v_add_f32_e32 v130, v136, v137
	v_mov_b32_e32 v131, v130
	s_nop 1
	v_permlane32_swap_b32_e32 v130, v131
	s_and_saveexec_b64 s[28:29], s[8:9]
	s_cbranch_execz .LBB0_982
	v_add_f32_e32 v130, v130, v131
	s_mov_b32 s40, 0x49800000
	v_fma_f32 v130, v130, s40, 0.5
	v_trunc_f32_e32 v130, v130
	v_mul_f32_e32 v131, 0x2f800000, v130
	v_floor_f32_e32 v131, v131
	v_fmac_f32_e32 v130, 0xcf800000, v131
	v_cvt_u32_f32_e32 v130, v130
	v_cvt_u32_f32_e32 v131, v131
	v_lshl_add_u64 v[132:133], v[206:207], 3, s[10:11]
	global_atomic_add_x2 v[132:133], v[130:131], off

; #define GAS __attribute__((address_space(1)))
; __device__ __forceinline__ unsigned cvt_pk_bf16(float lo, float hi) { unsigned r; asm("v_cvt_pk_bf16_f32 %0, %1, %2" : "=v"(r) : "v"(lo), "v"(hi)); return r; }
; template <int M> __device__ __forceinline__ float swz_xor(float v) { return __int_as_float(__builtin_amdgcn_ds_swizzle(__float_as_int(v), 0x1f | (M << 10))); }
; __device__ __forceinline__ float sum_x32(float v) { auto rr = __builtin_amdgcn_permlane32_swap(__float_as_uint(v), __float_as_uint(v), false, false); return __uint_as_float(rr[0]) + __uint_as_float(rr[1]); }
;     __device__ __forceinline__ void operator()(const f32x4 (&acc)[2][2][4][2], const Unit& u, int wr, int wc, int fr, int fq) const {
;     ...
;                 for (int mm = 0; mm < 2; ++mm) { const int m = 2 * mh + mm, row = row0 + ai * HALF + m * 16; const size_t off = (size_t)row * ldc + col0; float sq = 0.f;
; #pragma unroll
;                     for (int bj = 0; bj < 2; ++bj)
; #pragma unroll
;                         for (int n = 0; n < 2; ++n) { const f32x4 v = bsv[mm][bj][n] + acc[ai][bj][m][n]; *(GAS f32x4*)(out + off + bj * HALF + n * 16) = v;
;                             if (do_norm) { sq += (v[0] * v[0] + v[1] * v[1]) + (v[2] * v[2] + v[3] * v[3]); const f32x4 w = v * gv[bj][n];
;                                 u32x2 pk; pk.x = cvt_pk_bf16(w[0], w[1]); pk.y = cvt_pk_bf16(w[2], w[3]); *(GAS u32x2*)(xb + off + bj * HALF + n * 16) = pk; } }
;                     if (do_norm) { sq += swz_xor<16>(sq); sq = sum_x32(sq); if (fq == 0) (void)__hip_atomic_fetch_add(ssq + row, (unsigned long long)(sq * 1048576.f + 0.5f), __ATOMIC_RELAXED, __HIP_MEMORY_SCOPE_AGENT); } }
.LBB0_983:
	v_add_f32_e32 v140, v128, v160
	v_add_f32_e32 v141, v129, v161
	v_add_f32_e32 v138, v126, v158
	v_add_f32_e32 v139, v127, v159
	s_mov_b64 s[28:29], -1
	s_and_b64 vcc, exec, s[24:25]
	v_add_f32_e32 v134, v122, v154
	v_add_f32_e32 v135, v123, v155
	v_add_f32_e32 v130, v118, v150
	v_add_f32_e32 v131, v119, v151
	v_add_f32_e32 v126, v114, v146
	v_add_f32_e32 v127, v115, v147
	global_store_dwordx4 v[210:211], v[138:141], off
	s_cbranch_vccz .LBB0_985
	v_add_f32_e32 v136, v124, v156
	v_add_f32_e32 v137, v125, v157
	v_add_f32_e32 v132, v120, v152
	v_add_f32_e32 v133, v121, v153
	v_add_f32_e32 v128, v116, v148
	v_add_f32_e32 v129, v117, v149
	global_store_dwordx4 v[210:211], v[134:137], off offset:64
	global_store_dwordx4 v[210:211], v[130:133], off offset:512
	global_store_dwordx4 v[210:211], v[126:129], off offset:576
	s_mov_b64 s[28:29], 0
.LBB0_985:
	s_andn2_b64 vcc, exec, s[28:29]
	s_cbranch_vccnz .LBB0_989
	v_mul_f32_e32 v118, v139, v139
	v_mul_f32_e32 v119, v141, v141
	v_fmac_f32_e32 v118, v138, v138
	v_fmac_f32_e32 v119, v140, v140
	v_add_f32_e32 v128, v118, v119
	v_mul_f32_e32 v118, v80, v140
	v_mul_f32_e32 v119, v81, v141
	v_mul_f32_e32 v122, v78, v138
	v_mul_f32_e32 v123, v79, v139
	v_add_f32_e32 v136, v124, v156
	v_add_f32_e32 v137, v125, v157
	v_lshlrev_b64 v[114:115], 10, v[208:209]
	v_cvt_pk_bf16_f32 v122, v122, v123
	v_cvt_pk_bf16_f32 v123, v118, v119
	v_mul_f32_e32 v118, v135, v135
	v_mul_f32_e32 v119, v137, v137
	v_lshl_add_u64 v[114:115], v[114:115], 0, v[202:203]
	v_fmac_f32_e32 v118, v134, v134
	v_fmac_f32_e32 v119, v136, v136
	v_lshl_add_u64 v[114:115], v[114:115], 1, s[12:13]
	v_add_f32_e32 v118, v118, v119
	global_store_dwordx2 v[114:115], v[122:123], off
	v_add_f32_e32 v124, v128, v118
	v_mul_f32_e32 v118, v68, v136
	v_mul_f32_e32 v119, v69, v137
	v_mul_f32_e32 v122, v66, v134
	v_mul_f32_e32 v123, v67, v135
	v_add_f32_e32 v132, v120, v152
	v_add_f32_e32 v133, v121, v153
	v_cvt_pk_bf16_f32 v122, v122, v123
	v_cvt_pk_bf16_f32 v123, v118, v119
	v_mul_f32_e32 v118, v131, v131
	v_mul_f32_e32 v119, v133, v133
	v_fmac_f32_e32 v118, v130, v130
	v_fmac_f32_e32 v119, v132, v132
	v_add_f32_e32 v118, v118, v119
	global_store_dwordx4 v[210:211], v[134:137], off offset:64
	global_store_dwordx2 v[114:115], v[122:123], off offset:32
	v_add_f32_e32 v122, v124, v118
	v_mul_f32_e32 v118, v76, v132
	v_mul_f32_e32 v119, v77, v133
	v_mul_f32_e32 v120, v74, v130
	v_mul_f32_e32 v121, v75, v131
	v_add_f32_e32 v128, v116, v148
	v_add_f32_e32 v129, v117, v149
	v_cvt_pk_bf16_f32 v120, v120, v121
	v_cvt_pk_bf16_f32 v121, v118, v119
	v_mul_f32_e32 v118, v127, v127
	v_mul_f32_e32 v119, v129, v129
	v_fmac_f32_e32 v118, v126, v126
	v_fmac_f32_e32 v119, v128, v128
	v_add_f32_e32 v118, v118, v119
	global_store_dwordx4 v[210:211], v[130:133], off offset:512
	global_store_dwordx2 v[114:115], v[120:121], off offset:256
	v_add_f32_e32 v120, v122, v118
	ds_swizzle_b32 v121, v120 offset:swizzle(SWAP,16)
	v_mul_f32_e32 v118, v62, v126
	v_mul_f32_e32 v119, v63, v127
	global_store_dwordx4 v[210:211], v[126:129], off offset:576
	v_mul_f32_e32 v116, v64, v128
	v_mul_f32_e32 v117, v65, v129
	v_cvt_pk_bf16_f32 v118, v118, v119
	s_nop 0
	v_cvt_pk_bf16_f32 v119, v116, v117
	global_store_dwordx2 v[114:115], v[118:119], off offset:288
	s_waitcnt lgkmcnt(0)
	v_add_f32_e32 v114, v120, v121
	v_mov_b32_e32 v115, v114
	s_nop 1
	v_permlane32_swap_b32_e32 v114, v115
	s_and_saveexec_b64 s[28:29], s[8:9]
	s_cbranch_execz .LBB0_988
	v_add_f32_e32 v114, v114, v115
	s_mov_b32 s40, 0x49800000
	v_fma_f32 v114, v114, s40, 0.5
	v_trunc_f32_e32 v114, v114
	v_mul_f32_e32 v115, 0x2f800000, v114
	v_floor_f32_e32 v115, v115
	v_fmac_f32_e32 v114, 0xcf800000, v115
	v_cvt_u32_f32_e32 v114, v114
	v_cvt_u32_f32_e32 v115, v115
	v_lshl_add_u64 v[116:117], v[208:209], 3, s[10:11]
	global_atomic_add_x2 v[116:117], v[114:115], off

; #define GAS __attribute__((address_space(1)))
; __device__ __forceinline__ unsigned cvt_pk_bf16(float lo, float hi) { unsigned r; asm("v_cvt_pk_bf16_f32 %0, %1, %2" : "=v"(r) : "v"(lo), "v"(hi)); return r; }
; template <int M> __device__ __forceinline__ float swz_xor(float v) { return __int_as_float(__builtin_amdgcn_ds_swizzle(__float_as_int(v), 0x1f | (M << 10))); }
; __device__ __forceinline__ float sum_x32(float v) { auto rr = __builtin_amdgcn_permlane32_swap(__float_as_uint(v), __float_as_uint(v), false, false); return __uint_as_float(rr[0]) + __uint_as_float(rr[1]); }
;     __device__ __forceinline__ void operator()(const f32x4 (&acc)[2][2][4][2], const Unit& u, int wr, int wc, int fr, int fq) const {
;     ...
;                 f32x4 bsv[2][2][2];
; #pragma unroll
;                 for (int mm = 0; mm < 2; ++mm) { const size_t off = (size_t)(row0 + ai * HALF + (2 * mh + mm) * 16) * ldc + col0;
; #pragma unroll
;                     for (int bj = 0; bj < 2; ++bj)
; #pragma unroll
;                         for (int n = 0; n < 2; ++n) bsv[mm][bj][n] = *(const GAS f32x4*)(base + off + bj * HALF + n * 16); }
; #pragma unroll
;                 for (int mm = 0; mm < 2; ++mm) { const int m = 2 * mh + mm, row = row0 + ai * HALF + m * 16; const size_t off = (size_t)row * ldc + col0; float sq = 0.f;
; #pragma unroll
;                     for (int bj = 0; bj < 2; ++bj)
; #pragma unroll
;                         for (int n = 0; n < 2; ++n) { const f32x4 v = bsv[mm][bj][n] + acc[ai][bj][m][n]; *(GAS f32x4*)(out + off + bj * HALF + n * 16) = v;
;                             if (do_norm) { sq += (v[0] * v[0] + v[1] * v[1]) + (v[2] * v[2] + v[3] * v[3]); const f32x4 w = v * gv[bj][n];
;                                 u32x2 pk; pk.x = cvt_pk_bf16(w[0], w[1]); pk.y = cvt_pk_bf16(w[2], w[3]); *(GAS u32x2*)(xb + off + bj * HALF + n * 16) = pk; } }
;                     if (do_norm) { sq += swz_xor<16>(sq); sq = sum_x32(sq); if (fq == 0) (void)__hip_atomic_fetch_add(ssq + row, (unsigned long long)(sq * 1048576.f + 0.5f), __ATOMIC_RELAXED, __HIP_MEMORY_SCOPE_AGENT); } }
.LBB0_989:
	v_add_u32_e32 v156, 32, v206
	v_ashrrev_i32_e32 v157, 31, v156
	v_add_u32_e32 v152, 48, v206
	v_lshlrev_b64 v[114:115], 12, v[156:157]
	v_ashrrev_i32_e32 v153, 31, v152
	v_lshl_add_u64 v[158:159], v[204:205], 0, v[114:115]
	v_lshlrev_b64 v[114:115], 12, v[152:153]
	v_lshl_add_u64 v[154:155], v[204:205], 0, v[114:115]
	global_load_dwordx4 v[144:147], v[158:159], off
	global_load_dwordx4 v[140:143], v[158:159], off offset:64
	global_load_dwordx4 v[134:137], v[158:159], off offset:512
	global_load_dwordx4 v[130:133], v[158:159], off offset:576
	global_load_dwordx4 v[126:129], v[154:155], off
	global_load_dwordx4 v[122:125], v[154:155], off offset:64
	global_load_dwordx4 v[118:121], v[154:155], off offset:512
	global_load_dwordx4 v[114:117], v[154:155], off offset:576
	s_mov_b64 s[28:29], -1
	s_and_b64 vcc, exec, s[24:25]
	s_waitcnt vmcnt(7)
	v_add_f32_e32 v150, v112, v146
	v_add_f32_e32 v151, v113, v147
	v_add_f32_e32 v148, v110, v144
	v_add_f32_e32 v149, v111, v145
	s_waitcnt vmcnt(6)
	v_add_f32_e32 v144, v106, v140
	v_add_f32_e32 v145, v107, v141
	s_waitcnt vmcnt(5)
	v_add_f32_e32 v138, v102, v134
	v_add_f32_e32 v139, v103, v135
	s_waitcnt vmcnt(4)
	v_add_f32_e32 v110, v98, v130
	v_add_f32_e32 v111, v99, v131
	global_store_dwordx4 v[158:159], v[148:151], off
	s_cbranch_vccz .LBB0_991
	v_add_f32_e32 v146, v108, v142
	v_add_f32_e32 v147, v109, v143
	v_add_f32_e32 v140, v104, v136
	v_add_f32_e32 v141, v105, v137
	v_add_f32_e32 v112, v100, v132
	v_add_f32_e32 v113, v101, v133
	global_store_dwordx4 v[158:159], v[144:147], off offset:64
	global_store_dwordx4 v[158:159], v[138:141], off offset:512
	global_store_dwordx4 v[158:159], v[110:113], off offset:576
	s_mov_b64 s[28:29], 0
.LBB0_991:
	s_andn2_b64 vcc, exec, s[28:29]
	s_cbranch_vccnz .LBB0_995
	v_mul_f32_e32 v102, v149, v149
	v_mul_f32_e32 v103, v151, v151
	v_fmac_f32_e32 v102, v148, v148
	v_fmac_f32_e32 v103, v150, v150
	v_add_f32_e32 v112, v102, v103
	v_mul_f32_e32 v102, v80, v150
	v_mul_f32_e32 v103, v81, v151
	v_mul_f32_e32 v106, v78, v148
	v_mul_f32_e32 v107, v79, v149
	v_add_f32_e32 v146, v108, v142
	v_add_f32_e32 v147, v109, v143
	v_lshlrev_b64 v[98:99], 10, v[156:157]
	v_cvt_pk_bf16_f32 v106, v106, v107
	v_cvt_pk_bf16_f32 v107, v102, v103
	v_mul_f32_e32 v102, v145, v145
	v_mul_f32_e32 v103, v147, v147
	v_lshl_add_u64 v[98:99], v[98:99], 0, v[202:203]
	v_fmac_f32_e32 v102, v144, v144
	v_fmac_f32_e32 v103, v146, v146
	v_lshl_add_u64 v[98:99], v[98:99], 1, s[12:13]
	v_add_f32_e32 v102, v102, v103
	global_store_dwordx2 v[98:99], v[106:107], off
	v_add_f32_e32 v108, v112, v102
	v_mul_f32_e32 v102, v68, v146
	v_mul_f32_e32 v103, v69, v147
	v_mul_f32_e32 v106, v66, v144
	v_mul_f32_e32 v107, v67, v145
	v_add_f32_e32 v140, v104, v136
	v_add_f32_e32 v141, v105, v137
	v_cvt_pk_bf16_f32 v106, v106, v107
	v_cvt_pk_bf16_f32 v107, v102, v103
	v_mul_f32_e32 v102, v139, v139
	v_mul_f32_e32 v103, v141, v141
	v_fmac_f32_e32 v102, v138, v138
	v_fmac_f32_e32 v103, v140, v140
	v_add_f32_e32 v102, v102, v103
	global_store_dwordx4 v[158:159], v[144:147], off offset:64
	global_store_dwordx2 v[98:99], v[106:107], off offset:32
	v_add_f32_e32 v106, v108, v102
	v_mul_f32_e32 v102, v76, v140
	v_mul_f32_e32 v103, v77, v141
	v_mul_f32_e32 v104, v74, v138
	v_mul_f32_e32 v105, v75, v139
	v_add_f32_e32 v112, v100, v132
	v_add_f32_e32 v113, v101, v133
	v_cvt_pk_bf16_f32 v104, v104, v105
	v_cvt_pk_bf16_f32 v105, v102, v103
	v_mul_f32_e32 v102, v111, v111
	v_mul_f32_e32 v103, v113, v113
	v_fmac_f32_e32 v102, v110, v110
	v_fmac_f32_e32 v103, v112, v112
	v_add_f32_e32 v102, v102, v103
	global_store_dwordx4 v[158:159], v[138:141], off offset:512
	global_store_dwordx2 v[98:99], v[104:105], off offset:256
	v_add_f32_e32 v104, v106, v102
	ds_swizzle_b32 v105, v104 offset:swizzle(SWAP,16)
	v_mul_f32_e32 v102, v62, v110
	v_mul_f32_e32 v103, v63, v111
	global_store_dwordx4 v[158:159], v[110:113], off offset:576
	v_mul_f32_e32 v100, v64, v112
	v_mul_f32_e32 v101, v65, v113
	v_cvt_pk_bf16_f32 v102, v102, v103
	s_nop 0
	v_cvt_pk_bf16_f32 v103, v100, v101
	global_store_dwordx2 v[98:99], v[102:103], off offset:288
	s_waitcnt lgkmcnt(0)
	v_add_f32_e32 v98, v104, v105
	v_mov_b32_e32 v99, v98
	s_nop 1
	v_permlane32_swap_b32_e32 v98, v99
	s_and_saveexec_b64 s[28:29], s[8:9]
	s_cbranch_execz .LBB0_994
	v_add_f32_e32 v98, v98, v99
	s_mov_b32 s40, 0x49800000
	v_fma_f32 v98, v98, s40, 0.5
	v_trunc_f32_e32 v98, v98
	v_mul_f32_e32 v99, 0x2f800000, v98
	v_floor_f32_e32 v99, v99
	v_fmac_f32_e32 v98, 0xcf800000, v99
	v_cvt_u32_f32_e32 v98, v98
	v_cvt_u32_f32_e32 v99, v99
	v_lshl_add_u64 v[100:101], v[156:157], 3, s[10:11]
	global_atomic_add_x2 v[100:101], v[98:99], off

; #define GAS __attribute__((address_space(1)))
; __device__ __forceinline__ unsigned cvt_pk_bf16(float lo, float hi) { unsigned r; asm("v_cvt_pk_bf16_f32 %0, %1, %2" : "=v"(r) : "v"(lo), "v"(hi)); return r; }
; template <int M> __device__ __forceinline__ float swz_xor(float v) { return __int_as_float(__builtin_amdgcn_ds_swizzle(__float_as_int(v), 0x1f | (M << 10))); }
; __device__ __forceinline__ float sum_x32(float v) { auto rr = __builtin_amdgcn_permlane32_swap(__float_as_uint(v), __float_as_uint(v), false, false); return __uint_as_float(rr[0]) + __uint_as_float(rr[1]); }
;     __device__ __forceinline__ void operator()(const f32x4 (&acc)[2][2][4][2], const Unit& u, int wr, int wc, int fr, int fq) const {
;     ...
;                 for (int mm = 0; mm < 2; ++mm) { const int m = 2 * mh + mm, row = row0 + ai * HALF + m * 16; const size_t off = (size_t)row * ldc + col0; float sq = 0.f;
; #pragma unroll
;                     for (int bj = 0; bj < 2; ++bj)
; #pragma unroll
;                         for (int n = 0; n < 2; ++n) { const f32x4 v = bsv[mm][bj][n] + acc[ai][bj][m][n]; *(GAS f32x4*)(out + off + bj * HALF + n * 16) = v;
;                             if (do_norm) { sq += (v[0] * v[0] + v[1] * v[1]) + (v[2] * v[2] + v[3] * v[3]); const f32x4 w = v * gv[bj][n];
;                                 u32x2 pk; pk.x = cvt_pk_bf16(w[0], w[1]); pk.y = cvt_pk_bf16(w[2], w[3]); *(GAS u32x2*)(xb + off + bj * HALF + n * 16) = pk; } }
;                     if (do_norm) { sq += swz_xor<16>(sq); sq = sum_x32(sq); if (fq == 0) (void)__hip_atomic_fetch_add(ssq + row, (unsigned long long)(sq * 1048576.f + 0.5f), __ATOMIC_RELAXED, __HIP_MEMORY_SCOPE_AGENT); } }
.LBB0_995:
	s_waitcnt vmcnt(4)
	v_add_f32_e32 v108, v96, v128
	v_add_f32_e32 v109, v97, v129
	v_add_f32_e32 v106, v94, v126
	v_add_f32_e32 v107, v95, v127
	s_mov_b64 s[28:29], -1
	s_and_b64 vcc, exec, s[24:25]
	s_waitcnt vmcnt(3)
	v_add_f32_e32 v102, v90, v122
	v_add_f32_e32 v103, v91, v123
	s_waitcnt vmcnt(2)
	v_add_f32_e32 v98, v86, v118
	v_add_f32_e32 v99, v87, v119
	s_waitcnt vmcnt(1)
	v_add_f32_e32 v94, v82, v114
	v_add_f32_e32 v95, v83, v115
	global_store_dwordx4 v[154:155], v[106:109], off
	s_cbranch_vccz .LBB0_997
	v_add_f32_e32 v104, v92, v124
	v_add_f32_e32 v105, v93, v125
	v_add_f32_e32 v100, v88, v120
	v_add_f32_e32 v101, v89, v121
	v_add_f32_e32 v96, v84, v116
	v_add_f32_e32 v97, v85, v117
	global_store_dwordx4 v[154:155], v[102:105], off offset:64
	global_store_dwordx4 v[154:155], v[98:101], off offset:512
	global_store_dwordx4 v[154:155], v[94:97], off offset:576
	s_mov_b64 s[28:29], 0
.LBB0_997:
	s_andn2_b64 vcc, exec, s[28:29]
	s_cbranch_vccnz .LBB0_1001
	v_mul_f32_e32 v86, v107, v107
	v_mul_f32_e32 v87, v109, v109
	v_fmac_f32_e32 v86, v106, v106
	v_fmac_f32_e32 v87, v108, v108
	v_add_f32_e32 v96, v86, v87
	v_mul_f32_e32 v86, v80, v108
	v_mul_f32_e32 v87, v81, v109
	v_mul_f32_e32 v90, v78, v106
	v_mul_f32_e32 v91, v79, v107
	v_add_f32_e32 v104, v92, v124
	v_add_f32_e32 v105, v93, v125
	v_lshlrev_b64 v[82:83], 10, v[152:153]
	v_cvt_pk_bf16_f32 v90, v90, v91
	v_cvt_pk_bf16_f32 v91, v86, v87
	v_mul_f32_e32 v86, v103, v103
	v_mul_f32_e32 v87, v105, v105
	v_lshl_add_u64 v[82:83], v[82:83], 0, v[202:203]
	v_fmac_f32_e32 v86, v102, v102
	v_fmac_f32_e32 v87, v104, v104
	v_lshl_add_u64 v[82:83], v[82:83], 1, s[12:13]
	v_add_f32_e32 v86, v86, v87
	global_store_dwordx2 v[82:83], v[90:91], off
	v_add_f32_e32 v92, v96, v86
	v_mul_f32_e32 v86, v68, v104
	v_mul_f32_e32 v87, v69, v105
	v_mul_f32_e32 v90, v66, v102
	v_mul_f32_e32 v91, v67, v103
	v_add_f32_e32 v100, v88, v120
	v_add_f32_e32 v101, v89, v121
	v_cvt_pk_bf16_f32 v90, v90, v91
	v_cvt_pk_bf16_f32 v91, v86, v87
	v_mul_f32_e32 v86, v99, v99
	v_mul_f32_e32 v87, v101, v101
	v_fmac_f32_e32 v86, v98, v98
	v_fmac_f32_e32 v87, v100, v100
	v_add_f32_e32 v86, v86, v87
	global_store_dwordx4 v[154:155], v[102:105], off offset:64
	global_store_dwordx2 v[82:83], v[90:91], off offset:32
	v_add_f32_e32 v90, v92, v86
	v_mul_f32_e32 v86, v76, v100
	v_mul_f32_e32 v87, v77, v101
	v_mul_f32_e32 v88, v74, v98
	v_mul_f32_e32 v89, v75, v99
	v_add_f32_e32 v96, v84, v116
	v_add_f32_e32 v97, v85, v117
	v_cvt_pk_bf16_f32 v88, v88, v89
	v_cvt_pk_bf16_f32 v89, v86, v87
	v_mul_f32_e32 v86, v95, v95
	v_mul_f32_e32 v87, v97, v97
	v_fmac_f32_e32 v86, v94, v94
	v_fmac_f32_e32 v87, v96, v96
	v_add_f32_e32 v86, v86, v87
	global_store_dwordx4 v[154:155], v[98:101], off offset:512
	global_store_dwordx2 v[82:83], v[88:89], off offset:256
	v_add_f32_e32 v88, v90, v86
	ds_swizzle_b32 v89, v88 offset:swizzle(SWAP,16)
	v_mul_f32_e32 v86, v62, v94
	v_mul_f32_e32 v87, v63, v95
	global_store_dwordx4 v[154:155], v[94:97], off offset:576
	v_mul_f32_e32 v84, v64, v96
	v_mul_f32_e32 v85, v65, v97
	v_cvt_pk_bf16_f32 v86, v86, v87
	s_nop 0
	v_cvt_pk_bf16_f32 v87, v84, v85
	global_store_dwordx2 v[82:83], v[86:87], off offset:288
	s_waitcnt lgkmcnt(0)
	v_add_f32_e32 v82, v88, v89
	v_mov_b32_e32 v83, v82
	s_nop 1
	v_permlane32_swap_b32_e32 v82, v83
	s_and_saveexec_b64 s[28:29], s[8:9]
	s_cbranch_execz .LBB0_1000
	v_add_f32_e32 v82, v82, v83
	s_mov_b32 s40, 0x49800000
	v_fma_f32 v82, v82, s40, 0.5
	v_trunc_f32_e32 v82, v82
	v_mul_f32_e32 v83, 0x2f800000, v82
	v_floor_f32_e32 v83, v83
	v_fmac_f32_e32 v82, 0xcf800000, v83
	v_cvt_u32_f32_e32 v82, v82
	v_cvt_u32_f32_e32 v83, v83
	v_lshl_add_u64 v[84:85], v[152:153], 3, s[10:11]
	global_atomic_add_x2 v[84:85], v[82:83], off

; #define GAS __attribute__((address_space(1)))
; __device__ __forceinline__ unsigned cvt_pk_bf16(float lo, float hi) { unsigned r; asm("v_cvt_pk_bf16_f32 %0, %1, %2" : "=v"(r) : "v"(lo), "v"(hi)); return r; }
; template <int M> __device__ __forceinline__ float swz_xor(float v) { return __int_as_float(__builtin_amdgcn_ds_swizzle(__float_as_int(v), 0x1f | (M << 10))); }
; __device__ __forceinline__ float sum_x32(float v) { auto rr = __builtin_amdgcn_permlane32_swap(__float_as_uint(v), __float_as_uint(v), false, false); return __uint_as_float(rr[0]) + __uint_as_float(rr[1]); }
;     __device__ __forceinline__ void operator()(const f32x4 (&acc)[2][2][4][2], const Unit& u, int wr, int wc, int fr, int fq) const {
;     ...
;                 f32x4 bsv[2][2][2];
; #pragma unroll
;                 for (int mm = 0; mm < 2; ++mm) { const size_t off = (size_t)(row0 + ai * HALF + (2 * mh + mm) * 16) * ldc + col0;
; #pragma unroll
;                     for (int bj = 0; bj < 2; ++bj)
; #pragma unroll
;                         for (int n = 0; n < 2; ++n) bsv[mm][bj][n] = *(const GAS f32x4*)(base + off + bj * HALF + n * 16); }
; #pragma unroll
;                 for (int mm = 0; mm < 2; ++mm) { const int m = 2 * mh + mm, row = row0 + ai * HALF + m * 16; const size_t off = (size_t)row * ldc + col0; float sq = 0.f;
; #pragma unroll
;                     for (int bj = 0; bj < 2; ++bj)
; #pragma unroll
;                         for (int n = 0; n < 2; ++n) { const f32x4 v = bsv[mm][bj][n] + acc[ai][bj][m][n]; *(GAS f32x4*)(out + off + bj * HALF + n * 16) = v;
;                             if (do_norm) { sq += (v[0] * v[0] + v[1] * v[1]) + (v[2] * v[2] + v[3] * v[3]); const f32x4 w = v * gv[bj][n];
;                                 u32x2 pk; pk.x = cvt_pk_bf16(w[0], w[1]); pk.y = cvt_pk_bf16(w[2], w[3]); *(GAS u32x2*)(xb + off + bj * HALF + n * 16) = pk; } }
;                     if (do_norm) { sq += swz_xor<16>(sq); sq = sum_x32(sq); if (fq == 0) (void)__hip_atomic_fetch_add(ssq + row, (unsigned long long)(sq * 1048576.f + 0.5f), __ATOMIC_RELAXED, __HIP_MEMORY_SCOPE_AGENT); } }
.LBB0_1001:
	v_add_u32_e32 v124, 0x80, v206
	v_ashrrev_i32_e32 v125, 31, v124
	v_add_u32_e32 v120, 0x90, v206
	v_lshlrev_b64 v[82:83], 12, v[124:125]
	v_ashrrev_i32_e32 v121, 31, v120
	v_lshl_add_u64 v[126:127], v[204:205], 0, v[82:83]
	v_lshlrev_b64 v[82:83], 12, v[120:121]
	v_lshl_add_u64 v[122:123], v[204:205], 0, v[82:83]
	global_load_dwordx4 v[112:115], v[126:127], off
	global_load_dwordx4 v[108:111], v[126:127], off offset:64
	global_load_dwordx4 v[102:105], v[126:127], off offset:512
	global_load_dwordx4 v[98:101], v[126:127], off offset:576
	global_load_dwordx4 v[94:97], v[122:123], off
	global_load_dwordx4 v[90:93], v[122:123], off offset:64
	global_load_dwordx4 v[86:89], v[122:123], off offset:512
	global_load_dwordx4 v[82:85], v[122:123], off offset:576
	s_mov_b64 s[28:29], -1
	s_and_b64 vcc, exec, s[24:25]
	s_waitcnt vmcnt(7)
	v_add_f32_e32 v118, v72, v114
	v_add_f32_e32 v119, v73, v115
	v_add_f32_e32 v116, v70, v112
	v_add_f32_e32 v117, v71, v113
	s_waitcnt vmcnt(6)
	v_add_f32_e32 v112, v58, v108
	v_add_f32_e32 v113, v59, v109
	s_waitcnt vmcnt(5)
	v_add_f32_e32 v106, v54, v102
	v_add_f32_e32 v107, v55, v103
	s_waitcnt vmcnt(4)
	v_add_f32_e32 v70, v50, v98
	v_add_f32_e32 v71, v51, v99
	global_store_dwordx4 v[126:127], v[116:119], off
	s_cbranch_vccz .LBB0_1003
	v_add_f32_e32 v114, v60, v110
	v_add_f32_e32 v115, v61, v111
	v_add_f32_e32 v108, v56, v104
	v_add_f32_e32 v109, v57, v105
	v_add_f32_e32 v72, v52, v100
	v_add_f32_e32 v73, v53, v101
	global_store_dwordx4 v[126:127], v[112:115], off offset:64
	global_store_dwordx4 v[126:127], v[106:109], off offset:512
	global_store_dwordx4 v[126:127], v[70:73], off offset:576
	s_mov_b64 s[28:29], 0
.LBB0_1003:
	s_andn2_b64 vcc, exec, s[28:29]
	s_cbranch_vccnz .LBB0_1007
	v_mul_f32_e32 v54, v117, v117
	v_mul_f32_e32 v55, v119, v119
	v_fmac_f32_e32 v54, v116, v116
	v_fmac_f32_e32 v55, v118, v118
	v_add_f32_e32 v72, v54, v55
	v_mul_f32_e32 v54, v80, v118
	v_mul_f32_e32 v55, v81, v119
	v_mul_f32_e32 v58, v78, v116
	v_mul_f32_e32 v59, v79, v117
	v_add_f32_e32 v114, v60, v110
	v_add_f32_e32 v115, v61, v111
	v_lshlrev_b64 v[50:51], 10, v[124:125]
	v_cvt_pk_bf16_f32 v58, v58, v59
	v_cvt_pk_bf16_f32 v59, v54, v55
	v_mul_f32_e32 v54, v113, v113
	v_mul_f32_e32 v55, v115, v115
	v_lshl_add_u64 v[50:51], v[50:51], 0, v[202:203]
	v_fmac_f32_e32 v54, v112, v112
	v_fmac_f32_e32 v55, v114, v114
	v_lshl_add_u64 v[50:51], v[50:51], 1, s[12:13]
	v_add_f32_e32 v54, v54, v55
	global_store_dwordx2 v[50:51], v[58:59], off
	v_add_f32_e32 v60, v72, v54
	v_mul_f32_e32 v54, v68, v114
	v_mul_f32_e32 v55, v69, v115
	v_mul_f32_e32 v58, v66, v112
	v_mul_f32_e32 v59, v67, v113
	v_add_f32_e32 v108, v56, v104
	v_add_f32_e32 v109, v57, v105
	v_cvt_pk_bf16_f32 v58, v58, v59
	v_cvt_pk_bf16_f32 v59, v54, v55
	v_mul_f32_e32 v54, v107, v107
	v_mul_f32_e32 v55, v109, v109
	v_fmac_f32_e32 v54, v106, v106
	v_fmac_f32_e32 v55, v108, v108
	v_add_f32_e32 v54, v54, v55
	global_store_dwordx4 v[126:127], v[112:115], off offset:64
	global_store_dwordx2 v[50:51], v[58:59], off offset:32
	v_add_f32_e32 v58, v60, v54
	v_mul_f32_e32 v54, v76, v108
	v_mul_f32_e32 v55, v77, v109
	v_mul_f32_e32 v56, v74, v106
	v_mul_f32_e32 v57, v75, v107
	v_add_f32_e32 v72, v52, v100
	v_add_f32_e32 v73, v53, v101
	v_cvt_pk_bf16_f32 v56, v56, v57
	v_cvt_pk_bf16_f32 v57, v54, v55
	v_mul_f32_e32 v54, v71, v71
	v_mul_f32_e32 v55, v73, v73
	v_fmac_f32_e32 v54, v70, v70
	v_fmac_f32_e32 v55, v72, v72
	v_add_f32_e32 v54, v54, v55
	global_store_dwordx4 v[126:127], v[106:109], off offset:512
	global_store_dwordx2 v[50:51], v[56:57], off offset:256
	v_add_f32_e32 v56, v58, v54
	ds_swizzle_b32 v57, v56 offset:swizzle(SWAP,16)
	v_mul_f32_e32 v54, v62, v70
	v_mul_f32_e32 v55, v63, v71
	global_store_dwordx4 v[126:127], v[70:73], off offset:576
	v_mul_f32_e32 v52, v64, v72
	v_mul_f32_e32 v53, v65, v73
	v_cvt_pk_bf16_f32 v54, v54, v55
	s_nop 0
	v_cvt_pk_bf16_f32 v55, v52, v53
	global_store_dwordx2 v[50:51], v[54:55], off offset:288
	s_waitcnt lgkmcnt(0)
	v_add_f32_e32 v50, v56, v57
	v_mov_b32_e32 v51, v50
	s_nop 1
	v_permlane32_swap_b32_e32 v50, v51
	s_and_saveexec_b64 s[28:29], s[8:9]
	s_cbranch_execz .LBB0_1006
	v_add_f32_e32 v50, v50, v51
	s_mov_b32 s40, 0x49800000
	v_fma_f32 v50, v50, s40, 0.5
	v_trunc_f32_e32 v50, v50
	v_mul_f32_e32 v51, 0x2f800000, v50
	v_floor_f32_e32 v51, v51
	v_fmac_f32_e32 v50, 0xcf800000, v51
	v_cvt_u32_f32_e32 v50, v50
	v_cvt_u32_f32_e32 v51, v51
	v_lshl_add_u64 v[52:53], v[124:125], 3, s[10:11]
	global_atomic_add_x2 v[52:53], v[50:51], off

; #define GAS __attribute__((address_space(1)))
; __device__ __forceinline__ unsigned cvt_pk_bf16(float lo, float hi) { unsigned r; asm("v_cvt_pk_bf16_f32 %0, %1, %2" : "=v"(r) : "v"(lo), "v"(hi)); return r; }
; template <int M> __device__ __forceinline__ float swz_xor(float v) { return __int_as_float(__builtin_amdgcn_ds_swizzle(__float_as_int(v), 0x1f | (M << 10))); }
; __device__ __forceinline__ float sum_x32(float v) { auto rr = __builtin_amdgcn_permlane32_swap(__float_as_uint(v), __float_as_uint(v), false, false); return __uint_as_float(rr[0]) + __uint_as_float(rr[1]); }
;     __device__ __forceinline__ void operator()(const f32x4 (&acc)[2][2][4][2], const Unit& u, int wr, int wc, int fr, int fq) const {
;     ...
;                 for (int mm = 0; mm < 2; ++mm) { const int m = 2 * mh + mm, row = row0 + ai * HALF + m * 16; const size_t off = (size_t)row * ldc + col0; float sq = 0.f;
; #pragma unroll
;                     for (int bj = 0; bj < 2; ++bj)
; #pragma unroll
;                         for (int n = 0; n < 2; ++n) { const f32x4 v = bsv[mm][bj][n] + acc[ai][bj][m][n]; *(GAS f32x4*)(out + off + bj * HALF + n * 16) = v;
;                             if (do_norm) { sq += (v[0] * v[0] + v[1] * v[1]) + (v[2] * v[2] + v[3] * v[3]); const f32x4 w = v * gv[bj][n];
;                                 u32x2 pk; pk.x = cvt_pk_bf16(w[0], w[1]); pk.y = cvt_pk_bf16(w[2], w[3]); *(GAS u32x2*)(xb + off + bj * HALF + n * 16) = pk; } }
;                     if (do_norm) { sq += swz_xor<16>(sq); sq = sum_x32(sq); if (fq == 0) (void)__hip_atomic_fetch_add(ssq + row, (unsigned long long)(sq * 1048576.f + 0.5f), __ATOMIC_RELAXED, __HIP_MEMORY_SCOPE_AGENT); } }
.LBB0_1007:
	s_waitcnt vmcnt(4)
	v_add_f32_e32 v60, v48, v96
	v_add_f32_e32 v61, v49, v97
	v_add_f32_e32 v58, v46, v94
	v_add_f32_e32 v59, v47, v95
	s_mov_b64 s[28:29], -1
	s_and_b64 vcc, exec, s[24:25]
	s_waitcnt vmcnt(3)
	v_add_f32_e32 v54, v42, v90
	v_add_f32_e32 v55, v43, v91
	s_waitcnt vmcnt(2)
	v_add_f32_e32 v50, v38, v86
	v_add_f32_e32 v51, v39, v87
	s_waitcnt vmcnt(1)
	v_add_f32_e32 v46, v34, v82
	v_add_f32_e32 v47, v35, v83
	global_store_dwordx4 v[122:123], v[58:61], off
	s_cbranch_vccz .LBB0_1009
	v_add_f32_e32 v56, v44, v92
	v_add_f32_e32 v57, v45, v93
	v_add_f32_e32 v52, v40, v88
	v_add_f32_e32 v53, v41, v89
	v_add_f32_e32 v48, v36, v84
	v_add_f32_e32 v49, v37, v85
	global_store_dwordx4 v[122:123], v[54:57], off offset:64
	global_store_dwordx4 v[122:123], v[50:53], off offset:512
	global_store_dwordx4 v[122:123], v[46:49], off offset:576
	s_mov_b64 s[28:29], 0
.LBB0_1009:
	s_andn2_b64 vcc, exec, s[28:29]
	s_cbranch_vccnz .LBB0_1013
	v_mul_f32_e32 v38, v59, v59
	v_mul_f32_e32 v39, v61, v61
	v_fmac_f32_e32 v38, v58, v58
	v_fmac_f32_e32 v39, v60, v60
	v_add_f32_e32 v48, v38, v39
	v_mul_f32_e32 v38, v80, v60
	v_mul_f32_e32 v39, v81, v61
	v_mul_f32_e32 v42, v78, v58
	v_mul_f32_e32 v43, v79, v59
	v_add_f32_e32 v56, v44, v92
	v_add_f32_e32 v57, v45, v93
	v_lshlrev_b64 v[34:35], 10, v[120:121]
	v_cvt_pk_bf16_f32 v42, v42, v43
	v_cvt_pk_bf16_f32 v43, v38, v39
	v_mul_f32_e32 v38, v55, v55
	v_mul_f32_e32 v39, v57, v57
	v_lshl_add_u64 v[34:35], v[34:35], 0, v[202:203]
	v_fmac_f32_e32 v38, v54, v54
	v_fmac_f32_e32 v39, v56, v56
	v_lshl_add_u64 v[34:35], v[34:35], 1, s[12:13]
	v_add_f32_e32 v38, v38, v39
	global_store_dwordx2 v[34:35], v[42:43], off
	v_add_f32_e32 v44, v48, v38
	v_mul_f32_e32 v38, v68, v56
	v_mul_f32_e32 v39, v69, v57
	v_mul_f32_e32 v42, v66, v54
	v_mul_f32_e32 v43, v67, v55
	v_add_f32_e32 v52, v40, v88
	v_add_f32_e32 v53, v41, v89
	v_cvt_pk_bf16_f32 v42, v42, v43
	v_cvt_pk_bf16_f32 v43, v38, v39
	v_mul_f32_e32 v38, v51, v51
	v_mul_f32_e32 v39, v53, v53
	v_fmac_f32_e32 v38, v50, v50
	v_fmac_f32_e32 v39, v52, v52
	v_add_f32_e32 v38, v38, v39
	global_store_dwordx4 v[122:123], v[54:57], off offset:64
	global_store_dwordx2 v[34:35], v[42:43], off offset:32
	v_add_f32_e32 v42, v44, v38
	v_mul_f32_e32 v38, v76, v52
	v_mul_f32_e32 v39, v77, v53
	v_mul_f32_e32 v40, v74, v50
	v_mul_f32_e32 v41, v75, v51
	v_add_f32_e32 v48, v36, v84
	v_add_f32_e32 v49, v37, v85
	v_cvt_pk_bf16_f32 v40, v40, v41
	v_cvt_pk_bf16_f32 v41, v38, v39
	v_mul_f32_e32 v38, v47, v47
	v_mul_f32_e32 v39, v49, v49
	v_fmac_f32_e32 v38, v46, v46
	v_fmac_f32_e32 v39, v48, v48
	v_add_f32_e32 v38, v38, v39
	global_store_dwordx4 v[122:123], v[50:53], off offset:512
	global_store_dwordx2 v[34:35], v[40:41], off offset:256
	v_add_f32_e32 v40, v42, v38
	ds_swizzle_b32 v41, v40 offset:swizzle(SWAP,16)
	v_mul_f32_e32 v38, v62, v46
	v_mul_f32_e32 v39, v63, v47
	global_store_dwordx4 v[122:123], v[46:49], off offset:576
	v_mul_f32_e32 v36, v64, v48
	v_mul_f32_e32 v37, v65, v49
	v_cvt_pk_bf16_f32 v38, v38, v39
	s_nop 0
	v_cvt_pk_bf16_f32 v39, v36, v37
	global_store_dwordx2 v[34:35], v[38:39], off offset:288
	s_waitcnt lgkmcnt(0)
	v_add_f32_e32 v34, v40, v41
	v_mov_b32_e32 v35, v34
	s_nop 1
	v_permlane32_swap_b32_e32 v34, v35
	s_and_saveexec_b64 s[28:29], s[8:9]
	s_cbranch_execz .LBB0_1012
	v_add_f32_e32 v34, v34, v35
	s_mov_b32 s40, 0x49800000
	v_fma_f32 v34, v34, s40, 0.5
	v_trunc_f32_e32 v34, v34
	v_mul_f32_e32 v35, 0x2f800000, v34
	v_floor_f32_e32 v35, v35
	v_fmac_f32_e32 v34, 0xcf800000, v35
	v_cvt_u32_f32_e32 v34, v34
	v_cvt_u32_f32_e32 v35, v35
	v_lshl_add_u64 v[36:37], v[120:121], 3, s[10:11]
	global_atomic_add_x2 v[36:37], v[34:35], off

; #define GAS __attribute__((address_space(1)))
; __device__ __forceinline__ unsigned cvt_pk_bf16(float lo, float hi) { unsigned r; asm("v_cvt_pk_bf16_f32 %0, %1, %2" : "=v"(r) : "v"(lo), "v"(hi)); return r; }
; template <int M> __device__ __forceinline__ float swz_xor(float v) { return __int_as_float(__builtin_amdgcn_ds_swizzle(__float_as_int(v), 0x1f | (M << 10))); }
; __device__ __forceinline__ float sum_x32(float v) { auto rr = __builtin_amdgcn_permlane32_swap(__float_as_uint(v), __float_as_uint(v), false, false); return __uint_as_float(rr[0]) + __uint_as_float(rr[1]); }
;     __device__ __forceinline__ void operator()(const f32x4 (&acc)[2][2][4][2], const Unit& u, int wr, int wc, int fr, int fq) const {
;     ...
;                 f32x4 bsv[2][2][2];
; #pragma unroll
;                 for (int mm = 0; mm < 2; ++mm) { const size_t off = (size_t)(row0 + ai * HALF + (2 * mh + mm) * 16) * ldc + col0;
; #pragma unroll
;                     for (int bj = 0; bj < 2; ++bj)
; #pragma unroll
;                         for (int n = 0; n < 2; ++n) bsv[mm][bj][n] = *(const GAS f32x4*)(base + off + bj * HALF + n * 16); }
; #pragma unroll
;                 for (int mm = 0; mm < 2; ++mm) { const int m = 2 * mh + mm, row = row0 + ai * HALF + m * 16; const size_t off = (size_t)row * ldc + col0; float sq = 0.f;
; #pragma unroll
;                     for (int bj = 0; bj < 2; ++bj)
; #pragma unroll
;                         for (int n = 0; n < 2; ++n) { const f32x4 v = bsv[mm][bj][n] + acc[ai][bj][m][n]; *(GAS f32x4*)(out + off + bj * HALF + n * 16) = v;
;                             if (do_norm) { sq += (v[0] * v[0] + v[1] * v[1]) + (v[2] * v[2] + v[3] * v[3]); const f32x4 w = v * gv[bj][n];
;                                 u32x2 pk; pk.x = cvt_pk_bf16(w[0], w[1]); pk.y = cvt_pk_bf16(w[2], w[3]); *(GAS u32x2*)(xb + off + bj * HALF + n * 16) = pk; } }
;                     if (do_norm) { sq += swz_xor<16>(sq); sq = sum_x32(sq); if (fq == 0) (void)__hip_atomic_fetch_add(ssq + row, (unsigned long long)(sq * 1048576.f + 0.5f), __ATOMIC_RELAXED, __HIP_MEMORY_SCOPE_AGENT); } }
.LBB0_1013:
	v_add_u32_e32 v94, 0xa0, v206
	v_ashrrev_i32_e32 v95, 31, v94
	v_add_u32_e32 v90, 0xb0, v206
	v_lshlrev_b64 v[34:35], 12, v[94:95]
	v_ashrrev_i32_e32 v91, 31, v90
	v_lshl_add_u64 v[96:97], v[204:205], 0, v[34:35]
	v_lshlrev_b64 v[34:35], 12, v[90:91]
	v_lshl_add_u64 v[92:93], v[204:205], 0, v[34:35]
	global_load_dwordx4 v[58:61], v[96:97], off
	global_load_dwordx4 v[70:73], v[96:97], off offset:64
	global_load_dwordx4 v[54:57], v[96:97], off offset:512
	global_load_dwordx4 v[50:53], v[96:97], off offset:576
	global_load_dwordx4 v[46:49], v[92:93], off
	global_load_dwordx4 v[42:45], v[92:93], off offset:64
	global_load_dwordx4 v[38:41], v[92:93], off offset:512
	global_load_dwordx4 v[34:37], v[92:93], off offset:576
	s_mov_b64 s[28:29], -1
	s_and_b64 vcc, exec, s[24:25]
	s_waitcnt vmcnt(7)
	v_add_f32_e32 v88, v32, v60
	v_add_f32_e32 v89, v33, v61
	v_add_f32_e32 v86, v30, v58
	v_add_f32_e32 v87, v31, v59
	s_waitcnt vmcnt(6)
	v_add_f32_e32 v82, v26, v70
	v_add_f32_e32 v83, v27, v71
	s_waitcnt vmcnt(5)
	v_add_f32_e32 v58, v22, v54
	v_add_f32_e32 v59, v23, v55
	s_waitcnt vmcnt(4)
	v_add_f32_e32 v30, v18, v50
	v_add_f32_e32 v31, v19, v51
	global_store_dwordx4 v[96:97], v[86:89], off
	s_cbranch_vccz .LBB0_1015
	v_add_f32_e32 v84, v28, v72
	v_add_f32_e32 v85, v29, v73
	v_add_f32_e32 v60, v24, v56
	v_add_f32_e32 v61, v25, v57
	v_add_f32_e32 v32, v20, v52
	v_add_f32_e32 v33, v21, v53
	global_store_dwordx4 v[96:97], v[82:85], off offset:64
	global_store_dwordx4 v[96:97], v[58:61], off offset:512
	global_store_dwordx4 v[96:97], v[30:33], off offset:576
	s_mov_b64 s[28:29], 0
.LBB0_1015:
	s_andn2_b64 vcc, exec, s[28:29]
	s_cbranch_vccnz .LBB0_1019
	v_mul_f32_e32 v22, v87, v87
	v_mul_f32_e32 v23, v89, v89
	v_fmac_f32_e32 v22, v86, v86
	v_fmac_f32_e32 v23, v88, v88
	v_add_f32_e32 v32, v22, v23
	v_mul_f32_e32 v22, v80, v88
	v_mul_f32_e32 v23, v81, v89
	v_mul_f32_e32 v26, v78, v86
	v_mul_f32_e32 v27, v79, v87
	v_add_f32_e32 v84, v28, v72
	v_add_f32_e32 v85, v29, v73
	v_lshlrev_b64 v[18:19], 10, v[94:95]
	v_cvt_pk_bf16_f32 v26, v26, v27
	v_cvt_pk_bf16_f32 v27, v22, v23
	v_mul_f32_e32 v22, v83, v83
	v_mul_f32_e32 v23, v85, v85
	v_lshl_add_u64 v[18:19], v[18:19], 0, v[202:203]
	v_fmac_f32_e32 v22, v82, v82
	v_fmac_f32_e32 v23, v84, v84
	v_lshl_add_u64 v[18:19], v[18:19], 1, s[12:13]
	v_add_f32_e32 v22, v22, v23
	global_store_dwordx2 v[18:19], v[26:27], off
	v_add_f32_e32 v28, v32, v22
	v_mul_f32_e32 v22, v68, v84
	v_mul_f32_e32 v23, v69, v85
	v_mul_f32_e32 v26, v66, v82
	v_mul_f32_e32 v27, v67, v83
	v_add_f32_e32 v60, v24, v56
	v_add_f32_e32 v61, v25, v57
	v_cvt_pk_bf16_f32 v26, v26, v27
	v_cvt_pk_bf16_f32 v27, v22, v23
	v_mul_f32_e32 v22, v59, v59
	v_mul_f32_e32 v23, v61, v61
	v_fmac_f32_e32 v22, v58, v58
	v_fmac_f32_e32 v23, v60, v60
	v_add_f32_e32 v22, v22, v23
	global_store_dwordx4 v[96:97], v[82:85], off offset:64
	global_store_dwordx2 v[18:19], v[26:27], off offset:32
	v_add_f32_e32 v26, v28, v22
	v_mul_f32_e32 v22, v76, v60
	v_mul_f32_e32 v23, v77, v61
	v_mul_f32_e32 v24, v74, v58
	v_mul_f32_e32 v25, v75, v59
	v_add_f32_e32 v32, v20, v52
	v_add_f32_e32 v33, v21, v53
	v_cvt_pk_bf16_f32 v24, v24, v25
	v_cvt_pk_bf16_f32 v25, v22, v23
	v_mul_f32_e32 v22, v31, v31
	v_mul_f32_e32 v23, v33, v33
	v_fmac_f32_e32 v22, v30, v30
	v_fmac_f32_e32 v23, v32, v32
	v_add_f32_e32 v22, v22, v23
	global_store_dwordx4 v[96:97], v[58:61], off offset:512
	global_store_dwordx2 v[18:19], v[24:25], off offset:256
	v_add_f32_e32 v24, v26, v22
	ds_swizzle_b32 v25, v24 offset:swizzle(SWAP,16)
	v_mul_f32_e32 v22, v62, v30
	v_mul_f32_e32 v23, v63, v31
	global_store_dwordx4 v[96:97], v[30:33], off offset:576
	v_mul_f32_e32 v20, v64, v32
	v_mul_f32_e32 v21, v65, v33
	v_cvt_pk_bf16_f32 v22, v22, v23
	s_nop 0
	v_cvt_pk_bf16_f32 v23, v20, v21
	global_store_dwordx2 v[18:19], v[22:23], off offset:288
	s_waitcnt lgkmcnt(0)
	v_add_f32_e32 v18, v24, v25
	v_mov_b32_e32 v19, v18
	s_nop 1
	v_permlane32_swap_b32_e32 v18, v19
	s_and_saveexec_b64 s[28:29], s[8:9]
	s_cbranch_execz .LBB0_1018
	v_add_f32_e32 v18, v18, v19
	s_mov_b32 s40, 0x49800000
	v_fma_f32 v18, v18, s40, 0.5
	v_trunc_f32_e32 v18, v18
	v_mul_f32_e32 v19, 0x2f800000, v18
	v_floor_f32_e32 v19, v19
	v_fmac_f32_e32 v18, 0xcf800000, v19
	v_cvt_u32_f32_e32 v18, v18
	v_cvt_u32_f32_e32 v19, v19
	v_lshl_add_u64 v[20:21], v[94:95], 3, s[10:11]
	global_atomic_add_x2 v[20:21], v[18:19], off

; #define GAS __attribute__((address_space(1)))
;     __device__ __forceinline__ void operator()(const f32x4 (&acc)[2][2][4][2], const Unit& u, int wr, int wc, int fr, int fq) const {
;     ...
;                 for (int mm = 0; mm < 2; ++mm) { const int m = 2 * mh + mm, row = row0 + ai * HALF + m * 16; const size_t off = (size_t)row * ldc + col0; float sq = 0.f;
; #pragma unroll
;                     for (int bj = 0; bj < 2; ++bj)
; #pragma unroll
;                         for (int n = 0; n < 2; ++n) { const f32x4 v = bsv[mm][bj][n] + acc[ai][bj][m][n]; *(GAS f32x4*)(out + off + bj * HALF + n * 16) = v;
.LBB0_1019:
	s_waitcnt vmcnt(4)
	v_add_f32_e32 v28, v16, v48
	v_add_f32_e32 v29, v17, v49
	v_add_f32_e32 v26, v14, v46
	v_add_f32_e32 v27, v15, v47
	s_mov_b64 s[28:29], -1
	s_and_b64 vcc, exec, s[24:25]
	s_waitcnt vmcnt(3)
	v_add_f32_e32 v22, v10, v42
	v_add_f32_e32 v23, v11, v43
	s_waitcnt vmcnt(2)
	v_add_f32_e32 v18, v6, v38
	v_add_f32_e32 v19, v7, v39
	s_waitcnt vmcnt(1)
	v_add_f32_e32 v14, v2, v34
	v_add_f32_e32 v15, v3, v35
	global_store_dwordx4 v[92:93], v[26:29], off
	s_cbranch_vccz .LBB0_1022
	v_add_f32_e32 v24, v12, v44
	v_add_f32_e32 v25, v13, v45
	v_add_f32_e32 v20, v8, v40
	v_add_f32_e32 v21, v9, v41
	v_add_f32_e32 v16, v4, v36
	v_add_f32_e32 v17, v5, v37
	global_store_dwordx4 v[92:93], v[22:25], off offset:64
	global_store_dwordx4 v[92:93], v[18:21], off offset:512
	global_store_dwordx4 v[92:93], v[14:17], off offset:576
	s_cbranch_execz .LBB0_1023

; #define GAS __attribute__((address_space(1)))
; __device__ __forceinline__ unsigned cvt_pk_bf16(float lo, float hi) { unsigned r; asm("v_cvt_pk_bf16_f32 %0, %1, %2" : "=v"(r) : "v"(lo), "v"(hi)); return r; }
; template <int M> __device__ __forceinline__ float swz_xor(float v) { return __int_as_float(__builtin_amdgcn_ds_swizzle(__float_as_int(v), 0x1f | (M << 10))); }
; __device__ __forceinline__ float sum_x32(float v) { auto rr = __builtin_amdgcn_permlane32_swap(__float_as_uint(v), __float_as_uint(v), false, false); return __uint_as_float(rr[0]) + __uint_as_float(rr[1]); }
;     __device__ __forceinline__ void operator()(const f32x4 (&acc)[2][2][4][2], const Unit& u, int wr, int wc, int fr, int fq) const {
;     ...
;                 for (int mm = 0; mm < 2; ++mm) { const int m = 2 * mh + mm, row = row0 + ai * HALF + m * 16; const size_t off = (size_t)row * ldc + col0; float sq = 0.f;
; #pragma unroll
;                     for (int bj = 0; bj < 2; ++bj)
; #pragma unroll
;                         for (int n = 0; n < 2; ++n) { const f32x4 v = bsv[mm][bj][n] + acc[ai][bj][m][n]; *(GAS f32x4*)(out + off + bj * HALF + n * 16) = v;
;                             if (do_norm) { sq += (v[0] * v[0] + v[1] * v[1]) + (v[2] * v[2] + v[3] * v[3]); const f32x4 w = v * gv[bj][n];
;                                 u32x2 pk; pk.x = cvt_pk_bf16(w[0], w[1]); pk.y = cvt_pk_bf16(w[2], w[3]); *(GAS u32x2*)(xb + off + bj * HALF + n * 16) = pk; } }
;                     if (do_norm) { sq += swz_xor<16>(sq); sq = sum_x32(sq); if (fq == 0) (void)__hip_atomic_fetch_add(ssq + row, (unsigned long long)(sq * 1048576.f + 0.5f), __ATOMIC_RELAXED, __HIP_MEMORY_SCOPE_AGENT); } }
.LBB0_1023:
	v_mul_f32_e32 v6, v27, v27
	v_mul_f32_e32 v7, v29, v29
	v_fmac_f32_e32 v6, v26, v26
	v_fmac_f32_e32 v7, v28, v28
	v_add_f32_e32 v16, v6, v7
	v_mul_f32_e32 v6, v80, v28
	v_mul_f32_e32 v7, v81, v29
	v_mul_f32_e32 v10, v78, v26
	v_mul_f32_e32 v11, v79, v27
	v_add_f32_e32 v24, v12, v44
	v_add_f32_e32 v25, v13, v45
	v_lshlrev_b64 v[2:3], 10, v[90:91]
	v_cvt_pk_bf16_f32 v10, v10, v11
	v_cvt_pk_bf16_f32 v11, v6, v7
	v_mul_f32_e32 v6, v23, v23
	v_mul_f32_e32 v7, v25, v25
	v_lshl_add_u64 v[2:3], v[2:3], 0, v[202:203]
	v_fmac_f32_e32 v6, v22, v22
	v_fmac_f32_e32 v7, v24, v24
	v_lshl_add_u64 v[2:3], v[2:3], 1, s[12:13]
	v_add_f32_e32 v6, v6, v7
	global_store_dwordx2 v[2:3], v[10:11], off
	v_add_f32_e32 v12, v16, v6
	v_mul_f32_e32 v6, v68, v24
	v_mul_f32_e32 v7, v69, v25
	v_mul_f32_e32 v10, v66, v22
	v_mul_f32_e32 v11, v67, v23
	v_add_f32_e32 v20, v8, v40
	v_add_f32_e32 v21, v9, v41
	v_cvt_pk_bf16_f32 v10, v10, v11
	v_cvt_pk_bf16_f32 v11, v6, v7
	v_mul_f32_e32 v6, v19, v19
	v_mul_f32_e32 v7, v21, v21
	v_fmac_f32_e32 v6, v18, v18
	v_fmac_f32_e32 v7, v20, v20
	v_add_f32_e32 v6, v6, v7
	global_store_dwordx4 v[92:93], v[22:25], off offset:64
	global_store_dwordx2 v[2:3], v[10:11], off offset:32
	v_add_f32_e32 v10, v12, v6
	v_mul_f32_e32 v6, v76, v20
	v_mul_f32_e32 v7, v77, v21
	v_mul_f32_e32 v8, v74, v18
	v_mul_f32_e32 v9, v75, v19
	v_add_f32_e32 v16, v4, v36
	v_add_f32_e32 v17, v5, v37
	v_cvt_pk_bf16_f32 v8, v8, v9
	v_cvt_pk_bf16_f32 v9, v6, v7
	v_mul_f32_e32 v6, v15, v15
	v_mul_f32_e32 v7, v17, v17
	v_fmac_f32_e32 v6, v14, v14
	v_fmac_f32_e32 v7, v16, v16
	v_add_f32_e32 v6, v6, v7
	global_store_dwordx4 v[92:93], v[18:21], off offset:512
	global_store_dwordx2 v[2:3], v[8:9], off offset:256
	v_add_f32_e32 v8, v10, v6
	ds_swizzle_b32 v9, v8 offset:swizzle(SWAP,16)
	v_mul_f32_e32 v6, v62, v14
	v_mul_f32_e32 v7, v63, v15
	global_store_dwordx4 v[92:93], v[14:17], off offset:576
	v_mul_f32_e32 v4, v64, v16
	v_mul_f32_e32 v5, v65, v17
	v_cvt_pk_bf16_f32 v6, v6, v7
	s_nop 0
	v_cvt_pk_bf16_f32 v7, v4, v5
	global_store_dwordx2 v[2:3], v[6:7], off offset:288
	s_waitcnt lgkmcnt(0)
	v_add_f32_e32 v2, v8, v9
	v_mov_b32_e32 v3, v2
	s_nop 1
	v_permlane32_swap_b32_e32 v2, v3
	s_and_saveexec_b64 s[28:29], s[8:9]
	s_cbranch_execz .LBB0_1025
	v_add_f32_e32 v2, v2, v3
	s_mov_b32 s8, 0x49800000
	v_fma_f32 v2, v2, s8, 0.5
	v_trunc_f32_e32 v2, v2
	v_mul_f32_e32 v3, 0x2f800000, v2
	v_floor_f32_e32 v3, v3
	v_fmac_f32_e32 v2, 0xcf800000, v3
	v_cvt_u32_f32_e32 v2, v2
	v_cvt_u32_f32_e32 v3, v3
	v_lshl_add_u64 v[4:5], v[90:91], 3, s[10:11]
	global_atomic_add_x2 v[4:5], v[2:3], off

; #define GAS __attribute__((address_space(1)))
; __device__ __forceinline__ float wave_sum(float v) { return sum_x32(sum_row32(v)); }
; __device__ __forceinline__ void final_norm_phase(gfl* x, const gfl* g, int gw, int NGW, int lane) {
;     ...
;     for (int m = gw; m < MG; m += NGW) {
;         const int mn = m + NGW < MG ? m + NGW : m;
;         { const GAS f32x4* xr = (const GAS f32x4*)(x + (size_t)mn * DM) + lane;
; #pragma unroll
;           for (int j = 0; j < 4; ++j) vn[j] = xr[64 * j]; }
;         float s = 0.f;
; #pragma unroll
;         for (int j = 0; j < 4; ++j) s += (v[j].x * v[j].x + v[j].y * v[j].y) + (v[j].z * v[j].z + v[j].w * v[j].w);
;         const float rstd = __builtin_amdgcn_rsqf(wave_sum(s) * (1.f / DM) + EPS);
;         GAS f32x4* xw = (GAS f32x4*)(x + (size_t)m * DM) + lane;
; #pragma unroll
;         for (int j = 0; j < 4; ++j) xw[64 * j] = v[j] * rstd * gv[j];
; #pragma unroll
;         for (int j = 0; j < 4; ++j) v[j] = vn[j];
;     }
.LBB0_1085:
	s_add_i32 s0, s8, s4
	s_cmp_lt_i32 s0, 0x10000
	s_cselect_b64 s[10:11], -1, 0
	s_and_b64 vcc, s[10:11], exec
	s_cselect_b32 s8, s0, s8
	s_ashr_i32 s9, s8, 31
	s_lshl_b64 s[8:9], s[8:9], 12
	v_lshl_add_u64 v[18:19], v[50:51], 0, s[8:9]
	global_load_dwordx4 v[30:33], v[18:19], off
	global_load_dwordx4 v[26:29], v[18:19], off offset:1024
	global_load_dwordx4 v[22:25], v[18:19], off offset:2048
	s_nop 0
	global_load_dwordx4 v[18:21], v[18:19], off offset:3072
	s_waitcnt vmcnt(5)
	v_mul_f32_e32 v57, v43, v43
	v_mul_f32_e32 v58, v45, v45
	v_fmac_f32_e32 v57, v42, v42
	v_fmac_f32_e32 v58, v44, v44
	v_add_f32_e32 v57, v57, v58
	s_waitcnt vmcnt(4)
	v_mul_f32_e32 v58, v47, v47
	v_mul_f32_e32 v59, v49, v49
	v_fmac_f32_e32 v58, v46, v46
	v_fmac_f32_e32 v59, v48, v48
	v_add_f32_e32 v58, v58, v59
	v_add_f32_e32 v57, v57, v58
	v_mul_f32_e32 v58, v39, v39
	v_mul_f32_e32 v59, v41, v41
	v_fmac_f32_e32 v58, v38, v38
	v_fmac_f32_e32 v59, v40, v40
	v_mul_f32_e32 v56, v56, v56
	v_mul_f32_e32 v54, v54, v54
	v_add_f32_e32 v58, v58, v59
	v_fmac_f32_e32 v56, v55, v55
	v_fmac_f32_e32 v54, v0, v0
	v_add_f32_e32 v57, v58, v57
	v_add_f32_e32 v0, v56, v54
	v_add_f32_e32 v0, v0, v57
	ds_swizzle_b32 v54, v0 offset:swizzle(SWAP,1)
	s_mov_b32 s8, s0
	s_waitcnt lgkmcnt(0)
	v_add_f32_e32 v0, v0, v54
	ds_swizzle_b32 v54, v0 offset:swizzle(SWAP,2)
	s_waitcnt lgkmcnt(0)
	v_add_f32_e32 v0, v0, v54
	ds_swizzle_b32 v54, v0 offset:swizzle(SWAP,4)
	s_waitcnt lgkmcnt(0)
	v_add_f32_e32 v0, v0, v54
	ds_swizzle_b32 v54, v0 offset:swizzle(SWAP,8)
	s_waitcnt lgkmcnt(0)
	v_add_f32_e32 v0, v0, v54
	ds_swizzle_b32 v54, v0 offset:swizzle(SWAP,16)
	s_waitcnt lgkmcnt(0)
	v_add_f32_e32 v0, v0, v54
	v_mov_b32_e32 v54, v0
	s_nop 1
	v_permlane32_swap_b32_e32 v0, v54
	v_add_f32_e32 v0, v0, v54
	v_fmamk_f32 v0, v0, 0x3a800000, v218
	v_rsq_f32_e32 v0, v0
	s_waitcnt vmcnt(0)
	v_mov_b32_e32 v55, v18
	v_mul_f32_e32 v42, v42, v0
	v_mul_f32_e32 v43, v43, v0
	v_mul_f32_e32 v44, v44, v0
	v_mul_f32_e32 v45, v45, v0
	v_mul_f32_e32 v42, v2, v42
	v_mul_f32_e32 v43, v3, v43
	v_mul_f32_e32 v44, v4, v44
	v_mul_f32_e32 v45, v5, v45
	v_mul_f32_e32 v34, v34, v0
	v_mul_f32_e32 v35, v35, v0
	v_mul_f32_e32 v36, v36, v0
	v_mul_f32_e32 v37, v37, v0
	global_store_dwordx4 v[52:53], v[42:45], off offset:-2048
	v_mul_f32_e32 v38, v38, v0
	v_mul_f32_e32 v39, v39, v0
	v_mul_f32_e32 v40, v40, v0
	v_mul_f32_e32 v41, v41, v0
	v_mul_f32_e32 v42, v46, v0
	v_mul_f32_e32 v43, v47, v0
	v_mul_f32_e32 v44, v48, v0
	v_mul_f32_e32 v45, v49, v0
	v_mul_f32_e32 v36, v16, v36
	v_mul_f32_e32 v37, v17, v37
	v_mul_f32_e32 v34, v14, v34
	v_mul_f32_e32 v35, v15, v35
	v_mul_f32_e32 v44, v8, v44
	v_mul_f32_e32 v45, v9, v45
	v_mul_f32_e32 v42, v6, v42
	v_mul_f32_e32 v43, v7, v43
	v_mul_f32_e32 v40, v12, v40
	v_mul_f32_e32 v41, v13, v41
	v_mul_f32_e32 v38, v10, v38
	v_mul_f32_e32 v39, v11, v39
	global_store_dwordx4 v[52:53], v[34:37], off offset:1024
	global_store_dwordx4 v[52:53], v[42:45], off offset:-1024
	global_store_dwordx4 v[52:53], v[38:41], off
	v_mov_b64_e32 v[36:37], v[20:21]
	v_lshl_add_u64 v[52:53], v[52:53], 0, s[6:7]
	v_mov_b64_e32 v[34:35], v[18:19]
	v_mov_b32_e32 v42, v30
	v_mov_b32_e32 v43, v31
	v_mov_b32_e32 v44, v32
	v_mov_b32_e32 v45, v33
	v_mov_b32_e32 v46, v26
	v_mov_b32_e32 v47, v27
	v_mov_b32_e32 v48, v28
	v_mov_b32_e32 v49, v29
	v_mov_b32_e32 v38, v22
	v_mov_b32_e32 v39, v23
	v_mov_b32_e32 v40, v24
	v_mov_b32_e32 v41, v25
	v_mov_b32_e32 v56, v19
	v_mov_b32_e32 v0, v20
	v_mov_b32_e32 v54, v21
	s_cbranch_vccnz .LBB0_1085
	s_getpc_b64 s[98:99]
